# GEMM mainloops: the second lgkmcnt(0) wait after each barrier (nothing outstanding there) removed
# baseline (speedup 1.0000x reference)
; #define PG8_STAGE(bufoff, gbase, voff) do { _Pragma("unroll") for (int _i = 0; _i < 2; ++_i) \
;         __builtin_amdgcn_global_load_lds((const unsigned*)((const char*)(gbase) + (voff)[_i]), (PG8_LAS unsigned*)(lds + (bufoff) + ldsw + _i * 8192), 16, 0, 0); } while (0)
; #define PG8_WAIT_V(n) asm volatile("s_waitcnt vmcnt(" #n ")" ::: "memory")
; #define PG8_WAIT_L(n) asm volatile("s_waitcnt lgkmcnt(" #n ")" ::: "memory")
; #define PG8_BAR __builtin_amdgcn_s_barrier()
; #define PG8_SCHED __builtin_amdgcn_sched_barrier(0)
; template <class Epi, class Sched, bool ALIGN_EPI = false, bool SP2 = false, bool F8 = false>
; __device__ __forceinline__ void gemm_phase(PG8_LAS unsigned char* lds, const Gemm g, const Sched& S, const Epi& E) {
;     ...
;         const bool has_next = S.next(ui + 1, nxt);
;         const char* nA = has_next ? (const char*)g.A + (size_t)nxt.pm * tstep : cA; const char* nB = has_next ? (const char*)g.Bt + (size_t)nxt.pn * tstep : cB;
;         for (int t = 0; t < nt; t += 2) {
;             const bool last = (t == nt - 2);
;             const char* a1 = cA + (size_t)(t + 1) * kstep;
;             const char* a2 = last ? nA : cA + (size_t)(t + 2) * kstep; const char* b2 = last ? nB : cB + (size_t)(t + 2) * kstep;
;             const char* a3 = a2 + kstep; const char* b3 = b2 + kstep;
;             if (last && has_next) S.a_ready(nxt);
;             if constexpr (SP2) {
;             PG8_LDB(B0, 0, 0); PG8_LDB(B1, 0, 1); PG8_SCHED; PG8_LDA(At, 0, 0); PG8_STAGE(PG8_SA(1, 1), a1 + hstep, voffA);
;             PG8_WAIT_V(8); PG8_WAIT_L(0); PG8_BAR; PG8_MMA(0, 0, At, B0); PG8_MMA(0, 1, At, B1); PG8_BAR; PG8_SCHED;
;             PG8_LDA(At, 0, 1); PG8_STAGE(PG8_SB(0, 0), b2, voffB); PG8_STAGE(PG8_SB(0, 1), b2 + hstep, voffB); PG8_STAGE(PG8_SA(0, 0), a2, voffA);
;             PG8_WAIT_V(8); PG8_WAIT_L(0); PG8_BAR; PG8_MMA(1, 0, At, B0); PG8_MMA(1, 1, At, B1); PG8_BAR; PG8_SCHED;
.LBB0_31:
	s_ashr_i32 s47, s46, 31
	s_lshl_b64 s[16:17], s[46:47], 20
	v_readlane_b32 s28, v251, 7
	v_readlane_b32 s29, v251, 8
	s_add_u32 s48, s28, s16
	s_addc_u32 s49, s29, s17
	s_and_b64 s[16:17], s[38:39], exec
	s_cselect_b32 s19, s49, s1
	s_cselect_b32 s23, s48, s0
	s_ashr_i32 s45, s44, 31
	s_lshl_b64 s[16:17], s[44:45], 20
	s_add_u32 s50, s13, s16
	s_addc_u32 s51, s22, s17
	s_and_b64 s[16:17], s[38:39], exec
	s_cselect_b32 s28, s51, s11
	s_cselect_b32 s29, s50, s10
	s_add_u32 s0, s0, 0x80080
	s_addc_u32 s1, s1, 0
	s_add_u32 s45, s10, 0x100
	s_addc_u32 s47, s11, 0
	s_mov_b32 s52, -2
	s_add_u32 s10, s0, 0xfff80080
	s_addc_u32 s11, s1, -1
	s_add_i32 s53, 0, 0x10000
	s_cmp_eq_u32 s52, 28
	s_cselect_b32 s17, s19, s11
	s_cselect_b32 s16, s23, s10
	v_add_u32_e32 v146, s53, v149
	s_cselect_b32 s11, s28, s47
	s_cselect_b32 s10, s29, s45
	s_add_i32 s56, 0, 0x14000
	ds_read_b128 v[138:141], v146
	ds_read_b128 v[142:145], v146 offset:1024
	ds_read_b128 v[152:155], v146 offset:2048
	ds_read_b128 v[156:159], v146 offset:3072
	v_add_u32_e32 v146, s56, v149
	ds_read_b128 v[184:187], v146
	ds_read_b128 v[188:191], v146 offset:1024
	ds_read_b128 v[192:195], v146 offset:2048
	ds_read_b128 v[196:199], v146 offset:3072
	v_lshl_add_u64 v[146:147], s[0:1], 0, v[134:135]
	s_add_i32 m0, s35, 0xc000
	ds_read_b128 v[200:203], v151
	ds_read_b128 v[214:217], v151 offset:1024
	ds_read_b128 v[218:221], v151 offset:2048
	ds_read_b128 v[222:225], v151 offset:3072
	ds_read_b128 v[226:229], v151 offset:4096
	ds_read_b128 v[230:233], v151 offset:5120
	ds_read_b128 v[234:237], v151 offset:6144
	ds_read_b128 v[238:241], v151 offset:7168
	global_load_lds_dwordx4 v[146:147], off
	v_lshl_add_u64 v[146:147], s[0:1], 0, v[136:137]
	s_add_i32 m0, s35, 0xe000
	s_nop 0
	global_load_lds_dwordx4 v[146:147], off
	s_waitcnt vmcnt(8)
	s_waitcnt lgkmcnt(0)
	s_barrier
	s_setprio 1
	v_mfma_f32_16x16x32_bf16 v[124:127], v[138:141], v[200:203], 0
	v_mfma_f32_16x16x32_bf16 v[120:123], v[152:155], v[200:203], 0
	v_mfma_f32_16x16x32_bf16 v[108:111], v[138:141], v[218:221], 0
	v_mfma_f32_16x16x32_bf16 v[104:107], v[152:155], v[218:221], 0
	v_mfma_f32_16x16x32_bf16 v[92:95], v[138:141], v[226:229], 0
	v_mfma_f32_16x16x32_bf16 v[88:91], v[152:155], v[226:229], 0
	v_mfma_f32_16x16x32_bf16 v[76:79], v[138:141], v[234:237], 0
	v_mfma_f32_16x16x32_bf16 v[72:75], v[152:155], v[234:237], 0
	v_mfma_f32_16x16x32_bf16 v[124:127], v[142:145], v[214:217], v[124:127]
	v_mfma_f32_16x16x32_bf16 v[120:123], v[156:159], v[214:217], v[120:123]
	v_mfma_f32_16x16x32_bf16 v[108:111], v[142:145], v[222:225], v[108:111]
	v_mfma_f32_16x16x32_bf16 v[104:107], v[156:159], v[222:225], v[104:107]
	v_mfma_f32_16x16x32_bf16 v[92:95], v[142:145], v[230:233], v[92:95]
	v_mfma_f32_16x16x32_bf16 v[88:91], v[156:159], v[230:233], v[88:91]
	v_mfma_f32_16x16x32_bf16 v[76:79], v[142:145], v[238:241], v[76:79]
	v_mfma_f32_16x16x32_bf16 v[72:75], v[156:159], v[238:241], v[72:75]
	s_setprio 0
	s_setprio 1
	v_mfma_f32_16x16x32_bf16 v[116:119], v[184:187], v[200:203], 0
	v_mfma_f32_16x16x32_bf16 v[112:115], v[192:195], v[200:203], 0
	v_mfma_f32_16x16x32_bf16 v[100:103], v[184:187], v[218:221], 0
	v_mfma_f32_16x16x32_bf16 v[96:99], v[192:195], v[218:221], 0
	v_mfma_f32_16x16x32_bf16 v[84:87], v[184:187], v[226:229], 0
	v_mfma_f32_16x16x32_bf16 v[80:83], v[192:195], v[226:229], 0
	v_mfma_f32_16x16x32_bf16 v[68:71], v[184:187], v[234:237], 0
	v_mfma_f32_16x16x32_bf16 v[64:67], v[192:195], v[234:237], 0
	v_mfma_f32_16x16x32_bf16 v[116:119], v[188:191], v[214:217], v[116:119]
	v_mfma_f32_16x16x32_bf16 v[112:115], v[196:199], v[214:217], v[112:115]
	v_mfma_f32_16x16x32_bf16 v[100:103], v[188:191], v[222:225], v[100:103]
	v_mfma_f32_16x16x32_bf16 v[96:99], v[196:199], v[222:225], v[96:99]
	v_mfma_f32_16x16x32_bf16 v[84:87], v[188:191], v[230:233], v[84:87]
	v_mfma_f32_16x16x32_bf16 v[80:83], v[196:199], v[230:233], v[80:83]
	v_mfma_f32_16x16x32_bf16 v[68:71], v[188:191], v[238:241], v[68:71]
	v_mfma_f32_16x16x32_bf16 v[64:67], v[196:199], v[238:241], v[64:67]
	s_setprio 0
	s_barrier
	s_add_i32 s53, s53, s34
	v_lshl_add_u64 v[146:147], s[10:11], 0, v[160:161]
	s_mov_b32 m0, s53
	ds_read_b128 v[200:203], v151 offset:16384
	ds_read_b128 v[214:217], v151 offset:17408
	ds_read_b128 v[218:221], v151 offset:18432
	ds_read_b128 v[222:225], v151 offset:19456
	ds_read_b128 v[226:229], v151 offset:20480
	ds_read_b128 v[230:233], v151 offset:21504
	ds_read_b128 v[234:237], v151 offset:22528
	ds_read_b128 v[238:241], v151 offset:23552
	global_load_lds_dwordx4 v[146:147], off
	s_add_i32 m0, s53, 0x2000
	s_add_u32 s60, s10, 0x80000
	v_lshl_add_u64 v[162:163], s[10:11], 0, v[128:129]
	s_addc_u32 s61, s11, 0
	s_add_i32 s53, s56, s34
	global_load_lds_dwordx4 v[162:163], off
	v_lshl_add_u64 v[242:243], s[60:61], 0, v[160:161]
	s_mov_b32 m0, s53
	v_lshl_add_u64 v[244:245], s[16:17], 0, v[130:131]
	global_load_lds_dwordx4 v[242:243], off
	v_lshl_add_u64 v[242:243], s[60:61], 0, v[128:129]
	s_add_i32 m0, s53, 0x2000
	s_nop 0
	global_load_lds_dwordx4 v[242:243], off
	v_lshl_add_u64 v[242:243], s[16:17], 0, v[132:133]
	s_mov_b32 m0, s35
	s_nop 0
	global_load_lds_dwordx4 v[242:243], off
	s_mov_b32 m0, s36
	s_nop 0
	global_load_lds_dwordx4 v[244:245], off
	s_waitcnt vmcnt(8)
	s_waitcnt lgkmcnt(0)
	s_barrier
; #define PG8_STAGE(bufoff, gbase, voff) do { _Pragma("unroll") for (int _i = 0; _i < 2; ++_i) \
;         __builtin_amdgcn_global_load_lds((const unsigned*)((const char*)(gbase) + (voff)[_i]), (PG8_LAS unsigned*)(lds + (bufoff) + ldsw + _i * 8192), 16, 0, 0); } while (0)
; #define PG8_WAIT_V(n) asm volatile("s_waitcnt vmcnt(" #n ")" ::: "memory")
; #define PG8_WAIT_L(n) asm volatile("s_waitcnt lgkmcnt(" #n ")" ::: "memory")
; #define PG8_BAR __builtin_amdgcn_s_barrier()
; #define PG8_SCHED __builtin_amdgcn_sched_barrier(0)
; template <class Epi, class Sched, bool ALIGN_EPI = false, bool SP2 = false, bool F8 = false>
; __device__ __forceinline__ void gemm_phase(PG8_LAS unsigned char* lds, const Gemm g, const Sched& S, const Epi& E) {
;     ...
;             PG8_WAIT_V(8); PG8_WAIT_L(0); PG8_BAR; PG8_MMA(1, 0, At, B0); PG8_MMA(1, 1, At, B1); PG8_BAR; PG8_SCHED;
;             PG8_LDB(B0, 1, 0); PG8_LDB(B1, 1, 1); PG8_SCHED; PG8_LDA(At, 1, 0); PG8_STAGE(PG8_SA(0, 1), a2 + hstep, voffA);
;             PG8_WAIT_V(8); PG8_WAIT_L(0); PG8_BAR; PG8_MMA(0, 0, At, B0); PG8_MMA(0, 1, At, B1); PG8_BAR; PG8_SCHED;
	s_setprio 1
	v_mfma_f32_16x16x32_bf16 v[60:63], v[138:141], v[200:203], 0
	v_mfma_f32_16x16x32_bf16 v[56:59], v[152:155], v[200:203], 0
	v_mfma_f32_16x16x32_bf16 v[44:47], v[138:141], v[218:221], 0
	v_mfma_f32_16x16x32_bf16 v[40:43], v[152:155], v[218:221], 0
	v_mfma_f32_16x16x32_bf16 v[28:31], v[138:141], v[226:229], 0
	v_mfma_f32_16x16x32_bf16 v[24:27], v[152:155], v[226:229], 0
	v_mfma_f32_16x16x32_bf16 v[12:15], v[138:141], v[234:237], 0
	v_mfma_f32_16x16x32_bf16 v[8:11], v[152:155], v[234:237], 0
	v_mfma_f32_16x16x32_bf16 v[60:63], v[142:145], v[214:217], v[60:63]
	v_mfma_f32_16x16x32_bf16 v[56:59], v[156:159], v[214:217], v[56:59]
	v_mfma_f32_16x16x32_bf16 v[44:47], v[142:145], v[222:225], v[44:47]
	v_mfma_f32_16x16x32_bf16 v[40:43], v[156:159], v[222:225], v[40:43]
	v_mfma_f32_16x16x32_bf16 v[28:31], v[142:145], v[230:233], v[28:31]
	v_mfma_f32_16x16x32_bf16 v[24:27], v[156:159], v[230:233], v[24:27]
	v_mfma_f32_16x16x32_bf16 v[12:15], v[142:145], v[238:241], v[12:15]
	v_mfma_f32_16x16x32_bf16 v[8:11], v[156:159], v[238:241], v[8:11]
	s_setprio 0
	s_setprio 1
	v_mfma_f32_16x16x32_bf16 v[52:55], v[184:187], v[200:203], 0
	v_mfma_f32_16x16x32_bf16 v[48:51], v[192:195], v[200:203], 0
	v_mfma_f32_16x16x32_bf16 v[36:39], v[184:187], v[218:221], 0
	v_mfma_f32_16x16x32_bf16 v[32:35], v[192:195], v[218:221], 0
	v_mfma_f32_16x16x32_bf16 v[20:23], v[184:187], v[226:229], 0
	v_mfma_f32_16x16x32_bf16 v[16:19], v[192:195], v[226:229], 0
	v_mfma_f32_16x16x32_bf16 v[4:7], v[184:187], v[234:237], 0
	v_mfma_f32_16x16x32_bf16 v[0:3], v[192:195], v[234:237], 0
	v_mfma_f32_16x16x32_bf16 v[52:55], v[188:191], v[214:217], v[52:55]
	v_mfma_f32_16x16x32_bf16 v[48:51], v[196:199], v[214:217], v[48:51]
	v_mfma_f32_16x16x32_bf16 v[36:39], v[188:191], v[222:225], v[36:39]
	v_mfma_f32_16x16x32_bf16 v[32:35], v[196:199], v[222:225], v[32:35]
	v_mfma_f32_16x16x32_bf16 v[20:23], v[188:191], v[230:233], v[20:23]
	v_mfma_f32_16x16x32_bf16 v[16:19], v[196:199], v[230:233], v[16:19]
	v_mfma_f32_16x16x32_bf16 v[4:7], v[188:191], v[238:241], v[4:7]
	v_mfma_f32_16x16x32_bf16 v[0:3], v[196:199], v[238:241], v[0:3]
	s_setprio 0
	s_barrier
	s_add_i32 s53, 0, 0x18000
	s_add_i32 s56, 0, 0x1c000
	v_add_u32_e32 v156, s53, v149
	v_add_u32_e32 v196, s56, v149
	ds_read_b128 v[138:141], v156
	ds_read_b128 v[142:145], v156 offset:1024
	ds_read_b128 v[152:155], v156 offset:2048
	ds_read_b128 v[156:159], v156 offset:3072
	ds_read_b128 v[184:187], v196
	ds_read_b128 v[188:191], v196 offset:1024
	ds_read_b128 v[192:195], v196 offset:2048
	ds_read_b128 v[196:199], v196 offset:3072
	s_add_u32 s16, s16, 0x80000
	s_addc_u32 s17, s17, 0
	s_mov_b32 m0, s37
	v_lshl_add_u64 v[246:247], s[16:17], 0, v[132:133]
	ds_read_b128 v[200:203], v151 offset:32768
	ds_read_b128 v[214:217], v151 offset:33792
	ds_read_b128 v[218:221], v151 offset:34816
	ds_read_b128 v[222:225], v151 offset:35840
	ds_read_b128 v[226:229], v151 offset:36864
	ds_read_b128 v[230:233], v151 offset:37888
	ds_read_b128 v[234:237], v151 offset:38912
	ds_read_b128 v[238:241], v151 offset:39936
	global_load_lds_dwordx4 v[246:247], off
	v_lshl_add_u64 v[246:247], s[16:17], 0, v[130:131]
	s_mov_b32 m0, s54
	s_nop 0
	global_load_lds_dwordx4 v[246:247], off
	s_waitcnt vmcnt(8)
	s_waitcnt lgkmcnt(0)
	s_barrier
	s_setprio 1
	v_mfma_f32_16x16x32_bf16 v[124:127], v[138:141], v[200:203], v[124:127]
	v_mfma_f32_16x16x32_bf16 v[120:123], v[152:155], v[200:203], v[120:123]
	v_mfma_f32_16x16x32_bf16 v[108:111], v[138:141], v[218:221], v[108:111]
	v_mfma_f32_16x16x32_bf16 v[104:107], v[152:155], v[218:221], v[104:107]
	v_mfma_f32_16x16x32_bf16 v[92:95], v[138:141], v[226:229], v[92:95]
	v_mfma_f32_16x16x32_bf16 v[88:91], v[152:155], v[226:229], v[88:91]
	v_mfma_f32_16x16x32_bf16 v[76:79], v[138:141], v[234:237], v[76:79]
	v_mfma_f32_16x16x32_bf16 v[72:75], v[152:155], v[234:237], v[72:75]
	v_mfma_f32_16x16x32_bf16 v[124:127], v[142:145], v[214:217], v[124:127]
	v_mfma_f32_16x16x32_bf16 v[120:123], v[156:159], v[214:217], v[120:123]
	v_mfma_f32_16x16x32_bf16 v[108:111], v[142:145], v[222:225], v[108:111]
	v_mfma_f32_16x16x32_bf16 v[104:107], v[156:159], v[222:225], v[104:107]
	v_mfma_f32_16x16x32_bf16 v[92:95], v[142:145], v[230:233], v[92:95]
	v_mfma_f32_16x16x32_bf16 v[88:91], v[156:159], v[230:233], v[88:91]
	v_mfma_f32_16x16x32_bf16 v[76:79], v[142:145], v[238:241], v[76:79]
	v_mfma_f32_16x16x32_bf16 v[72:75], v[156:159], v[238:241], v[72:75]
	s_setprio 0
	s_setprio 1
	v_mfma_f32_16x16x32_bf16 v[116:119], v[184:187], v[200:203], v[116:119]
	v_mfma_f32_16x16x32_bf16 v[112:115], v[192:195], v[200:203], v[112:115]
	v_mfma_f32_16x16x32_bf16 v[100:103], v[184:187], v[218:221], v[100:103]
	v_mfma_f32_16x16x32_bf16 v[96:99], v[192:195], v[218:221], v[96:99]
	v_mfma_f32_16x16x32_bf16 v[84:87], v[184:187], v[226:229], v[84:87]
	v_mfma_f32_16x16x32_bf16 v[80:83], v[192:195], v[226:229], v[80:83]
	v_mfma_f32_16x16x32_bf16 v[68:71], v[184:187], v[234:237], v[68:71]
	v_mfma_f32_16x16x32_bf16 v[64:67], v[192:195], v[234:237], v[64:67]
	v_mfma_f32_16x16x32_bf16 v[116:119], v[188:191], v[214:217], v[116:119]
	v_mfma_f32_16x16x32_bf16 v[112:115], v[196:199], v[214:217], v[112:115]
	v_mfma_f32_16x16x32_bf16 v[100:103], v[188:191], v[222:225], v[100:103]
	v_mfma_f32_16x16x32_bf16 v[96:99], v[196:199], v[222:225], v[96:99]
	v_mfma_f32_16x16x32_bf16 v[84:87], v[188:191], v[230:233], v[84:87]
	v_mfma_f32_16x16x32_bf16 v[80:83], v[196:199], v[230:233], v[80:83]
	v_mfma_f32_16x16x32_bf16 v[68:71], v[188:191], v[238:241], v[68:71]
	v_mfma_f32_16x16x32_bf16 v[64:67], v[196:199], v[238:241], v[64:67]
	s_setprio 0
	s_barrier
; #define PG8_STAGE(bufoff, gbase, voff) do { _Pragma("unroll") for (int _i = 0; _i < 2; ++_i) \
;         __builtin_amdgcn_global_load_lds((const unsigned*)((const char*)(gbase) + (voff)[_i]), (PG8_LAS unsigned*)(lds + (bufoff) + ldsw + _i * 8192), 16, 0, 0); } while (0)
; #define PG8_WAIT_V(n) asm volatile("s_waitcnt vmcnt(" #n ")" ::: "memory")
; #define PG8_WAIT_L(n) asm volatile("s_waitcnt lgkmcnt(" #n ")" ::: "memory")
; #define PG8_BAR __builtin_amdgcn_s_barrier()
; #define PG8_SCHED __builtin_amdgcn_sched_barrier(0)
; template <class Epi, class Sched, bool ALIGN_EPI = false, bool SP2 = false, bool F8 = false>
; __device__ __forceinline__ void gemm_phase(PG8_LAS unsigned char* lds, const Gemm g, const Sched& S, const Epi& E) {
;     ...
;             const bool last = (t == nt - 2);
;             const char* a1 = cA + (size_t)(t + 1) * kstep;
;             const char* a2 = last ? nA : cA + (size_t)(t + 2) * kstep; const char* b2 = last ? nB : cB + (size_t)(t + 2) * kstep;
;             const char* a3 = a2 + kstep; const char* b3 = b2 + kstep;
;             if (last && has_next) S.a_ready(nxt);
;             if constexpr (SP2) {
;             PG8_LDB(B0, 0, 0); PG8_LDB(B1, 0, 1); PG8_SCHED; PG8_LDA(At, 0, 0); PG8_STAGE(PG8_SA(1, 1), a1 + hstep, voffA);
;             PG8_WAIT_V(8); PG8_WAIT_L(0); PG8_BAR; PG8_MMA(0, 0, At, B0); PG8_MMA(0, 1, At, B1); PG8_BAR; PG8_SCHED;
;             PG8_LDA(At, 0, 1); PG8_STAGE(PG8_SB(0, 0), b2, voffB); PG8_STAGE(PG8_SB(0, 1), b2 + hstep, voffB); PG8_STAGE(PG8_SA(0, 0), a2, voffA);
;             PG8_WAIT_V(8); PG8_WAIT_L(0); PG8_BAR; PG8_MMA(1, 0, At, B0); PG8_MMA(1, 1, At, B1); PG8_BAR; PG8_SCHED;
;             PG8_LDB(B0, 1, 0); PG8_LDB(B1, 1, 1); PG8_SCHED; PG8_LDA(At, 1, 0); PG8_STAGE(PG8_SA(0, 1), a2 + hstep, voffA);
;             PG8_WAIT_V(8); PG8_WAIT_L(0); PG8_BAR; PG8_MMA(0, 0, At, B0); PG8_MMA(0, 1, At, B1); PG8_BAR; PG8_SCHED;
;             PG8_LDA(At, 1, 1); PG8_STAGE(PG8_SB(1, 0), b3, voffB); PG8_STAGE(PG8_SB(1, 1), b3 + hstep, voffB); PG8_STAGE(PG8_SA(1, 0), a3, voffA);
;             PG8_WAIT_V(8); PG8_WAIT_L(0); PG8_BAR; PG8_MMA(1, 0, At, B0); PG8_MMA(1, 1, At, B1); PG8_BAR; PG8_SCHED;
	s_add_i32 s16, s53, s34
	v_lshl_add_u64 v[146:147], v[146:147], 0, s[14:15]
	s_mov_b32 m0, s16
	ds_read_b128 v[200:203], v151 offset:49152
	ds_read_b128 v[214:217], v151 offset:50176
	ds_read_b128 v[218:221], v151 offset:51200
	ds_read_b128 v[222:225], v151 offset:52224
	ds_read_b128 v[226:229], v151 offset:53248
	ds_read_b128 v[230:233], v151 offset:54272
	ds_read_b128 v[234:237], v151 offset:55296
	ds_read_b128 v[238:241], v151 offset:56320
	global_load_lds_dwordx4 v[146:147], off
	s_add_i32 m0, s16, 0x2000
	s_add_u32 s10, s10, 0x80080
	v_lshl_add_u64 v[146:147], v[162:163], 0, s[14:15]
	s_addc_u32 s11, s11, 0
	s_add_i32 s16, s56, s34
	global_load_lds_dwordx4 v[146:147], off
	v_lshl_add_u64 v[146:147], s[10:11], 0, v[160:161]
	s_mov_b32 m0, s16
	s_nop 0
	global_load_lds_dwordx4 v[146:147], off
	v_lshl_add_u64 v[146:147], s[10:11], 0, v[128:129]
	s_add_i32 m0, s16, 0x2000
	s_nop 0
	global_load_lds_dwordx4 v[146:147], off
	v_lshl_add_u64 v[146:147], v[242:243], 0, s[14:15]
	s_mov_b32 m0, s55
	s_nop 0
	global_load_lds_dwordx4 v[146:147], off
	v_lshl_add_u64 v[146:147], v[244:245], 0, s[14:15]
	s_mov_b32 m0, s58
	s_nop 0
	global_load_lds_dwordx4 v[146:147], off
	s_waitcnt vmcnt(8)
	s_waitcnt lgkmcnt(0)
	s_barrier
	s_setprio 1
	v_mfma_f32_16x16x32_bf16 v[60:63], v[138:141], v[200:203], v[60:63]
	v_mfma_f32_16x16x32_bf16 v[56:59], v[152:155], v[200:203], v[56:59]
	v_mfma_f32_16x16x32_bf16 v[44:47], v[138:141], v[218:221], v[44:47]
	v_mfma_f32_16x16x32_bf16 v[40:43], v[152:155], v[218:221], v[40:43]
	v_mfma_f32_16x16x32_bf16 v[28:31], v[138:141], v[226:229], v[28:31]
	v_mfma_f32_16x16x32_bf16 v[24:27], v[152:155], v[226:229], v[24:27]
	v_mfma_f32_16x16x32_bf16 v[12:15], v[138:141], v[234:237], v[12:15]
	v_mfma_f32_16x16x32_bf16 v[8:11], v[152:155], v[234:237], v[8:11]
	v_mfma_f32_16x16x32_bf16 v[60:63], v[142:145], v[214:217], v[60:63]
	v_mfma_f32_16x16x32_bf16 v[56:59], v[156:159], v[214:217], v[56:59]
	v_mfma_f32_16x16x32_bf16 v[44:47], v[142:145], v[222:225], v[44:47]
	v_mfma_f32_16x16x32_bf16 v[40:43], v[156:159], v[222:225], v[40:43]
	v_mfma_f32_16x16x32_bf16 v[28:31], v[142:145], v[230:233], v[28:31]
	v_mfma_f32_16x16x32_bf16 v[24:27], v[156:159], v[230:233], v[24:27]
	v_mfma_f32_16x16x32_bf16 v[12:15], v[142:145], v[238:241], v[12:15]
	v_mfma_f32_16x16x32_bf16 v[8:11], v[156:159], v[238:241], v[8:11]
	s_setprio 0
	s_setprio 1
	v_mfma_f32_16x16x32_bf16 v[52:55], v[184:187], v[200:203], v[52:55]
	v_mfma_f32_16x16x32_bf16 v[48:51], v[192:195], v[200:203], v[48:51]
	v_mfma_f32_16x16x32_bf16 v[36:39], v[184:187], v[218:221], v[36:39]
	v_mfma_f32_16x16x32_bf16 v[32:35], v[192:195], v[218:221], v[32:35]
	v_mfma_f32_16x16x32_bf16 v[20:23], v[184:187], v[226:229], v[20:23]
	v_mfma_f32_16x16x32_bf16 v[16:19], v[192:195], v[226:229], v[16:19]
	v_mfma_f32_16x16x32_bf16 v[4:7], v[184:187], v[234:237], v[4:7]
	v_mfma_f32_16x16x32_bf16 v[0:3], v[192:195], v[234:237], v[0:3]
	v_mfma_f32_16x16x32_bf16 v[52:55], v[188:191], v[214:217], v[52:55]
	v_mfma_f32_16x16x32_bf16 v[48:51], v[196:199], v[214:217], v[48:51]
	v_mfma_f32_16x16x32_bf16 v[36:39], v[188:191], v[222:225], v[36:39]
	v_mfma_f32_16x16x32_bf16 v[32:35], v[196:199], v[222:225], v[32:35]
	v_mfma_f32_16x16x32_bf16 v[20:23], v[188:191], v[230:233], v[20:23]
	v_mfma_f32_16x16x32_bf16 v[16:19], v[196:199], v[230:233], v[16:19]
	v_mfma_f32_16x16x32_bf16 v[4:7], v[188:191], v[238:241], v[4:7]
	v_mfma_f32_16x16x32_bf16 v[0:3], v[196:199], v[238:241], v[0:3]
	s_setprio 0
	s_barrier
	s_add_i32 s52, s52, 2
	s_add_u32 s0, s0, 0x100
	s_addc_u32 s1, s1, 0
	s_add_u32 s45, s45, 0x100
	s_addc_u32 s47, s47, 0
	s_cmp_gt_u32 s52, 29
	s_cbranch_scc0 .LBB0_32
	s_branch .Lgk_after_32
.LBB0_32:
	s_add_u32 s10, s0, 0xfff80080
	s_addc_u32 s11, s1, -1
	s_add_i32 s53, 0, 0x10000
	s_cmp_eq_u32 s52, 28
	s_cselect_b32 s17, s19, s11
	s_cselect_b32 s16, s23, s10
	v_add_u32_e32 v146, s53, v149
	s_cselect_b32 s11, s28, s47
	s_cselect_b32 s10, s29, s45
	s_add_i32 s56, 0, 0x14000
	ds_read_b128 v[138:141], v146
	ds_read_b128 v[142:145], v146 offset:1024
	ds_read_b128 v[152:155], v146 offset:2048
	ds_read_b128 v[156:159], v146 offset:3072
	v_add_u32_e32 v146, s56, v149
	ds_read_b128 v[184:187], v146
	ds_read_b128 v[188:191], v146 offset:1024
	ds_read_b128 v[192:195], v146 offset:2048
	ds_read_b128 v[196:199], v146 offset:3072
	v_lshl_add_u64 v[146:147], s[0:1], 0, v[134:135]
	s_add_i32 m0, s35, 0xc000
	ds_read_b128 v[200:203], v151
	ds_read_b128 v[214:217], v151 offset:1024
	ds_read_b128 v[218:221], v151 offset:2048
	ds_read_b128 v[222:225], v151 offset:3072
	ds_read_b128 v[226:229], v151 offset:4096
	ds_read_b128 v[230:233], v151 offset:5120
	ds_read_b128 v[234:237], v151 offset:6144
	ds_read_b128 v[238:241], v151 offset:7168
	global_load_lds_dwordx4 v[146:147], off
	v_lshl_add_u64 v[146:147], s[0:1], 0, v[136:137]
	s_add_i32 m0, s35, 0xe000
	s_nop 0
	global_load_lds_dwordx4 v[146:147], off
	s_waitcnt vmcnt(8)
	s_waitcnt lgkmcnt(0)
	s_barrier
; #define PG8_STAGE(bufoff, gbase, voff) do { _Pragma("unroll") for (int _i = 0; _i < 2; ++_i) \
;         __builtin_amdgcn_global_load_lds((const unsigned*)((const char*)(gbase) + (voff)[_i]), (PG8_LAS unsigned*)(lds + (bufoff) + ldsw + _i * 8192), 16, 0, 0); } while (0)
; #define PG8_WAIT_V(n) asm volatile("s_waitcnt vmcnt(" #n ")" ::: "memory")
; #define PG8_WAIT_L(n) asm volatile("s_waitcnt lgkmcnt(" #n ")" ::: "memory")
; #define PG8_BAR __builtin_amdgcn_s_barrier()
; #define PG8_SCHED __builtin_amdgcn_sched_barrier(0)
; template <class Epi, class Sched, bool ALIGN_EPI = false, bool SP2 = false, bool F8 = false>
; __device__ __forceinline__ void gemm_phase(PG8_LAS unsigned char* lds, const Gemm g, const Sched& S, const Epi& E) {
;     ...
;             PG8_LDB(B0, 0, 0); PG8_LDB(B1, 0, 1); PG8_SCHED; PG8_LDA(At, 0, 0); PG8_STAGE(PG8_SA(1, 1), a1 + hstep, voffA);
;             PG8_WAIT_V(8); PG8_WAIT_L(0); PG8_BAR; PG8_MMA(0, 0, At, B0); PG8_MMA(0, 1, At, B1); PG8_BAR; PG8_SCHED;
;             PG8_LDA(At, 0, 1); PG8_STAGE(PG8_SB(0, 0), b2, voffB); PG8_STAGE(PG8_SB(0, 1), b2 + hstep, voffB); PG8_STAGE(PG8_SA(0, 0), a2, voffA);
;             PG8_WAIT_V(8); PG8_WAIT_L(0); PG8_BAR; PG8_MMA(1, 0, At, B0); PG8_MMA(1, 1, At, B1); PG8_BAR; PG8_SCHED;
	s_setprio 1
	v_mfma_f32_16x16x32_bf16 v[124:127], v[138:141], v[200:203], v[124:127]
	v_mfma_f32_16x16x32_bf16 v[120:123], v[152:155], v[200:203], v[120:123]
	v_mfma_f32_16x16x32_bf16 v[108:111], v[138:141], v[218:221], v[108:111]
	v_mfma_f32_16x16x32_bf16 v[104:107], v[152:155], v[218:221], v[104:107]
	v_mfma_f32_16x16x32_bf16 v[92:95], v[138:141], v[226:229], v[92:95]
	v_mfma_f32_16x16x32_bf16 v[88:91], v[152:155], v[226:229], v[88:91]
	v_mfma_f32_16x16x32_bf16 v[76:79], v[138:141], v[234:237], v[76:79]
	v_mfma_f32_16x16x32_bf16 v[72:75], v[152:155], v[234:237], v[72:75]
	v_mfma_f32_16x16x32_bf16 v[124:127], v[142:145], v[214:217], v[124:127]
	v_mfma_f32_16x16x32_bf16 v[120:123], v[156:159], v[214:217], v[120:123]
	v_mfma_f32_16x16x32_bf16 v[108:111], v[142:145], v[222:225], v[108:111]
	v_mfma_f32_16x16x32_bf16 v[104:107], v[156:159], v[222:225], v[104:107]
	v_mfma_f32_16x16x32_bf16 v[92:95], v[142:145], v[230:233], v[92:95]
	v_mfma_f32_16x16x32_bf16 v[88:91], v[156:159], v[230:233], v[88:91]
	v_mfma_f32_16x16x32_bf16 v[76:79], v[142:145], v[238:241], v[76:79]
	v_mfma_f32_16x16x32_bf16 v[72:75], v[156:159], v[238:241], v[72:75]
	s_setprio 0
	s_setprio 1
	v_mfma_f32_16x16x32_bf16 v[116:119], v[184:187], v[200:203], v[116:119]
	v_mfma_f32_16x16x32_bf16 v[112:115], v[192:195], v[200:203], v[112:115]
	v_mfma_f32_16x16x32_bf16 v[100:103], v[184:187], v[218:221], v[100:103]
	v_mfma_f32_16x16x32_bf16 v[96:99], v[192:195], v[218:221], v[96:99]
	v_mfma_f32_16x16x32_bf16 v[84:87], v[184:187], v[226:229], v[84:87]
	v_mfma_f32_16x16x32_bf16 v[80:83], v[192:195], v[226:229], v[80:83]
	v_mfma_f32_16x16x32_bf16 v[68:71], v[184:187], v[234:237], v[68:71]
	v_mfma_f32_16x16x32_bf16 v[64:67], v[192:195], v[234:237], v[64:67]
	v_mfma_f32_16x16x32_bf16 v[116:119], v[188:191], v[214:217], v[116:119]
	v_mfma_f32_16x16x32_bf16 v[112:115], v[196:199], v[214:217], v[112:115]
	v_mfma_f32_16x16x32_bf16 v[100:103], v[188:191], v[222:225], v[100:103]
	v_mfma_f32_16x16x32_bf16 v[96:99], v[196:199], v[222:225], v[96:99]
	v_mfma_f32_16x16x32_bf16 v[84:87], v[188:191], v[230:233], v[84:87]
	v_mfma_f32_16x16x32_bf16 v[80:83], v[196:199], v[230:233], v[80:83]
	v_mfma_f32_16x16x32_bf16 v[68:71], v[188:191], v[238:241], v[68:71]
	v_mfma_f32_16x16x32_bf16 v[64:67], v[196:199], v[238:241], v[64:67]
	s_setprio 0
	s_barrier
	s_add_i32 s53, s53, s34
	v_lshl_add_u64 v[146:147], s[10:11], 0, v[160:161]
	s_mov_b32 m0, s53
	ds_read_b128 v[200:203], v151 offset:16384
	ds_read_b128 v[214:217], v151 offset:17408
	ds_read_b128 v[218:221], v151 offset:18432
	ds_read_b128 v[222:225], v151 offset:19456
	ds_read_b128 v[226:229], v151 offset:20480
	ds_read_b128 v[230:233], v151 offset:21504
	ds_read_b128 v[234:237], v151 offset:22528
	ds_read_b128 v[238:241], v151 offset:23552
	global_load_lds_dwordx4 v[146:147], off
	s_add_i32 m0, s53, 0x2000
	s_add_u32 s60, s10, 0x80000
	v_lshl_add_u64 v[162:163], s[10:11], 0, v[128:129]
	s_addc_u32 s61, s11, 0
	s_add_i32 s53, s56, s34
	global_load_lds_dwordx4 v[162:163], off
	v_lshl_add_u64 v[242:243], s[60:61], 0, v[160:161]
	s_mov_b32 m0, s53
	v_lshl_add_u64 v[244:245], s[16:17], 0, v[130:131]
	global_load_lds_dwordx4 v[242:243], off
	v_lshl_add_u64 v[242:243], s[60:61], 0, v[128:129]
	s_add_i32 m0, s53, 0x2000
	s_nop 0
	global_load_lds_dwordx4 v[242:243], off
	v_lshl_add_u64 v[242:243], s[16:17], 0, v[132:133]
	s_mov_b32 m0, s35
	s_nop 0
	global_load_lds_dwordx4 v[242:243], off
	s_mov_b32 m0, s36
	s_nop 0
	global_load_lds_dwordx4 v[244:245], off
	s_waitcnt vmcnt(8)
	s_waitcnt lgkmcnt(0)
	s_barrier
	s_setprio 1
	v_mfma_f32_16x16x32_bf16 v[60:63], v[138:141], v[200:203], v[60:63]
	v_mfma_f32_16x16x32_bf16 v[56:59], v[152:155], v[200:203], v[56:59]
	v_mfma_f32_16x16x32_bf16 v[44:47], v[138:141], v[218:221], v[44:47]
	v_mfma_f32_16x16x32_bf16 v[40:43], v[152:155], v[218:221], v[40:43]
	v_mfma_f32_16x16x32_bf16 v[28:31], v[138:141], v[226:229], v[28:31]
	v_mfma_f32_16x16x32_bf16 v[24:27], v[152:155], v[226:229], v[24:27]
	v_mfma_f32_16x16x32_bf16 v[12:15], v[138:141], v[234:237], v[12:15]
	v_mfma_f32_16x16x32_bf16 v[8:11], v[152:155], v[234:237], v[8:11]
	v_mfma_f32_16x16x32_bf16 v[60:63], v[142:145], v[214:217], v[60:63]
	v_mfma_f32_16x16x32_bf16 v[56:59], v[156:159], v[214:217], v[56:59]
	v_mfma_f32_16x16x32_bf16 v[44:47], v[142:145], v[222:225], v[44:47]
	v_mfma_f32_16x16x32_bf16 v[40:43], v[156:159], v[222:225], v[40:43]
	v_mfma_f32_16x16x32_bf16 v[28:31], v[142:145], v[230:233], v[28:31]
	v_mfma_f32_16x16x32_bf16 v[24:27], v[156:159], v[230:233], v[24:27]
	v_mfma_f32_16x16x32_bf16 v[12:15], v[142:145], v[238:241], v[12:15]
	v_mfma_f32_16x16x32_bf16 v[8:11], v[156:159], v[238:241], v[8:11]
	s_setprio 0
	s_setprio 1
	v_mfma_f32_16x16x32_bf16 v[52:55], v[184:187], v[200:203], v[52:55]
	v_mfma_f32_16x16x32_bf16 v[48:51], v[192:195], v[200:203], v[48:51]
	v_mfma_f32_16x16x32_bf16 v[36:39], v[184:187], v[218:221], v[36:39]
	v_mfma_f32_16x16x32_bf16 v[32:35], v[192:195], v[218:221], v[32:35]
	v_mfma_f32_16x16x32_bf16 v[20:23], v[184:187], v[226:229], v[20:23]
	v_mfma_f32_16x16x32_bf16 v[16:19], v[192:195], v[226:229], v[16:19]
	v_mfma_f32_16x16x32_bf16 v[4:7], v[184:187], v[234:237], v[4:7]
	v_mfma_f32_16x16x32_bf16 v[0:3], v[192:195], v[234:237], v[0:3]
	v_mfma_f32_16x16x32_bf16 v[52:55], v[188:191], v[214:217], v[52:55]
	v_mfma_f32_16x16x32_bf16 v[48:51], v[196:199], v[214:217], v[48:51]
	v_mfma_f32_16x16x32_bf16 v[36:39], v[188:191], v[222:225], v[36:39]
	v_mfma_f32_16x16x32_bf16 v[32:35], v[196:199], v[222:225], v[32:35]
	v_mfma_f32_16x16x32_bf16 v[20:23], v[188:191], v[230:233], v[20:23]
	v_mfma_f32_16x16x32_bf16 v[16:19], v[196:199], v[230:233], v[16:19]
	v_mfma_f32_16x16x32_bf16 v[4:7], v[188:191], v[238:241], v[4:7]
	v_mfma_f32_16x16x32_bf16 v[0:3], v[196:199], v[238:241], v[0:3]
	s_setprio 0
	s_barrier
; #define PG8_STAGE(bufoff, gbase, voff) do { _Pragma("unroll") for (int _i = 0; _i < 2; ++_i) \
;         __builtin_amdgcn_global_load_lds((const unsigned*)((const char*)(gbase) + (voff)[_i]), (PG8_LAS unsigned*)(lds + (bufoff) + ldsw + _i * 8192), 16, 0, 0); } while (0)
; #define PG8_WAIT_V(n) asm volatile("s_waitcnt vmcnt(" #n ")" ::: "memory")
; #define PG8_WAIT_L(n) asm volatile("s_waitcnt lgkmcnt(" #n ")" ::: "memory")
; #define PG8_BAR __builtin_amdgcn_s_barrier()
; #define PG8_SCHED __builtin_amdgcn_sched_barrier(0)
; template <class Epi, class Sched, bool ALIGN_EPI = false, bool SP2 = false, bool F8 = false>
; __device__ __forceinline__ void gemm_phase(PG8_LAS unsigned char* lds, const Gemm g, const Sched& S, const Epi& E) {
;     ...
;             PG8_LDB(B0, 1, 0); PG8_LDB(B1, 1, 1); PG8_SCHED; PG8_LDA(At, 1, 0); PG8_STAGE(PG8_SA(0, 1), a2 + hstep, voffA);
;             PG8_WAIT_V(8); PG8_WAIT_L(0); PG8_BAR; PG8_MMA(0, 0, At, B0); PG8_MMA(0, 1, At, B1); PG8_BAR; PG8_SCHED;
	s_add_i32 s53, 0, 0x18000
	s_add_i32 s56, 0, 0x1c000
	v_add_u32_e32 v156, s53, v149
	v_add_u32_e32 v196, s56, v149
	ds_read_b128 v[138:141], v156
	ds_read_b128 v[142:145], v156 offset:1024
	ds_read_b128 v[152:155], v156 offset:2048
	ds_read_b128 v[156:159], v156 offset:3072
	ds_read_b128 v[184:187], v196
	ds_read_b128 v[188:191], v196 offset:1024
	ds_read_b128 v[192:195], v196 offset:2048
	ds_read_b128 v[196:199], v196 offset:3072
	s_add_u32 s16, s16, 0x80000
	s_addc_u32 s17, s17, 0
	s_mov_b32 m0, s37
	v_lshl_add_u64 v[246:247], s[16:17], 0, v[132:133]
	ds_read_b128 v[200:203], v151 offset:32768
	ds_read_b128 v[214:217], v151 offset:33792
	ds_read_b128 v[218:221], v151 offset:34816
	ds_read_b128 v[222:225], v151 offset:35840
	ds_read_b128 v[226:229], v151 offset:36864
	ds_read_b128 v[230:233], v151 offset:37888
	ds_read_b128 v[234:237], v151 offset:38912
	ds_read_b128 v[238:241], v151 offset:39936
	global_load_lds_dwordx4 v[246:247], off
	v_lshl_add_u64 v[246:247], s[16:17], 0, v[130:131]
	s_mov_b32 m0, s54
	s_nop 0
	global_load_lds_dwordx4 v[246:247], off
	s_waitcnt vmcnt(8)
	s_waitcnt lgkmcnt(0)
	s_barrier
	s_setprio 1
	v_mfma_f32_16x16x32_bf16 v[124:127], v[138:141], v[200:203], v[124:127]
	v_mfma_f32_16x16x32_bf16 v[120:123], v[152:155], v[200:203], v[120:123]
	v_mfma_f32_16x16x32_bf16 v[108:111], v[138:141], v[218:221], v[108:111]
	v_mfma_f32_16x16x32_bf16 v[104:107], v[152:155], v[218:221], v[104:107]
	v_mfma_f32_16x16x32_bf16 v[92:95], v[138:141], v[226:229], v[92:95]
	v_mfma_f32_16x16x32_bf16 v[88:91], v[152:155], v[226:229], v[88:91]
	v_mfma_f32_16x16x32_bf16 v[76:79], v[138:141], v[234:237], v[76:79]
	v_mfma_f32_16x16x32_bf16 v[72:75], v[152:155], v[234:237], v[72:75]
	v_mfma_f32_16x16x32_bf16 v[124:127], v[142:145], v[214:217], v[124:127]
	v_mfma_f32_16x16x32_bf16 v[120:123], v[156:159], v[214:217], v[120:123]
	v_mfma_f32_16x16x32_bf16 v[108:111], v[142:145], v[222:225], v[108:111]
	v_mfma_f32_16x16x32_bf16 v[104:107], v[156:159], v[222:225], v[104:107]
	v_mfma_f32_16x16x32_bf16 v[92:95], v[142:145], v[230:233], v[92:95]
	v_mfma_f32_16x16x32_bf16 v[88:91], v[156:159], v[230:233], v[88:91]
	v_mfma_f32_16x16x32_bf16 v[76:79], v[142:145], v[238:241], v[76:79]
	v_mfma_f32_16x16x32_bf16 v[72:75], v[156:159], v[238:241], v[72:75]
	s_setprio 0
	s_setprio 1
	v_mfma_f32_16x16x32_bf16 v[116:119], v[184:187], v[200:203], v[116:119]
	v_mfma_f32_16x16x32_bf16 v[112:115], v[192:195], v[200:203], v[112:115]
	v_mfma_f32_16x16x32_bf16 v[100:103], v[184:187], v[218:221], v[100:103]
	v_mfma_f32_16x16x32_bf16 v[96:99], v[192:195], v[218:221], v[96:99]
	v_mfma_f32_16x16x32_bf16 v[84:87], v[184:187], v[226:229], v[84:87]
	v_mfma_f32_16x16x32_bf16 v[80:83], v[192:195], v[226:229], v[80:83]
	v_mfma_f32_16x16x32_bf16 v[68:71], v[184:187], v[234:237], v[68:71]
	v_mfma_f32_16x16x32_bf16 v[64:67], v[192:195], v[234:237], v[64:67]
	v_mfma_f32_16x16x32_bf16 v[116:119], v[188:191], v[214:217], v[116:119]
	v_mfma_f32_16x16x32_bf16 v[112:115], v[196:199], v[214:217], v[112:115]
	v_mfma_f32_16x16x32_bf16 v[100:103], v[188:191], v[222:225], v[100:103]
	v_mfma_f32_16x16x32_bf16 v[96:99], v[196:199], v[222:225], v[96:99]
	v_mfma_f32_16x16x32_bf16 v[84:87], v[188:191], v[230:233], v[84:87]
	v_mfma_f32_16x16x32_bf16 v[80:83], v[196:199], v[230:233], v[80:83]
	v_mfma_f32_16x16x32_bf16 v[68:71], v[188:191], v[238:241], v[68:71]
	v_mfma_f32_16x16x32_bf16 v[64:67], v[196:199], v[238:241], v[64:67]
	s_setprio 0
	s_barrier
; #define PG8_STAGE(bufoff, gbase, voff) do { _Pragma("unroll") for (int _i = 0; _i < 2; ++_i) \
;         __builtin_amdgcn_global_load_lds((const unsigned*)((const char*)(gbase) + (voff)[_i]), (PG8_LAS unsigned*)(lds + (bufoff) + ldsw + _i * 8192), 16, 0, 0); } while (0)
; #define PG8_WAIT_V(n) asm volatile("s_waitcnt vmcnt(" #n ")" ::: "memory")
; #define PG8_WAIT_L(n) asm volatile("s_waitcnt lgkmcnt(" #n ")" ::: "memory")
; #define PG8_BAR __builtin_amdgcn_s_barrier()
; #define PG8_SCHED __builtin_amdgcn_sched_barrier(0)
; template <class Epi, class Sched, bool ALIGN_EPI = false, bool SP2 = false, bool F8 = false>
; __device__ __forceinline__ void gemm_phase(PG8_LAS unsigned char* lds, const Gemm g, const Sched& S, const Epi& E) {
;     ...
;             PG8_LDA(At, 1, 1); PG8_STAGE(PG8_SB(1, 0), b3, voffB); PG8_STAGE(PG8_SB(1, 1), b3 + hstep, voffB); PG8_STAGE(PG8_SA(1, 0), a3, voffA);
;             PG8_WAIT_V(8); PG8_WAIT_L(0); PG8_BAR; PG8_MMA(1, 0, At, B0); PG8_MMA(1, 1, At, B1); PG8_BAR; PG8_SCHED;
	s_add_i32 s16, s53, s34
	v_lshl_add_u64 v[146:147], v[146:147], 0, s[14:15]
	s_mov_b32 m0, s16
	ds_read_b128 v[200:203], v151 offset:49152
	ds_read_b128 v[214:217], v151 offset:50176
	ds_read_b128 v[218:221], v151 offset:51200
	ds_read_b128 v[222:225], v151 offset:52224
	ds_read_b128 v[226:229], v151 offset:53248
	ds_read_b128 v[230:233], v151 offset:54272
	ds_read_b128 v[234:237], v151 offset:55296
	ds_read_b128 v[238:241], v151 offset:56320
	global_load_lds_dwordx4 v[146:147], off
	s_add_i32 m0, s16, 0x2000
	s_add_u32 s10, s10, 0x80080
	v_lshl_add_u64 v[146:147], v[162:163], 0, s[14:15]
	s_addc_u32 s11, s11, 0
	s_add_i32 s16, s56, s34
	global_load_lds_dwordx4 v[146:147], off
	v_lshl_add_u64 v[146:147], s[10:11], 0, v[160:161]
	s_mov_b32 m0, s16
	s_nop 0
	global_load_lds_dwordx4 v[146:147], off
	v_lshl_add_u64 v[146:147], s[10:11], 0, v[128:129]
	s_add_i32 m0, s16, 0x2000
	s_nop 0
	global_load_lds_dwordx4 v[146:147], off
	v_lshl_add_u64 v[146:147], v[242:243], 0, s[14:15]
	s_mov_b32 m0, s55
	s_nop 0
	global_load_lds_dwordx4 v[146:147], off
	v_lshl_add_u64 v[146:147], v[244:245], 0, s[14:15]
	s_mov_b32 m0, s58
	s_nop 0
	global_load_lds_dwordx4 v[146:147], off
	s_waitcnt vmcnt(8)
	s_waitcnt lgkmcnt(0)
	s_barrier
	s_setprio 1
	v_mfma_f32_16x16x32_bf16 v[60:63], v[138:141], v[200:203], v[60:63]
	v_mfma_f32_16x16x32_bf16 v[56:59], v[152:155], v[200:203], v[56:59]
	v_mfma_f32_16x16x32_bf16 v[44:47], v[138:141], v[218:221], v[44:47]
	v_mfma_f32_16x16x32_bf16 v[40:43], v[152:155], v[218:221], v[40:43]
	v_mfma_f32_16x16x32_bf16 v[28:31], v[138:141], v[226:229], v[28:31]
	v_mfma_f32_16x16x32_bf16 v[24:27], v[152:155], v[226:229], v[24:27]
	v_mfma_f32_16x16x32_bf16 v[12:15], v[138:141], v[234:237], v[12:15]
	v_mfma_f32_16x16x32_bf16 v[8:11], v[152:155], v[234:237], v[8:11]
	v_mfma_f32_16x16x32_bf16 v[60:63], v[142:145], v[214:217], v[60:63]
	v_mfma_f32_16x16x32_bf16 v[56:59], v[156:159], v[214:217], v[56:59]
	v_mfma_f32_16x16x32_bf16 v[44:47], v[142:145], v[222:225], v[44:47]
	v_mfma_f32_16x16x32_bf16 v[40:43], v[156:159], v[222:225], v[40:43]
	v_mfma_f32_16x16x32_bf16 v[28:31], v[142:145], v[230:233], v[28:31]
	v_mfma_f32_16x16x32_bf16 v[24:27], v[156:159], v[230:233], v[24:27]
	v_mfma_f32_16x16x32_bf16 v[12:15], v[142:145], v[238:241], v[12:15]
	v_mfma_f32_16x16x32_bf16 v[8:11], v[156:159], v[238:241], v[8:11]
	s_setprio 0
	s_setprio 1
	v_mfma_f32_16x16x32_bf16 v[52:55], v[184:187], v[200:203], v[52:55]
	v_mfma_f32_16x16x32_bf16 v[48:51], v[192:195], v[200:203], v[48:51]
	v_mfma_f32_16x16x32_bf16 v[36:39], v[184:187], v[218:221], v[36:39]
	v_mfma_f32_16x16x32_bf16 v[32:35], v[192:195], v[218:221], v[32:35]
	v_mfma_f32_16x16x32_bf16 v[20:23], v[184:187], v[226:229], v[20:23]
	v_mfma_f32_16x16x32_bf16 v[16:19], v[192:195], v[226:229], v[16:19]
	v_mfma_f32_16x16x32_bf16 v[4:7], v[184:187], v[234:237], v[4:7]
	v_mfma_f32_16x16x32_bf16 v[0:3], v[192:195], v[234:237], v[0:3]
	v_mfma_f32_16x16x32_bf16 v[52:55], v[188:191], v[214:217], v[52:55]
	v_mfma_f32_16x16x32_bf16 v[48:51], v[196:199], v[214:217], v[48:51]
	v_mfma_f32_16x16x32_bf16 v[36:39], v[188:191], v[222:225], v[36:39]
	v_mfma_f32_16x16x32_bf16 v[32:35], v[196:199], v[222:225], v[32:35]
	v_mfma_f32_16x16x32_bf16 v[20:23], v[188:191], v[230:233], v[20:23]
	v_mfma_f32_16x16x32_bf16 v[16:19], v[196:199], v[230:233], v[16:19]
	v_mfma_f32_16x16x32_bf16 v[4:7], v[188:191], v[238:241], v[4:7]
	v_mfma_f32_16x16x32_bf16 v[0:3], v[196:199], v[238:241], v[0:3]
	s_setprio 0
	s_barrier
	s_add_i32 s52, s52, 2
	s_add_u32 s0, s0, 0x100
	s_addc_u32 s1, s1, 0
	s_add_u32 s45, s45, 0x100
	s_addc_u32 s47, s47, 0
	s_cmp_gt_u32 s52, 29
	s_cbranch_scc0 .LBB0_32

; #define PG8_STAGE(bufoff, gbase, voff) do { _Pragma("unroll") for (int _i = 0; _i < 2; ++_i) \
;         __builtin_amdgcn_global_load_lds((const unsigned*)((const char*)(gbase) + (voff)[_i]), (PG8_LAS unsigned*)(lds + (bufoff) + ldsw + _i * 8192), 16, 0, 0); } while (0)
; #define PG8_WAIT_V(n) asm volatile("s_waitcnt vmcnt(" #n ")" ::: "memory")
; #define PG8_WAIT_L(n) asm volatile("s_waitcnt lgkmcnt(" #n ")" ::: "memory")
; #define PG8_BAR __builtin_amdgcn_s_barrier()
; #define PG8_SCHED __builtin_amdgcn_sched_barrier(0)
; template <class Epi, class Sched, bool ALIGN_EPI = false, bool SP2 = false, bool F8 = false>
; __device__ __forceinline__ void gemm_phase(PG8_LAS unsigned char* lds, const Gemm g, const Sched& S, const Epi& E) {
;     ...
;         const bool has_next = S.next(ui + 1, nxt);
;         const char* nA = has_next ? (const char*)g.A + (size_t)nxt.pm * tstep : cA; const char* nB = has_next ? (const char*)g.Bt + (size_t)nxt.pn * tstep : cB;
;         for (int t = 0; t < nt; t += 2) {
;             const bool last = (t == nt - 2);
;             const char* a1 = cA + (size_t)(t + 1) * kstep;
;             const char* a2 = last ? nA : cA + (size_t)(t + 2) * kstep; const char* b2 = last ? nB : cB + (size_t)(t + 2) * kstep;
;             const char* a3 = a2 + kstep; const char* b3 = b2 + kstep;
;             if (last && has_next) S.a_ready(nxt);
;             if constexpr (SP2) {
;             PG8_LDB(B0, 0, 0); PG8_LDB(B1, 0, 1); PG8_SCHED; PG8_LDA(At, 0, 0); PG8_STAGE(PG8_SA(1, 1), a1 + hstep, voffA);
;             PG8_WAIT_V(8); PG8_WAIT_L(0); PG8_BAR; PG8_MMA(0, 0, At, B0); PG8_MMA(0, 1, At, B1); PG8_BAR; PG8_SCHED;
;             PG8_LDA(At, 0, 1); PG8_STAGE(PG8_SB(0, 0), b2, voffB); PG8_STAGE(PG8_SB(0, 1), b2 + hstep, voffB); PG8_STAGE(PG8_SA(0, 0), a2, voffA);
;             PG8_WAIT_V(8); PG8_WAIT_L(0); PG8_BAR; PG8_MMA(1, 0, At, B0); PG8_MMA(1, 1, At, B1); PG8_BAR; PG8_SCHED;
.LBB0_58:
	s_ashr_i32 s49, s48, 31
	s_lshl_b64 s[8:9], s[48:49], 20
	s_add_u32 s50, s26, s8
	s_addc_u32 s51, s27, s9
	s_and_b64 s[8:9], s[40:41], exec
	s_cselect_b32 s1, s51, s37
	s_cselect_b32 s8, s50, s36
	s_ashr_i32 s47, s46, 31
	s_lshl_b64 s[28:29], s[46:47], 20
	s_add_u32 s54, s13, s28
	s_addc_u32 s55, s22, s29
	s_and_b64 s[28:29], s[40:41], exec
	s_cselect_b32 s9, s55, s59
	s_cselect_b32 s11, s54, s58
	s_add_u32 s36, s36, 0x80080
	s_addc_u32 s37, s37, 0
	s_add_u32 s19, s58, 0x100
	s_addc_u32 s23, s59, 0
	s_mov_b32 s28, -2
	s_add_u32 s29, s36, 0xfff80080
	s_addc_u32 s34, s37, -1
	s_add_i32 s35, 0, 0x10000
	s_cmp_eq_u32 s28, 28
	s_cselect_b32 s61, s1, s34
	s_cselect_b32 s60, s8, s29
	s_cselect_b32 s59, s9, s23
	s_cselect_b32 s58, s11, s19
	s_add_i32 s29, 0, 0x14000
	v_add_u32_e32 v154, s35, v151
	v_add_u32_e32 v158, s29, v151
	ds_read_b128 v[138:141], v154
	ds_read_b128 v[142:145], v154 offset:1024
	ds_read_b128 v[146:149], v154 offset:2048
	ds_read_b128 v[154:157], v154 offset:3072
	ds_read_b128 v[184:187], v158
	ds_read_b128 v[188:191], v158 offset:1024
	ds_read_b128 v[192:195], v158 offset:2048
	ds_read_b128 v[196:199], v158 offset:3072
	v_lshl_add_u64 v[158:159], s[36:37], 0, v[134:135]
	s_add_i32 m0, s17, 0xc000
	ds_read_b128 v[200:203], v153
	ds_read_b128 v[214:217], v153 offset:1024
	ds_read_b128 v[218:221], v153 offset:2048
	ds_read_b128 v[222:225], v153 offset:3072
	ds_read_b128 v[226:229], v153 offset:4096
	ds_read_b128 v[230:233], v153 offset:5120
	ds_read_b128 v[234:237], v153 offset:6144
	ds_read_b128 v[238:241], v153 offset:7168
	global_load_lds_dwordx4 v[158:159], off
	v_lshl_add_u64 v[158:159], s[36:37], 0, v[136:137]
	s_add_i32 m0, s17, 0xe000
	s_nop 0
	global_load_lds_dwordx4 v[158:159], off
	s_waitcnt vmcnt(8)
	s_waitcnt lgkmcnt(0)
	s_barrier
	s_setprio 1
	v_mfma_f32_16x16x32_bf16 v[124:127], v[138:141], v[200:203], 0
	v_mfma_f32_16x16x32_bf16 v[120:123], v[146:149], v[200:203], 0
	v_mfma_f32_16x16x32_bf16 v[108:111], v[138:141], v[218:221], 0
	v_mfma_f32_16x16x32_bf16 v[104:107], v[146:149], v[218:221], 0
	v_mfma_f32_16x16x32_bf16 v[92:95], v[138:141], v[226:229], 0
	v_mfma_f32_16x16x32_bf16 v[88:91], v[146:149], v[226:229], 0
	v_mfma_f32_16x16x32_bf16 v[76:79], v[138:141], v[234:237], 0
	v_mfma_f32_16x16x32_bf16 v[72:75], v[146:149], v[234:237], 0
	v_mfma_f32_16x16x32_bf16 v[124:127], v[142:145], v[214:217], v[124:127]
	v_mfma_f32_16x16x32_bf16 v[120:123], v[154:157], v[214:217], v[120:123]
	v_mfma_f32_16x16x32_bf16 v[108:111], v[142:145], v[222:225], v[108:111]
	v_mfma_f32_16x16x32_bf16 v[104:107], v[154:157], v[222:225], v[104:107]
	v_mfma_f32_16x16x32_bf16 v[92:95], v[142:145], v[230:233], v[92:95]
	v_mfma_f32_16x16x32_bf16 v[88:91], v[154:157], v[230:233], v[88:91]
	v_mfma_f32_16x16x32_bf16 v[76:79], v[142:145], v[238:241], v[76:79]
	v_mfma_f32_16x16x32_bf16 v[72:75], v[154:157], v[238:241], v[72:75]
	s_setprio 0
	s_setprio 1
	v_mfma_f32_16x16x32_bf16 v[116:119], v[184:187], v[200:203], 0
	v_mfma_f32_16x16x32_bf16 v[112:115], v[192:195], v[200:203], 0
	v_mfma_f32_16x16x32_bf16 v[100:103], v[184:187], v[218:221], 0
	v_mfma_f32_16x16x32_bf16 v[96:99], v[192:195], v[218:221], 0
	v_mfma_f32_16x16x32_bf16 v[84:87], v[184:187], v[226:229], 0
	v_mfma_f32_16x16x32_bf16 v[80:83], v[192:195], v[226:229], 0
	v_mfma_f32_16x16x32_bf16 v[68:71], v[184:187], v[234:237], 0
	v_mfma_f32_16x16x32_bf16 v[64:67], v[192:195], v[234:237], 0
	v_mfma_f32_16x16x32_bf16 v[116:119], v[188:191], v[214:217], v[116:119]
	v_mfma_f32_16x16x32_bf16 v[112:115], v[196:199], v[214:217], v[112:115]
	v_mfma_f32_16x16x32_bf16 v[100:103], v[188:191], v[222:225], v[100:103]
	v_mfma_f32_16x16x32_bf16 v[96:99], v[196:199], v[222:225], v[96:99]
	v_mfma_f32_16x16x32_bf16 v[84:87], v[188:191], v[230:233], v[84:87]
	v_mfma_f32_16x16x32_bf16 v[80:83], v[196:199], v[230:233], v[80:83]
	v_mfma_f32_16x16x32_bf16 v[68:71], v[188:191], v[238:241], v[68:71]
	v_mfma_f32_16x16x32_bf16 v[64:67], v[196:199], v[238:241], v[64:67]
	s_setprio 0
	s_barrier
	s_add_i32 s34, s35, s64
	v_lshl_add_u64 v[158:159], s[58:59], 0, v[160:161]
	s_mov_b32 m0, s34
	ds_read_b128 v[200:203], v153 offset:16384
	ds_read_b128 v[214:217], v153 offset:17408
	ds_read_b128 v[218:221], v153 offset:18432
	ds_read_b128 v[222:225], v153 offset:19456
	ds_read_b128 v[226:229], v153 offset:20480
	ds_read_b128 v[230:233], v153 offset:21504
	ds_read_b128 v[234:237], v153 offset:22528
	ds_read_b128 v[238:241], v153 offset:23552
	global_load_lds_dwordx4 v[158:159], off
	s_add_i32 m0, s34, 0x2000
	s_add_u32 s34, s58, 0x80000
	v_lshl_add_u64 v[162:163], s[58:59], 0, v[132:133]
	s_addc_u32 s35, s59, 0
	s_add_i32 s29, s29, s64
	global_load_lds_dwordx4 v[162:163], off
	v_lshl_add_u64 v[242:243], s[34:35], 0, v[160:161]
	s_mov_b32 m0, s29
	v_lshl_add_u64 v[244:245], s[60:61], 0, v[130:131]
	global_load_lds_dwordx4 v[242:243], off
	v_lshl_add_u64 v[242:243], s[34:35], 0, v[132:133]
	s_add_i32 m0, s29, 0x2000
	s_nop 0
	global_load_lds_dwordx4 v[242:243], off
	v_lshl_add_u64 v[242:243], s[60:61], 0, v[128:129]
	s_mov_b32 m0, s17
	s_nop 0
	global_load_lds_dwordx4 v[242:243], off
	s_mov_b32 m0, s65
	s_nop 0
	global_load_lds_dwordx4 v[244:245], off
	s_waitcnt vmcnt(8)
	s_waitcnt lgkmcnt(0)
	s_barrier
; #define PG8_STAGE(bufoff, gbase, voff) do { _Pragma("unroll") for (int _i = 0; _i < 2; ++_i) \
;         __builtin_amdgcn_global_load_lds((const unsigned*)((const char*)(gbase) + (voff)[_i]), (PG8_LAS unsigned*)(lds + (bufoff) + ldsw + _i * 8192), 16, 0, 0); } while (0)
; #define PG8_WAIT_V(n) asm volatile("s_waitcnt vmcnt(" #n ")" ::: "memory")
; #define PG8_WAIT_L(n) asm volatile("s_waitcnt lgkmcnt(" #n ")" ::: "memory")
; #define PG8_BAR __builtin_amdgcn_s_barrier()
; #define PG8_SCHED __builtin_amdgcn_sched_barrier(0)
; template <class Epi, class Sched, bool ALIGN_EPI = false, bool SP2 = false, bool F8 = false>
; __device__ __forceinline__ void gemm_phase(PG8_LAS unsigned char* lds, const Gemm g, const Sched& S, const Epi& E) {
;     ...
;             PG8_WAIT_V(8); PG8_WAIT_L(0); PG8_BAR; PG8_MMA(1, 0, At, B0); PG8_MMA(1, 1, At, B1); PG8_BAR; PG8_SCHED;
;             PG8_LDB(B0, 1, 0); PG8_LDB(B1, 1, 1); PG8_SCHED; PG8_LDA(At, 1, 0); PG8_STAGE(PG8_SA(0, 1), a2 + hstep, voffA);
;             PG8_WAIT_V(8); PG8_WAIT_L(0); PG8_BAR; PG8_MMA(0, 0, At, B0); PG8_MMA(0, 1, At, B1); PG8_BAR; PG8_SCHED;
	s_setprio 1
	v_mfma_f32_16x16x32_bf16 v[60:63], v[138:141], v[200:203], 0
	v_mfma_f32_16x16x32_bf16 v[56:59], v[146:149], v[200:203], 0
	v_mfma_f32_16x16x32_bf16 v[44:47], v[138:141], v[218:221], 0
	v_mfma_f32_16x16x32_bf16 v[40:43], v[146:149], v[218:221], 0
	v_mfma_f32_16x16x32_bf16 v[28:31], v[138:141], v[226:229], 0
	v_mfma_f32_16x16x32_bf16 v[24:27], v[146:149], v[226:229], 0
	v_mfma_f32_16x16x32_bf16 v[12:15], v[138:141], v[234:237], 0
	v_mfma_f32_16x16x32_bf16 v[8:11], v[146:149], v[234:237], 0
	v_mfma_f32_16x16x32_bf16 v[60:63], v[142:145], v[214:217], v[60:63]
	v_mfma_f32_16x16x32_bf16 v[56:59], v[154:157], v[214:217], v[56:59]
	v_mfma_f32_16x16x32_bf16 v[44:47], v[142:145], v[222:225], v[44:47]
	v_mfma_f32_16x16x32_bf16 v[40:43], v[154:157], v[222:225], v[40:43]
	v_mfma_f32_16x16x32_bf16 v[28:31], v[142:145], v[230:233], v[28:31]
	v_mfma_f32_16x16x32_bf16 v[24:27], v[154:157], v[230:233], v[24:27]
	v_mfma_f32_16x16x32_bf16 v[12:15], v[142:145], v[238:241], v[12:15]
	v_mfma_f32_16x16x32_bf16 v[8:11], v[154:157], v[238:241], v[8:11]
	s_setprio 0
	s_setprio 1
	v_mfma_f32_16x16x32_bf16 v[52:55], v[184:187], v[200:203], 0
	v_mfma_f32_16x16x32_bf16 v[48:51], v[192:195], v[200:203], 0
	v_mfma_f32_16x16x32_bf16 v[36:39], v[184:187], v[218:221], 0
	v_mfma_f32_16x16x32_bf16 v[32:35], v[192:195], v[218:221], 0
	v_mfma_f32_16x16x32_bf16 v[20:23], v[184:187], v[226:229], 0
	v_mfma_f32_16x16x32_bf16 v[16:19], v[192:195], v[226:229], 0
	v_mfma_f32_16x16x32_bf16 v[4:7], v[184:187], v[234:237], 0
	v_mfma_f32_16x16x32_bf16 v[0:3], v[192:195], v[234:237], 0
	v_mfma_f32_16x16x32_bf16 v[52:55], v[188:191], v[214:217], v[52:55]
	v_mfma_f32_16x16x32_bf16 v[48:51], v[196:199], v[214:217], v[48:51]
	v_mfma_f32_16x16x32_bf16 v[36:39], v[188:191], v[222:225], v[36:39]
	v_mfma_f32_16x16x32_bf16 v[32:35], v[196:199], v[222:225], v[32:35]
	v_mfma_f32_16x16x32_bf16 v[20:23], v[188:191], v[230:233], v[20:23]
	v_mfma_f32_16x16x32_bf16 v[16:19], v[196:199], v[230:233], v[16:19]
	v_mfma_f32_16x16x32_bf16 v[4:7], v[188:191], v[238:241], v[4:7]
	v_mfma_f32_16x16x32_bf16 v[0:3], v[196:199], v[238:241], v[0:3]
	s_setprio 0
	s_barrier
	s_add_i32 s29, 0, 0x18000
	s_add_i32 s47, 0, 0x1c000
	v_add_u32_e32 v154, s29, v151
	v_add_u32_e32 v196, s47, v151
	ds_read_b128 v[138:141], v154
	ds_read_b128 v[142:145], v154 offset:1024
	ds_read_b128 v[146:149], v154 offset:2048
	ds_read_b128 v[154:157], v154 offset:3072
	ds_read_b128 v[184:187], v196
	ds_read_b128 v[188:191], v196 offset:1024
	ds_read_b128 v[192:195], v196 offset:2048
	ds_read_b128 v[196:199], v196 offset:3072
	s_add_u32 s34, s60, 0x80000
	s_addc_u32 s35, s61, 0
	s_mov_b32 m0, s74
	v_lshl_add_u64 v[246:247], s[34:35], 0, v[128:129]
	ds_read_b128 v[200:203], v153 offset:32768
	ds_read_b128 v[214:217], v153 offset:33792
	ds_read_b128 v[218:221], v153 offset:34816
	ds_read_b128 v[222:225], v153 offset:35840
	ds_read_b128 v[226:229], v153 offset:36864
	ds_read_b128 v[230:233], v153 offset:37888
	ds_read_b128 v[234:237], v153 offset:38912
	ds_read_b128 v[238:241], v153 offset:39936
	global_load_lds_dwordx4 v[246:247], off
	v_lshl_add_u64 v[246:247], s[34:35], 0, v[130:131]
	s_mov_b32 m0, s75
	s_nop 0
	global_load_lds_dwordx4 v[246:247], off
	s_waitcnt vmcnt(8)
	s_waitcnt lgkmcnt(0)
	s_barrier
	s_setprio 1
	v_mfma_f32_16x16x32_bf16 v[124:127], v[138:141], v[200:203], v[124:127]
	v_mfma_f32_16x16x32_bf16 v[120:123], v[146:149], v[200:203], v[120:123]
	v_mfma_f32_16x16x32_bf16 v[108:111], v[138:141], v[218:221], v[108:111]
	v_mfma_f32_16x16x32_bf16 v[104:107], v[146:149], v[218:221], v[104:107]
	v_mfma_f32_16x16x32_bf16 v[92:95], v[138:141], v[226:229], v[92:95]
	v_mfma_f32_16x16x32_bf16 v[88:91], v[146:149], v[226:229], v[88:91]
	v_mfma_f32_16x16x32_bf16 v[76:79], v[138:141], v[234:237], v[76:79]
	v_mfma_f32_16x16x32_bf16 v[72:75], v[146:149], v[234:237], v[72:75]
	v_mfma_f32_16x16x32_bf16 v[124:127], v[142:145], v[214:217], v[124:127]
	v_mfma_f32_16x16x32_bf16 v[120:123], v[154:157], v[214:217], v[120:123]
	v_mfma_f32_16x16x32_bf16 v[108:111], v[142:145], v[222:225], v[108:111]
	v_mfma_f32_16x16x32_bf16 v[104:107], v[154:157], v[222:225], v[104:107]
	v_mfma_f32_16x16x32_bf16 v[92:95], v[142:145], v[230:233], v[92:95]
	v_mfma_f32_16x16x32_bf16 v[88:91], v[154:157], v[230:233], v[88:91]
	v_mfma_f32_16x16x32_bf16 v[76:79], v[142:145], v[238:241], v[76:79]
	v_mfma_f32_16x16x32_bf16 v[72:75], v[154:157], v[238:241], v[72:75]
	s_setprio 0
	s_setprio 1
	v_mfma_f32_16x16x32_bf16 v[116:119], v[184:187], v[200:203], v[116:119]
	v_mfma_f32_16x16x32_bf16 v[112:115], v[192:195], v[200:203], v[112:115]
	v_mfma_f32_16x16x32_bf16 v[100:103], v[184:187], v[218:221], v[100:103]
	v_mfma_f32_16x16x32_bf16 v[96:99], v[192:195], v[218:221], v[96:99]
	v_mfma_f32_16x16x32_bf16 v[84:87], v[184:187], v[226:229], v[84:87]
	v_mfma_f32_16x16x32_bf16 v[80:83], v[192:195], v[226:229], v[80:83]
	v_mfma_f32_16x16x32_bf16 v[68:71], v[184:187], v[234:237], v[68:71]
	v_mfma_f32_16x16x32_bf16 v[64:67], v[192:195], v[234:237], v[64:67]
	v_mfma_f32_16x16x32_bf16 v[116:119], v[188:191], v[214:217], v[116:119]
	v_mfma_f32_16x16x32_bf16 v[112:115], v[196:199], v[214:217], v[112:115]
	v_mfma_f32_16x16x32_bf16 v[100:103], v[188:191], v[222:225], v[100:103]
	v_mfma_f32_16x16x32_bf16 v[96:99], v[196:199], v[222:225], v[96:99]
	v_mfma_f32_16x16x32_bf16 v[84:87], v[188:191], v[230:233], v[84:87]
	v_mfma_f32_16x16x32_bf16 v[80:83], v[196:199], v[230:233], v[80:83]
	v_mfma_f32_16x16x32_bf16 v[68:71], v[188:191], v[238:241], v[68:71]
	v_mfma_f32_16x16x32_bf16 v[64:67], v[196:199], v[238:241], v[64:67]
	s_setprio 0
	s_barrier
; #define PG8_STAGE(bufoff, gbase, voff) do { _Pragma("unroll") for (int _i = 0; _i < 2; ++_i) \
;         __builtin_amdgcn_global_load_lds((const unsigned*)((const char*)(gbase) + (voff)[_i]), (PG8_LAS unsigned*)(lds + (bufoff) + ldsw + _i * 8192), 16, 0, 0); } while (0)
; #define PG8_WAIT_V(n) asm volatile("s_waitcnt vmcnt(" #n ")" ::: "memory")
; #define PG8_WAIT_L(n) asm volatile("s_waitcnt lgkmcnt(" #n ")" ::: "memory")
; #define PG8_BAR __builtin_amdgcn_s_barrier()
; #define PG8_SCHED __builtin_amdgcn_sched_barrier(0)
; template <class Epi, class Sched, bool ALIGN_EPI = false, bool SP2 = false, bool F8 = false>
; __device__ __forceinline__ void gemm_phase(PG8_LAS unsigned char* lds, const Gemm g, const Sched& S, const Epi& E) {
;     ...
;             const bool last = (t == nt - 2);
;             const char* a1 = cA + (size_t)(t + 1) * kstep;
;             const char* a2 = last ? nA : cA + (size_t)(t + 2) * kstep; const char* b2 = last ? nB : cB + (size_t)(t + 2) * kstep;
;             const char* a3 = a2 + kstep; const char* b3 = b2 + kstep;
;             if (last && has_next) S.a_ready(nxt);
;             if constexpr (SP2) {
;             PG8_LDB(B0, 0, 0); PG8_LDB(B1, 0, 1); PG8_SCHED; PG8_LDA(At, 0, 0); PG8_STAGE(PG8_SA(1, 1), a1 + hstep, voffA);
;             PG8_WAIT_V(8); PG8_WAIT_L(0); PG8_BAR; PG8_MMA(0, 0, At, B0); PG8_MMA(0, 1, At, B1); PG8_BAR; PG8_SCHED;
;             PG8_LDA(At, 0, 1); PG8_STAGE(PG8_SB(0, 0), b2, voffB); PG8_STAGE(PG8_SB(0, 1), b2 + hstep, voffB); PG8_STAGE(PG8_SA(0, 0), a2, voffA);
;             PG8_WAIT_V(8); PG8_WAIT_L(0); PG8_BAR; PG8_MMA(1, 0, At, B0); PG8_MMA(1, 1, At, B1); PG8_BAR; PG8_SCHED;
;             PG8_LDB(B0, 1, 0); PG8_LDB(B1, 1, 1); PG8_SCHED; PG8_LDA(At, 1, 0); PG8_STAGE(PG8_SA(0, 1), a2 + hstep, voffA);
;             PG8_WAIT_V(8); PG8_WAIT_L(0); PG8_BAR; PG8_MMA(0, 0, At, B0); PG8_MMA(0, 1, At, B1); PG8_BAR; PG8_SCHED;
;             PG8_LDA(At, 1, 1); PG8_STAGE(PG8_SB(1, 0), b3, voffB); PG8_STAGE(PG8_SB(1, 1), b3 + hstep, voffB); PG8_STAGE(PG8_SA(1, 0), a3, voffA);
;             PG8_WAIT_V(8); PG8_WAIT_L(0); PG8_BAR; PG8_MMA(1, 0, At, B0); PG8_MMA(1, 1, At, B1); PG8_BAR; PG8_SCHED;
	s_add_i32 s29, s29, s64
	v_lshl_add_u64 v[158:159], v[158:159], 0, s[14:15]
	s_mov_b32 m0, s29
	ds_read_b128 v[200:203], v153 offset:49152
	ds_read_b128 v[214:217], v153 offset:50176
	ds_read_b128 v[218:221], v153 offset:51200
	ds_read_b128 v[222:225], v153 offset:52224
	ds_read_b128 v[226:229], v153 offset:53248
	ds_read_b128 v[230:233], v153 offset:54272
	ds_read_b128 v[234:237], v153 offset:55296
	ds_read_b128 v[238:241], v153 offset:56320
	global_load_lds_dwordx4 v[158:159], off
	s_add_i32 m0, s29, 0x2000
	s_add_u32 s34, s58, 0x80080
	v_lshl_add_u64 v[158:159], v[162:163], 0, s[14:15]
	s_addc_u32 s35, s59, 0
	s_add_i32 s29, s47, s64
	global_load_lds_dwordx4 v[158:159], off
	v_lshl_add_u64 v[158:159], s[34:35], 0, v[160:161]
	s_mov_b32 m0, s29
	s_nop 0
	global_load_lds_dwordx4 v[158:159], off
	v_lshl_add_u64 v[158:159], s[34:35], 0, v[132:133]
	s_add_i32 m0, s29, 0x2000
	s_nop 0
	global_load_lds_dwordx4 v[158:159], off
	v_lshl_add_u64 v[158:159], v[242:243], 0, s[14:15]
	s_mov_b32 m0, s52
	s_nop 0
	global_load_lds_dwordx4 v[158:159], off
	v_lshl_add_u64 v[158:159], v[244:245], 0, s[14:15]
	s_mov_b32 m0, s53
	s_nop 0
	global_load_lds_dwordx4 v[158:159], off
	s_waitcnt vmcnt(8)
	s_waitcnt lgkmcnt(0)
	s_barrier
	s_setprio 1
	v_mfma_f32_16x16x32_bf16 v[60:63], v[138:141], v[200:203], v[60:63]
	v_mfma_f32_16x16x32_bf16 v[56:59], v[146:149], v[200:203], v[56:59]
	v_mfma_f32_16x16x32_bf16 v[44:47], v[138:141], v[218:221], v[44:47]
	v_mfma_f32_16x16x32_bf16 v[40:43], v[146:149], v[218:221], v[40:43]
	v_mfma_f32_16x16x32_bf16 v[28:31], v[138:141], v[226:229], v[28:31]
	v_mfma_f32_16x16x32_bf16 v[24:27], v[146:149], v[226:229], v[24:27]
	v_mfma_f32_16x16x32_bf16 v[12:15], v[138:141], v[234:237], v[12:15]
	v_mfma_f32_16x16x32_bf16 v[8:11], v[146:149], v[234:237], v[8:11]
	v_mfma_f32_16x16x32_bf16 v[60:63], v[142:145], v[214:217], v[60:63]
	v_mfma_f32_16x16x32_bf16 v[56:59], v[154:157], v[214:217], v[56:59]
	v_mfma_f32_16x16x32_bf16 v[44:47], v[142:145], v[222:225], v[44:47]
	v_mfma_f32_16x16x32_bf16 v[40:43], v[154:157], v[222:225], v[40:43]
	v_mfma_f32_16x16x32_bf16 v[28:31], v[142:145], v[230:233], v[28:31]
	v_mfma_f32_16x16x32_bf16 v[24:27], v[154:157], v[230:233], v[24:27]
	v_mfma_f32_16x16x32_bf16 v[12:15], v[142:145], v[238:241], v[12:15]
	v_mfma_f32_16x16x32_bf16 v[8:11], v[154:157], v[238:241], v[8:11]
	s_setprio 0
	s_setprio 1
	v_mfma_f32_16x16x32_bf16 v[52:55], v[184:187], v[200:203], v[52:55]
	v_mfma_f32_16x16x32_bf16 v[48:51], v[192:195], v[200:203], v[48:51]
	v_mfma_f32_16x16x32_bf16 v[36:39], v[184:187], v[218:221], v[36:39]
	v_mfma_f32_16x16x32_bf16 v[32:35], v[192:195], v[218:221], v[32:35]
	v_mfma_f32_16x16x32_bf16 v[20:23], v[184:187], v[226:229], v[20:23]
	v_mfma_f32_16x16x32_bf16 v[16:19], v[192:195], v[226:229], v[16:19]
	v_mfma_f32_16x16x32_bf16 v[4:7], v[184:187], v[234:237], v[4:7]
	v_mfma_f32_16x16x32_bf16 v[0:3], v[192:195], v[234:237], v[0:3]
	v_mfma_f32_16x16x32_bf16 v[52:55], v[188:191], v[214:217], v[52:55]
	v_mfma_f32_16x16x32_bf16 v[48:51], v[196:199], v[214:217], v[48:51]
	v_mfma_f32_16x16x32_bf16 v[36:39], v[188:191], v[222:225], v[36:39]
	v_mfma_f32_16x16x32_bf16 v[32:35], v[196:199], v[222:225], v[32:35]
	v_mfma_f32_16x16x32_bf16 v[20:23], v[188:191], v[230:233], v[20:23]
	v_mfma_f32_16x16x32_bf16 v[16:19], v[196:199], v[230:233], v[16:19]
	v_mfma_f32_16x16x32_bf16 v[4:7], v[188:191], v[238:241], v[4:7]
	v_mfma_f32_16x16x32_bf16 v[0:3], v[196:199], v[238:241], v[0:3]
	s_setprio 0
	s_barrier
	s_add_i32 s28, s28, 2
	s_add_u32 s36, s36, 0x100
	s_addc_u32 s37, s37, 0
	s_add_u32 s19, s19, 0x100
	s_addc_u32 s23, s23, 0
	s_cmp_gt_u32 s28, 29
	s_cbranch_scc0 .LBB0_59
	s_branch .Lgk_after_59
.LBB0_59:
	s_add_u32 s29, s36, 0xfff80080
	s_addc_u32 s34, s37, -1
	s_add_i32 s35, 0, 0x10000
	s_cmp_eq_u32 s28, 28
	s_cselect_b32 s61, s1, s34
	s_cselect_b32 s60, s8, s29
	s_cselect_b32 s59, s9, s23
	s_cselect_b32 s58, s11, s19
	s_add_i32 s29, 0, 0x14000
	v_add_u32_e32 v154, s35, v151
	v_add_u32_e32 v158, s29, v151
	ds_read_b128 v[138:141], v154
	ds_read_b128 v[142:145], v154 offset:1024
	ds_read_b128 v[146:149], v154 offset:2048
	ds_read_b128 v[154:157], v154 offset:3072
	ds_read_b128 v[184:187], v158
	ds_read_b128 v[188:191], v158 offset:1024
	ds_read_b128 v[192:195], v158 offset:2048
	ds_read_b128 v[196:199], v158 offset:3072
	v_lshl_add_u64 v[158:159], s[36:37], 0, v[134:135]
	s_add_i32 m0, s17, 0xc000
	ds_read_b128 v[200:203], v153
	ds_read_b128 v[214:217], v153 offset:1024
	ds_read_b128 v[218:221], v153 offset:2048
	ds_read_b128 v[222:225], v153 offset:3072
	ds_read_b128 v[226:229], v153 offset:4096
	ds_read_b128 v[230:233], v153 offset:5120
	ds_read_b128 v[234:237], v153 offset:6144
	ds_read_b128 v[238:241], v153 offset:7168
	global_load_lds_dwordx4 v[158:159], off
	v_lshl_add_u64 v[158:159], s[36:37], 0, v[136:137]
	s_add_i32 m0, s17, 0xe000
	s_nop 0
	global_load_lds_dwordx4 v[158:159], off
	s_waitcnt vmcnt(8)
	s_waitcnt lgkmcnt(0)
	s_barrier
; #define PG8_STAGE(bufoff, gbase, voff) do { _Pragma("unroll") for (int _i = 0; _i < 2; ++_i) \
;         __builtin_amdgcn_global_load_lds((const unsigned*)((const char*)(gbase) + (voff)[_i]), (PG8_LAS unsigned*)(lds + (bufoff) + ldsw + _i * 8192), 16, 0, 0); } while (0)
; #define PG8_WAIT_V(n) asm volatile("s_waitcnt vmcnt(" #n ")" ::: "memory")
; #define PG8_WAIT_L(n) asm volatile("s_waitcnt lgkmcnt(" #n ")" ::: "memory")
; #define PG8_BAR __builtin_amdgcn_s_barrier()
; #define PG8_SCHED __builtin_amdgcn_sched_barrier(0)
; template <class Epi, class Sched, bool ALIGN_EPI = false, bool SP2 = false, bool F8 = false>
; __device__ __forceinline__ void gemm_phase(PG8_LAS unsigned char* lds, const Gemm g, const Sched& S, const Epi& E) {
;     ...
;             PG8_LDB(B0, 0, 0); PG8_LDB(B1, 0, 1); PG8_SCHED; PG8_LDA(At, 0, 0); PG8_STAGE(PG8_SA(1, 1), a1 + hstep, voffA);
;             PG8_WAIT_V(8); PG8_WAIT_L(0); PG8_BAR; PG8_MMA(0, 0, At, B0); PG8_MMA(0, 1, At, B1); PG8_BAR; PG8_SCHED;
;             PG8_LDA(At, 0, 1); PG8_STAGE(PG8_SB(0, 0), b2, voffB); PG8_STAGE(PG8_SB(0, 1), b2 + hstep, voffB); PG8_STAGE(PG8_SA(0, 0), a2, voffA);
;             PG8_WAIT_V(8); PG8_WAIT_L(0); PG8_BAR; PG8_MMA(1, 0, At, B0); PG8_MMA(1, 1, At, B1); PG8_BAR; PG8_SCHED;
	s_setprio 1
	v_mfma_f32_16x16x32_bf16 v[124:127], v[138:141], v[200:203], v[124:127]
	v_mfma_f32_16x16x32_bf16 v[120:123], v[146:149], v[200:203], v[120:123]
	v_mfma_f32_16x16x32_bf16 v[108:111], v[138:141], v[218:221], v[108:111]
	v_mfma_f32_16x16x32_bf16 v[104:107], v[146:149], v[218:221], v[104:107]
	v_mfma_f32_16x16x32_bf16 v[92:95], v[138:141], v[226:229], v[92:95]
	v_mfma_f32_16x16x32_bf16 v[88:91], v[146:149], v[226:229], v[88:91]
	v_mfma_f32_16x16x32_bf16 v[76:79], v[138:141], v[234:237], v[76:79]
	v_mfma_f32_16x16x32_bf16 v[72:75], v[146:149], v[234:237], v[72:75]
	v_mfma_f32_16x16x32_bf16 v[124:127], v[142:145], v[214:217], v[124:127]
	v_mfma_f32_16x16x32_bf16 v[120:123], v[154:157], v[214:217], v[120:123]
	v_mfma_f32_16x16x32_bf16 v[108:111], v[142:145], v[222:225], v[108:111]
	v_mfma_f32_16x16x32_bf16 v[104:107], v[154:157], v[222:225], v[104:107]
	v_mfma_f32_16x16x32_bf16 v[92:95], v[142:145], v[230:233], v[92:95]
	v_mfma_f32_16x16x32_bf16 v[88:91], v[154:157], v[230:233], v[88:91]
	v_mfma_f32_16x16x32_bf16 v[76:79], v[142:145], v[238:241], v[76:79]
	v_mfma_f32_16x16x32_bf16 v[72:75], v[154:157], v[238:241], v[72:75]
	s_setprio 0
	s_setprio 1
	v_mfma_f32_16x16x32_bf16 v[116:119], v[184:187], v[200:203], v[116:119]
	v_mfma_f32_16x16x32_bf16 v[112:115], v[192:195], v[200:203], v[112:115]
	v_mfma_f32_16x16x32_bf16 v[100:103], v[184:187], v[218:221], v[100:103]
	v_mfma_f32_16x16x32_bf16 v[96:99], v[192:195], v[218:221], v[96:99]
	v_mfma_f32_16x16x32_bf16 v[84:87], v[184:187], v[226:229], v[84:87]
	v_mfma_f32_16x16x32_bf16 v[80:83], v[192:195], v[226:229], v[80:83]
	v_mfma_f32_16x16x32_bf16 v[68:71], v[184:187], v[234:237], v[68:71]
	v_mfma_f32_16x16x32_bf16 v[64:67], v[192:195], v[234:237], v[64:67]
	v_mfma_f32_16x16x32_bf16 v[116:119], v[188:191], v[214:217], v[116:119]
	v_mfma_f32_16x16x32_bf16 v[112:115], v[196:199], v[214:217], v[112:115]
	v_mfma_f32_16x16x32_bf16 v[100:103], v[188:191], v[222:225], v[100:103]
	v_mfma_f32_16x16x32_bf16 v[96:99], v[196:199], v[222:225], v[96:99]
	v_mfma_f32_16x16x32_bf16 v[84:87], v[188:191], v[230:233], v[84:87]
	v_mfma_f32_16x16x32_bf16 v[80:83], v[196:199], v[230:233], v[80:83]
	v_mfma_f32_16x16x32_bf16 v[68:71], v[188:191], v[238:241], v[68:71]
	v_mfma_f32_16x16x32_bf16 v[64:67], v[196:199], v[238:241], v[64:67]
	s_setprio 0
	s_barrier
	s_add_i32 s34, s35, s64
	v_lshl_add_u64 v[158:159], s[58:59], 0, v[160:161]
	s_mov_b32 m0, s34
	ds_read_b128 v[200:203], v153 offset:16384
	ds_read_b128 v[214:217], v153 offset:17408
	ds_read_b128 v[218:221], v153 offset:18432
	ds_read_b128 v[222:225], v153 offset:19456
	ds_read_b128 v[226:229], v153 offset:20480
	ds_read_b128 v[230:233], v153 offset:21504
	ds_read_b128 v[234:237], v153 offset:22528
	ds_read_b128 v[238:241], v153 offset:23552
	global_load_lds_dwordx4 v[158:159], off
	s_add_i32 m0, s34, 0x2000
	s_add_u32 s34, s58, 0x80000
	v_lshl_add_u64 v[162:163], s[58:59], 0, v[132:133]
	s_addc_u32 s35, s59, 0
	s_add_i32 s29, s29, s64
	global_load_lds_dwordx4 v[162:163], off
	v_lshl_add_u64 v[242:243], s[34:35], 0, v[160:161]
	s_mov_b32 m0, s29
	v_lshl_add_u64 v[244:245], s[60:61], 0, v[130:131]
	global_load_lds_dwordx4 v[242:243], off
	v_lshl_add_u64 v[242:243], s[34:35], 0, v[132:133]
	s_add_i32 m0, s29, 0x2000
	s_nop 0
	global_load_lds_dwordx4 v[242:243], off
	v_lshl_add_u64 v[242:243], s[60:61], 0, v[128:129]
	s_mov_b32 m0, s17
	s_nop 0
	global_load_lds_dwordx4 v[242:243], off
	s_mov_b32 m0, s65
	s_nop 0
	global_load_lds_dwordx4 v[244:245], off
	s_waitcnt vmcnt(8)
	s_waitcnt lgkmcnt(0)
	s_barrier
	s_setprio 1
	v_mfma_f32_16x16x32_bf16 v[60:63], v[138:141], v[200:203], v[60:63]
	v_mfma_f32_16x16x32_bf16 v[56:59], v[146:149], v[200:203], v[56:59]
	v_mfma_f32_16x16x32_bf16 v[44:47], v[138:141], v[218:221], v[44:47]
	v_mfma_f32_16x16x32_bf16 v[40:43], v[146:149], v[218:221], v[40:43]
	v_mfma_f32_16x16x32_bf16 v[28:31], v[138:141], v[226:229], v[28:31]
	v_mfma_f32_16x16x32_bf16 v[24:27], v[146:149], v[226:229], v[24:27]
	v_mfma_f32_16x16x32_bf16 v[12:15], v[138:141], v[234:237], v[12:15]
	v_mfma_f32_16x16x32_bf16 v[8:11], v[146:149], v[234:237], v[8:11]
	v_mfma_f32_16x16x32_bf16 v[60:63], v[142:145], v[214:217], v[60:63]
	v_mfma_f32_16x16x32_bf16 v[56:59], v[154:157], v[214:217], v[56:59]
	v_mfma_f32_16x16x32_bf16 v[44:47], v[142:145], v[222:225], v[44:47]
	v_mfma_f32_16x16x32_bf16 v[40:43], v[154:157], v[222:225], v[40:43]
	v_mfma_f32_16x16x32_bf16 v[28:31], v[142:145], v[230:233], v[28:31]
	v_mfma_f32_16x16x32_bf16 v[24:27], v[154:157], v[230:233], v[24:27]
	v_mfma_f32_16x16x32_bf16 v[12:15], v[142:145], v[238:241], v[12:15]
	v_mfma_f32_16x16x32_bf16 v[8:11], v[154:157], v[238:241], v[8:11]
	s_setprio 0
	s_setprio 1
	v_mfma_f32_16x16x32_bf16 v[52:55], v[184:187], v[200:203], v[52:55]
	v_mfma_f32_16x16x32_bf16 v[48:51], v[192:195], v[200:203], v[48:51]
	v_mfma_f32_16x16x32_bf16 v[36:39], v[184:187], v[218:221], v[36:39]
	v_mfma_f32_16x16x32_bf16 v[32:35], v[192:195], v[218:221], v[32:35]
	v_mfma_f32_16x16x32_bf16 v[20:23], v[184:187], v[226:229], v[20:23]
	v_mfma_f32_16x16x32_bf16 v[16:19], v[192:195], v[226:229], v[16:19]
	v_mfma_f32_16x16x32_bf16 v[4:7], v[184:187], v[234:237], v[4:7]
	v_mfma_f32_16x16x32_bf16 v[0:3], v[192:195], v[234:237], v[0:3]
	v_mfma_f32_16x16x32_bf16 v[52:55], v[188:191], v[214:217], v[52:55]
	v_mfma_f32_16x16x32_bf16 v[48:51], v[196:199], v[214:217], v[48:51]
	v_mfma_f32_16x16x32_bf16 v[36:39], v[188:191], v[222:225], v[36:39]
	v_mfma_f32_16x16x32_bf16 v[32:35], v[196:199], v[222:225], v[32:35]
	v_mfma_f32_16x16x32_bf16 v[20:23], v[188:191], v[230:233], v[20:23]
	v_mfma_f32_16x16x32_bf16 v[16:19], v[196:199], v[230:233], v[16:19]
	v_mfma_f32_16x16x32_bf16 v[4:7], v[188:191], v[238:241], v[4:7]
	v_mfma_f32_16x16x32_bf16 v[0:3], v[196:199], v[238:241], v[0:3]
	s_setprio 0
	s_barrier
; #define PG8_STAGE(bufoff, gbase, voff) do { _Pragma("unroll") for (int _i = 0; _i < 2; ++_i) \
;         __builtin_amdgcn_global_load_lds((const unsigned*)((const char*)(gbase) + (voff)[_i]), (PG8_LAS unsigned*)(lds + (bufoff) + ldsw + _i * 8192), 16, 0, 0); } while (0)
; #define PG8_WAIT_V(n) asm volatile("s_waitcnt vmcnt(" #n ")" ::: "memory")
; #define PG8_WAIT_L(n) asm volatile("s_waitcnt lgkmcnt(" #n ")" ::: "memory")
; #define PG8_BAR __builtin_amdgcn_s_barrier()
; #define PG8_SCHED __builtin_amdgcn_sched_barrier(0)
; template <class Epi, class Sched, bool ALIGN_EPI = false, bool SP2 = false, bool F8 = false>
; __device__ __forceinline__ void gemm_phase(PG8_LAS unsigned char* lds, const Gemm g, const Sched& S, const Epi& E) {
;     ...
;             PG8_LDB(B0, 1, 0); PG8_LDB(B1, 1, 1); PG8_SCHED; PG8_LDA(At, 1, 0); PG8_STAGE(PG8_SA(0, 1), a2 + hstep, voffA);
;             PG8_WAIT_V(8); PG8_WAIT_L(0); PG8_BAR; PG8_MMA(0, 0, At, B0); PG8_MMA(0, 1, At, B1); PG8_BAR; PG8_SCHED;
	s_add_i32 s29, 0, 0x18000
	s_add_i32 s47, 0, 0x1c000
	v_add_u32_e32 v154, s29, v151
	v_add_u32_e32 v196, s47, v151
	ds_read_b128 v[138:141], v154
	ds_read_b128 v[142:145], v154 offset:1024
	ds_read_b128 v[146:149], v154 offset:2048
	ds_read_b128 v[154:157], v154 offset:3072
	ds_read_b128 v[184:187], v196
	ds_read_b128 v[188:191], v196 offset:1024
	ds_read_b128 v[192:195], v196 offset:2048
	ds_read_b128 v[196:199], v196 offset:3072
	s_add_u32 s34, s60, 0x80000
	s_addc_u32 s35, s61, 0
	s_mov_b32 m0, s74
	v_lshl_add_u64 v[246:247], s[34:35], 0, v[128:129]
	ds_read_b128 v[200:203], v153 offset:32768
	ds_read_b128 v[214:217], v153 offset:33792
	ds_read_b128 v[218:221], v153 offset:34816
	ds_read_b128 v[222:225], v153 offset:35840
	ds_read_b128 v[226:229], v153 offset:36864
	ds_read_b128 v[230:233], v153 offset:37888
	ds_read_b128 v[234:237], v153 offset:38912
	ds_read_b128 v[238:241], v153 offset:39936
	global_load_lds_dwordx4 v[246:247], off
	v_lshl_add_u64 v[246:247], s[34:35], 0, v[130:131]
	s_mov_b32 m0, s75
	s_nop 0
	global_load_lds_dwordx4 v[246:247], off
	s_waitcnt vmcnt(8)
	s_waitcnt lgkmcnt(0)
	s_barrier
	s_setprio 1
	v_mfma_f32_16x16x32_bf16 v[124:127], v[138:141], v[200:203], v[124:127]
	v_mfma_f32_16x16x32_bf16 v[120:123], v[146:149], v[200:203], v[120:123]
	v_mfma_f32_16x16x32_bf16 v[108:111], v[138:141], v[218:221], v[108:111]
	v_mfma_f32_16x16x32_bf16 v[104:107], v[146:149], v[218:221], v[104:107]
	v_mfma_f32_16x16x32_bf16 v[92:95], v[138:141], v[226:229], v[92:95]
	v_mfma_f32_16x16x32_bf16 v[88:91], v[146:149], v[226:229], v[88:91]
	v_mfma_f32_16x16x32_bf16 v[76:79], v[138:141], v[234:237], v[76:79]
	v_mfma_f32_16x16x32_bf16 v[72:75], v[146:149], v[234:237], v[72:75]
	v_mfma_f32_16x16x32_bf16 v[124:127], v[142:145], v[214:217], v[124:127]
	v_mfma_f32_16x16x32_bf16 v[120:123], v[154:157], v[214:217], v[120:123]
	v_mfma_f32_16x16x32_bf16 v[108:111], v[142:145], v[222:225], v[108:111]
	v_mfma_f32_16x16x32_bf16 v[104:107], v[154:157], v[222:225], v[104:107]
	v_mfma_f32_16x16x32_bf16 v[92:95], v[142:145], v[230:233], v[92:95]
	v_mfma_f32_16x16x32_bf16 v[88:91], v[154:157], v[230:233], v[88:91]
	v_mfma_f32_16x16x32_bf16 v[76:79], v[142:145], v[238:241], v[76:79]
	v_mfma_f32_16x16x32_bf16 v[72:75], v[154:157], v[238:241], v[72:75]
	s_setprio 0
	s_setprio 1
	v_mfma_f32_16x16x32_bf16 v[116:119], v[184:187], v[200:203], v[116:119]
	v_mfma_f32_16x16x32_bf16 v[112:115], v[192:195], v[200:203], v[112:115]
	v_mfma_f32_16x16x32_bf16 v[100:103], v[184:187], v[218:221], v[100:103]
	v_mfma_f32_16x16x32_bf16 v[96:99], v[192:195], v[218:221], v[96:99]
	v_mfma_f32_16x16x32_bf16 v[84:87], v[184:187], v[226:229], v[84:87]
	v_mfma_f32_16x16x32_bf16 v[80:83], v[192:195], v[226:229], v[80:83]
	v_mfma_f32_16x16x32_bf16 v[68:71], v[184:187], v[234:237], v[68:71]
	v_mfma_f32_16x16x32_bf16 v[64:67], v[192:195], v[234:237], v[64:67]
	v_mfma_f32_16x16x32_bf16 v[116:119], v[188:191], v[214:217], v[116:119]
	v_mfma_f32_16x16x32_bf16 v[112:115], v[196:199], v[214:217], v[112:115]
	v_mfma_f32_16x16x32_bf16 v[100:103], v[188:191], v[222:225], v[100:103]
	v_mfma_f32_16x16x32_bf16 v[96:99], v[196:199], v[222:225], v[96:99]
	v_mfma_f32_16x16x32_bf16 v[84:87], v[188:191], v[230:233], v[84:87]
	v_mfma_f32_16x16x32_bf16 v[80:83], v[196:199], v[230:233], v[80:83]
	v_mfma_f32_16x16x32_bf16 v[68:71], v[188:191], v[238:241], v[68:71]
	v_mfma_f32_16x16x32_bf16 v[64:67], v[196:199], v[238:241], v[64:67]
	s_setprio 0
	s_barrier
; #define PG8_STAGE(bufoff, gbase, voff) do { _Pragma("unroll") for (int _i = 0; _i < 2; ++_i) \
;         __builtin_amdgcn_global_load_lds((const unsigned*)((const char*)(gbase) + (voff)[_i]), (PG8_LAS unsigned*)(lds + (bufoff) + ldsw + _i * 8192), 16, 0, 0); } while (0)
; #define PG8_WAIT_V(n) asm volatile("s_waitcnt vmcnt(" #n ")" ::: "memory")
; #define PG8_WAIT_L(n) asm volatile("s_waitcnt lgkmcnt(" #n ")" ::: "memory")
; #define PG8_BAR __builtin_amdgcn_s_barrier()
; #define PG8_SCHED __builtin_amdgcn_sched_barrier(0)
; template <class Epi, class Sched, bool ALIGN_EPI = false, bool SP2 = false, bool F8 = false>
; __device__ __forceinline__ void gemm_phase(PG8_LAS unsigned char* lds, const Gemm g, const Sched& S, const Epi& E) {
;     ...
;             PG8_LDA(At, 1, 1); PG8_STAGE(PG8_SB(1, 0), b3, voffB); PG8_STAGE(PG8_SB(1, 1), b3 + hstep, voffB); PG8_STAGE(PG8_SA(1, 0), a3, voffA);
;             PG8_WAIT_V(8); PG8_WAIT_L(0); PG8_BAR; PG8_MMA(1, 0, At, B0); PG8_MMA(1, 1, At, B1); PG8_BAR; PG8_SCHED;
	s_add_i32 s29, s29, s64
	v_lshl_add_u64 v[158:159], v[158:159], 0, s[14:15]
	s_mov_b32 m0, s29
	ds_read_b128 v[200:203], v153 offset:49152
	ds_read_b128 v[214:217], v153 offset:50176
	ds_read_b128 v[218:221], v153 offset:51200
	ds_read_b128 v[222:225], v153 offset:52224
	ds_read_b128 v[226:229], v153 offset:53248
	ds_read_b128 v[230:233], v153 offset:54272
	ds_read_b128 v[234:237], v153 offset:55296
	ds_read_b128 v[238:241], v153 offset:56320
	global_load_lds_dwordx4 v[158:159], off
	s_add_i32 m0, s29, 0x2000
	s_add_u32 s34, s58, 0x80080
	v_lshl_add_u64 v[158:159], v[162:163], 0, s[14:15]
	s_addc_u32 s35, s59, 0
	s_add_i32 s29, s47, s64
	global_load_lds_dwordx4 v[158:159], off
	v_lshl_add_u64 v[158:159], s[34:35], 0, v[160:161]
	s_mov_b32 m0, s29
	s_nop 0
	global_load_lds_dwordx4 v[158:159], off
	v_lshl_add_u64 v[158:159], s[34:35], 0, v[132:133]
	s_add_i32 m0, s29, 0x2000
	s_nop 0
	global_load_lds_dwordx4 v[158:159], off
	v_lshl_add_u64 v[158:159], v[242:243], 0, s[14:15]
	s_mov_b32 m0, s52
	s_nop 0
	global_load_lds_dwordx4 v[158:159], off
	v_lshl_add_u64 v[158:159], v[244:245], 0, s[14:15]
	s_mov_b32 m0, s53
	s_nop 0
	global_load_lds_dwordx4 v[158:159], off
	s_waitcnt vmcnt(8)
	s_waitcnt lgkmcnt(0)
	s_barrier
	s_setprio 1
	v_mfma_f32_16x16x32_bf16 v[60:63], v[138:141], v[200:203], v[60:63]
	v_mfma_f32_16x16x32_bf16 v[56:59], v[146:149], v[200:203], v[56:59]
	v_mfma_f32_16x16x32_bf16 v[44:47], v[138:141], v[218:221], v[44:47]
	v_mfma_f32_16x16x32_bf16 v[40:43], v[146:149], v[218:221], v[40:43]
	v_mfma_f32_16x16x32_bf16 v[28:31], v[138:141], v[226:229], v[28:31]
	v_mfma_f32_16x16x32_bf16 v[24:27], v[146:149], v[226:229], v[24:27]
	v_mfma_f32_16x16x32_bf16 v[12:15], v[138:141], v[234:237], v[12:15]
	v_mfma_f32_16x16x32_bf16 v[8:11], v[146:149], v[234:237], v[8:11]
	v_mfma_f32_16x16x32_bf16 v[60:63], v[142:145], v[214:217], v[60:63]
	v_mfma_f32_16x16x32_bf16 v[56:59], v[154:157], v[214:217], v[56:59]
	v_mfma_f32_16x16x32_bf16 v[44:47], v[142:145], v[222:225], v[44:47]
	v_mfma_f32_16x16x32_bf16 v[40:43], v[154:157], v[222:225], v[40:43]
	v_mfma_f32_16x16x32_bf16 v[28:31], v[142:145], v[230:233], v[28:31]
	v_mfma_f32_16x16x32_bf16 v[24:27], v[154:157], v[230:233], v[24:27]
	v_mfma_f32_16x16x32_bf16 v[12:15], v[142:145], v[238:241], v[12:15]
	v_mfma_f32_16x16x32_bf16 v[8:11], v[154:157], v[238:241], v[8:11]
	s_setprio 0
	s_setprio 1
	v_mfma_f32_16x16x32_bf16 v[52:55], v[184:187], v[200:203], v[52:55]
	v_mfma_f32_16x16x32_bf16 v[48:51], v[192:195], v[200:203], v[48:51]
	v_mfma_f32_16x16x32_bf16 v[36:39], v[184:187], v[218:221], v[36:39]
	v_mfma_f32_16x16x32_bf16 v[32:35], v[192:195], v[218:221], v[32:35]
	v_mfma_f32_16x16x32_bf16 v[20:23], v[184:187], v[226:229], v[20:23]
	v_mfma_f32_16x16x32_bf16 v[16:19], v[192:195], v[226:229], v[16:19]
	v_mfma_f32_16x16x32_bf16 v[4:7], v[184:187], v[234:237], v[4:7]
	v_mfma_f32_16x16x32_bf16 v[0:3], v[192:195], v[234:237], v[0:3]
	v_mfma_f32_16x16x32_bf16 v[52:55], v[188:191], v[214:217], v[52:55]
	v_mfma_f32_16x16x32_bf16 v[48:51], v[196:199], v[214:217], v[48:51]
	v_mfma_f32_16x16x32_bf16 v[36:39], v[188:191], v[222:225], v[36:39]
	v_mfma_f32_16x16x32_bf16 v[32:35], v[196:199], v[222:225], v[32:35]
	v_mfma_f32_16x16x32_bf16 v[20:23], v[188:191], v[230:233], v[20:23]
	v_mfma_f32_16x16x32_bf16 v[16:19], v[196:199], v[230:233], v[16:19]
	v_mfma_f32_16x16x32_bf16 v[4:7], v[188:191], v[238:241], v[4:7]
	v_mfma_f32_16x16x32_bf16 v[0:3], v[196:199], v[238:241], v[0:3]
	s_setprio 0
	s_barrier
	s_add_i32 s28, s28, 2
	s_add_u32 s36, s36, 0x100
	s_addc_u32 s37, s37, 0
	s_add_u32 s19, s19, 0x100
	s_addc_u32 s23, s23, 0
	s_cmp_gt_u32 s28, 29
	s_cbranch_scc0 .LBB0_59

; #define PG8_STAGE(bufoff, gbase, voff) do { _Pragma("unroll") for (int _i = 0; _i < 2; ++_i) \
;         __builtin_amdgcn_global_load_lds((const unsigned*)((const char*)(gbase) + (voff)[_i]), (PG8_LAS unsigned*)(lds + (bufoff) + ldsw + _i * 8192), 16, 0, 0); } while (0)
; #define PG8_WAIT_V(n) asm volatile("s_waitcnt vmcnt(" #n ")" ::: "memory")
; #define PG8_WAIT_L(n) asm volatile("s_waitcnt lgkmcnt(" #n ")" ::: "memory")
; #define PG8_BAR __builtin_amdgcn_s_barrier()
; #define PG8_SCHED __builtin_amdgcn_sched_barrier(0)
; template <class Epi, class Sched, bool ALIGN_EPI = false, bool SP2 = false, bool F8 = false>
; __device__ __forceinline__ void gemm_phase(PG8_LAS unsigned char* lds, const Gemm g, const Sched& S, const Epi& E) {
;     ...
;         const bool has_next = S.next(ui + 1, nxt);
;         const char* nA = has_next ? (const char*)g.A + (size_t)nxt.pm * tstep : cA; const char* nB = has_next ? (const char*)g.Bt + (size_t)nxt.pn * tstep : cB;
;         for (int t = 0; t < nt; t += 2) {
;             const bool last = (t == nt - 2);
;             const char* a1 = cA + (size_t)(t + 1) * kstep;
;             const char* a2 = last ? nA : cA + (size_t)(t + 2) * kstep; const char* b2 = last ? nB : cB + (size_t)(t + 2) * kstep;
;             const char* a3 = a2 + kstep; const char* b3 = b2 + kstep;
;             if (last && has_next) S.a_ready(nxt);
;             if constexpr (SP2) {
;             PG8_LDB(B0, 0, 0); PG8_LDB(B1, 0, 1); PG8_SCHED; PG8_LDA(At, 0, 0); PG8_STAGE(PG8_SA(1, 1), a1 + hstep, voffA);
;             PG8_WAIT_V(8); PG8_WAIT_L(0); PG8_BAR; PG8_MMA(0, 0, At, B0); PG8_MMA(0, 1, At, B1); PG8_BAR; PG8_SCHED;
;             PG8_LDA(At, 0, 1); PG8_STAGE(PG8_SB(0, 0), b2, voffB); PG8_STAGE(PG8_SB(0, 1), b2 + hstep, voffB); PG8_STAGE(PG8_SA(0, 0), a2, voffA);
;             PG8_WAIT_V(8); PG8_WAIT_L(0); PG8_BAR; PG8_MMA(1, 0, At, B0); PG8_MMA(1, 1, At, B1); PG8_BAR; PG8_SCHED;
.LBB0_96:
	s_ashr_i32 s17, s16, 31
	s_lshl_b64 s[28:29], s[16:17], 18
	s_add_u32 s36, s62, s28
	s_addc_u32 s37, s63, s29
	s_and_b64 s[28:29], s[38:39], exec
	s_cselect_b32 s17, s37, s43
	s_cselect_b32 s19, s36, s42
	s_ashr_i32 s11, s10, 31
	s_lshl_b64 s[28:29], s[10:11], 18
	s_add_u32 s40, s13, s28
	s_addc_u32 s41, s22, s29
	s_and_b64 s[28:29], s[38:39], exec
	s_cselect_b32 s11, s41, s45
	s_cselect_b32 s23, s40, s44
	s_add_u32 s42, s42, 0x20080
	s_addc_u32 s43, s43, 0
	s_add_u32 s28, s44, 0x100
	s_addc_u32 s29, s45, 0
	s_mov_b32 s54, -2
	s_add_u32 s44, s42, 0xfffe0080
	s_addc_u32 s45, s43, -1
	s_add_i32 s55, 0, 0x10000
	s_cmp_eq_u32 s54, 4
	s_cselect_b32 s47, s17, s45
	s_cselect_b32 s46, s19, s44
	s_cselect_b32 s45, s11, s29
	s_cselect_b32 s44, s23, s28
	s_add_i32 s56, 0, 0x14000
	v_add_u32_e32 v154, s55, v143
	v_add_u32_e32 v158, s56, v143
	ds_read_b128 v[138:141], v154
	ds_read_b128 v[146:149], v154 offset:1024
	ds_read_b128 v[150:153], v154 offset:2048
	ds_read_b128 v[154:157], v154 offset:3072
	ds_read_b128 v[184:187], v158
	ds_read_b128 v[188:191], v158 offset:1024
	ds_read_b128 v[192:195], v158 offset:2048
	ds_read_b128 v[196:199], v158 offset:3072
	v_lshl_add_u64 v[158:159], s[42:43], 0, v[134:135]
	s_add_i32 m0, s35, 0xc000
	ds_read_b128 v[200:203], v145
	ds_read_b128 v[214:217], v145 offset:1024
	ds_read_b128 v[218:221], v145 offset:2048
	ds_read_b128 v[222:225], v145 offset:3072
	ds_read_b128 v[226:229], v145 offset:4096
	ds_read_b128 v[230:233], v145 offset:5120
	ds_read_b128 v[234:237], v145 offset:6144
	ds_read_b128 v[238:241], v145 offset:7168
	global_load_lds_dwordx4 v[158:159], off
	v_lshl_add_u64 v[158:159], s[42:43], 0, v[136:137]
	s_add_i32 m0, s35, 0xe000
	s_nop 0
	global_load_lds_dwordx4 v[158:159], off
	s_waitcnt vmcnt(8)
	s_waitcnt lgkmcnt(0)
	s_barrier
	s_setprio 1
	v_mfma_f32_16x16x32_bf16 v[124:127], v[138:141], v[200:203], 0
	v_mfma_f32_16x16x32_bf16 v[120:123], v[150:153], v[200:203], 0
	v_mfma_f32_16x16x32_bf16 v[108:111], v[138:141], v[218:221], 0
	v_mfma_f32_16x16x32_bf16 v[104:107], v[150:153], v[218:221], 0
	v_mfma_f32_16x16x32_bf16 v[92:95], v[138:141], v[226:229], 0
	v_mfma_f32_16x16x32_bf16 v[88:91], v[150:153], v[226:229], 0
	v_mfma_f32_16x16x32_bf16 v[76:79], v[138:141], v[234:237], 0
	v_mfma_f32_16x16x32_bf16 v[72:75], v[150:153], v[234:237], 0
	v_mfma_f32_16x16x32_bf16 v[124:127], v[146:149], v[214:217], v[124:127]
	v_mfma_f32_16x16x32_bf16 v[120:123], v[154:157], v[214:217], v[120:123]
	v_mfma_f32_16x16x32_bf16 v[108:111], v[146:149], v[222:225], v[108:111]
	v_mfma_f32_16x16x32_bf16 v[104:107], v[154:157], v[222:225], v[104:107]
	v_mfma_f32_16x16x32_bf16 v[92:95], v[146:149], v[230:233], v[92:95]
	v_mfma_f32_16x16x32_bf16 v[88:91], v[154:157], v[230:233], v[88:91]
	v_mfma_f32_16x16x32_bf16 v[76:79], v[146:149], v[238:241], v[76:79]
	v_mfma_f32_16x16x32_bf16 v[72:75], v[154:157], v[238:241], v[72:75]
	s_setprio 0
	s_setprio 1
	v_mfma_f32_16x16x32_bf16 v[116:119], v[184:187], v[200:203], 0
	v_mfma_f32_16x16x32_bf16 v[112:115], v[192:195], v[200:203], 0
	v_mfma_f32_16x16x32_bf16 v[100:103], v[184:187], v[218:221], 0
	v_mfma_f32_16x16x32_bf16 v[96:99], v[192:195], v[218:221], 0
	v_mfma_f32_16x16x32_bf16 v[84:87], v[184:187], v[226:229], 0
	v_mfma_f32_16x16x32_bf16 v[80:83], v[192:195], v[226:229], 0
	v_mfma_f32_16x16x32_bf16 v[68:71], v[184:187], v[234:237], 0
	v_mfma_f32_16x16x32_bf16 v[64:67], v[192:195], v[234:237], 0
	v_mfma_f32_16x16x32_bf16 v[116:119], v[188:191], v[214:217], v[116:119]
	v_mfma_f32_16x16x32_bf16 v[112:115], v[196:199], v[214:217], v[112:115]
	v_mfma_f32_16x16x32_bf16 v[100:103], v[188:191], v[222:225], v[100:103]
	v_mfma_f32_16x16x32_bf16 v[96:99], v[196:199], v[222:225], v[96:99]
	v_mfma_f32_16x16x32_bf16 v[84:87], v[188:191], v[230:233], v[84:87]
	v_mfma_f32_16x16x32_bf16 v[80:83], v[196:199], v[230:233], v[80:83]
	v_mfma_f32_16x16x32_bf16 v[68:71], v[188:191], v[238:241], v[68:71]
	v_mfma_f32_16x16x32_bf16 v[64:67], v[196:199], v[238:241], v[64:67]
	s_setprio 0
	s_barrier
	s_add_i32 s55, s55, s34
	v_lshl_add_u64 v[158:159], s[44:45], 0, v[160:161]
	s_mov_b32 m0, s55
	ds_read_b128 v[200:203], v145 offset:16384
	ds_read_b128 v[214:217], v145 offset:17408
	ds_read_b128 v[218:221], v145 offset:18432
	ds_read_b128 v[222:225], v145 offset:19456
	ds_read_b128 v[226:229], v145 offset:20480
	ds_read_b128 v[230:233], v145 offset:21504
	ds_read_b128 v[234:237], v145 offset:22528
	ds_read_b128 v[238:241], v145 offset:23552
	global_load_lds_dwordx4 v[158:159], off
	s_add_i32 m0, s55, 0x2000
	s_add_u32 s58, s44, 0x20000
	v_lshl_add_u64 v[162:163], s[44:45], 0, v[128:129]
	s_addc_u32 s59, s45, 0
	s_add_i32 s55, s56, s34
	global_load_lds_dwordx4 v[162:163], off
	v_lshl_add_u64 v[242:243], s[58:59], 0, v[160:161]
	s_mov_b32 m0, s55
	v_lshl_add_u64 v[244:245], s[46:47], 0, v[130:131]
	global_load_lds_dwordx4 v[242:243], off
	v_lshl_add_u64 v[242:243], s[58:59], 0, v[128:129]
	s_add_i32 m0, s55, 0x2000
	s_nop 0
	global_load_lds_dwordx4 v[242:243], off
	v_lshl_add_u64 v[242:243], s[46:47], 0, v[132:133]
	s_mov_b32 m0, s35
	s_nop 0
	global_load_lds_dwordx4 v[242:243], off
	s_mov_b32 m0, s48
	s_nop 0
	global_load_lds_dwordx4 v[244:245], off
	s_waitcnt vmcnt(8)
	s_waitcnt lgkmcnt(0)
	s_barrier
; #define PG8_STAGE(bufoff, gbase, voff) do { _Pragma("unroll") for (int _i = 0; _i < 2; ++_i) \
;         __builtin_amdgcn_global_load_lds((const unsigned*)((const char*)(gbase) + (voff)[_i]), (PG8_LAS unsigned*)(lds + (bufoff) + ldsw + _i * 8192), 16, 0, 0); } while (0)
; #define PG8_WAIT_V(n) asm volatile("s_waitcnt vmcnt(" #n ")" ::: "memory")
; #define PG8_WAIT_L(n) asm volatile("s_waitcnt lgkmcnt(" #n ")" ::: "memory")
; #define PG8_BAR __builtin_amdgcn_s_barrier()
; #define PG8_SCHED __builtin_amdgcn_sched_barrier(0)
; template <class Epi, class Sched, bool ALIGN_EPI = false, bool SP2 = false, bool F8 = false>
; __device__ __forceinline__ void gemm_phase(PG8_LAS unsigned char* lds, const Gemm g, const Sched& S, const Epi& E) {
;     ...
;             PG8_WAIT_V(8); PG8_WAIT_L(0); PG8_BAR; PG8_MMA(1, 0, At, B0); PG8_MMA(1, 1, At, B1); PG8_BAR; PG8_SCHED;
;             PG8_LDB(B0, 1, 0); PG8_LDB(B1, 1, 1); PG8_SCHED; PG8_LDA(At, 1, 0); PG8_STAGE(PG8_SA(0, 1), a2 + hstep, voffA);
;             PG8_WAIT_V(8); PG8_WAIT_L(0); PG8_BAR; PG8_MMA(0, 0, At, B0); PG8_MMA(0, 1, At, B1); PG8_BAR; PG8_SCHED;
	s_setprio 1
	v_mfma_f32_16x16x32_bf16 v[60:63], v[138:141], v[200:203], 0
	v_mfma_f32_16x16x32_bf16 v[56:59], v[150:153], v[200:203], 0
	v_mfma_f32_16x16x32_bf16 v[44:47], v[138:141], v[218:221], 0
	v_mfma_f32_16x16x32_bf16 v[40:43], v[150:153], v[218:221], 0
	v_mfma_f32_16x16x32_bf16 v[28:31], v[138:141], v[226:229], 0
	v_mfma_f32_16x16x32_bf16 v[24:27], v[150:153], v[226:229], 0
	v_mfma_f32_16x16x32_bf16 v[12:15], v[138:141], v[234:237], 0
	v_mfma_f32_16x16x32_bf16 v[8:11], v[150:153], v[234:237], 0
	v_mfma_f32_16x16x32_bf16 v[60:63], v[146:149], v[214:217], v[60:63]
	v_mfma_f32_16x16x32_bf16 v[56:59], v[154:157], v[214:217], v[56:59]
	v_mfma_f32_16x16x32_bf16 v[44:47], v[146:149], v[222:225], v[44:47]
	v_mfma_f32_16x16x32_bf16 v[40:43], v[154:157], v[222:225], v[40:43]
	v_mfma_f32_16x16x32_bf16 v[28:31], v[146:149], v[230:233], v[28:31]
	v_mfma_f32_16x16x32_bf16 v[24:27], v[154:157], v[230:233], v[24:27]
	v_mfma_f32_16x16x32_bf16 v[12:15], v[146:149], v[238:241], v[12:15]
	v_mfma_f32_16x16x32_bf16 v[8:11], v[154:157], v[238:241], v[8:11]
	s_setprio 0
	s_setprio 1
	v_mfma_f32_16x16x32_bf16 v[52:55], v[184:187], v[200:203], 0
	v_mfma_f32_16x16x32_bf16 v[48:51], v[192:195], v[200:203], 0
	v_mfma_f32_16x16x32_bf16 v[36:39], v[184:187], v[218:221], 0
	v_mfma_f32_16x16x32_bf16 v[32:35], v[192:195], v[218:221], 0
	v_mfma_f32_16x16x32_bf16 v[20:23], v[184:187], v[226:229], 0
	v_mfma_f32_16x16x32_bf16 v[16:19], v[192:195], v[226:229], 0
	v_mfma_f32_16x16x32_bf16 v[4:7], v[184:187], v[234:237], 0
	v_mfma_f32_16x16x32_bf16 v[0:3], v[192:195], v[234:237], 0
	v_mfma_f32_16x16x32_bf16 v[52:55], v[188:191], v[214:217], v[52:55]
	v_mfma_f32_16x16x32_bf16 v[48:51], v[196:199], v[214:217], v[48:51]
	v_mfma_f32_16x16x32_bf16 v[36:39], v[188:191], v[222:225], v[36:39]
	v_mfma_f32_16x16x32_bf16 v[32:35], v[196:199], v[222:225], v[32:35]
	v_mfma_f32_16x16x32_bf16 v[20:23], v[188:191], v[230:233], v[20:23]
	v_mfma_f32_16x16x32_bf16 v[16:19], v[196:199], v[230:233], v[16:19]
	v_mfma_f32_16x16x32_bf16 v[4:7], v[188:191], v[238:241], v[4:7]
	v_mfma_f32_16x16x32_bf16 v[0:3], v[196:199], v[238:241], v[0:3]
	s_setprio 0
	s_barrier
	s_add_i32 s55, 0, 0x18000
	s_add_i32 s56, 0, 0x1c000
	v_add_u32_e32 v154, s55, v143
	v_add_u32_e32 v196, s56, v143
	ds_read_b128 v[138:141], v154
	ds_read_b128 v[146:149], v154 offset:1024
	ds_read_b128 v[150:153], v154 offset:2048
	ds_read_b128 v[154:157], v154 offset:3072
	ds_read_b128 v[184:187], v196
	ds_read_b128 v[188:191], v196 offset:1024
	ds_read_b128 v[192:195], v196 offset:2048
	ds_read_b128 v[196:199], v196 offset:3072
	s_add_u32 s46, s46, 0x20000
	s_addc_u32 s47, s47, 0
	s_mov_b32 m0, s49
	v_lshl_add_u64 v[246:247], s[46:47], 0, v[132:133]
	ds_read_b128 v[200:203], v145 offset:32768
	ds_read_b128 v[214:217], v145 offset:33792
	ds_read_b128 v[218:221], v145 offset:34816
	ds_read_b128 v[222:225], v145 offset:35840
	ds_read_b128 v[226:229], v145 offset:36864
	ds_read_b128 v[230:233], v145 offset:37888
	ds_read_b128 v[234:237], v145 offset:38912
	ds_read_b128 v[238:241], v145 offset:39936
	global_load_lds_dwordx4 v[246:247], off
	v_lshl_add_u64 v[246:247], s[46:47], 0, v[130:131]
	s_mov_b32 m0, s50
	s_nop 0
	global_load_lds_dwordx4 v[246:247], off
	s_waitcnt vmcnt(8)
	s_waitcnt lgkmcnt(0)
	s_barrier
	s_setprio 1
	v_mfma_f32_16x16x32_bf16 v[124:127], v[138:141], v[200:203], v[124:127]
	v_mfma_f32_16x16x32_bf16 v[120:123], v[150:153], v[200:203], v[120:123]
	v_mfma_f32_16x16x32_bf16 v[108:111], v[138:141], v[218:221], v[108:111]
	v_mfma_f32_16x16x32_bf16 v[104:107], v[150:153], v[218:221], v[104:107]
	v_mfma_f32_16x16x32_bf16 v[92:95], v[138:141], v[226:229], v[92:95]
	v_mfma_f32_16x16x32_bf16 v[88:91], v[150:153], v[226:229], v[88:91]
	v_mfma_f32_16x16x32_bf16 v[76:79], v[138:141], v[234:237], v[76:79]
	v_mfma_f32_16x16x32_bf16 v[72:75], v[150:153], v[234:237], v[72:75]
	v_mfma_f32_16x16x32_bf16 v[124:127], v[146:149], v[214:217], v[124:127]
	v_mfma_f32_16x16x32_bf16 v[120:123], v[154:157], v[214:217], v[120:123]
	v_mfma_f32_16x16x32_bf16 v[108:111], v[146:149], v[222:225], v[108:111]
	v_mfma_f32_16x16x32_bf16 v[104:107], v[154:157], v[222:225], v[104:107]
	v_mfma_f32_16x16x32_bf16 v[92:95], v[146:149], v[230:233], v[92:95]
	v_mfma_f32_16x16x32_bf16 v[88:91], v[154:157], v[230:233], v[88:91]
	v_mfma_f32_16x16x32_bf16 v[76:79], v[146:149], v[238:241], v[76:79]
	v_mfma_f32_16x16x32_bf16 v[72:75], v[154:157], v[238:241], v[72:75]
	s_setprio 0
	s_setprio 1
	v_mfma_f32_16x16x32_bf16 v[116:119], v[184:187], v[200:203], v[116:119]
	v_mfma_f32_16x16x32_bf16 v[112:115], v[192:195], v[200:203], v[112:115]
	v_mfma_f32_16x16x32_bf16 v[100:103], v[184:187], v[218:221], v[100:103]
	v_mfma_f32_16x16x32_bf16 v[96:99], v[192:195], v[218:221], v[96:99]
	v_mfma_f32_16x16x32_bf16 v[84:87], v[184:187], v[226:229], v[84:87]
	v_mfma_f32_16x16x32_bf16 v[80:83], v[192:195], v[226:229], v[80:83]
	v_mfma_f32_16x16x32_bf16 v[68:71], v[184:187], v[234:237], v[68:71]
	v_mfma_f32_16x16x32_bf16 v[64:67], v[192:195], v[234:237], v[64:67]
	v_mfma_f32_16x16x32_bf16 v[116:119], v[188:191], v[214:217], v[116:119]
	v_mfma_f32_16x16x32_bf16 v[112:115], v[196:199], v[214:217], v[112:115]
	v_mfma_f32_16x16x32_bf16 v[100:103], v[188:191], v[222:225], v[100:103]
	v_mfma_f32_16x16x32_bf16 v[96:99], v[196:199], v[222:225], v[96:99]
	v_mfma_f32_16x16x32_bf16 v[84:87], v[188:191], v[230:233], v[84:87]
	v_mfma_f32_16x16x32_bf16 v[80:83], v[196:199], v[230:233], v[80:83]
	v_mfma_f32_16x16x32_bf16 v[68:71], v[188:191], v[238:241], v[68:71]
	v_mfma_f32_16x16x32_bf16 v[64:67], v[196:199], v[238:241], v[64:67]
	s_setprio 0
	s_barrier
; #define PG8_STAGE(bufoff, gbase, voff) do { _Pragma("unroll") for (int _i = 0; _i < 2; ++_i) \
;         __builtin_amdgcn_global_load_lds((const unsigned*)((const char*)(gbase) + (voff)[_i]), (PG8_LAS unsigned*)(lds + (bufoff) + ldsw + _i * 8192), 16, 0, 0); } while (0)
; #define PG8_WAIT_V(n) asm volatile("s_waitcnt vmcnt(" #n ")" ::: "memory")
; #define PG8_WAIT_L(n) asm volatile("s_waitcnt lgkmcnt(" #n ")" ::: "memory")
; #define PG8_BAR __builtin_amdgcn_s_barrier()
; #define PG8_SCHED __builtin_amdgcn_sched_barrier(0)
; template <class Epi, class Sched, bool ALIGN_EPI = false, bool SP2 = false, bool F8 = false>
; __device__ __forceinline__ void gemm_phase(PG8_LAS unsigned char* lds, const Gemm g, const Sched& S, const Epi& E) {
;     ...
;             const bool last = (t == nt - 2);
;             const char* a1 = cA + (size_t)(t + 1) * kstep;
;             const char* a2 = last ? nA : cA + (size_t)(t + 2) * kstep; const char* b2 = last ? nB : cB + (size_t)(t + 2) * kstep;
;             const char* a3 = a2 + kstep; const char* b3 = b2 + kstep;
;             if (last && has_next) S.a_ready(nxt);
;             if constexpr (SP2) {
;             PG8_LDB(B0, 0, 0); PG8_LDB(B1, 0, 1); PG8_SCHED; PG8_LDA(At, 0, 0); PG8_STAGE(PG8_SA(1, 1), a1 + hstep, voffA);
;             PG8_WAIT_V(8); PG8_WAIT_L(0); PG8_BAR; PG8_MMA(0, 0, At, B0); PG8_MMA(0, 1, At, B1); PG8_BAR; PG8_SCHED;
;             PG8_LDA(At, 0, 1); PG8_STAGE(PG8_SB(0, 0), b2, voffB); PG8_STAGE(PG8_SB(0, 1), b2 + hstep, voffB); PG8_STAGE(PG8_SA(0, 0), a2, voffA);
;             PG8_WAIT_V(8); PG8_WAIT_L(0); PG8_BAR; PG8_MMA(1, 0, At, B0); PG8_MMA(1, 1, At, B1); PG8_BAR; PG8_SCHED;
;             PG8_LDB(B0, 1, 0); PG8_LDB(B1, 1, 1); PG8_SCHED; PG8_LDA(At, 1, 0); PG8_STAGE(PG8_SA(0, 1), a2 + hstep, voffA);
;             PG8_WAIT_V(8); PG8_WAIT_L(0); PG8_BAR; PG8_MMA(0, 0, At, B0); PG8_MMA(0, 1, At, B1); PG8_BAR; PG8_SCHED;
;             PG8_LDA(At, 1, 1); PG8_STAGE(PG8_SB(1, 0), b3, voffB); PG8_STAGE(PG8_SB(1, 1), b3 + hstep, voffB); PG8_STAGE(PG8_SA(1, 0), a3, voffA);
;             PG8_WAIT_V(8); PG8_WAIT_L(0); PG8_BAR; PG8_MMA(1, 0, At, B0); PG8_MMA(1, 1, At, B1); PG8_BAR; PG8_SCHED;
	s_add_i32 s46, s55, s34
	v_lshl_add_u64 v[158:159], v[158:159], 0, s[14:15]
	s_mov_b32 m0, s46
	ds_read_b128 v[200:203], v145 offset:49152
	ds_read_b128 v[214:217], v145 offset:50176
	ds_read_b128 v[218:221], v145 offset:51200
	ds_read_b128 v[222:225], v145 offset:52224
	ds_read_b128 v[226:229], v145 offset:53248
	ds_read_b128 v[230:233], v145 offset:54272
	ds_read_b128 v[234:237], v145 offset:55296
	ds_read_b128 v[238:241], v145 offset:56320
	global_load_lds_dwordx4 v[158:159], off
	s_add_i32 m0, s46, 0x2000
	s_add_u32 s44, s44, 0x20080
	v_lshl_add_u64 v[158:159], v[162:163], 0, s[14:15]
	s_addc_u32 s45, s45, 0
	s_add_i32 s46, s56, s34
	global_load_lds_dwordx4 v[158:159], off
	v_lshl_add_u64 v[158:159], s[44:45], 0, v[160:161]
	s_mov_b32 m0, s46
	s_nop 0
	global_load_lds_dwordx4 v[158:159], off
	v_lshl_add_u64 v[158:159], s[44:45], 0, v[128:129]
	s_add_i32 m0, s46, 0x2000
	s_nop 0
	global_load_lds_dwordx4 v[158:159], off
	v_lshl_add_u64 v[158:159], v[242:243], 0, s[14:15]
	s_mov_b32 m0, s51
	s_nop 0
	global_load_lds_dwordx4 v[158:159], off
	v_lshl_add_u64 v[158:159], v[244:245], 0, s[14:15]
	s_mov_b32 m0, s52
	s_nop 0
	global_load_lds_dwordx4 v[158:159], off
	s_waitcnt vmcnt(8)
	s_waitcnt lgkmcnt(0)
	s_barrier
	s_setprio 1
	v_mfma_f32_16x16x32_bf16 v[60:63], v[138:141], v[200:203], v[60:63]
	v_mfma_f32_16x16x32_bf16 v[56:59], v[150:153], v[200:203], v[56:59]
	v_mfma_f32_16x16x32_bf16 v[44:47], v[138:141], v[218:221], v[44:47]
	v_mfma_f32_16x16x32_bf16 v[40:43], v[150:153], v[218:221], v[40:43]
	v_mfma_f32_16x16x32_bf16 v[28:31], v[138:141], v[226:229], v[28:31]
	v_mfma_f32_16x16x32_bf16 v[24:27], v[150:153], v[226:229], v[24:27]
	v_mfma_f32_16x16x32_bf16 v[12:15], v[138:141], v[234:237], v[12:15]
	v_mfma_f32_16x16x32_bf16 v[8:11], v[150:153], v[234:237], v[8:11]
	v_mfma_f32_16x16x32_bf16 v[60:63], v[146:149], v[214:217], v[60:63]
	v_mfma_f32_16x16x32_bf16 v[56:59], v[154:157], v[214:217], v[56:59]
	v_mfma_f32_16x16x32_bf16 v[44:47], v[146:149], v[222:225], v[44:47]
	v_mfma_f32_16x16x32_bf16 v[40:43], v[154:157], v[222:225], v[40:43]
	v_mfma_f32_16x16x32_bf16 v[28:31], v[146:149], v[230:233], v[28:31]
	v_mfma_f32_16x16x32_bf16 v[24:27], v[154:157], v[230:233], v[24:27]
	v_mfma_f32_16x16x32_bf16 v[12:15], v[146:149], v[238:241], v[12:15]
	v_mfma_f32_16x16x32_bf16 v[8:11], v[154:157], v[238:241], v[8:11]
	s_setprio 0
	s_setprio 1
	v_mfma_f32_16x16x32_bf16 v[52:55], v[184:187], v[200:203], v[52:55]
	v_mfma_f32_16x16x32_bf16 v[48:51], v[192:195], v[200:203], v[48:51]
	v_mfma_f32_16x16x32_bf16 v[36:39], v[184:187], v[218:221], v[36:39]
	v_mfma_f32_16x16x32_bf16 v[32:35], v[192:195], v[218:221], v[32:35]
	v_mfma_f32_16x16x32_bf16 v[20:23], v[184:187], v[226:229], v[20:23]
	v_mfma_f32_16x16x32_bf16 v[16:19], v[192:195], v[226:229], v[16:19]
	v_mfma_f32_16x16x32_bf16 v[4:7], v[184:187], v[234:237], v[4:7]
	v_mfma_f32_16x16x32_bf16 v[0:3], v[192:195], v[234:237], v[0:3]
	v_mfma_f32_16x16x32_bf16 v[52:55], v[188:191], v[214:217], v[52:55]
	v_mfma_f32_16x16x32_bf16 v[48:51], v[196:199], v[214:217], v[48:51]
	v_mfma_f32_16x16x32_bf16 v[36:39], v[188:191], v[222:225], v[36:39]
	v_mfma_f32_16x16x32_bf16 v[32:35], v[196:199], v[222:225], v[32:35]
	v_mfma_f32_16x16x32_bf16 v[20:23], v[188:191], v[230:233], v[20:23]
	v_mfma_f32_16x16x32_bf16 v[16:19], v[196:199], v[230:233], v[16:19]
	v_mfma_f32_16x16x32_bf16 v[4:7], v[188:191], v[238:241], v[4:7]
	v_mfma_f32_16x16x32_bf16 v[0:3], v[196:199], v[238:241], v[0:3]
	s_setprio 0
	s_barrier
	s_add_i32 s54, s54, 2
	s_add_u32 s42, s42, 0x100
	s_addc_u32 s43, s43, 0
	s_add_u32 s28, s28, 0x100
	s_addc_u32 s29, s29, 0
	s_cmp_gt_u32 s54, 5
	s_cbranch_scc0 .LBB0_97
	s_branch .Lgk_after_97
.LBB0_97:
	s_add_u32 s44, s42, 0xfffe0080
	s_addc_u32 s45, s43, -1
	s_add_i32 s55, 0, 0x10000
	s_cmp_eq_u32 s54, 4
	s_cselect_b32 s47, s17, s45
	s_cselect_b32 s46, s19, s44
	s_cselect_b32 s45, s11, s29
	s_cselect_b32 s44, s23, s28
	s_add_i32 s56, 0, 0x14000
	v_add_u32_e32 v154, s55, v143
	v_add_u32_e32 v158, s56, v143
	ds_read_b128 v[138:141], v154
	ds_read_b128 v[146:149], v154 offset:1024
	ds_read_b128 v[150:153], v154 offset:2048
	ds_read_b128 v[154:157], v154 offset:3072
	ds_read_b128 v[184:187], v158
	ds_read_b128 v[188:191], v158 offset:1024
	ds_read_b128 v[192:195], v158 offset:2048
	ds_read_b128 v[196:199], v158 offset:3072
	v_lshl_add_u64 v[158:159], s[42:43], 0, v[134:135]
	s_add_i32 m0, s35, 0xc000
	ds_read_b128 v[200:203], v145
	ds_read_b128 v[214:217], v145 offset:1024
	ds_read_b128 v[218:221], v145 offset:2048
	ds_read_b128 v[222:225], v145 offset:3072
	ds_read_b128 v[226:229], v145 offset:4096
	ds_read_b128 v[230:233], v145 offset:5120
	ds_read_b128 v[234:237], v145 offset:6144
	ds_read_b128 v[238:241], v145 offset:7168
	global_load_lds_dwordx4 v[158:159], off
	v_lshl_add_u64 v[158:159], s[42:43], 0, v[136:137]
	s_add_i32 m0, s35, 0xe000
	s_nop 0
	global_load_lds_dwordx4 v[158:159], off
	s_waitcnt vmcnt(8)
	s_waitcnt lgkmcnt(0)
	s_barrier
; #define PG8_STAGE(bufoff, gbase, voff) do { _Pragma("unroll") for (int _i = 0; _i < 2; ++_i) \
;         __builtin_amdgcn_global_load_lds((const unsigned*)((const char*)(gbase) + (voff)[_i]), (PG8_LAS unsigned*)(lds + (bufoff) + ldsw + _i * 8192), 16, 0, 0); } while (0)
; #define PG8_WAIT_V(n) asm volatile("s_waitcnt vmcnt(" #n ")" ::: "memory")
; #define PG8_WAIT_L(n) asm volatile("s_waitcnt lgkmcnt(" #n ")" ::: "memory")
; #define PG8_BAR __builtin_amdgcn_s_barrier()
; #define PG8_SCHED __builtin_amdgcn_sched_barrier(0)
; template <class Epi, class Sched, bool ALIGN_EPI = false, bool SP2 = false, bool F8 = false>
; __device__ __forceinline__ void gemm_phase(PG8_LAS unsigned char* lds, const Gemm g, const Sched& S, const Epi& E) {
;     ...
;             PG8_LDB(B0, 0, 0); PG8_LDB(B1, 0, 1); PG8_SCHED; PG8_LDA(At, 0, 0); PG8_STAGE(PG8_SA(1, 1), a1 + hstep, voffA);
;             PG8_WAIT_V(8); PG8_WAIT_L(0); PG8_BAR; PG8_MMA(0, 0, At, B0); PG8_MMA(0, 1, At, B1); PG8_BAR; PG8_SCHED;
;             PG8_LDA(At, 0, 1); PG8_STAGE(PG8_SB(0, 0), b2, voffB); PG8_STAGE(PG8_SB(0, 1), b2 + hstep, voffB); PG8_STAGE(PG8_SA(0, 0), a2, voffA);
;             PG8_WAIT_V(8); PG8_WAIT_L(0); PG8_BAR; PG8_MMA(1, 0, At, B0); PG8_MMA(1, 1, At, B1); PG8_BAR; PG8_SCHED;
	s_setprio 1
	v_mfma_f32_16x16x32_bf16 v[124:127], v[138:141], v[200:203], v[124:127]
	v_mfma_f32_16x16x32_bf16 v[120:123], v[150:153], v[200:203], v[120:123]
	v_mfma_f32_16x16x32_bf16 v[108:111], v[138:141], v[218:221], v[108:111]
	v_mfma_f32_16x16x32_bf16 v[104:107], v[150:153], v[218:221], v[104:107]
	v_mfma_f32_16x16x32_bf16 v[92:95], v[138:141], v[226:229], v[92:95]
	v_mfma_f32_16x16x32_bf16 v[88:91], v[150:153], v[226:229], v[88:91]
	v_mfma_f32_16x16x32_bf16 v[76:79], v[138:141], v[234:237], v[76:79]
	v_mfma_f32_16x16x32_bf16 v[72:75], v[150:153], v[234:237], v[72:75]
	v_mfma_f32_16x16x32_bf16 v[124:127], v[146:149], v[214:217], v[124:127]
	v_mfma_f32_16x16x32_bf16 v[120:123], v[154:157], v[214:217], v[120:123]
	v_mfma_f32_16x16x32_bf16 v[108:111], v[146:149], v[222:225], v[108:111]
	v_mfma_f32_16x16x32_bf16 v[104:107], v[154:157], v[222:225], v[104:107]
	v_mfma_f32_16x16x32_bf16 v[92:95], v[146:149], v[230:233], v[92:95]
	v_mfma_f32_16x16x32_bf16 v[88:91], v[154:157], v[230:233], v[88:91]
	v_mfma_f32_16x16x32_bf16 v[76:79], v[146:149], v[238:241], v[76:79]
	v_mfma_f32_16x16x32_bf16 v[72:75], v[154:157], v[238:241], v[72:75]
	s_setprio 0
	s_setprio 1
	v_mfma_f32_16x16x32_bf16 v[116:119], v[184:187], v[200:203], v[116:119]
	v_mfma_f32_16x16x32_bf16 v[112:115], v[192:195], v[200:203], v[112:115]
	v_mfma_f32_16x16x32_bf16 v[100:103], v[184:187], v[218:221], v[100:103]
	v_mfma_f32_16x16x32_bf16 v[96:99], v[192:195], v[218:221], v[96:99]
	v_mfma_f32_16x16x32_bf16 v[84:87], v[184:187], v[226:229], v[84:87]
	v_mfma_f32_16x16x32_bf16 v[80:83], v[192:195], v[226:229], v[80:83]
	v_mfma_f32_16x16x32_bf16 v[68:71], v[184:187], v[234:237], v[68:71]
	v_mfma_f32_16x16x32_bf16 v[64:67], v[192:195], v[234:237], v[64:67]
	v_mfma_f32_16x16x32_bf16 v[116:119], v[188:191], v[214:217], v[116:119]
	v_mfma_f32_16x16x32_bf16 v[112:115], v[196:199], v[214:217], v[112:115]
	v_mfma_f32_16x16x32_bf16 v[100:103], v[188:191], v[222:225], v[100:103]
	v_mfma_f32_16x16x32_bf16 v[96:99], v[196:199], v[222:225], v[96:99]
	v_mfma_f32_16x16x32_bf16 v[84:87], v[188:191], v[230:233], v[84:87]
	v_mfma_f32_16x16x32_bf16 v[80:83], v[196:199], v[230:233], v[80:83]
	v_mfma_f32_16x16x32_bf16 v[68:71], v[188:191], v[238:241], v[68:71]
	v_mfma_f32_16x16x32_bf16 v[64:67], v[196:199], v[238:241], v[64:67]
	s_setprio 0
	s_barrier
	s_add_i32 s55, s55, s34
	v_lshl_add_u64 v[158:159], s[44:45], 0, v[160:161]
	s_mov_b32 m0, s55
	ds_read_b128 v[200:203], v145 offset:16384
	ds_read_b128 v[214:217], v145 offset:17408
	ds_read_b128 v[218:221], v145 offset:18432
	ds_read_b128 v[222:225], v145 offset:19456
	ds_read_b128 v[226:229], v145 offset:20480
	ds_read_b128 v[230:233], v145 offset:21504
	ds_read_b128 v[234:237], v145 offset:22528
	ds_read_b128 v[238:241], v145 offset:23552
	global_load_lds_dwordx4 v[158:159], off
	s_add_i32 m0, s55, 0x2000
	s_add_u32 s58, s44, 0x20000
	v_lshl_add_u64 v[162:163], s[44:45], 0, v[128:129]
	s_addc_u32 s59, s45, 0
	s_add_i32 s55, s56, s34
	global_load_lds_dwordx4 v[162:163], off
	v_lshl_add_u64 v[242:243], s[58:59], 0, v[160:161]
	s_mov_b32 m0, s55
	v_lshl_add_u64 v[244:245], s[46:47], 0, v[130:131]
	global_load_lds_dwordx4 v[242:243], off
	v_lshl_add_u64 v[242:243], s[58:59], 0, v[128:129]
	s_add_i32 m0, s55, 0x2000
	s_nop 0
	global_load_lds_dwordx4 v[242:243], off
	v_lshl_add_u64 v[242:243], s[46:47], 0, v[132:133]
	s_mov_b32 m0, s35
	s_nop 0
	global_load_lds_dwordx4 v[242:243], off
	s_mov_b32 m0, s48
	s_nop 0
	global_load_lds_dwordx4 v[244:245], off
	s_waitcnt vmcnt(8)
	s_waitcnt lgkmcnt(0)
	s_barrier
	s_setprio 1
	v_mfma_f32_16x16x32_bf16 v[60:63], v[138:141], v[200:203], v[60:63]
	v_mfma_f32_16x16x32_bf16 v[56:59], v[150:153], v[200:203], v[56:59]
	v_mfma_f32_16x16x32_bf16 v[44:47], v[138:141], v[218:221], v[44:47]
	v_mfma_f32_16x16x32_bf16 v[40:43], v[150:153], v[218:221], v[40:43]
	v_mfma_f32_16x16x32_bf16 v[28:31], v[138:141], v[226:229], v[28:31]
	v_mfma_f32_16x16x32_bf16 v[24:27], v[150:153], v[226:229], v[24:27]
	v_mfma_f32_16x16x32_bf16 v[12:15], v[138:141], v[234:237], v[12:15]
	v_mfma_f32_16x16x32_bf16 v[8:11], v[150:153], v[234:237], v[8:11]
	v_mfma_f32_16x16x32_bf16 v[60:63], v[146:149], v[214:217], v[60:63]
	v_mfma_f32_16x16x32_bf16 v[56:59], v[154:157], v[214:217], v[56:59]
	v_mfma_f32_16x16x32_bf16 v[44:47], v[146:149], v[222:225], v[44:47]
	v_mfma_f32_16x16x32_bf16 v[40:43], v[154:157], v[222:225], v[40:43]
	v_mfma_f32_16x16x32_bf16 v[28:31], v[146:149], v[230:233], v[28:31]
	v_mfma_f32_16x16x32_bf16 v[24:27], v[154:157], v[230:233], v[24:27]
	v_mfma_f32_16x16x32_bf16 v[12:15], v[146:149], v[238:241], v[12:15]
	v_mfma_f32_16x16x32_bf16 v[8:11], v[154:157], v[238:241], v[8:11]
	s_setprio 0
	s_setprio 1
	v_mfma_f32_16x16x32_bf16 v[52:55], v[184:187], v[200:203], v[52:55]
	v_mfma_f32_16x16x32_bf16 v[48:51], v[192:195], v[200:203], v[48:51]
	v_mfma_f32_16x16x32_bf16 v[36:39], v[184:187], v[218:221], v[36:39]
	v_mfma_f32_16x16x32_bf16 v[32:35], v[192:195], v[218:221], v[32:35]
	v_mfma_f32_16x16x32_bf16 v[20:23], v[184:187], v[226:229], v[20:23]
	v_mfma_f32_16x16x32_bf16 v[16:19], v[192:195], v[226:229], v[16:19]
	v_mfma_f32_16x16x32_bf16 v[4:7], v[184:187], v[234:237], v[4:7]
	v_mfma_f32_16x16x32_bf16 v[0:3], v[192:195], v[234:237], v[0:3]
	v_mfma_f32_16x16x32_bf16 v[52:55], v[188:191], v[214:217], v[52:55]
	v_mfma_f32_16x16x32_bf16 v[48:51], v[196:199], v[214:217], v[48:51]
	v_mfma_f32_16x16x32_bf16 v[36:39], v[188:191], v[222:225], v[36:39]
	v_mfma_f32_16x16x32_bf16 v[32:35], v[196:199], v[222:225], v[32:35]
	v_mfma_f32_16x16x32_bf16 v[20:23], v[188:191], v[230:233], v[20:23]
	v_mfma_f32_16x16x32_bf16 v[16:19], v[196:199], v[230:233], v[16:19]
	v_mfma_f32_16x16x32_bf16 v[4:7], v[188:191], v[238:241], v[4:7]
	v_mfma_f32_16x16x32_bf16 v[0:3], v[196:199], v[238:241], v[0:3]
	s_setprio 0
	s_barrier
; #define PG8_STAGE(bufoff, gbase, voff) do { _Pragma("unroll") for (int _i = 0; _i < 2; ++_i) \
;         __builtin_amdgcn_global_load_lds((const unsigned*)((const char*)(gbase) + (voff)[_i]), (PG8_LAS unsigned*)(lds + (bufoff) + ldsw + _i * 8192), 16, 0, 0); } while (0)
; #define PG8_WAIT_V(n) asm volatile("s_waitcnt vmcnt(" #n ")" ::: "memory")
; #define PG8_WAIT_L(n) asm volatile("s_waitcnt lgkmcnt(" #n ")" ::: "memory")
; #define PG8_BAR __builtin_amdgcn_s_barrier()
; #define PG8_SCHED __builtin_amdgcn_sched_barrier(0)
; template <class Epi, class Sched, bool ALIGN_EPI = false, bool SP2 = false, bool F8 = false>
; __device__ __forceinline__ void gemm_phase(PG8_LAS unsigned char* lds, const Gemm g, const Sched& S, const Epi& E) {
;     ...
;             PG8_LDB(B0, 1, 0); PG8_LDB(B1, 1, 1); PG8_SCHED; PG8_LDA(At, 1, 0); PG8_STAGE(PG8_SA(0, 1), a2 + hstep, voffA);
;             PG8_WAIT_V(8); PG8_WAIT_L(0); PG8_BAR; PG8_MMA(0, 0, At, B0); PG8_MMA(0, 1, At, B1); PG8_BAR; PG8_SCHED;
	s_add_i32 s55, 0, 0x18000
	s_add_i32 s56, 0, 0x1c000
	v_add_u32_e32 v154, s55, v143
	v_add_u32_e32 v196, s56, v143
	ds_read_b128 v[138:141], v154
	ds_read_b128 v[146:149], v154 offset:1024
	ds_read_b128 v[150:153], v154 offset:2048
	ds_read_b128 v[154:157], v154 offset:3072
	ds_read_b128 v[184:187], v196
	ds_read_b128 v[188:191], v196 offset:1024
	ds_read_b128 v[192:195], v196 offset:2048
	ds_read_b128 v[196:199], v196 offset:3072
	s_add_u32 s46, s46, 0x20000
	s_addc_u32 s47, s47, 0
	s_mov_b32 m0, s49
	v_lshl_add_u64 v[246:247], s[46:47], 0, v[132:133]
	ds_read_b128 v[200:203], v145 offset:32768
	ds_read_b128 v[214:217], v145 offset:33792
	ds_read_b128 v[218:221], v145 offset:34816
	ds_read_b128 v[222:225], v145 offset:35840
	ds_read_b128 v[226:229], v145 offset:36864
	ds_read_b128 v[230:233], v145 offset:37888
	ds_read_b128 v[234:237], v145 offset:38912
	ds_read_b128 v[238:241], v145 offset:39936
	global_load_lds_dwordx4 v[246:247], off
	v_lshl_add_u64 v[246:247], s[46:47], 0, v[130:131]
	s_mov_b32 m0, s50
	s_nop 0
	global_load_lds_dwordx4 v[246:247], off
	s_waitcnt vmcnt(8)
	s_waitcnt lgkmcnt(0)
	s_barrier
	s_setprio 1
	v_mfma_f32_16x16x32_bf16 v[124:127], v[138:141], v[200:203], v[124:127]
	v_mfma_f32_16x16x32_bf16 v[120:123], v[150:153], v[200:203], v[120:123]
	v_mfma_f32_16x16x32_bf16 v[108:111], v[138:141], v[218:221], v[108:111]
	v_mfma_f32_16x16x32_bf16 v[104:107], v[150:153], v[218:221], v[104:107]
	v_mfma_f32_16x16x32_bf16 v[92:95], v[138:141], v[226:229], v[92:95]
	v_mfma_f32_16x16x32_bf16 v[88:91], v[150:153], v[226:229], v[88:91]
	v_mfma_f32_16x16x32_bf16 v[76:79], v[138:141], v[234:237], v[76:79]
	v_mfma_f32_16x16x32_bf16 v[72:75], v[150:153], v[234:237], v[72:75]
	v_mfma_f32_16x16x32_bf16 v[124:127], v[146:149], v[214:217], v[124:127]
	v_mfma_f32_16x16x32_bf16 v[120:123], v[154:157], v[214:217], v[120:123]
	v_mfma_f32_16x16x32_bf16 v[108:111], v[146:149], v[222:225], v[108:111]
	v_mfma_f32_16x16x32_bf16 v[104:107], v[154:157], v[222:225], v[104:107]
	v_mfma_f32_16x16x32_bf16 v[92:95], v[146:149], v[230:233], v[92:95]
	v_mfma_f32_16x16x32_bf16 v[88:91], v[154:157], v[230:233], v[88:91]
	v_mfma_f32_16x16x32_bf16 v[76:79], v[146:149], v[238:241], v[76:79]
	v_mfma_f32_16x16x32_bf16 v[72:75], v[154:157], v[238:241], v[72:75]
	s_setprio 0
	s_setprio 1
	v_mfma_f32_16x16x32_bf16 v[116:119], v[184:187], v[200:203], v[116:119]
	v_mfma_f32_16x16x32_bf16 v[112:115], v[192:195], v[200:203], v[112:115]
	v_mfma_f32_16x16x32_bf16 v[100:103], v[184:187], v[218:221], v[100:103]
	v_mfma_f32_16x16x32_bf16 v[96:99], v[192:195], v[218:221], v[96:99]
	v_mfma_f32_16x16x32_bf16 v[84:87], v[184:187], v[226:229], v[84:87]
	v_mfma_f32_16x16x32_bf16 v[80:83], v[192:195], v[226:229], v[80:83]
	v_mfma_f32_16x16x32_bf16 v[68:71], v[184:187], v[234:237], v[68:71]
	v_mfma_f32_16x16x32_bf16 v[64:67], v[192:195], v[234:237], v[64:67]
	v_mfma_f32_16x16x32_bf16 v[116:119], v[188:191], v[214:217], v[116:119]
	v_mfma_f32_16x16x32_bf16 v[112:115], v[196:199], v[214:217], v[112:115]
	v_mfma_f32_16x16x32_bf16 v[100:103], v[188:191], v[222:225], v[100:103]
	v_mfma_f32_16x16x32_bf16 v[96:99], v[196:199], v[222:225], v[96:99]
	v_mfma_f32_16x16x32_bf16 v[84:87], v[188:191], v[230:233], v[84:87]
	v_mfma_f32_16x16x32_bf16 v[80:83], v[196:199], v[230:233], v[80:83]
	v_mfma_f32_16x16x32_bf16 v[68:71], v[188:191], v[238:241], v[68:71]
	v_mfma_f32_16x16x32_bf16 v[64:67], v[196:199], v[238:241], v[64:67]
	s_setprio 0
	s_barrier
; #define PG8_STAGE(bufoff, gbase, voff) do { _Pragma("unroll") for (int _i = 0; _i < 2; ++_i) \
;         __builtin_amdgcn_global_load_lds((const unsigned*)((const char*)(gbase) + (voff)[_i]), (PG8_LAS unsigned*)(lds + (bufoff) + ldsw + _i * 8192), 16, 0, 0); } while (0)
; #define PG8_WAIT_V(n) asm volatile("s_waitcnt vmcnt(" #n ")" ::: "memory")
; #define PG8_WAIT_L(n) asm volatile("s_waitcnt lgkmcnt(" #n ")" ::: "memory")
; #define PG8_BAR __builtin_amdgcn_s_barrier()
; #define PG8_SCHED __builtin_amdgcn_sched_barrier(0)
; template <class Epi, class Sched, bool ALIGN_EPI = false, bool SP2 = false, bool F8 = false>
; __device__ __forceinline__ void gemm_phase(PG8_LAS unsigned char* lds, const Gemm g, const Sched& S, const Epi& E) {
;     ...
;         for (int t = 0; t < nt; t += 2) {
;             const bool last = (t == nt - 2);
;             const char* a1 = cA + (size_t)(t + 1) * kstep;
;             const char* a2 = last ? nA : cA + (size_t)(t + 2) * kstep; const char* b2 = last ? nB : cB + (size_t)(t + 2) * kstep;
;             const char* a3 = a2 + kstep; const char* b3 = b2 + kstep;
;     ...
;             PG8_LDA(At, 1, 1); PG8_STAGE(PG8_SB(1, 0), b3, voffB); PG8_STAGE(PG8_SB(1, 1), b3 + hstep, voffB); PG8_STAGE(PG8_SA(1, 0), a3, voffA);
;             PG8_WAIT_V(8); PG8_WAIT_L(0); PG8_BAR; PG8_MMA(1, 0, At, B0); PG8_MMA(1, 1, At, B1); PG8_BAR; PG8_SCHED;
	s_add_i32 s46, s55, s34
	v_lshl_add_u64 v[158:159], v[158:159], 0, s[14:15]
	s_mov_b32 m0, s46
	ds_read_b128 v[200:203], v145 offset:49152
	ds_read_b128 v[214:217], v145 offset:50176
	ds_read_b128 v[218:221], v145 offset:51200
	ds_read_b128 v[222:225], v145 offset:52224
	ds_read_b128 v[226:229], v145 offset:53248
	ds_read_b128 v[230:233], v145 offset:54272
	ds_read_b128 v[234:237], v145 offset:55296
	ds_read_b128 v[238:241], v145 offset:56320
	global_load_lds_dwordx4 v[158:159], off
	s_add_i32 m0, s46, 0x2000
	s_add_u32 s44, s44, 0x20080
	v_lshl_add_u64 v[158:159], v[162:163], 0, s[14:15]
	s_addc_u32 s45, s45, 0
	s_add_i32 s46, s56, s34
	global_load_lds_dwordx4 v[158:159], off
	v_lshl_add_u64 v[158:159], s[44:45], 0, v[160:161]
	s_mov_b32 m0, s46
	s_nop 0
	global_load_lds_dwordx4 v[158:159], off
	v_lshl_add_u64 v[158:159], s[44:45], 0, v[128:129]
	s_add_i32 m0, s46, 0x2000
	s_nop 0
	global_load_lds_dwordx4 v[158:159], off
	v_lshl_add_u64 v[158:159], v[242:243], 0, s[14:15]
	s_mov_b32 m0, s51
	s_nop 0
	global_load_lds_dwordx4 v[158:159], off
	v_lshl_add_u64 v[158:159], v[244:245], 0, s[14:15]
	s_mov_b32 m0, s52
	s_nop 0
	global_load_lds_dwordx4 v[158:159], off
	s_waitcnt vmcnt(8)
	s_waitcnt lgkmcnt(0)
	s_barrier
	s_setprio 1
	v_mfma_f32_16x16x32_bf16 v[60:63], v[138:141], v[200:203], v[60:63]
	v_mfma_f32_16x16x32_bf16 v[56:59], v[150:153], v[200:203], v[56:59]
	v_mfma_f32_16x16x32_bf16 v[44:47], v[138:141], v[218:221], v[44:47]
	v_mfma_f32_16x16x32_bf16 v[40:43], v[150:153], v[218:221], v[40:43]
	v_mfma_f32_16x16x32_bf16 v[28:31], v[138:141], v[226:229], v[28:31]
	v_mfma_f32_16x16x32_bf16 v[24:27], v[150:153], v[226:229], v[24:27]
	v_mfma_f32_16x16x32_bf16 v[12:15], v[138:141], v[234:237], v[12:15]
	v_mfma_f32_16x16x32_bf16 v[8:11], v[150:153], v[234:237], v[8:11]
	v_mfma_f32_16x16x32_bf16 v[60:63], v[146:149], v[214:217], v[60:63]
	v_mfma_f32_16x16x32_bf16 v[56:59], v[154:157], v[214:217], v[56:59]
	v_mfma_f32_16x16x32_bf16 v[44:47], v[146:149], v[222:225], v[44:47]
	v_mfma_f32_16x16x32_bf16 v[40:43], v[154:157], v[222:225], v[40:43]
	v_mfma_f32_16x16x32_bf16 v[28:31], v[146:149], v[230:233], v[28:31]
	v_mfma_f32_16x16x32_bf16 v[24:27], v[154:157], v[230:233], v[24:27]
	v_mfma_f32_16x16x32_bf16 v[12:15], v[146:149], v[238:241], v[12:15]
	v_mfma_f32_16x16x32_bf16 v[8:11], v[154:157], v[238:241], v[8:11]
	s_setprio 0
	s_setprio 1
	v_mfma_f32_16x16x32_bf16 v[52:55], v[184:187], v[200:203], v[52:55]
	v_mfma_f32_16x16x32_bf16 v[48:51], v[192:195], v[200:203], v[48:51]
	v_mfma_f32_16x16x32_bf16 v[36:39], v[184:187], v[218:221], v[36:39]
	v_mfma_f32_16x16x32_bf16 v[32:35], v[192:195], v[218:221], v[32:35]
	v_mfma_f32_16x16x32_bf16 v[20:23], v[184:187], v[226:229], v[20:23]
	v_mfma_f32_16x16x32_bf16 v[16:19], v[192:195], v[226:229], v[16:19]
	v_mfma_f32_16x16x32_bf16 v[4:7], v[184:187], v[234:237], v[4:7]
	v_mfma_f32_16x16x32_bf16 v[0:3], v[192:195], v[234:237], v[0:3]
	v_mfma_f32_16x16x32_bf16 v[52:55], v[188:191], v[214:217], v[52:55]
	v_mfma_f32_16x16x32_bf16 v[48:51], v[196:199], v[214:217], v[48:51]
	v_mfma_f32_16x16x32_bf16 v[36:39], v[188:191], v[222:225], v[36:39]
	v_mfma_f32_16x16x32_bf16 v[32:35], v[196:199], v[222:225], v[32:35]
	v_mfma_f32_16x16x32_bf16 v[20:23], v[188:191], v[230:233], v[20:23]
	v_mfma_f32_16x16x32_bf16 v[16:19], v[196:199], v[230:233], v[16:19]
	v_mfma_f32_16x16x32_bf16 v[4:7], v[188:191], v[238:241], v[4:7]
	v_mfma_f32_16x16x32_bf16 v[0:3], v[196:199], v[238:241], v[0:3]
	s_setprio 0
	s_barrier
	s_add_i32 s54, s54, 2
	s_add_u32 s42, s42, 0x100
	s_addc_u32 s43, s43, 0
	s_add_u32 s28, s28, 0x100
	s_addc_u32 s29, s29, 0
	s_cmp_gt_u32 s54, 5
	s_cbranch_scc0 .LBB0_97

; #define PG8_STAGE(bufoff, gbase, voff) do { _Pragma("unroll") for (int _i = 0; _i < 2; ++_i) \
;         __builtin_amdgcn_global_load_lds((const unsigned*)((const char*)(gbase) + (voff)[_i]), (PG8_LAS unsigned*)(lds + (bufoff) + ldsw + _i * 8192), 16, 0, 0); } while (0)
; #define PG8_WAIT_V(n) asm volatile("s_waitcnt vmcnt(" #n ")" ::: "memory")
; #define PG8_WAIT_L(n) asm volatile("s_waitcnt lgkmcnt(" #n ")" ::: "memory")
; #define PG8_BAR __builtin_amdgcn_s_barrier()
; #define PG8_SCHED __builtin_amdgcn_sched_barrier(0)
; template <class Epi, class Sched, bool ALIGN_EPI = false, bool SP2 = false, bool F8 = false>
; __device__ __forceinline__ void gemm_phase(PG8_LAS unsigned char* lds, const Gemm g, const Sched& S, const Epi& E) {
;     ...
;         const bool has_next = S.next(ui + 1, nxt);
;         const char* nA = has_next ? (const char*)g.A + (size_t)nxt.pm * tstep : cA; const char* nB = has_next ? (const char*)g.Bt + (size_t)nxt.pn * tstep : cB;
;         for (int t = 0; t < nt; t += 2) {
;             const bool last = (t == nt - 2);
;             const char* a1 = cA + (size_t)(t + 1) * kstep;
;             const char* a2 = last ? nA : cA + (size_t)(t + 2) * kstep; const char* b2 = last ? nB : cB + (size_t)(t + 2) * kstep;
;             const char* a3 = a2 + kstep; const char* b3 = b2 + kstep;
;             if (last && has_next) S.a_ready(nxt);
;             if constexpr (SP2) {
;             PG8_LDB(B0, 0, 0); PG8_LDB(B1, 0, 1); PG8_SCHED; PG8_LDA(At, 0, 0); PG8_STAGE(PG8_SA(1, 1), a1 + hstep, voffA);
;             PG8_WAIT_V(8); PG8_WAIT_L(0); PG8_BAR; PG8_MMA(0, 0, At, B0); PG8_MMA(0, 1, At, B1); PG8_BAR; PG8_SCHED;
;             PG8_LDA(At, 0, 1); PG8_STAGE(PG8_SB(0, 0), b2, voffB); PG8_STAGE(PG8_SB(0, 1), b2 + hstep, voffB); PG8_STAGE(PG8_SA(0, 0), a2, voffA);
;             PG8_WAIT_V(8); PG8_WAIT_L(0); PG8_BAR; PG8_MMA(1, 0, At, B0); PG8_MMA(1, 1, At, B1); PG8_BAR; PG8_SCHED;
.LBB0_116:
	s_ashr_i32 s41, s40, 31
	s_lshl_b64 s[28:29], s[40:41], 19
	s_add_u32 s42, s96, s28
	v_readlane_b32 s17, v253, 22
	s_addc_u32 s43, s17, s29
	s_and_b64 s[28:29], s[38:39], exec
	s_cselect_b32 s19, s43, s11
	s_cselect_b32 s23, s42, s10
	s_ashr_i32 s17, s16, 31
	s_lshl_b64 s[28:29], s[16:17], 19
	s_add_u32 s44, s22, s28
	s_addc_u32 s45, s34, s29
	s_and_b64 s[28:29], s[38:39], exec
	s_cselect_b32 s17, s45, s37
	s_cselect_b32 s28, s44, s36
	s_add_u32 s10, s10, 0x40080
	s_addc_u32 s11, s11, 0
	s_add_u32 s29, s36, 0x100
	s_addc_u32 s41, s37, 0
	s_mov_b32 s54, -2
	s_add_u32 s36, s10, 0xfffc0080
	s_addc_u32 s37, s11, -1
	s_add_i32 s55, 0, 0x10000
	s_cmp_eq_u32 s54, 12
	s_cselect_b32 s47, s19, s37
	s_cselect_b32 s46, s23, s36
	v_add_u32_e32 v142, s55, v145
	s_cselect_b32 s37, s17, s41
	s_cselect_b32 s36, s28, s29
	s_add_i32 s56, 0, 0x14000
	ds_read_b128 v[138:141], v142
	ds_read_b128 v[148:151], v142 offset:1024
	ds_read_b128 v[152:155], v142 offset:2048
	ds_read_b128 v[156:159], v142 offset:3072
	v_add_u32_e32 v142, s56, v145
	ds_read_b128 v[184:187], v142
	ds_read_b128 v[188:191], v142 offset:1024
	ds_read_b128 v[192:195], v142 offset:2048
	ds_read_b128 v[196:199], v142 offset:3072
	v_lshl_add_u64 v[142:143], s[10:11], 0, v[134:135]
	s_add_i32 m0, s35, 0xc000
	ds_read_b128 v[200:203], v147
	ds_read_b128 v[214:217], v147 offset:1024
	ds_read_b128 v[218:221], v147 offset:2048
	ds_read_b128 v[222:225], v147 offset:3072
	ds_read_b128 v[226:229], v147 offset:4096
	ds_read_b128 v[230:233], v147 offset:5120
	ds_read_b128 v[234:237], v147 offset:6144
	ds_read_b128 v[238:241], v147 offset:7168
	global_load_lds_dwordx4 v[142:143], off
	v_lshl_add_u64 v[142:143], s[10:11], 0, v[136:137]
	s_add_i32 m0, s35, 0xe000
	s_nop 0
	global_load_lds_dwordx4 v[142:143], off
	s_waitcnt vmcnt(8)
	s_waitcnt lgkmcnt(0)
	s_barrier
	s_setprio 1
	v_mfma_f32_16x16x32_bf16 v[124:127], v[138:141], v[200:203], 0
	v_mfma_f32_16x16x32_bf16 v[120:123], v[152:155], v[200:203], 0
	v_mfma_f32_16x16x32_bf16 v[108:111], v[138:141], v[218:221], 0
	v_mfma_f32_16x16x32_bf16 v[104:107], v[152:155], v[218:221], 0
	v_mfma_f32_16x16x32_bf16 v[92:95], v[138:141], v[226:229], 0
	v_mfma_f32_16x16x32_bf16 v[88:91], v[152:155], v[226:229], 0
	v_mfma_f32_16x16x32_bf16 v[76:79], v[138:141], v[234:237], 0
	v_mfma_f32_16x16x32_bf16 v[72:75], v[152:155], v[234:237], 0
	v_mfma_f32_16x16x32_bf16 v[124:127], v[148:151], v[214:217], v[124:127]
	v_mfma_f32_16x16x32_bf16 v[120:123], v[156:159], v[214:217], v[120:123]
	v_mfma_f32_16x16x32_bf16 v[108:111], v[148:151], v[222:225], v[108:111]
	v_mfma_f32_16x16x32_bf16 v[104:107], v[156:159], v[222:225], v[104:107]
	v_mfma_f32_16x16x32_bf16 v[92:95], v[148:151], v[230:233], v[92:95]
	v_mfma_f32_16x16x32_bf16 v[88:91], v[156:159], v[230:233], v[88:91]
	v_mfma_f32_16x16x32_bf16 v[76:79], v[148:151], v[238:241], v[76:79]
	v_mfma_f32_16x16x32_bf16 v[72:75], v[156:159], v[238:241], v[72:75]
	s_setprio 0
	s_setprio 1
	v_mfma_f32_16x16x32_bf16 v[116:119], v[184:187], v[200:203], 0
	v_mfma_f32_16x16x32_bf16 v[112:115], v[192:195], v[200:203], 0
	v_mfma_f32_16x16x32_bf16 v[100:103], v[184:187], v[218:221], 0
	v_mfma_f32_16x16x32_bf16 v[96:99], v[192:195], v[218:221], 0
	v_mfma_f32_16x16x32_bf16 v[84:87], v[184:187], v[226:229], 0
	v_mfma_f32_16x16x32_bf16 v[80:83], v[192:195], v[226:229], 0
	v_mfma_f32_16x16x32_bf16 v[68:71], v[184:187], v[234:237], 0
	v_mfma_f32_16x16x32_bf16 v[64:67], v[192:195], v[234:237], 0
	v_mfma_f32_16x16x32_bf16 v[116:119], v[188:191], v[214:217], v[116:119]
	v_mfma_f32_16x16x32_bf16 v[112:115], v[196:199], v[214:217], v[112:115]
	v_mfma_f32_16x16x32_bf16 v[100:103], v[188:191], v[222:225], v[100:103]
	v_mfma_f32_16x16x32_bf16 v[96:99], v[196:199], v[222:225], v[96:99]
	v_mfma_f32_16x16x32_bf16 v[84:87], v[188:191], v[230:233], v[84:87]
	v_mfma_f32_16x16x32_bf16 v[80:83], v[196:199], v[230:233], v[80:83]
	v_mfma_f32_16x16x32_bf16 v[68:71], v[188:191], v[238:241], v[68:71]
	v_mfma_f32_16x16x32_bf16 v[64:67], v[196:199], v[238:241], v[64:67]
	s_setprio 0
	s_barrier
	s_add_i32 s55, s55, s13
	v_lshl_add_u64 v[142:143], s[36:37], 0, v[160:161]
	s_mov_b32 m0, s55
	ds_read_b128 v[200:203], v147 offset:16384
	ds_read_b128 v[214:217], v147 offset:17408
	ds_read_b128 v[218:221], v147 offset:18432
	ds_read_b128 v[222:225], v147 offset:19456
	ds_read_b128 v[226:229], v147 offset:20480
	ds_read_b128 v[230:233], v147 offset:21504
	ds_read_b128 v[234:237], v147 offset:22528
	ds_read_b128 v[238:241], v147 offset:23552
	global_load_lds_dwordx4 v[142:143], off
	s_add_i32 m0, s55, 0x2000
	s_add_u32 s58, s36, 0x40000
	v_lshl_add_u64 v[162:163], s[36:37], 0, v[128:129]
	s_addc_u32 s59, s37, 0
	s_add_i32 s55, s56, s13
	global_load_lds_dwordx4 v[162:163], off
	v_lshl_add_u64 v[242:243], s[58:59], 0, v[160:161]
	s_mov_b32 m0, s55
	v_lshl_add_u64 v[244:245], s[46:47], 0, v[130:131]
	global_load_lds_dwordx4 v[242:243], off
	v_lshl_add_u64 v[242:243], s[58:59], 0, v[128:129]
	s_add_i32 m0, s55, 0x2000
	s_nop 0
	global_load_lds_dwordx4 v[242:243], off
	v_lshl_add_u64 v[242:243], s[46:47], 0, v[132:133]
	s_mov_b32 m0, s35
	s_nop 0
	global_load_lds_dwordx4 v[242:243], off
	s_mov_b32 m0, s48
	s_nop 0
	global_load_lds_dwordx4 v[244:245], off
	s_waitcnt vmcnt(8)
	s_waitcnt lgkmcnt(0)
	s_barrier
; #define PG8_STAGE(bufoff, gbase, voff) do { _Pragma("unroll") for (int _i = 0; _i < 2; ++_i) \
;         __builtin_amdgcn_global_load_lds((const unsigned*)((const char*)(gbase) + (voff)[_i]), (PG8_LAS unsigned*)(lds + (bufoff) + ldsw + _i * 8192), 16, 0, 0); } while (0)
; #define PG8_WAIT_V(n) asm volatile("s_waitcnt vmcnt(" #n ")" ::: "memory")
; #define PG8_WAIT_L(n) asm volatile("s_waitcnt lgkmcnt(" #n ")" ::: "memory")
; #define PG8_BAR __builtin_amdgcn_s_barrier()
; #define PG8_SCHED __builtin_amdgcn_sched_barrier(0)
; template <class Epi, class Sched, bool ALIGN_EPI = false, bool SP2 = false, bool F8 = false>
; __device__ __forceinline__ void gemm_phase(PG8_LAS unsigned char* lds, const Gemm g, const Sched& S, const Epi& E) {
;     ...
;             PG8_WAIT_V(8); PG8_WAIT_L(0); PG8_BAR; PG8_MMA(0, 0, At, B0); PG8_MMA(0, 1, At, B1); PG8_BAR; PG8_SCHED;
;             PG8_LDA(At, 0, 1); PG8_STAGE(PG8_SB(0, 0), b2, voffB); PG8_STAGE(PG8_SB(0, 1), b2 + hstep, voffB); PG8_STAGE(PG8_SA(0, 0), a2, voffA);
;             PG8_WAIT_V(8); PG8_WAIT_L(0); PG8_BAR; PG8_MMA(1, 0, At, B0); PG8_MMA(1, 1, At, B1); PG8_BAR; PG8_SCHED;
;             PG8_LDB(B0, 1, 0); PG8_LDB(B1, 1, 1); PG8_SCHED; PG8_LDA(At, 1, 0); PG8_STAGE(PG8_SA(0, 1), a2 + hstep, voffA);
;             PG8_WAIT_V(8); PG8_WAIT_L(0); PG8_BAR; PG8_MMA(0, 0, At, B0); PG8_MMA(0, 1, At, B1); PG8_BAR; PG8_SCHED;
	s_setprio 1
	v_mfma_f32_16x16x32_bf16 v[60:63], v[138:141], v[200:203], 0
	v_mfma_f32_16x16x32_bf16 v[56:59], v[152:155], v[200:203], 0
	v_mfma_f32_16x16x32_bf16 v[44:47], v[138:141], v[218:221], 0
	v_mfma_f32_16x16x32_bf16 v[40:43], v[152:155], v[218:221], 0
	v_mfma_f32_16x16x32_bf16 v[28:31], v[138:141], v[226:229], 0
	v_mfma_f32_16x16x32_bf16 v[24:27], v[152:155], v[226:229], 0
	v_mfma_f32_16x16x32_bf16 v[12:15], v[138:141], v[234:237], 0
	v_mfma_f32_16x16x32_bf16 v[8:11], v[152:155], v[234:237], 0
	v_mfma_f32_16x16x32_bf16 v[60:63], v[148:151], v[214:217], v[60:63]
	v_mfma_f32_16x16x32_bf16 v[56:59], v[156:159], v[214:217], v[56:59]
	v_mfma_f32_16x16x32_bf16 v[44:47], v[148:151], v[222:225], v[44:47]
	v_mfma_f32_16x16x32_bf16 v[40:43], v[156:159], v[222:225], v[40:43]
	v_mfma_f32_16x16x32_bf16 v[28:31], v[148:151], v[230:233], v[28:31]
	v_mfma_f32_16x16x32_bf16 v[24:27], v[156:159], v[230:233], v[24:27]
	v_mfma_f32_16x16x32_bf16 v[12:15], v[148:151], v[238:241], v[12:15]
	v_mfma_f32_16x16x32_bf16 v[8:11], v[156:159], v[238:241], v[8:11]
	s_setprio 0
	s_setprio 1
	v_mfma_f32_16x16x32_bf16 v[52:55], v[184:187], v[200:203], 0
	v_mfma_f32_16x16x32_bf16 v[48:51], v[192:195], v[200:203], 0
	v_mfma_f32_16x16x32_bf16 v[36:39], v[184:187], v[218:221], 0
	v_mfma_f32_16x16x32_bf16 v[32:35], v[192:195], v[218:221], 0
	v_mfma_f32_16x16x32_bf16 v[20:23], v[184:187], v[226:229], 0
	v_mfma_f32_16x16x32_bf16 v[16:19], v[192:195], v[226:229], 0
	v_mfma_f32_16x16x32_bf16 v[4:7], v[184:187], v[234:237], 0
	v_mfma_f32_16x16x32_bf16 v[0:3], v[192:195], v[234:237], 0
	v_mfma_f32_16x16x32_bf16 v[52:55], v[188:191], v[214:217], v[52:55]
	v_mfma_f32_16x16x32_bf16 v[48:51], v[196:199], v[214:217], v[48:51]
	v_mfma_f32_16x16x32_bf16 v[36:39], v[188:191], v[222:225], v[36:39]
	v_mfma_f32_16x16x32_bf16 v[32:35], v[196:199], v[222:225], v[32:35]
	v_mfma_f32_16x16x32_bf16 v[20:23], v[188:191], v[230:233], v[20:23]
	v_mfma_f32_16x16x32_bf16 v[16:19], v[196:199], v[230:233], v[16:19]
	v_mfma_f32_16x16x32_bf16 v[4:7], v[188:191], v[238:241], v[4:7]
	v_mfma_f32_16x16x32_bf16 v[0:3], v[196:199], v[238:241], v[0:3]
	s_setprio 0
	s_barrier
	s_add_i32 s55, 0, 0x18000
	s_add_i32 s56, 0, 0x1c000
	v_add_u32_e32 v156, s55, v145
	v_add_u32_e32 v196, s56, v145
	ds_read_b128 v[138:141], v156
	ds_read_b128 v[148:151], v156 offset:1024
	ds_read_b128 v[152:155], v156 offset:2048
	ds_read_b128 v[156:159], v156 offset:3072
	ds_read_b128 v[184:187], v196
	ds_read_b128 v[188:191], v196 offset:1024
	ds_read_b128 v[192:195], v196 offset:2048
	ds_read_b128 v[196:199], v196 offset:3072
	s_add_u32 s46, s46, 0x40000
	s_addc_u32 s47, s47, 0
	s_mov_b32 m0, s49
	v_lshl_add_u64 v[246:247], s[46:47], 0, v[132:133]
	ds_read_b128 v[200:203], v147 offset:32768
	ds_read_b128 v[214:217], v147 offset:33792
	ds_read_b128 v[218:221], v147 offset:34816
	ds_read_b128 v[222:225], v147 offset:35840
	ds_read_b128 v[226:229], v147 offset:36864
	ds_read_b128 v[230:233], v147 offset:37888
	ds_read_b128 v[234:237], v147 offset:38912
	ds_read_b128 v[238:241], v147 offset:39936
	global_load_lds_dwordx4 v[246:247], off
	v_lshl_add_u64 v[246:247], s[46:47], 0, v[130:131]
	s_mov_b32 m0, s50
	s_nop 0
	global_load_lds_dwordx4 v[246:247], off
	s_waitcnt vmcnt(8)
	s_waitcnt lgkmcnt(0)
	s_barrier
	s_setprio 1
	v_mfma_f32_16x16x32_bf16 v[124:127], v[138:141], v[200:203], v[124:127]
	v_mfma_f32_16x16x32_bf16 v[120:123], v[152:155], v[200:203], v[120:123]
	v_mfma_f32_16x16x32_bf16 v[108:111], v[138:141], v[218:221], v[108:111]
	v_mfma_f32_16x16x32_bf16 v[104:107], v[152:155], v[218:221], v[104:107]
	v_mfma_f32_16x16x32_bf16 v[92:95], v[138:141], v[226:229], v[92:95]
	v_mfma_f32_16x16x32_bf16 v[88:91], v[152:155], v[226:229], v[88:91]
	v_mfma_f32_16x16x32_bf16 v[76:79], v[138:141], v[234:237], v[76:79]
	v_mfma_f32_16x16x32_bf16 v[72:75], v[152:155], v[234:237], v[72:75]
	v_mfma_f32_16x16x32_bf16 v[124:127], v[148:151], v[214:217], v[124:127]
	v_mfma_f32_16x16x32_bf16 v[120:123], v[156:159], v[214:217], v[120:123]
	v_mfma_f32_16x16x32_bf16 v[108:111], v[148:151], v[222:225], v[108:111]
	v_mfma_f32_16x16x32_bf16 v[104:107], v[156:159], v[222:225], v[104:107]
	v_mfma_f32_16x16x32_bf16 v[92:95], v[148:151], v[230:233], v[92:95]
	v_mfma_f32_16x16x32_bf16 v[88:91], v[156:159], v[230:233], v[88:91]
	v_mfma_f32_16x16x32_bf16 v[76:79], v[148:151], v[238:241], v[76:79]
	v_mfma_f32_16x16x32_bf16 v[72:75], v[156:159], v[238:241], v[72:75]
	s_setprio 0
	s_setprio 1
	v_mfma_f32_16x16x32_bf16 v[116:119], v[184:187], v[200:203], v[116:119]
	v_mfma_f32_16x16x32_bf16 v[112:115], v[192:195], v[200:203], v[112:115]
	v_mfma_f32_16x16x32_bf16 v[100:103], v[184:187], v[218:221], v[100:103]
	v_mfma_f32_16x16x32_bf16 v[96:99], v[192:195], v[218:221], v[96:99]
	v_mfma_f32_16x16x32_bf16 v[84:87], v[184:187], v[226:229], v[84:87]
	v_mfma_f32_16x16x32_bf16 v[80:83], v[192:195], v[226:229], v[80:83]
	v_mfma_f32_16x16x32_bf16 v[68:71], v[184:187], v[234:237], v[68:71]
	v_mfma_f32_16x16x32_bf16 v[64:67], v[192:195], v[234:237], v[64:67]
	v_mfma_f32_16x16x32_bf16 v[116:119], v[188:191], v[214:217], v[116:119]
	v_mfma_f32_16x16x32_bf16 v[112:115], v[196:199], v[214:217], v[112:115]
	v_mfma_f32_16x16x32_bf16 v[100:103], v[188:191], v[222:225], v[100:103]
	v_mfma_f32_16x16x32_bf16 v[96:99], v[196:199], v[222:225], v[96:99]
	v_mfma_f32_16x16x32_bf16 v[84:87], v[188:191], v[230:233], v[84:87]
	v_mfma_f32_16x16x32_bf16 v[80:83], v[196:199], v[230:233], v[80:83]
	v_mfma_f32_16x16x32_bf16 v[68:71], v[188:191], v[238:241], v[68:71]
	v_mfma_f32_16x16x32_bf16 v[64:67], v[196:199], v[238:241], v[64:67]
	s_setprio 0
	s_barrier
; #define PG8_STAGE(bufoff, gbase, voff) do { _Pragma("unroll") for (int _i = 0; _i < 2; ++_i) \
;         __builtin_amdgcn_global_load_lds((const unsigned*)((const char*)(gbase) + (voff)[_i]), (PG8_LAS unsigned*)(lds + (bufoff) + ldsw + _i * 8192), 16, 0, 0); } while (0)
; #define PG8_WAIT_V(n) asm volatile("s_waitcnt vmcnt(" #n ")" ::: "memory")
; #define PG8_WAIT_L(n) asm volatile("s_waitcnt lgkmcnt(" #n ")" ::: "memory")
; #define PG8_BAR __builtin_amdgcn_s_barrier()
; #define PG8_SCHED __builtin_amdgcn_sched_barrier(0)
; template <class Epi, class Sched, bool ALIGN_EPI = false, bool SP2 = false, bool F8 = false>
; __device__ __forceinline__ void gemm_phase(PG8_LAS unsigned char* lds, const Gemm g, const Sched& S, const Epi& E) {
;     ...
;         for (int t = 0; t < nt; t += 2) {
;             const bool last = (t == nt - 2);
;             const char* a1 = cA + (size_t)(t + 1) * kstep;
;             const char* a2 = last ? nA : cA + (size_t)(t + 2) * kstep; const char* b2 = last ? nB : cB + (size_t)(t + 2) * kstep;
;             const char* a3 = a2 + kstep; const char* b3 = b2 + kstep;
;             if (last && has_next) S.a_ready(nxt);
;             if constexpr (SP2) {
;             PG8_LDB(B0, 0, 0); PG8_LDB(B1, 0, 1); PG8_SCHED; PG8_LDA(At, 0, 0); PG8_STAGE(PG8_SA(1, 1), a1 + hstep, voffA);
;             PG8_WAIT_V(8); PG8_WAIT_L(0); PG8_BAR; PG8_MMA(0, 0, At, B0); PG8_MMA(0, 1, At, B1); PG8_BAR; PG8_SCHED;
;             PG8_LDA(At, 0, 1); PG8_STAGE(PG8_SB(0, 0), b2, voffB); PG8_STAGE(PG8_SB(0, 1), b2 + hstep, voffB); PG8_STAGE(PG8_SA(0, 0), a2, voffA);
;             PG8_WAIT_V(8); PG8_WAIT_L(0); PG8_BAR; PG8_MMA(1, 0, At, B0); PG8_MMA(1, 1, At, B1); PG8_BAR; PG8_SCHED;
;             PG8_LDB(B0, 1, 0); PG8_LDB(B1, 1, 1); PG8_SCHED; PG8_LDA(At, 1, 0); PG8_STAGE(PG8_SA(0, 1), a2 + hstep, voffA);
;             PG8_WAIT_V(8); PG8_WAIT_L(0); PG8_BAR; PG8_MMA(0, 0, At, B0); PG8_MMA(0, 1, At, B1); PG8_BAR; PG8_SCHED;
;             PG8_LDA(At, 1, 1); PG8_STAGE(PG8_SB(1, 0), b3, voffB); PG8_STAGE(PG8_SB(1, 1), b3 + hstep, voffB); PG8_STAGE(PG8_SA(1, 0), a3, voffA);
;             PG8_WAIT_V(8); PG8_WAIT_L(0); PG8_BAR; PG8_MMA(1, 0, At, B0); PG8_MMA(1, 1, At, B1); PG8_BAR; PG8_SCHED;
	s_add_i32 s46, s55, s13
	v_lshl_add_u64 v[142:143], v[142:143], 0, s[14:15]
	s_mov_b32 m0, s46
	ds_read_b128 v[200:203], v147 offset:49152
	ds_read_b128 v[214:217], v147 offset:50176
	ds_read_b128 v[218:221], v147 offset:51200
	ds_read_b128 v[222:225], v147 offset:52224
	ds_read_b128 v[226:229], v147 offset:53248
	ds_read_b128 v[230:233], v147 offset:54272
	ds_read_b128 v[234:237], v147 offset:55296
	ds_read_b128 v[238:241], v147 offset:56320
	global_load_lds_dwordx4 v[142:143], off
	s_add_i32 m0, s46, 0x2000
	s_add_u32 s36, s36, 0x40080
	v_lshl_add_u64 v[142:143], v[162:163], 0, s[14:15]
	s_addc_u32 s37, s37, 0
	s_add_i32 s46, s56, s13
	global_load_lds_dwordx4 v[142:143], off
	v_lshl_add_u64 v[142:143], s[36:37], 0, v[160:161]
	s_mov_b32 m0, s46
	s_nop 0
	global_load_lds_dwordx4 v[142:143], off
	v_lshl_add_u64 v[142:143], s[36:37], 0, v[128:129]
	s_add_i32 m0, s46, 0x2000
	s_nop 0
	global_load_lds_dwordx4 v[142:143], off
	v_lshl_add_u64 v[142:143], v[242:243], 0, s[14:15]
	s_mov_b32 m0, s51
	s_nop 0
	global_load_lds_dwordx4 v[142:143], off
	v_lshl_add_u64 v[142:143], v[244:245], 0, s[14:15]
	s_mov_b32 m0, s52
	s_nop 0
	global_load_lds_dwordx4 v[142:143], off
	s_waitcnt vmcnt(8)
	s_waitcnt lgkmcnt(0)
	s_barrier
	s_setprio 1
	v_mfma_f32_16x16x32_bf16 v[60:63], v[138:141], v[200:203], v[60:63]
	v_mfma_f32_16x16x32_bf16 v[56:59], v[152:155], v[200:203], v[56:59]
	v_mfma_f32_16x16x32_bf16 v[44:47], v[138:141], v[218:221], v[44:47]
	v_mfma_f32_16x16x32_bf16 v[40:43], v[152:155], v[218:221], v[40:43]
	v_mfma_f32_16x16x32_bf16 v[28:31], v[138:141], v[226:229], v[28:31]
	v_mfma_f32_16x16x32_bf16 v[24:27], v[152:155], v[226:229], v[24:27]
	v_mfma_f32_16x16x32_bf16 v[12:15], v[138:141], v[234:237], v[12:15]
	v_mfma_f32_16x16x32_bf16 v[8:11], v[152:155], v[234:237], v[8:11]
	v_mfma_f32_16x16x32_bf16 v[60:63], v[148:151], v[214:217], v[60:63]
	v_mfma_f32_16x16x32_bf16 v[56:59], v[156:159], v[214:217], v[56:59]
	v_mfma_f32_16x16x32_bf16 v[44:47], v[148:151], v[222:225], v[44:47]
	v_mfma_f32_16x16x32_bf16 v[40:43], v[156:159], v[222:225], v[40:43]
	v_mfma_f32_16x16x32_bf16 v[28:31], v[148:151], v[230:233], v[28:31]
	v_mfma_f32_16x16x32_bf16 v[24:27], v[156:159], v[230:233], v[24:27]
	v_mfma_f32_16x16x32_bf16 v[12:15], v[148:151], v[238:241], v[12:15]
	v_mfma_f32_16x16x32_bf16 v[8:11], v[156:159], v[238:241], v[8:11]
	s_setprio 0
	s_setprio 1
	v_mfma_f32_16x16x32_bf16 v[52:55], v[184:187], v[200:203], v[52:55]
	v_mfma_f32_16x16x32_bf16 v[48:51], v[192:195], v[200:203], v[48:51]
	v_mfma_f32_16x16x32_bf16 v[36:39], v[184:187], v[218:221], v[36:39]
	v_mfma_f32_16x16x32_bf16 v[32:35], v[192:195], v[218:221], v[32:35]
	v_mfma_f32_16x16x32_bf16 v[20:23], v[184:187], v[226:229], v[20:23]
	v_mfma_f32_16x16x32_bf16 v[16:19], v[192:195], v[226:229], v[16:19]
	v_mfma_f32_16x16x32_bf16 v[4:7], v[184:187], v[234:237], v[4:7]
	v_mfma_f32_16x16x32_bf16 v[0:3], v[192:195], v[234:237], v[0:3]
	v_mfma_f32_16x16x32_bf16 v[52:55], v[188:191], v[214:217], v[52:55]
	v_mfma_f32_16x16x32_bf16 v[48:51], v[196:199], v[214:217], v[48:51]
	v_mfma_f32_16x16x32_bf16 v[36:39], v[188:191], v[222:225], v[36:39]
	v_mfma_f32_16x16x32_bf16 v[32:35], v[196:199], v[222:225], v[32:35]
	v_mfma_f32_16x16x32_bf16 v[20:23], v[188:191], v[230:233], v[20:23]
	v_mfma_f32_16x16x32_bf16 v[16:19], v[196:199], v[230:233], v[16:19]
	v_mfma_f32_16x16x32_bf16 v[4:7], v[188:191], v[238:241], v[4:7]
	v_mfma_f32_16x16x32_bf16 v[0:3], v[196:199], v[238:241], v[0:3]
	s_setprio 0
	s_barrier
	s_add_i32 s54, s54, 2
	s_add_u32 s10, s10, 0x100
	s_addc_u32 s11, s11, 0
	s_add_u32 s29, s29, 0x100
	s_addc_u32 s41, s41, 0
	s_cmp_gt_u32 s54, 13
	s_cbranch_scc0 .LBB0_117
	s_branch .Lgk_after_117
.LBB0_117:
	s_add_u32 s36, s10, 0xfffc0080
	s_addc_u32 s37, s11, -1
	s_add_i32 s55, 0, 0x10000
	s_cmp_eq_u32 s54, 12
	s_cselect_b32 s47, s19, s37
	s_cselect_b32 s46, s23, s36
	v_add_u32_e32 v142, s55, v145
	s_cselect_b32 s37, s17, s41
	s_cselect_b32 s36, s28, s29
	s_add_i32 s56, 0, 0x14000
	ds_read_b128 v[138:141], v142
	ds_read_b128 v[148:151], v142 offset:1024
	ds_read_b128 v[152:155], v142 offset:2048
	ds_read_b128 v[156:159], v142 offset:3072
	v_add_u32_e32 v142, s56, v145
	ds_read_b128 v[184:187], v142
	ds_read_b128 v[188:191], v142 offset:1024
	ds_read_b128 v[192:195], v142 offset:2048
	ds_read_b128 v[196:199], v142 offset:3072
	v_lshl_add_u64 v[142:143], s[10:11], 0, v[134:135]
	s_add_i32 m0, s35, 0xc000
	ds_read_b128 v[200:203], v147
	ds_read_b128 v[214:217], v147 offset:1024
	ds_read_b128 v[218:221], v147 offset:2048
	ds_read_b128 v[222:225], v147 offset:3072
	ds_read_b128 v[226:229], v147 offset:4096
	ds_read_b128 v[230:233], v147 offset:5120
	ds_read_b128 v[234:237], v147 offset:6144
	ds_read_b128 v[238:241], v147 offset:7168
	global_load_lds_dwordx4 v[142:143], off
	v_lshl_add_u64 v[142:143], s[10:11], 0, v[136:137]
	s_add_i32 m0, s35, 0xe000
	s_nop 0
	global_load_lds_dwordx4 v[142:143], off
	s_waitcnt vmcnt(8)
	s_waitcnt lgkmcnt(0)
	s_barrier
; #define PG8_STAGE(bufoff, gbase, voff) do { _Pragma("unroll") for (int _i = 0; _i < 2; ++_i) \
;         __builtin_amdgcn_global_load_lds((const unsigned*)((const char*)(gbase) + (voff)[_i]), (PG8_LAS unsigned*)(lds + (bufoff) + ldsw + _i * 8192), 16, 0, 0); } while (0)
; #define PG8_WAIT_V(n) asm volatile("s_waitcnt vmcnt(" #n ")" ::: "memory")
; #define PG8_WAIT_L(n) asm volatile("s_waitcnt lgkmcnt(" #n ")" ::: "memory")
; #define PG8_BAR __builtin_amdgcn_s_barrier()
; #define PG8_SCHED __builtin_amdgcn_sched_barrier(0)
; template <class Epi, class Sched, bool ALIGN_EPI = false, bool SP2 = false, bool F8 = false>
; __device__ __forceinline__ void gemm_phase(PG8_LAS unsigned char* lds, const Gemm g, const Sched& S, const Epi& E) {
;     ...
;             PG8_WAIT_V(8); PG8_WAIT_L(0); PG8_BAR; PG8_MMA(0, 0, At, B0); PG8_MMA(0, 1, At, B1); PG8_BAR; PG8_SCHED;
;             PG8_LDA(At, 0, 1); PG8_STAGE(PG8_SB(0, 0), b2, voffB); PG8_STAGE(PG8_SB(0, 1), b2 + hstep, voffB); PG8_STAGE(PG8_SA(0, 0), a2, voffA);
;             PG8_WAIT_V(8); PG8_WAIT_L(0); PG8_BAR; PG8_MMA(1, 0, At, B0); PG8_MMA(1, 1, At, B1); PG8_BAR; PG8_SCHED;
;             PG8_LDB(B0, 1, 0); PG8_LDB(B1, 1, 1); PG8_SCHED; PG8_LDA(At, 1, 0); PG8_STAGE(PG8_SA(0, 1), a2 + hstep, voffA);
;             PG8_WAIT_V(8); PG8_WAIT_L(0); PG8_BAR; PG8_MMA(0, 0, At, B0); PG8_MMA(0, 1, At, B1); PG8_BAR; PG8_SCHED;
	s_setprio 1
	v_mfma_f32_16x16x32_bf16 v[124:127], v[138:141], v[200:203], v[124:127]
	v_mfma_f32_16x16x32_bf16 v[120:123], v[152:155], v[200:203], v[120:123]
	v_mfma_f32_16x16x32_bf16 v[108:111], v[138:141], v[218:221], v[108:111]
	v_mfma_f32_16x16x32_bf16 v[104:107], v[152:155], v[218:221], v[104:107]
	v_mfma_f32_16x16x32_bf16 v[92:95], v[138:141], v[226:229], v[92:95]
	v_mfma_f32_16x16x32_bf16 v[88:91], v[152:155], v[226:229], v[88:91]
	v_mfma_f32_16x16x32_bf16 v[76:79], v[138:141], v[234:237], v[76:79]
	v_mfma_f32_16x16x32_bf16 v[72:75], v[152:155], v[234:237], v[72:75]
	v_mfma_f32_16x16x32_bf16 v[124:127], v[148:151], v[214:217], v[124:127]
	v_mfma_f32_16x16x32_bf16 v[120:123], v[156:159], v[214:217], v[120:123]
	v_mfma_f32_16x16x32_bf16 v[108:111], v[148:151], v[222:225], v[108:111]
	v_mfma_f32_16x16x32_bf16 v[104:107], v[156:159], v[222:225], v[104:107]
	v_mfma_f32_16x16x32_bf16 v[92:95], v[148:151], v[230:233], v[92:95]
	v_mfma_f32_16x16x32_bf16 v[88:91], v[156:159], v[230:233], v[88:91]
	v_mfma_f32_16x16x32_bf16 v[76:79], v[148:151], v[238:241], v[76:79]
	v_mfma_f32_16x16x32_bf16 v[72:75], v[156:159], v[238:241], v[72:75]
	s_setprio 0
	s_setprio 1
	v_mfma_f32_16x16x32_bf16 v[116:119], v[184:187], v[200:203], v[116:119]
	v_mfma_f32_16x16x32_bf16 v[112:115], v[192:195], v[200:203], v[112:115]
	v_mfma_f32_16x16x32_bf16 v[100:103], v[184:187], v[218:221], v[100:103]
	v_mfma_f32_16x16x32_bf16 v[96:99], v[192:195], v[218:221], v[96:99]
	v_mfma_f32_16x16x32_bf16 v[84:87], v[184:187], v[226:229], v[84:87]
	v_mfma_f32_16x16x32_bf16 v[80:83], v[192:195], v[226:229], v[80:83]
	v_mfma_f32_16x16x32_bf16 v[68:71], v[184:187], v[234:237], v[68:71]
	v_mfma_f32_16x16x32_bf16 v[64:67], v[192:195], v[234:237], v[64:67]
	v_mfma_f32_16x16x32_bf16 v[116:119], v[188:191], v[214:217], v[116:119]
	v_mfma_f32_16x16x32_bf16 v[112:115], v[196:199], v[214:217], v[112:115]
	v_mfma_f32_16x16x32_bf16 v[100:103], v[188:191], v[222:225], v[100:103]
	v_mfma_f32_16x16x32_bf16 v[96:99], v[196:199], v[222:225], v[96:99]
	v_mfma_f32_16x16x32_bf16 v[84:87], v[188:191], v[230:233], v[84:87]
	v_mfma_f32_16x16x32_bf16 v[80:83], v[196:199], v[230:233], v[80:83]
	v_mfma_f32_16x16x32_bf16 v[68:71], v[188:191], v[238:241], v[68:71]
	v_mfma_f32_16x16x32_bf16 v[64:67], v[196:199], v[238:241], v[64:67]
	s_setprio 0
	s_barrier
	s_add_i32 s55, s55, s13
	v_lshl_add_u64 v[142:143], s[36:37], 0, v[160:161]
	s_mov_b32 m0, s55
	ds_read_b128 v[200:203], v147 offset:16384
	ds_read_b128 v[214:217], v147 offset:17408
	ds_read_b128 v[218:221], v147 offset:18432
	ds_read_b128 v[222:225], v147 offset:19456
	ds_read_b128 v[226:229], v147 offset:20480
	ds_read_b128 v[230:233], v147 offset:21504
	ds_read_b128 v[234:237], v147 offset:22528
	ds_read_b128 v[238:241], v147 offset:23552
	global_load_lds_dwordx4 v[142:143], off
	s_add_i32 m0, s55, 0x2000
	s_add_u32 s58, s36, 0x40000
	v_lshl_add_u64 v[162:163], s[36:37], 0, v[128:129]
	s_addc_u32 s59, s37, 0
	s_add_i32 s55, s56, s13
	global_load_lds_dwordx4 v[162:163], off
	v_lshl_add_u64 v[242:243], s[58:59], 0, v[160:161]
	s_mov_b32 m0, s55
	v_lshl_add_u64 v[244:245], s[46:47], 0, v[130:131]
	global_load_lds_dwordx4 v[242:243], off
	v_lshl_add_u64 v[242:243], s[58:59], 0, v[128:129]
	s_add_i32 m0, s55, 0x2000
	s_nop 0
	global_load_lds_dwordx4 v[242:243], off
	v_lshl_add_u64 v[242:243], s[46:47], 0, v[132:133]
	s_mov_b32 m0, s35
	s_nop 0
	global_load_lds_dwordx4 v[242:243], off
	s_mov_b32 m0, s48
	s_nop 0
	global_load_lds_dwordx4 v[244:245], off
	s_waitcnt vmcnt(8)
	s_waitcnt lgkmcnt(0)
	s_barrier
	s_setprio 1
	v_mfma_f32_16x16x32_bf16 v[60:63], v[138:141], v[200:203], v[60:63]
	v_mfma_f32_16x16x32_bf16 v[56:59], v[152:155], v[200:203], v[56:59]
	v_mfma_f32_16x16x32_bf16 v[44:47], v[138:141], v[218:221], v[44:47]
	v_mfma_f32_16x16x32_bf16 v[40:43], v[152:155], v[218:221], v[40:43]
	v_mfma_f32_16x16x32_bf16 v[28:31], v[138:141], v[226:229], v[28:31]
	v_mfma_f32_16x16x32_bf16 v[24:27], v[152:155], v[226:229], v[24:27]
	v_mfma_f32_16x16x32_bf16 v[12:15], v[138:141], v[234:237], v[12:15]
	v_mfma_f32_16x16x32_bf16 v[8:11], v[152:155], v[234:237], v[8:11]
	v_mfma_f32_16x16x32_bf16 v[60:63], v[148:151], v[214:217], v[60:63]
	v_mfma_f32_16x16x32_bf16 v[56:59], v[156:159], v[214:217], v[56:59]
	v_mfma_f32_16x16x32_bf16 v[44:47], v[148:151], v[222:225], v[44:47]
	v_mfma_f32_16x16x32_bf16 v[40:43], v[156:159], v[222:225], v[40:43]
	v_mfma_f32_16x16x32_bf16 v[28:31], v[148:151], v[230:233], v[28:31]
	v_mfma_f32_16x16x32_bf16 v[24:27], v[156:159], v[230:233], v[24:27]
	v_mfma_f32_16x16x32_bf16 v[12:15], v[148:151], v[238:241], v[12:15]
	v_mfma_f32_16x16x32_bf16 v[8:11], v[156:159], v[238:241], v[8:11]
	s_setprio 0
	s_setprio 1
	v_mfma_f32_16x16x32_bf16 v[52:55], v[184:187], v[200:203], v[52:55]
	v_mfma_f32_16x16x32_bf16 v[48:51], v[192:195], v[200:203], v[48:51]
	v_mfma_f32_16x16x32_bf16 v[36:39], v[184:187], v[218:221], v[36:39]
	v_mfma_f32_16x16x32_bf16 v[32:35], v[192:195], v[218:221], v[32:35]
	v_mfma_f32_16x16x32_bf16 v[20:23], v[184:187], v[226:229], v[20:23]
	v_mfma_f32_16x16x32_bf16 v[16:19], v[192:195], v[226:229], v[16:19]
	v_mfma_f32_16x16x32_bf16 v[4:7], v[184:187], v[234:237], v[4:7]
	v_mfma_f32_16x16x32_bf16 v[0:3], v[192:195], v[234:237], v[0:3]
	v_mfma_f32_16x16x32_bf16 v[52:55], v[188:191], v[214:217], v[52:55]
	v_mfma_f32_16x16x32_bf16 v[48:51], v[196:199], v[214:217], v[48:51]
	v_mfma_f32_16x16x32_bf16 v[36:39], v[188:191], v[222:225], v[36:39]
	v_mfma_f32_16x16x32_bf16 v[32:35], v[196:199], v[222:225], v[32:35]
	v_mfma_f32_16x16x32_bf16 v[20:23], v[188:191], v[230:233], v[20:23]
	v_mfma_f32_16x16x32_bf16 v[16:19], v[196:199], v[230:233], v[16:19]
	v_mfma_f32_16x16x32_bf16 v[4:7], v[188:191], v[238:241], v[4:7]
	v_mfma_f32_16x16x32_bf16 v[0:3], v[196:199], v[238:241], v[0:3]
	s_setprio 0
	s_barrier
; #define PG8_STAGE(bufoff, gbase, voff) do { _Pragma("unroll") for (int _i = 0; _i < 2; ++_i) \
;         __builtin_amdgcn_global_load_lds((const unsigned*)((const char*)(gbase) + (voff)[_i]), (PG8_LAS unsigned*)(lds + (bufoff) + ldsw + _i * 8192), 16, 0, 0); } while (0)
; #define PG8_WAIT_V(n) asm volatile("s_waitcnt vmcnt(" #n ")" ::: "memory")
; #define PG8_WAIT_L(n) asm volatile("s_waitcnt lgkmcnt(" #n ")" ::: "memory")
; #define PG8_BAR __builtin_amdgcn_s_barrier()
; #define PG8_SCHED __builtin_amdgcn_sched_barrier(0)
; template <class Epi, class Sched, bool ALIGN_EPI = false, bool SP2 = false, bool F8 = false>
; __device__ __forceinline__ void gemm_phase(PG8_LAS unsigned char* lds, const Gemm g, const Sched& S, const Epi& E) {
;     ...
;             PG8_LDB(B0, 1, 0); PG8_LDB(B1, 1, 1); PG8_SCHED; PG8_LDA(At, 1, 0); PG8_STAGE(PG8_SA(0, 1), a2 + hstep, voffA);
;             PG8_WAIT_V(8); PG8_WAIT_L(0); PG8_BAR; PG8_MMA(0, 0, At, B0); PG8_MMA(0, 1, At, B1); PG8_BAR; PG8_SCHED;
	s_add_i32 s55, 0, 0x18000
	s_add_i32 s56, 0, 0x1c000
	v_add_u32_e32 v156, s55, v145
	v_add_u32_e32 v196, s56, v145
	ds_read_b128 v[138:141], v156
	ds_read_b128 v[148:151], v156 offset:1024
	ds_read_b128 v[152:155], v156 offset:2048
	ds_read_b128 v[156:159], v156 offset:3072
	ds_read_b128 v[184:187], v196
	ds_read_b128 v[188:191], v196 offset:1024
	ds_read_b128 v[192:195], v196 offset:2048
	ds_read_b128 v[196:199], v196 offset:3072
	s_add_u32 s46, s46, 0x40000
	s_addc_u32 s47, s47, 0
	s_mov_b32 m0, s49
	v_lshl_add_u64 v[246:247], s[46:47], 0, v[132:133]
	ds_read_b128 v[200:203], v147 offset:32768
	ds_read_b128 v[214:217], v147 offset:33792
	ds_read_b128 v[218:221], v147 offset:34816
	ds_read_b128 v[222:225], v147 offset:35840
	ds_read_b128 v[226:229], v147 offset:36864
	ds_read_b128 v[230:233], v147 offset:37888
	ds_read_b128 v[234:237], v147 offset:38912
	ds_read_b128 v[238:241], v147 offset:39936
	global_load_lds_dwordx4 v[246:247], off
	v_lshl_add_u64 v[246:247], s[46:47], 0, v[130:131]
	s_mov_b32 m0, s50
	s_nop 0
	global_load_lds_dwordx4 v[246:247], off
	s_waitcnt vmcnt(8)
	s_waitcnt lgkmcnt(0)
	s_barrier
	s_setprio 1
	v_mfma_f32_16x16x32_bf16 v[124:127], v[138:141], v[200:203], v[124:127]
	v_mfma_f32_16x16x32_bf16 v[120:123], v[152:155], v[200:203], v[120:123]
	v_mfma_f32_16x16x32_bf16 v[108:111], v[138:141], v[218:221], v[108:111]
	v_mfma_f32_16x16x32_bf16 v[104:107], v[152:155], v[218:221], v[104:107]
	v_mfma_f32_16x16x32_bf16 v[92:95], v[138:141], v[226:229], v[92:95]
	v_mfma_f32_16x16x32_bf16 v[88:91], v[152:155], v[226:229], v[88:91]
	v_mfma_f32_16x16x32_bf16 v[76:79], v[138:141], v[234:237], v[76:79]
	v_mfma_f32_16x16x32_bf16 v[72:75], v[152:155], v[234:237], v[72:75]
	v_mfma_f32_16x16x32_bf16 v[124:127], v[148:151], v[214:217], v[124:127]
	v_mfma_f32_16x16x32_bf16 v[120:123], v[156:159], v[214:217], v[120:123]
	v_mfma_f32_16x16x32_bf16 v[108:111], v[148:151], v[222:225], v[108:111]
	v_mfma_f32_16x16x32_bf16 v[104:107], v[156:159], v[222:225], v[104:107]
	v_mfma_f32_16x16x32_bf16 v[92:95], v[148:151], v[230:233], v[92:95]
	v_mfma_f32_16x16x32_bf16 v[88:91], v[156:159], v[230:233], v[88:91]
	v_mfma_f32_16x16x32_bf16 v[76:79], v[148:151], v[238:241], v[76:79]
	v_mfma_f32_16x16x32_bf16 v[72:75], v[156:159], v[238:241], v[72:75]
	s_setprio 0
	s_setprio 1
	v_mfma_f32_16x16x32_bf16 v[116:119], v[184:187], v[200:203], v[116:119]
	v_mfma_f32_16x16x32_bf16 v[112:115], v[192:195], v[200:203], v[112:115]
	v_mfma_f32_16x16x32_bf16 v[100:103], v[184:187], v[218:221], v[100:103]
	v_mfma_f32_16x16x32_bf16 v[96:99], v[192:195], v[218:221], v[96:99]
	v_mfma_f32_16x16x32_bf16 v[84:87], v[184:187], v[226:229], v[84:87]
	v_mfma_f32_16x16x32_bf16 v[80:83], v[192:195], v[226:229], v[80:83]
	v_mfma_f32_16x16x32_bf16 v[68:71], v[184:187], v[234:237], v[68:71]
	v_mfma_f32_16x16x32_bf16 v[64:67], v[192:195], v[234:237], v[64:67]
	v_mfma_f32_16x16x32_bf16 v[116:119], v[188:191], v[214:217], v[116:119]
	v_mfma_f32_16x16x32_bf16 v[112:115], v[196:199], v[214:217], v[112:115]
	v_mfma_f32_16x16x32_bf16 v[100:103], v[188:191], v[222:225], v[100:103]
	v_mfma_f32_16x16x32_bf16 v[96:99], v[196:199], v[222:225], v[96:99]
	v_mfma_f32_16x16x32_bf16 v[84:87], v[188:191], v[230:233], v[84:87]
	v_mfma_f32_16x16x32_bf16 v[80:83], v[196:199], v[230:233], v[80:83]
	v_mfma_f32_16x16x32_bf16 v[68:71], v[188:191], v[238:241], v[68:71]
	v_mfma_f32_16x16x32_bf16 v[64:67], v[196:199], v[238:241], v[64:67]
	s_setprio 0
	s_barrier
; #define PG8_STAGE(bufoff, gbase, voff) do { _Pragma("unroll") for (int _i = 0; _i < 2; ++_i) \
;         __builtin_amdgcn_global_load_lds((const unsigned*)((const char*)(gbase) + (voff)[_i]), (PG8_LAS unsigned*)(lds + (bufoff) + ldsw + _i * 8192), 16, 0, 0); } while (0)
; #define PG8_WAIT_V(n) asm volatile("s_waitcnt vmcnt(" #n ")" ::: "memory")
; #define PG8_WAIT_L(n) asm volatile("s_waitcnt lgkmcnt(" #n ")" ::: "memory")
; #define PG8_BAR __builtin_amdgcn_s_barrier()
; #define PG8_SCHED __builtin_amdgcn_sched_barrier(0)
; template <class Epi, class Sched, bool ALIGN_EPI = false, bool SP2 = false, bool F8 = false>
; __device__ __forceinline__ void gemm_phase(PG8_LAS unsigned char* lds, const Gemm g, const Sched& S, const Epi& E) {
;     ...
;         for (int t = 0; t < nt; t += 2) {
;             const bool last = (t == nt - 2);
;             const char* a1 = cA + (size_t)(t + 1) * kstep;
;             const char* a2 = last ? nA : cA + (size_t)(t + 2) * kstep; const char* b2 = last ? nB : cB + (size_t)(t + 2) * kstep;
;             const char* a3 = a2 + kstep; const char* b3 = b2 + kstep;
;     ...
;             PG8_LDA(At, 1, 1); PG8_STAGE(PG8_SB(1, 0), b3, voffB); PG8_STAGE(PG8_SB(1, 1), b3 + hstep, voffB); PG8_STAGE(PG8_SA(1, 0), a3, voffA);
;             PG8_WAIT_V(8); PG8_WAIT_L(0); PG8_BAR; PG8_MMA(1, 0, At, B0); PG8_MMA(1, 1, At, B1); PG8_BAR; PG8_SCHED;
	s_add_i32 s46, s55, s13
	v_lshl_add_u64 v[142:143], v[142:143], 0, s[14:15]
	s_mov_b32 m0, s46
	ds_read_b128 v[200:203], v147 offset:49152
	ds_read_b128 v[214:217], v147 offset:50176
	ds_read_b128 v[218:221], v147 offset:51200
	ds_read_b128 v[222:225], v147 offset:52224
	ds_read_b128 v[226:229], v147 offset:53248
	ds_read_b128 v[230:233], v147 offset:54272
	ds_read_b128 v[234:237], v147 offset:55296
	ds_read_b128 v[238:241], v147 offset:56320
	global_load_lds_dwordx4 v[142:143], off
	s_add_i32 m0, s46, 0x2000
	s_add_u32 s36, s36, 0x40080
	v_lshl_add_u64 v[142:143], v[162:163], 0, s[14:15]
	s_addc_u32 s37, s37, 0
	s_add_i32 s46, s56, s13
	global_load_lds_dwordx4 v[142:143], off
	v_lshl_add_u64 v[142:143], s[36:37], 0, v[160:161]
	s_mov_b32 m0, s46
	s_nop 0
	global_load_lds_dwordx4 v[142:143], off
	v_lshl_add_u64 v[142:143], s[36:37], 0, v[128:129]
	s_add_i32 m0, s46, 0x2000
	s_nop 0
	global_load_lds_dwordx4 v[142:143], off
	v_lshl_add_u64 v[142:143], v[242:243], 0, s[14:15]
	s_mov_b32 m0, s51
	s_nop 0
	global_load_lds_dwordx4 v[142:143], off
	v_lshl_add_u64 v[142:143], v[244:245], 0, s[14:15]
	s_mov_b32 m0, s52
	s_nop 0
	global_load_lds_dwordx4 v[142:143], off
	s_waitcnt vmcnt(8)
	s_waitcnt lgkmcnt(0)
	s_barrier
	s_setprio 1
	v_mfma_f32_16x16x32_bf16 v[60:63], v[138:141], v[200:203], v[60:63]
	v_mfma_f32_16x16x32_bf16 v[56:59], v[152:155], v[200:203], v[56:59]
	v_mfma_f32_16x16x32_bf16 v[44:47], v[138:141], v[218:221], v[44:47]
	v_mfma_f32_16x16x32_bf16 v[40:43], v[152:155], v[218:221], v[40:43]
	v_mfma_f32_16x16x32_bf16 v[28:31], v[138:141], v[226:229], v[28:31]
	v_mfma_f32_16x16x32_bf16 v[24:27], v[152:155], v[226:229], v[24:27]
	v_mfma_f32_16x16x32_bf16 v[12:15], v[138:141], v[234:237], v[12:15]
	v_mfma_f32_16x16x32_bf16 v[8:11], v[152:155], v[234:237], v[8:11]
	v_mfma_f32_16x16x32_bf16 v[60:63], v[148:151], v[214:217], v[60:63]
	v_mfma_f32_16x16x32_bf16 v[56:59], v[156:159], v[214:217], v[56:59]
	v_mfma_f32_16x16x32_bf16 v[44:47], v[148:151], v[222:225], v[44:47]
	v_mfma_f32_16x16x32_bf16 v[40:43], v[156:159], v[222:225], v[40:43]
	v_mfma_f32_16x16x32_bf16 v[28:31], v[148:151], v[230:233], v[28:31]
	v_mfma_f32_16x16x32_bf16 v[24:27], v[156:159], v[230:233], v[24:27]
	v_mfma_f32_16x16x32_bf16 v[12:15], v[148:151], v[238:241], v[12:15]
	v_mfma_f32_16x16x32_bf16 v[8:11], v[156:159], v[238:241], v[8:11]
	s_setprio 0
	s_setprio 1
	v_mfma_f32_16x16x32_bf16 v[52:55], v[184:187], v[200:203], v[52:55]
	v_mfma_f32_16x16x32_bf16 v[48:51], v[192:195], v[200:203], v[48:51]
	v_mfma_f32_16x16x32_bf16 v[36:39], v[184:187], v[218:221], v[36:39]
	v_mfma_f32_16x16x32_bf16 v[32:35], v[192:195], v[218:221], v[32:35]
	v_mfma_f32_16x16x32_bf16 v[20:23], v[184:187], v[226:229], v[20:23]
	v_mfma_f32_16x16x32_bf16 v[16:19], v[192:195], v[226:229], v[16:19]
	v_mfma_f32_16x16x32_bf16 v[4:7], v[184:187], v[234:237], v[4:7]
	v_mfma_f32_16x16x32_bf16 v[0:3], v[192:195], v[234:237], v[0:3]
	v_mfma_f32_16x16x32_bf16 v[52:55], v[188:191], v[214:217], v[52:55]
	v_mfma_f32_16x16x32_bf16 v[48:51], v[196:199], v[214:217], v[48:51]
	v_mfma_f32_16x16x32_bf16 v[36:39], v[188:191], v[222:225], v[36:39]
	v_mfma_f32_16x16x32_bf16 v[32:35], v[196:199], v[222:225], v[32:35]
	v_mfma_f32_16x16x32_bf16 v[20:23], v[188:191], v[230:233], v[20:23]
	v_mfma_f32_16x16x32_bf16 v[16:19], v[196:199], v[230:233], v[16:19]
	v_mfma_f32_16x16x32_bf16 v[4:7], v[188:191], v[238:241], v[4:7]
	v_mfma_f32_16x16x32_bf16 v[0:3], v[196:199], v[238:241], v[0:3]
	s_setprio 0
	s_barrier
	s_add_i32 s54, s54, 2
	s_add_u32 s10, s10, 0x100
	s_addc_u32 s11, s11, 0
	s_add_u32 s29, s29, 0x100
	s_addc_u32 s41, s41, 0
	s_cmp_gt_u32 s54, 13
	s_cbranch_scc0 .LBB0_117

; #define PG8_STAGE(bufoff, gbase, voff) do { _Pragma("unroll") for (int _i = 0; _i < 2; ++_i) \
;         __builtin_amdgcn_global_load_lds((const unsigned*)((const char*)(gbase) + (voff)[_i]), (PG8_LAS unsigned*)(lds + (bufoff) + ldsw + _i * 8192), 16, 0, 0); } while (0)
; #define PG8_WAIT_V(n) asm volatile("s_waitcnt vmcnt(" #n ")" ::: "memory")
; #define PG8_WAIT_L(n) asm volatile("s_waitcnt lgkmcnt(" #n ")" ::: "memory")
; #define PG8_BAR __builtin_amdgcn_s_barrier()
; #define PG8_SCHED __builtin_amdgcn_sched_barrier(0)
; template <class Epi, class Sched, bool ALIGN_EPI = false, bool SP2 = false, bool F8 = false>
; __device__ __forceinline__ void gemm_phase(PG8_LAS unsigned char* lds, const Gemm g, const Sched& S, const Epi& E) {
;     ...
;         const bool has_next = S.next(ui + 1, nxt);
;         const char* nA = has_next ? (const char*)g.A + (size_t)nxt.pm * tstep : cA; const char* nB = has_next ? (const char*)g.Bt + (size_t)nxt.pn * tstep : cB;
;         for (int t = 0; t < nt; t += 2) {
;             const bool last = (t == nt - 2);
;             const char* a1 = cA + (size_t)(t + 1) * kstep;
;             const char* a2 = last ? nA : cA + (size_t)(t + 2) * kstep; const char* b2 = last ? nB : cB + (size_t)(t + 2) * kstep;
;             const char* a3 = a2 + kstep; const char* b3 = b2 + kstep;
;             if (last && has_next) S.a_ready(nxt);
;             if constexpr (SP2) {
;             PG8_LDB(B0, 0, 0); PG8_LDB(B1, 0, 1); PG8_SCHED; PG8_LDA(At, 0, 0); PG8_STAGE(PG8_SA(1, 1), a1 + hstep, voffA);
;             PG8_WAIT_V(8); PG8_WAIT_L(0); PG8_BAR; PG8_MMA(0, 0, At, B0); PG8_MMA(0, 1, At, B1); PG8_BAR; PG8_SCHED;
;             PG8_LDA(At, 0, 1); PG8_STAGE(PG8_SB(0, 0), b2, voffB); PG8_STAGE(PG8_SB(0, 1), b2 + hstep, voffB); PG8_STAGE(PG8_SA(0, 0), a2, voffA);
;             PG8_WAIT_V(8); PG8_WAIT_L(0); PG8_BAR; PG8_MMA(1, 0, At, B0); PG8_MMA(1, 1, At, B1); PG8_BAR; PG8_SCHED;
.LBB0_1021:
	s_ashr_i32 s17, s16, 31
	s_lshl_b64 s[36:37], s[16:17], 19
	v_readlane_b32 s11, v253, 59
	s_add_u32 s36, s11, s36
	v_readlane_b32 s11, v253, 60
	s_addc_u32 s37, s11, s37
	s_and_b64 s[42:43], s[38:39], exec
	s_cselect_b32 s17, s37, s41
	s_cselect_b32 s50, s36, s40
	s_ashr_i32 s11, s10, 31
	s_lshl_b64 s[42:43], s[10:11], 19
	s_add_u32 s42, s13, s42
	s_addc_u32 s43, s19, s43
	s_and_b64 s[46:47], s[38:39], exec
	s_cselect_b32 s11, s43, s45
	s_cselect_b32 s51, s42, s44
	s_add_u32 s40, s40, 0x40080
	s_addc_u32 s41, s41, 0
	s_add_u32 s52, s44, 0x100
	s_addc_u32 s53, s45, 0
	s_mov_b32 s54, -2
	s_add_u32 s44, s40, 0xfffc0080
	s_addc_u32 s45, s41, -1
	s_add_i32 s55, 0, 0x10000
	s_cmp_eq_u32 s54, 12
	s_cselect_b32 s47, s17, s45
	s_cselect_b32 s46, s50, s44
	s_cselect_b32 s45, s11, s53
	s_cselect_b32 s44, s51, s52
	s_add_i32 s56, 0, 0x14000
	v_add_u32_e32 v0, s55, v215
	v_add_u32_e32 v12, s56, v215
	ds_read_b128 v[16:19], v0
	ds_read_b128 v[20:23], v0 offset:1024
	ds_read_b128 v[24:27], v0 offset:2048
	ds_read_b128 v[28:31], v0 offset:3072
	ds_read_b128 v[0:3], v12
	ds_read_b128 v[4:7], v12 offset:1024
	ds_read_b128 v[8:11], v12 offset:2048
	ds_read_b128 v[12:15], v12 offset:3072
	v_lshl_add_u64 v[242:243], s[40:41], 0, v[192:193]
	s_add_i32 m0, s23, 0xc000
	ds_read_b128 v[196:199], v217
	ds_read_b128 v[200:203], v217 offset:1024
	ds_read_b128 v[218:221], v217 offset:2048
	ds_read_b128 v[222:225], v217 offset:3072
	ds_read_b128 v[226:229], v217 offset:4096
	ds_read_b128 v[230:233], v217 offset:5120
	ds_read_b128 v[234:237], v217 offset:6144
	ds_read_b128 v[238:241], v217 offset:7168
	global_load_lds_dwordx4 v[242:243], off
	v_lshl_add_u64 v[242:243], s[40:41], 0, v[194:195]
	s_add_i32 m0, s23, 0xe000
	s_nop 0
	global_load_lds_dwordx4 v[242:243], off
	s_waitcnt vmcnt(8)
	s_waitcnt lgkmcnt(0)
	s_barrier
	s_setprio 1
	v_mfma_scale_f32_16x16x128_f8f6f4 v[156:159], v[16:23], v[196:203], 0, v213, v213 op_sel_hi:[0,0,0]
	v_mfma_scale_f32_16x16x128_f8f6f4 v[152:155], v[24:31], v[196:203], 0, v213, v213 op_sel_hi:[0,0,0]
	v_mfma_scale_f32_16x16x128_f8f6f4 v[140:143], v[16:23], v[218:225], 0, v213, v213 op_sel_hi:[0,0,0]
	v_mfma_scale_f32_16x16x128_f8f6f4 v[136:139], v[24:31], v[218:225], 0, v213, v213 op_sel_hi:[0,0,0]
	v_mfma_scale_f32_16x16x128_f8f6f4 v[124:127], v[16:23], v[226:233], 0, v213, v213 op_sel_hi:[0,0,0]
	v_mfma_scale_f32_16x16x128_f8f6f4 v[120:123], v[24:31], v[226:233], 0, v213, v213 op_sel_hi:[0,0,0]
	v_mfma_scale_f32_16x16x128_f8f6f4 v[108:111], v[16:23], v[234:241], 0, v213, v213 op_sel_hi:[0,0,0]
	v_mfma_scale_f32_16x16x128_f8f6f4 v[104:107], v[24:31], v[234:241], 0, v213, v213 op_sel_hi:[0,0,0]
	s_setprio 0
	s_setprio 1
	v_mfma_scale_f32_16x16x128_f8f6f4 v[148:151], v[0:7], v[196:203], 0, v213, v213 op_sel_hi:[0,0,0]
	v_mfma_scale_f32_16x16x128_f8f6f4 v[144:147], v[8:15], v[196:203], 0, v213, v213 op_sel_hi:[0,0,0]
	v_mfma_scale_f32_16x16x128_f8f6f4 v[132:135], v[0:7], v[218:225], 0, v213, v213 op_sel_hi:[0,0,0]
	v_mfma_scale_f32_16x16x128_f8f6f4 v[128:131], v[8:15], v[218:225], 0, v213, v213 op_sel_hi:[0,0,0]
	v_mfma_scale_f32_16x16x128_f8f6f4 v[116:119], v[0:7], v[226:233], 0, v213, v213 op_sel_hi:[0,0,0]
	v_mfma_scale_f32_16x16x128_f8f6f4 v[112:115], v[8:15], v[226:233], 0, v213, v213 op_sel_hi:[0,0,0]
	v_mfma_scale_f32_16x16x128_f8f6f4 v[100:103], v[0:7], v[234:241], 0, v213, v213 op_sel_hi:[0,0,0]
	v_mfma_scale_f32_16x16x128_f8f6f4 v[96:99], v[8:15], v[234:241], 0, v213, v213 op_sel_hi:[0,0,0]
	s_setprio 0
	s_barrier
	s_add_i32 s55, s55, s22
	v_lshl_add_u64 v[196:197], s[44:45], 0, v[188:189]
	s_mov_b32 m0, s55
	ds_read_b128 v[218:221], v217 offset:16384
	ds_read_b128 v[222:225], v217 offset:17408
	ds_read_b128 v[226:229], v217 offset:18432
	ds_read_b128 v[230:233], v217 offset:19456
	ds_read_b128 v[234:237], v217 offset:20480
	ds_read_b128 v[238:241], v217 offset:21504
	ds_read_b128 v[242:245], v217 offset:22528
	ds_read_b128 v[246:249], v217 offset:23552
	global_load_lds_dwordx4 v[196:197], off
	s_add_i32 m0, s55, 0x2000
	s_add_u32 s58, s44, 0x40000
	v_lshl_add_u64 v[198:199], s[44:45], 0, v[184:185]
	s_addc_u32 s59, s45, 0
	s_add_i32 s55, s56, s22
	global_load_lds_dwordx4 v[198:199], off
	v_lshl_add_u64 v[200:201], s[58:59], 0, v[188:189]
	s_mov_b32 m0, s55
	v_lshl_add_u64 v[202:203], s[46:47], 0, v[186:187]
	global_load_lds_dwordx4 v[200:201], off
	v_lshl_add_u64 v[200:201], s[58:59], 0, v[184:185]
	s_add_i32 m0, s55, 0x2000
	s_nop 0
	global_load_lds_dwordx4 v[200:201], off
	v_lshl_add_u64 v[200:201], s[46:47], 0, v[190:191]
	s_mov_b32 m0, s23
	s_nop 0
	global_load_lds_dwordx4 v[200:201], off
	s_mov_b32 m0, s8
	s_nop 0
	global_load_lds_dwordx4 v[202:203], off
	s_waitcnt vmcnt(8)
	s_waitcnt lgkmcnt(0)
	s_barrier
	s_setprio 1
	v_mfma_scale_f32_16x16x128_f8f6f4 v[92:95], v[16:23], v[218:225], 0, v213, v213 op_sel_hi:[0,0,0]
	v_mfma_scale_f32_16x16x128_f8f6f4 v[88:91], v[24:31], v[218:225], 0, v213, v213 op_sel_hi:[0,0,0]
	v_mfma_scale_f32_16x16x128_f8f6f4 v[76:79], v[16:23], v[226:233], 0, v213, v213 op_sel_hi:[0,0,0]
	v_mfma_scale_f32_16x16x128_f8f6f4 v[72:75], v[24:31], v[226:233], 0, v213, v213 op_sel_hi:[0,0,0]
	v_mfma_scale_f32_16x16x128_f8f6f4 v[60:63], v[16:23], v[234:241], 0, v213, v213 op_sel_hi:[0,0,0]
	v_mfma_scale_f32_16x16x128_f8f6f4 v[56:59], v[24:31], v[234:241], 0, v213, v213 op_sel_hi:[0,0,0]
	v_mfma_scale_f32_16x16x128_f8f6f4 v[44:47], v[16:23], v[242:249], 0, v213, v213 op_sel_hi:[0,0,0]
	v_mfma_scale_f32_16x16x128_f8f6f4 v[40:43], v[24:31], v[242:249], 0, v213, v213 op_sel_hi:[0,0,0]
	s_setprio 0
	s_setprio 1
	v_mfma_scale_f32_16x16x128_f8f6f4 v[84:87], v[0:7], v[218:225], 0, v213, v213 op_sel_hi:[0,0,0]
	v_mfma_scale_f32_16x16x128_f8f6f4 v[80:83], v[8:15], v[218:225], 0, v213, v213 op_sel_hi:[0,0,0]
	v_mfma_scale_f32_16x16x128_f8f6f4 v[68:71], v[0:7], v[226:233], 0, v213, v213 op_sel_hi:[0,0,0]
	v_mfma_scale_f32_16x16x128_f8f6f4 v[64:67], v[8:15], v[226:233], 0, v213, v213 op_sel_hi:[0,0,0]
	v_mfma_scale_f32_16x16x128_f8f6f4 v[52:55], v[0:7], v[234:241], 0, v213, v213 op_sel_hi:[0,0,0]
	v_mfma_scale_f32_16x16x128_f8f6f4 v[48:51], v[8:15], v[234:241], 0, v213, v213 op_sel_hi:[0,0,0]
	v_mfma_scale_f32_16x16x128_f8f6f4 v[36:39], v[0:7], v[242:249], 0, v213, v213 op_sel_hi:[0,0,0]
	v_mfma_scale_f32_16x16x128_f8f6f4 v[32:35], v[8:15], v[242:249], 0, v213, v213 op_sel_hi:[0,0,0]
	s_setprio 0
	s_barrier
; #define PG8_STAGE(bufoff, gbase, voff) do { _Pragma("unroll") for (int _i = 0; _i < 2; ++_i) \
;         __builtin_amdgcn_global_load_lds((const unsigned*)((const char*)(gbase) + (voff)[_i]), (PG8_LAS unsigned*)(lds + (bufoff) + ldsw + _i * 8192), 16, 0, 0); } while (0)
; #define PG8_WAIT_V(n) asm volatile("s_waitcnt vmcnt(" #n ")" ::: "memory")
; #define PG8_WAIT_L(n) asm volatile("s_waitcnt lgkmcnt(" #n ")" ::: "memory")
; #define PG8_BAR __builtin_amdgcn_s_barrier()
; #define PG8_SCHED __builtin_amdgcn_sched_barrier(0)
; template <class Epi, class Sched, bool ALIGN_EPI = false, bool SP2 = false, bool F8 = false>
; __device__ __forceinline__ void gemm_phase(PG8_LAS unsigned char* lds, const Gemm g, const Sched& S, const Epi& E) {
;     ...
;             PG8_LDB(B0, 1, 0); PG8_LDB(B1, 1, 1); PG8_SCHED; PG8_LDA(At, 1, 0); PG8_STAGE(PG8_SA(0, 1), a2 + hstep, voffA);
;             PG8_WAIT_V(8); PG8_WAIT_L(0); PG8_BAR; PG8_MMA(0, 0, At, B0); PG8_MMA(0, 1, At, B1); PG8_BAR; PG8_SCHED;
;             PG8_LDA(At, 1, 1); PG8_STAGE(PG8_SB(1, 0), b3, voffB); PG8_STAGE(PG8_SB(1, 1), b3 + hstep, voffB); PG8_STAGE(PG8_SA(1, 0), a3, voffA);
;             PG8_WAIT_V(8); PG8_WAIT_L(0); PG8_BAR; PG8_MMA(1, 0, At, B0); PG8_MMA(1, 1, At, B1); PG8_BAR; PG8_SCHED;
	s_add_i32 s55, 0, 0x18000
	s_add_i32 s56, 0, 0x1c000
	v_add_u32_e32 v12, s55, v215
	v_add_u32_e32 v28, s56, v215
	ds_read_b128 v[0:3], v12
	ds_read_b128 v[4:7], v12 offset:1024
	ds_read_b128 v[8:11], v12 offset:2048
	ds_read_b128 v[12:15], v12 offset:3072
	ds_read_b128 v[16:19], v28
	ds_read_b128 v[20:23], v28 offset:1024
	ds_read_b128 v[24:27], v28 offset:2048
	ds_read_b128 v[28:31], v28 offset:3072
	s_add_u32 s46, s46, 0x40000
	s_addc_u32 s47, s47, 0
	s_mov_b32 m0, s9
	v_lshl_add_u64 v[162:163], s[46:47], 0, v[190:191]
	ds_read_b128 v[218:221], v217 offset:32768
	ds_read_b128 v[222:225], v217 offset:33792
	ds_read_b128 v[226:229], v217 offset:34816
	ds_read_b128 v[230:233], v217 offset:35840
	ds_read_b128 v[234:237], v217 offset:36864
	ds_read_b128 v[238:241], v217 offset:37888
	ds_read_b128 v[242:245], v217 offset:38912
	ds_read_b128 v[246:249], v217 offset:39936
	global_load_lds_dwordx4 v[162:163], off
	v_lshl_add_u64 v[162:163], s[46:47], 0, v[186:187]
	s_mov_b32 m0, s28
	s_nop 0
	global_load_lds_dwordx4 v[162:163], off
	s_waitcnt vmcnt(8)
	s_waitcnt lgkmcnt(0)
	s_barrier
	s_setprio 1
	v_mfma_scale_f32_16x16x128_f8f6f4 v[156:159], v[0:7], v[218:225], v[156:159], v213, v213 op_sel_hi:[0,0,0]
	v_mfma_scale_f32_16x16x128_f8f6f4 v[152:155], v[8:15], v[218:225], v[152:155], v213, v213 op_sel_hi:[0,0,0]
	v_mfma_scale_f32_16x16x128_f8f6f4 v[140:143], v[0:7], v[226:233], v[140:143], v213, v213 op_sel_hi:[0,0,0]
	v_mfma_scale_f32_16x16x128_f8f6f4 v[136:139], v[8:15], v[226:233], v[136:139], v213, v213 op_sel_hi:[0,0,0]
	v_mfma_scale_f32_16x16x128_f8f6f4 v[124:127], v[0:7], v[234:241], v[124:127], v213, v213 op_sel_hi:[0,0,0]
	v_mfma_scale_f32_16x16x128_f8f6f4 v[120:123], v[8:15], v[234:241], v[120:123], v213, v213 op_sel_hi:[0,0,0]
	v_mfma_scale_f32_16x16x128_f8f6f4 v[108:111], v[0:7], v[242:249], v[108:111], v213, v213 op_sel_hi:[0,0,0]
	v_mfma_scale_f32_16x16x128_f8f6f4 v[104:107], v[8:15], v[242:249], v[104:107], v213, v213 op_sel_hi:[0,0,0]
	s_setprio 0
	s_setprio 1
	v_mfma_scale_f32_16x16x128_f8f6f4 v[148:151], v[16:23], v[218:225], v[148:151], v213, v213 op_sel_hi:[0,0,0]
	v_mfma_scale_f32_16x16x128_f8f6f4 v[144:147], v[24:31], v[218:225], v[144:147], v213, v213 op_sel_hi:[0,0,0]
	v_mfma_scale_f32_16x16x128_f8f6f4 v[132:135], v[16:23], v[226:233], v[132:135], v213, v213 op_sel_hi:[0,0,0]
	v_mfma_scale_f32_16x16x128_f8f6f4 v[128:131], v[24:31], v[226:233], v[128:131], v213, v213 op_sel_hi:[0,0,0]
	v_mfma_scale_f32_16x16x128_f8f6f4 v[116:119], v[16:23], v[234:241], v[116:119], v213, v213 op_sel_hi:[0,0,0]
	v_mfma_scale_f32_16x16x128_f8f6f4 v[112:115], v[24:31], v[234:241], v[112:115], v213, v213 op_sel_hi:[0,0,0]
	v_mfma_scale_f32_16x16x128_f8f6f4 v[100:103], v[16:23], v[242:249], v[100:103], v213, v213 op_sel_hi:[0,0,0]
	v_mfma_scale_f32_16x16x128_f8f6f4 v[96:99], v[24:31], v[242:249], v[96:99], v213, v213 op_sel_hi:[0,0,0]
	s_setprio 0
	s_barrier
	s_add_i32 s46, s55, s22
	v_lshl_add_u64 v[162:163], v[196:197], 0, s[14:15]
	s_mov_b32 m0, s46
	ds_read_b128 v[218:221], v217 offset:49152
	ds_read_b128 v[222:225], v217 offset:50176
	ds_read_b128 v[226:229], v217 offset:51200
	ds_read_b128 v[230:233], v217 offset:52224
	ds_read_b128 v[234:237], v217 offset:53248
	ds_read_b128 v[238:241], v217 offset:54272
	ds_read_b128 v[242:245], v217 offset:55296
	ds_read_b128 v[246:249], v217 offset:56320
	global_load_lds_dwordx4 v[162:163], off
	s_add_i32 m0, s46, 0x2000
	s_add_u32 s44, s44, 0x40080
	v_lshl_add_u64 v[162:163], v[198:199], 0, s[14:15]
	s_addc_u32 s45, s45, 0
	s_add_i32 s46, s56, s22
	global_load_lds_dwordx4 v[162:163], off
	v_lshl_add_u64 v[162:163], s[44:45], 0, v[188:189]
	s_mov_b32 m0, s46
	s_nop 0
	global_load_lds_dwordx4 v[162:163], off
	v_lshl_add_u64 v[162:163], s[44:45], 0, v[184:185]
	s_add_i32 m0, s46, 0x2000
	s_nop 0
	global_load_lds_dwordx4 v[162:163], off
	v_lshl_add_u64 v[162:163], v[200:201], 0, s[14:15]
	s_mov_b32 m0, s29
	s_nop 0
	global_load_lds_dwordx4 v[162:163], off
	v_lshl_add_u64 v[162:163], v[202:203], 0, s[14:15]
	s_mov_b32 m0, s48
	s_nop 0
	global_load_lds_dwordx4 v[162:163], off
	s_waitcnt vmcnt(8)
	s_waitcnt lgkmcnt(0)
	s_barrier
	s_setprio 1
	v_mfma_scale_f32_16x16x128_f8f6f4 v[92:95], v[0:7], v[218:225], v[92:95], v213, v213 op_sel_hi:[0,0,0]
	v_mfma_scale_f32_16x16x128_f8f6f4 v[88:91], v[8:15], v[218:225], v[88:91], v213, v213 op_sel_hi:[0,0,0]
	v_mfma_scale_f32_16x16x128_f8f6f4 v[76:79], v[0:7], v[226:233], v[76:79], v213, v213 op_sel_hi:[0,0,0]
	v_mfma_scale_f32_16x16x128_f8f6f4 v[72:75], v[8:15], v[226:233], v[72:75], v213, v213 op_sel_hi:[0,0,0]
	v_mfma_scale_f32_16x16x128_f8f6f4 v[60:63], v[0:7], v[234:241], v[60:63], v213, v213 op_sel_hi:[0,0,0]
	v_mfma_scale_f32_16x16x128_f8f6f4 v[56:59], v[8:15], v[234:241], v[56:59], v213, v213 op_sel_hi:[0,0,0]
	v_mfma_scale_f32_16x16x128_f8f6f4 v[44:47], v[0:7], v[242:249], v[44:47], v213, v213 op_sel_hi:[0,0,0]
	v_mfma_scale_f32_16x16x128_f8f6f4 v[40:43], v[8:15], v[242:249], v[40:43], v213, v213 op_sel_hi:[0,0,0]
	s_setprio 0
	s_setprio 1
	v_mfma_scale_f32_16x16x128_f8f6f4 v[84:87], v[16:23], v[218:225], v[84:87], v213, v213 op_sel_hi:[0,0,0]
	v_mfma_scale_f32_16x16x128_f8f6f4 v[80:83], v[24:31], v[218:225], v[80:83], v213, v213 op_sel_hi:[0,0,0]
	v_mfma_scale_f32_16x16x128_f8f6f4 v[68:71], v[16:23], v[226:233], v[68:71], v213, v213 op_sel_hi:[0,0,0]
	v_mfma_scale_f32_16x16x128_f8f6f4 v[64:67], v[24:31], v[226:233], v[64:67], v213, v213 op_sel_hi:[0,0,0]
	v_mfma_scale_f32_16x16x128_f8f6f4 v[52:55], v[16:23], v[234:241], v[52:55], v213, v213 op_sel_hi:[0,0,0]
	v_mfma_scale_f32_16x16x128_f8f6f4 v[48:51], v[24:31], v[234:241], v[48:51], v213, v213 op_sel_hi:[0,0,0]
	v_mfma_scale_f32_16x16x128_f8f6f4 v[36:39], v[16:23], v[242:249], v[36:39], v213, v213 op_sel_hi:[0,0,0]
	v_mfma_scale_f32_16x16x128_f8f6f4 v[32:35], v[24:31], v[242:249], v[32:35], v213, v213 op_sel_hi:[0,0,0]
	s_setprio 0
	s_barrier
	s_add_i32 s54, s54, 2
	s_add_u32 s40, s40, 0x100
	s_addc_u32 s41, s41, 0
	s_add_u32 s52, s52, 0x100
	s_addc_u32 s53, s53, 0
	s_cmp_gt_u32 s54, 13
	s_cbranch_scc0 .LBB0_1022
	s_branch .Lgk_after_1022
; #define PG8_STAGE(bufoff, gbase, voff) do { _Pragma("unroll") for (int _i = 0; _i < 2; ++_i) \
;         __builtin_amdgcn_global_load_lds((const unsigned*)((const char*)(gbase) + (voff)[_i]), (PG8_LAS unsigned*)(lds + (bufoff) + ldsw + _i * 8192), 16, 0, 0); } while (0)
; #define PG8_WAIT_V(n) asm volatile("s_waitcnt vmcnt(" #n ")" ::: "memory")
; #define PG8_WAIT_L(n) asm volatile("s_waitcnt lgkmcnt(" #n ")" ::: "memory")
; #define PG8_BAR __builtin_amdgcn_s_barrier()
; #define PG8_SCHED __builtin_amdgcn_sched_barrier(0)
; template <class Epi, class Sched, bool ALIGN_EPI = false, bool SP2 = false, bool F8 = false>
; __device__ __forceinline__ void gemm_phase(PG8_LAS unsigned char* lds, const Gemm g, const Sched& S, const Epi& E) {
;     ...
;             PG8_LDB(B0, 0, 0); PG8_LDB(B1, 0, 1); PG8_SCHED; PG8_LDA(At, 0, 0); PG8_STAGE(PG8_SA(1, 1), a1 + hstep, voffA);
;             PG8_WAIT_V(8); PG8_WAIT_L(0); PG8_BAR; PG8_MMA(0, 0, At, B0); PG8_MMA(0, 1, At, B1); PG8_BAR; PG8_SCHED;
;             PG8_LDA(At, 0, 1); PG8_STAGE(PG8_SB(0, 0), b2, voffB); PG8_STAGE(PG8_SB(0, 1), b2 + hstep, voffB); PG8_STAGE(PG8_SA(0, 0), a2, voffA);
;             PG8_WAIT_V(8); PG8_WAIT_L(0); PG8_BAR; PG8_MMA(1, 0, At, B0); PG8_MMA(1, 1, At, B1); PG8_BAR; PG8_SCHED;
.LBB0_1022:
	s_add_u32 s44, s40, 0xfffc0080
	s_addc_u32 s45, s41, -1
	s_add_i32 s55, 0, 0x10000
	s_cmp_eq_u32 s54, 12
	s_cselect_b32 s47, s17, s45
	s_cselect_b32 s46, s50, s44
	s_cselect_b32 s45, s11, s53
	s_cselect_b32 s44, s51, s52
	s_add_i32 s56, 0, 0x14000
	v_add_u32_e32 v0, s55, v215
	v_add_u32_e32 v12, s56, v215
	ds_read_b128 v[16:19], v0
	ds_read_b128 v[20:23], v0 offset:1024
	ds_read_b128 v[24:27], v0 offset:2048
	ds_read_b128 v[28:31], v0 offset:3072
	ds_read_b128 v[0:3], v12
	ds_read_b128 v[4:7], v12 offset:1024
	ds_read_b128 v[8:11], v12 offset:2048
	ds_read_b128 v[12:15], v12 offset:3072
	v_lshl_add_u64 v[242:243], s[40:41], 0, v[192:193]
	s_add_i32 m0, s23, 0xc000
	ds_read_b128 v[196:199], v217
	ds_read_b128 v[200:203], v217 offset:1024
	ds_read_b128 v[218:221], v217 offset:2048
	ds_read_b128 v[222:225], v217 offset:3072
	ds_read_b128 v[226:229], v217 offset:4096
	ds_read_b128 v[230:233], v217 offset:5120
	ds_read_b128 v[234:237], v217 offset:6144
	ds_read_b128 v[238:241], v217 offset:7168
	global_load_lds_dwordx4 v[242:243], off
	v_lshl_add_u64 v[242:243], s[40:41], 0, v[194:195]
	s_add_i32 m0, s23, 0xe000
	s_nop 0
	global_load_lds_dwordx4 v[242:243], off
	s_waitcnt vmcnt(8)
	s_waitcnt lgkmcnt(0)
	s_barrier
	s_setprio 1
	v_mfma_scale_f32_16x16x128_f8f6f4 v[156:159], v[16:23], v[196:203], v[156:159], v213, v213 op_sel_hi:[0,0,0]
	v_mfma_scale_f32_16x16x128_f8f6f4 v[152:155], v[24:31], v[196:203], v[152:155], v213, v213 op_sel_hi:[0,0,0]
	v_mfma_scale_f32_16x16x128_f8f6f4 v[140:143], v[16:23], v[218:225], v[140:143], v213, v213 op_sel_hi:[0,0,0]
	v_mfma_scale_f32_16x16x128_f8f6f4 v[136:139], v[24:31], v[218:225], v[136:139], v213, v213 op_sel_hi:[0,0,0]
	v_mfma_scale_f32_16x16x128_f8f6f4 v[124:127], v[16:23], v[226:233], v[124:127], v213, v213 op_sel_hi:[0,0,0]
	v_mfma_scale_f32_16x16x128_f8f6f4 v[120:123], v[24:31], v[226:233], v[120:123], v213, v213 op_sel_hi:[0,0,0]
	v_mfma_scale_f32_16x16x128_f8f6f4 v[108:111], v[16:23], v[234:241], v[108:111], v213, v213 op_sel_hi:[0,0,0]
	v_mfma_scale_f32_16x16x128_f8f6f4 v[104:107], v[24:31], v[234:241], v[104:107], v213, v213 op_sel_hi:[0,0,0]
	s_setprio 0
	s_setprio 1
	v_mfma_scale_f32_16x16x128_f8f6f4 v[148:151], v[0:7], v[196:203], v[148:151], v213, v213 op_sel_hi:[0,0,0]
	v_mfma_scale_f32_16x16x128_f8f6f4 v[144:147], v[8:15], v[196:203], v[144:147], v213, v213 op_sel_hi:[0,0,0]
	v_mfma_scale_f32_16x16x128_f8f6f4 v[132:135], v[0:7], v[218:225], v[132:135], v213, v213 op_sel_hi:[0,0,0]
	v_mfma_scale_f32_16x16x128_f8f6f4 v[128:131], v[8:15], v[218:225], v[128:131], v213, v213 op_sel_hi:[0,0,0]
	v_mfma_scale_f32_16x16x128_f8f6f4 v[116:119], v[0:7], v[226:233], v[116:119], v213, v213 op_sel_hi:[0,0,0]
	v_mfma_scale_f32_16x16x128_f8f6f4 v[112:115], v[8:15], v[226:233], v[112:115], v213, v213 op_sel_hi:[0,0,0]
	v_mfma_scale_f32_16x16x128_f8f6f4 v[100:103], v[0:7], v[234:241], v[100:103], v213, v213 op_sel_hi:[0,0,0]
	v_mfma_scale_f32_16x16x128_f8f6f4 v[96:99], v[8:15], v[234:241], v[96:99], v213, v213 op_sel_hi:[0,0,0]
	s_setprio 0
	s_barrier
	s_add_i32 s55, s55, s22
	v_lshl_add_u64 v[196:197], s[44:45], 0, v[188:189]
	s_mov_b32 m0, s55
	ds_read_b128 v[218:221], v217 offset:16384
	ds_read_b128 v[222:225], v217 offset:17408
	ds_read_b128 v[226:229], v217 offset:18432
	ds_read_b128 v[230:233], v217 offset:19456
	ds_read_b128 v[234:237], v217 offset:20480
	ds_read_b128 v[238:241], v217 offset:21504
	ds_read_b128 v[242:245], v217 offset:22528
	ds_read_b128 v[246:249], v217 offset:23552
	global_load_lds_dwordx4 v[196:197], off
	s_add_i32 m0, s55, 0x2000
	s_add_u32 s58, s44, 0x40000
	v_lshl_add_u64 v[198:199], s[44:45], 0, v[184:185]
	s_addc_u32 s59, s45, 0
	s_add_i32 s55, s56, s22
	global_load_lds_dwordx4 v[198:199], off
	v_lshl_add_u64 v[200:201], s[58:59], 0, v[188:189]
	s_mov_b32 m0, s55
	v_lshl_add_u64 v[202:203], s[46:47], 0, v[186:187]
	global_load_lds_dwordx4 v[200:201], off
	v_lshl_add_u64 v[200:201], s[58:59], 0, v[184:185]
	s_add_i32 m0, s55, 0x2000
	s_nop 0
	global_load_lds_dwordx4 v[200:201], off
	v_lshl_add_u64 v[200:201], s[46:47], 0, v[190:191]
	s_mov_b32 m0, s23
	s_nop 0
	global_load_lds_dwordx4 v[200:201], off
	s_mov_b32 m0, s8
	s_nop 0
	global_load_lds_dwordx4 v[202:203], off
	s_waitcnt vmcnt(8)
	s_waitcnt lgkmcnt(0)
	s_barrier
	s_setprio 1
	v_mfma_scale_f32_16x16x128_f8f6f4 v[92:95], v[16:23], v[218:225], v[92:95], v213, v213 op_sel_hi:[0,0,0]
	v_mfma_scale_f32_16x16x128_f8f6f4 v[88:91], v[24:31], v[218:225], v[88:91], v213, v213 op_sel_hi:[0,0,0]
	v_mfma_scale_f32_16x16x128_f8f6f4 v[76:79], v[16:23], v[226:233], v[76:79], v213, v213 op_sel_hi:[0,0,0]
	v_mfma_scale_f32_16x16x128_f8f6f4 v[72:75], v[24:31], v[226:233], v[72:75], v213, v213 op_sel_hi:[0,0,0]
	v_mfma_scale_f32_16x16x128_f8f6f4 v[60:63], v[16:23], v[234:241], v[60:63], v213, v213 op_sel_hi:[0,0,0]
	v_mfma_scale_f32_16x16x128_f8f6f4 v[56:59], v[24:31], v[234:241], v[56:59], v213, v213 op_sel_hi:[0,0,0]
	v_mfma_scale_f32_16x16x128_f8f6f4 v[44:47], v[16:23], v[242:249], v[44:47], v213, v213 op_sel_hi:[0,0,0]
	v_mfma_scale_f32_16x16x128_f8f6f4 v[40:43], v[24:31], v[242:249], v[40:43], v213, v213 op_sel_hi:[0,0,0]
	s_setprio 0
	s_setprio 1
	v_mfma_scale_f32_16x16x128_f8f6f4 v[84:87], v[0:7], v[218:225], v[84:87], v213, v213 op_sel_hi:[0,0,0]
	v_mfma_scale_f32_16x16x128_f8f6f4 v[80:83], v[8:15], v[218:225], v[80:83], v213, v213 op_sel_hi:[0,0,0]
	v_mfma_scale_f32_16x16x128_f8f6f4 v[68:71], v[0:7], v[226:233], v[68:71], v213, v213 op_sel_hi:[0,0,0]
	v_mfma_scale_f32_16x16x128_f8f6f4 v[64:67], v[8:15], v[226:233], v[64:67], v213, v213 op_sel_hi:[0,0,0]
	v_mfma_scale_f32_16x16x128_f8f6f4 v[52:55], v[0:7], v[234:241], v[52:55], v213, v213 op_sel_hi:[0,0,0]
	v_mfma_scale_f32_16x16x128_f8f6f4 v[48:51], v[8:15], v[234:241], v[48:51], v213, v213 op_sel_hi:[0,0,0]
	v_mfma_scale_f32_16x16x128_f8f6f4 v[36:39], v[0:7], v[242:249], v[36:39], v213, v213 op_sel_hi:[0,0,0]
	v_mfma_scale_f32_16x16x128_f8f6f4 v[32:35], v[8:15], v[242:249], v[32:35], v213, v213 op_sel_hi:[0,0,0]
	s_setprio 0
	s_barrier
; #define PG8_STAGE(bufoff, gbase, voff) do { _Pragma("unroll") for (int _i = 0; _i < 2; ++_i) \
;         __builtin_amdgcn_global_load_lds((const unsigned*)((const char*)(gbase) + (voff)[_i]), (PG8_LAS unsigned*)(lds + (bufoff) + ldsw + _i * 8192), 16, 0, 0); } while (0)
; #define PG8_WAIT_V(n) asm volatile("s_waitcnt vmcnt(" #n ")" ::: "memory")
; #define PG8_WAIT_L(n) asm volatile("s_waitcnt lgkmcnt(" #n ")" ::: "memory")
; #define PG8_BAR __builtin_amdgcn_s_barrier()
; #define PG8_SCHED __builtin_amdgcn_sched_barrier(0)
; template <class Epi, class Sched, bool ALIGN_EPI = false, bool SP2 = false, bool F8 = false>
; __device__ __forceinline__ void gemm_phase(PG8_LAS unsigned char* lds, const Gemm g, const Sched& S, const Epi& E) {
;     ...
;             PG8_LDB(B0, 1, 0); PG8_LDB(B1, 1, 1); PG8_SCHED; PG8_LDA(At, 1, 0); PG8_STAGE(PG8_SA(0, 1), a2 + hstep, voffA);
;             PG8_WAIT_V(8); PG8_WAIT_L(0); PG8_BAR; PG8_MMA(0, 0, At, B0); PG8_MMA(0, 1, At, B1); PG8_BAR; PG8_SCHED;
;             PG8_LDA(At, 1, 1); PG8_STAGE(PG8_SB(1, 0), b3, voffB); PG8_STAGE(PG8_SB(1, 1), b3 + hstep, voffB); PG8_STAGE(PG8_SA(1, 0), a3, voffA);
;             PG8_WAIT_V(8); PG8_WAIT_L(0); PG8_BAR; PG8_MMA(1, 0, At, B0); PG8_MMA(1, 1, At, B1); PG8_BAR; PG8_SCHED;
	s_add_i32 s55, 0, 0x18000
	s_add_i32 s56, 0, 0x1c000
	v_add_u32_e32 v12, s55, v215
	v_add_u32_e32 v28, s56, v215
	ds_read_b128 v[0:3], v12
	ds_read_b128 v[4:7], v12 offset:1024
	ds_read_b128 v[8:11], v12 offset:2048
	ds_read_b128 v[12:15], v12 offset:3072
	ds_read_b128 v[16:19], v28
	ds_read_b128 v[20:23], v28 offset:1024
	ds_read_b128 v[24:27], v28 offset:2048
	ds_read_b128 v[28:31], v28 offset:3072
	s_add_u32 s46, s46, 0x40000
	s_addc_u32 s47, s47, 0
	s_mov_b32 m0, s9
	v_lshl_add_u64 v[162:163], s[46:47], 0, v[190:191]
	ds_read_b128 v[218:221], v217 offset:32768
	ds_read_b128 v[222:225], v217 offset:33792
	ds_read_b128 v[226:229], v217 offset:34816
	ds_read_b128 v[230:233], v217 offset:35840
	ds_read_b128 v[234:237], v217 offset:36864
	ds_read_b128 v[238:241], v217 offset:37888
	ds_read_b128 v[242:245], v217 offset:38912
	ds_read_b128 v[246:249], v217 offset:39936
	global_load_lds_dwordx4 v[162:163], off
	v_lshl_add_u64 v[162:163], s[46:47], 0, v[186:187]
	s_mov_b32 m0, s28
	s_nop 0
	global_load_lds_dwordx4 v[162:163], off
	s_waitcnt vmcnt(8)
	s_waitcnt lgkmcnt(0)
	s_barrier
	s_setprio 1
	v_mfma_scale_f32_16x16x128_f8f6f4 v[156:159], v[0:7], v[218:225], v[156:159], v213, v213 op_sel_hi:[0,0,0]
	v_mfma_scale_f32_16x16x128_f8f6f4 v[152:155], v[8:15], v[218:225], v[152:155], v213, v213 op_sel_hi:[0,0,0]
	v_mfma_scale_f32_16x16x128_f8f6f4 v[140:143], v[0:7], v[226:233], v[140:143], v213, v213 op_sel_hi:[0,0,0]
	v_mfma_scale_f32_16x16x128_f8f6f4 v[136:139], v[8:15], v[226:233], v[136:139], v213, v213 op_sel_hi:[0,0,0]
	v_mfma_scale_f32_16x16x128_f8f6f4 v[124:127], v[0:7], v[234:241], v[124:127], v213, v213 op_sel_hi:[0,0,0]
	v_mfma_scale_f32_16x16x128_f8f6f4 v[120:123], v[8:15], v[234:241], v[120:123], v213, v213 op_sel_hi:[0,0,0]
	v_mfma_scale_f32_16x16x128_f8f6f4 v[108:111], v[0:7], v[242:249], v[108:111], v213, v213 op_sel_hi:[0,0,0]
	v_mfma_scale_f32_16x16x128_f8f6f4 v[104:107], v[8:15], v[242:249], v[104:107], v213, v213 op_sel_hi:[0,0,0]
	s_setprio 0
	s_setprio 1
	v_mfma_scale_f32_16x16x128_f8f6f4 v[148:151], v[16:23], v[218:225], v[148:151], v213, v213 op_sel_hi:[0,0,0]
	v_mfma_scale_f32_16x16x128_f8f6f4 v[144:147], v[24:31], v[218:225], v[144:147], v213, v213 op_sel_hi:[0,0,0]
	v_mfma_scale_f32_16x16x128_f8f6f4 v[132:135], v[16:23], v[226:233], v[132:135], v213, v213 op_sel_hi:[0,0,0]
	v_mfma_scale_f32_16x16x128_f8f6f4 v[128:131], v[24:31], v[226:233], v[128:131], v213, v213 op_sel_hi:[0,0,0]
	v_mfma_scale_f32_16x16x128_f8f6f4 v[116:119], v[16:23], v[234:241], v[116:119], v213, v213 op_sel_hi:[0,0,0]
	v_mfma_scale_f32_16x16x128_f8f6f4 v[112:115], v[24:31], v[234:241], v[112:115], v213, v213 op_sel_hi:[0,0,0]
	v_mfma_scale_f32_16x16x128_f8f6f4 v[100:103], v[16:23], v[242:249], v[100:103], v213, v213 op_sel_hi:[0,0,0]
	v_mfma_scale_f32_16x16x128_f8f6f4 v[96:99], v[24:31], v[242:249], v[96:99], v213, v213 op_sel_hi:[0,0,0]
	s_setprio 0
	s_barrier
	s_add_i32 s46, s55, s22
	v_lshl_add_u64 v[162:163], v[196:197], 0, s[14:15]
	s_mov_b32 m0, s46
	ds_read_b128 v[218:221], v217 offset:49152
	ds_read_b128 v[222:225], v217 offset:50176
	ds_read_b128 v[226:229], v217 offset:51200
	ds_read_b128 v[230:233], v217 offset:52224
	ds_read_b128 v[234:237], v217 offset:53248
	ds_read_b128 v[238:241], v217 offset:54272
	ds_read_b128 v[242:245], v217 offset:55296
	ds_read_b128 v[246:249], v217 offset:56320
	global_load_lds_dwordx4 v[162:163], off
	s_add_i32 m0, s46, 0x2000
	s_add_u32 s44, s44, 0x40080
	v_lshl_add_u64 v[162:163], v[198:199], 0, s[14:15]
	s_addc_u32 s45, s45, 0
	s_add_i32 s46, s56, s22
	global_load_lds_dwordx4 v[162:163], off
	v_lshl_add_u64 v[162:163], s[44:45], 0, v[188:189]
	s_mov_b32 m0, s46
	s_nop 0
	global_load_lds_dwordx4 v[162:163], off
	v_lshl_add_u64 v[162:163], s[44:45], 0, v[184:185]
	s_add_i32 m0, s46, 0x2000
	s_nop 0
	global_load_lds_dwordx4 v[162:163], off
	v_lshl_add_u64 v[162:163], v[200:201], 0, s[14:15]
	s_mov_b32 m0, s29
	s_nop 0
	global_load_lds_dwordx4 v[162:163], off
	v_lshl_add_u64 v[162:163], v[202:203], 0, s[14:15]
	s_mov_b32 m0, s48
	s_nop 0
	global_load_lds_dwordx4 v[162:163], off
	s_waitcnt vmcnt(8)
	s_waitcnt lgkmcnt(0)
	s_barrier
	s_setprio 1
	v_mfma_scale_f32_16x16x128_f8f6f4 v[92:95], v[0:7], v[218:225], v[92:95], v213, v213 op_sel_hi:[0,0,0]
	v_mfma_scale_f32_16x16x128_f8f6f4 v[88:91], v[8:15], v[218:225], v[88:91], v213, v213 op_sel_hi:[0,0,0]
	v_mfma_scale_f32_16x16x128_f8f6f4 v[76:79], v[0:7], v[226:233], v[76:79], v213, v213 op_sel_hi:[0,0,0]
	v_mfma_scale_f32_16x16x128_f8f6f4 v[72:75], v[8:15], v[226:233], v[72:75], v213, v213 op_sel_hi:[0,0,0]
	v_mfma_scale_f32_16x16x128_f8f6f4 v[60:63], v[0:7], v[234:241], v[60:63], v213, v213 op_sel_hi:[0,0,0]
	v_mfma_scale_f32_16x16x128_f8f6f4 v[56:59], v[8:15], v[234:241], v[56:59], v213, v213 op_sel_hi:[0,0,0]
	v_mfma_scale_f32_16x16x128_f8f6f4 v[44:47], v[0:7], v[242:249], v[44:47], v213, v213 op_sel_hi:[0,0,0]
	v_mfma_scale_f32_16x16x128_f8f6f4 v[40:43], v[8:15], v[242:249], v[40:43], v213, v213 op_sel_hi:[0,0,0]
	s_setprio 0
	s_setprio 1
	v_mfma_scale_f32_16x16x128_f8f6f4 v[84:87], v[16:23], v[218:225], v[84:87], v213, v213 op_sel_hi:[0,0,0]
	v_mfma_scale_f32_16x16x128_f8f6f4 v[80:83], v[24:31], v[218:225], v[80:83], v213, v213 op_sel_hi:[0,0,0]
	v_mfma_scale_f32_16x16x128_f8f6f4 v[68:71], v[16:23], v[226:233], v[68:71], v213, v213 op_sel_hi:[0,0,0]
	v_mfma_scale_f32_16x16x128_f8f6f4 v[64:67], v[24:31], v[226:233], v[64:67], v213, v213 op_sel_hi:[0,0,0]
	v_mfma_scale_f32_16x16x128_f8f6f4 v[52:55], v[16:23], v[234:241], v[52:55], v213, v213 op_sel_hi:[0,0,0]
	v_mfma_scale_f32_16x16x128_f8f6f4 v[48:51], v[24:31], v[234:241], v[48:51], v213, v213 op_sel_hi:[0,0,0]
	v_mfma_scale_f32_16x16x128_f8f6f4 v[36:39], v[16:23], v[242:249], v[36:39], v213, v213 op_sel_hi:[0,0,0]
	v_mfma_scale_f32_16x16x128_f8f6f4 v[32:35], v[24:31], v[242:249], v[32:35], v213, v213 op_sel_hi:[0,0,0]
	s_setprio 0
	s_barrier
	s_add_i32 s54, s54, 2
	s_add_u32 s40, s40, 0x100
	s_addc_u32 s41, s41, 0
	s_add_u32 s52, s52, 0x100
	s_addc_u32 s53, s53, 0
	s_cmp_gt_u32 s54, 13
	s_cbranch_scc0 .LBB0_1022

; #define PG8_STAGE(bufoff, gbase, voff) do { _Pragma("unroll") for (int _i = 0; _i < 2; ++_i) \
;         __builtin_amdgcn_global_load_lds((const unsigned*)((const char*)(gbase) + (voff)[_i]), (PG8_LAS unsigned*)(lds + (bufoff) + ldsw + _i * 8192), 16, 0, 0); } while (0)
; #define PG8_WAIT_V(n) asm volatile("s_waitcnt vmcnt(" #n ")" ::: "memory")
; #define PG8_WAIT_L(n) asm volatile("s_waitcnt lgkmcnt(" #n ")" ::: "memory")
; #define PG8_BAR __builtin_amdgcn_s_barrier()
; #define PG8_SCHED __builtin_amdgcn_sched_barrier(0)
; template <class Epi, class Sched, bool ALIGN_EPI = false, bool SP2 = false, bool F8 = false>
; __device__ __forceinline__ void gemm_phase(PG8_LAS unsigned char* lds, const Gemm g, const Sched& S, const Epi& E) {
;     ...
;         const bool has_next = S.next(ui + 1, nxt);
;         const char* nA = has_next ? (const char*)g.A + (size_t)nxt.pm * tstep : cA; const char* nB = has_next ? (const char*)g.Bt + (size_t)nxt.pn * tstep : cB;
;         for (int t = 0; t < nt; t += 2) {
;             const bool last = (t == nt - 2);
;             const char* a1 = cA + (size_t)(t + 1) * kstep;
;             const char* a2 = last ? nA : cA + (size_t)(t + 2) * kstep; const char* b2 = last ? nB : cB + (size_t)(t + 2) * kstep;
;             const char* a3 = a2 + kstep; const char* b3 = b2 + kstep;
;             if (last && has_next) S.a_ready(nxt);
;             if constexpr (SP2) {
;             PG8_LDB(B0, 0, 0); PG8_LDB(B1, 0, 1); PG8_SCHED; PG8_LDA(At, 0, 0); PG8_STAGE(PG8_SA(1, 1), a1 + hstep, voffA);
;             PG8_WAIT_V(8); PG8_WAIT_L(0); PG8_BAR; PG8_MMA(0, 0, At, B0); PG8_MMA(0, 1, At, B1); PG8_BAR; PG8_SCHED;
;             PG8_LDA(At, 0, 1); PG8_STAGE(PG8_SB(0, 0), b2, voffB); PG8_STAGE(PG8_SB(0, 1), b2 + hstep, voffB); PG8_STAGE(PG8_SA(0, 0), a2, voffA);
;             PG8_WAIT_V(8); PG8_WAIT_L(0); PG8_BAR; PG8_MMA(1, 0, At, B0); PG8_MMA(1, 1, At, B1); PG8_BAR; PG8_SCHED;
.LBB0_1101:
	s_ashr_i32 s17, s16, 31
	s_lshl_b64 s[36:37], s[16:17], 20
	v_readlane_b32 s40, v251, 7
	v_readlane_b32 s41, v251, 8
	s_add_u32 s36, s40, s36
	s_addc_u32 s37, s41, s37
	s_and_b64 s[40:41], s[38:39], exec
	s_cselect_b32 s17, s37, s43
	s_cselect_b32 s48, s36, s42
	s_ashr_i32 s11, s10, 31
	s_lshl_b64 s[40:41], s[10:11], 20
	v_readlane_b32 s11, v250, 22
	s_add_u32 s40, s11, s40
	v_readlane_b32 s11, v250, 23
	s_addc_u32 s41, s11, s41
	s_and_b64 s[46:47], s[38:39], exec
	s_cselect_b32 s11, s41, s45
	s_cselect_b32 s49, s40, s44
	s_add_u32 s42, s42, 0x80080
	s_addc_u32 s43, s43, 0
	s_add_u32 s50, s44, 0x100
	s_addc_u32 s51, s45, 0
	s_mov_b32 s52, -2
	s_add_u32 s44, s42, 0xfff80080
	s_addc_u32 s45, s43, -1
	s_add_i32 s53, 0, 0x10000
	s_cmp_eq_u32 s52, 28
	s_cselect_b32 s47, s17, s45
	s_cselect_b32 s46, s48, s44
	s_cselect_b32 s45, s11, s51
	s_cselect_b32 s44, s49, s50
	s_add_i32 s56, 0, 0x14000
	v_add_u32_e32 v154, s53, v139
	v_add_u32_e32 v158, s56, v139
	ds_read_b128 v[142:145], v154
	ds_read_b128 v[146:149], v154 offset:1024
	ds_read_b128 v[150:153], v154 offset:2048
	ds_read_b128 v[154:157], v154 offset:3072
	ds_read_b128 v[184:187], v158
	ds_read_b128 v[188:191], v158 offset:1024
	ds_read_b128 v[192:195], v158 offset:2048
	ds_read_b128 v[196:199], v158 offset:3072
	v_lshl_add_u64 v[158:159], s[42:43], 0, v[134:135]
	s_add_i32 m0, s9, 0xc000
	ds_read_b128 v[200:203], v141
	ds_read_b128 v[214:217], v141 offset:1024
	ds_read_b128 v[218:221], v141 offset:2048
	ds_read_b128 v[222:225], v141 offset:3072
	ds_read_b128 v[226:229], v141 offset:4096
	ds_read_b128 v[230:233], v141 offset:5120
	ds_read_b128 v[234:237], v141 offset:6144
	ds_read_b128 v[238:241], v141 offset:7168
	global_load_lds_dwordx4 v[158:159], off
	v_lshl_add_u64 v[158:159], s[42:43], 0, v[136:137]
	s_add_i32 m0, s9, 0xe000
	s_nop 0
	global_load_lds_dwordx4 v[158:159], off
	s_waitcnt vmcnt(8)
	s_waitcnt lgkmcnt(0)
	s_barrier
	s_setprio 1
	v_mfma_f32_16x16x32_bf16 v[124:127], v[142:145], v[200:203], 0
	v_mfma_f32_16x16x32_bf16 v[120:123], v[150:153], v[200:203], 0
	v_mfma_f32_16x16x32_bf16 v[116:119], v[142:145], v[218:221], 0
	v_mfma_f32_16x16x32_bf16 v[112:115], v[150:153], v[218:221], 0
	v_mfma_f32_16x16x32_bf16 v[108:111], v[142:145], v[226:229], 0
	v_mfma_f32_16x16x32_bf16 v[100:103], v[150:153], v[226:229], 0
	v_mfma_f32_16x16x32_bf16 v[92:95], v[142:145], v[234:237], 0
	v_mfma_f32_16x16x32_bf16 v[84:87], v[150:153], v[234:237], 0
	v_mfma_f32_16x16x32_bf16 v[124:127], v[146:149], v[214:217], v[124:127]
	v_mfma_f32_16x16x32_bf16 v[120:123], v[154:157], v[214:217], v[120:123]
	v_mfma_f32_16x16x32_bf16 v[116:119], v[146:149], v[222:225], v[116:119]
	v_mfma_f32_16x16x32_bf16 v[112:115], v[154:157], v[222:225], v[112:115]
	v_mfma_f32_16x16x32_bf16 v[108:111], v[146:149], v[230:233], v[108:111]
	v_mfma_f32_16x16x32_bf16 v[100:103], v[154:157], v[230:233], v[100:103]
	v_mfma_f32_16x16x32_bf16 v[92:95], v[146:149], v[238:241], v[92:95]
	v_mfma_f32_16x16x32_bf16 v[84:87], v[154:157], v[238:241], v[84:87]
	s_setprio 0
	s_setprio 1
	v_mfma_f32_16x16x32_bf16 v[104:107], v[184:187], v[200:203], 0
	v_mfma_f32_16x16x32_bf16 v[96:99], v[192:195], v[200:203], 0
	v_mfma_f32_16x16x32_bf16 v[88:91], v[184:187], v[218:221], 0
	v_mfma_f32_16x16x32_bf16 v[80:83], v[192:195], v[218:221], 0
	v_mfma_f32_16x16x32_bf16 v[76:79], v[184:187], v[226:229], 0
	v_mfma_f32_16x16x32_bf16 v[72:75], v[192:195], v[226:229], 0
	v_mfma_f32_16x16x32_bf16 v[68:71], v[184:187], v[234:237], 0
	v_mfma_f32_16x16x32_bf16 v[64:67], v[192:195], v[234:237], 0
	v_mfma_f32_16x16x32_bf16 v[104:107], v[188:191], v[214:217], v[104:107]
	v_mfma_f32_16x16x32_bf16 v[96:99], v[196:199], v[214:217], v[96:99]
	v_mfma_f32_16x16x32_bf16 v[88:91], v[188:191], v[222:225], v[88:91]
	v_mfma_f32_16x16x32_bf16 v[80:83], v[196:199], v[222:225], v[80:83]
	v_mfma_f32_16x16x32_bf16 v[76:79], v[188:191], v[230:233], v[76:79]
	v_mfma_f32_16x16x32_bf16 v[72:75], v[196:199], v[230:233], v[72:75]
	v_mfma_f32_16x16x32_bf16 v[68:71], v[188:191], v[238:241], v[68:71]
	v_mfma_f32_16x16x32_bf16 v[64:67], v[196:199], v[238:241], v[64:67]
	s_setprio 0
	s_barrier
	s_add_i32 s53, s53, s8
	v_lshl_add_u64 v[158:159], s[44:45], 0, v[160:161]
	s_mov_b32 m0, s53
	ds_read_b128 v[200:203], v141 offset:16384
	ds_read_b128 v[214:217], v141 offset:17408
	ds_read_b128 v[218:221], v141 offset:18432
	ds_read_b128 v[222:225], v141 offset:19456
	ds_read_b128 v[226:229], v141 offset:20480
	ds_read_b128 v[230:233], v141 offset:21504
	ds_read_b128 v[234:237], v141 offset:22528
	ds_read_b128 v[238:241], v141 offset:23552
	global_load_lds_dwordx4 v[158:159], off
	s_add_i32 m0, s53, 0x2000
	s_add_u32 s54, s44, 0x80000
	v_lshl_add_u64 v[162:163], s[44:45], 0, v[128:129]
	s_addc_u32 s55, s45, 0
	s_add_i32 s53, s56, s8
	global_load_lds_dwordx4 v[162:163], off
	v_lshl_add_u64 v[242:243], s[54:55], 0, v[160:161]
	s_mov_b32 m0, s53
	v_lshl_add_u64 v[244:245], s[46:47], 0, v[130:131]
	global_load_lds_dwordx4 v[242:243], off
	v_lshl_add_u64 v[242:243], s[54:55], 0, v[128:129]
	s_add_i32 m0, s53, 0x2000
	s_nop 0
	global_load_lds_dwordx4 v[242:243], off
	v_lshl_add_u64 v[242:243], s[46:47], 0, v[132:133]
	s_mov_b32 m0, s9
	s_nop 0
	global_load_lds_dwordx4 v[242:243], off
	s_mov_b32 m0, s13
	s_nop 0
	global_load_lds_dwordx4 v[244:245], off
	s_waitcnt vmcnt(8)
	s_waitcnt lgkmcnt(0)
	s_barrier
; #define PG8_STAGE(bufoff, gbase, voff) do { _Pragma("unroll") for (int _i = 0; _i < 2; ++_i) \
;         __builtin_amdgcn_global_load_lds((const unsigned*)((const char*)(gbase) + (voff)[_i]), (PG8_LAS unsigned*)(lds + (bufoff) + ldsw + _i * 8192), 16, 0, 0); } while (0)
; #define PG8_WAIT_V(n) asm volatile("s_waitcnt vmcnt(" #n ")" ::: "memory")
; #define PG8_WAIT_L(n) asm volatile("s_waitcnt lgkmcnt(" #n ")" ::: "memory")
; #define PG8_BAR __builtin_amdgcn_s_barrier()
; #define PG8_SCHED __builtin_amdgcn_sched_barrier(0)
; template <class Epi, class Sched, bool ALIGN_EPI = false, bool SP2 = false, bool F8 = false>
; __device__ __forceinline__ void gemm_phase(PG8_LAS unsigned char* lds, const Gemm g, const Sched& S, const Epi& E) {
;     ...
;             PG8_WAIT_V(8); PG8_WAIT_L(0); PG8_BAR; PG8_MMA(0, 0, At, B0); PG8_MMA(0, 1, At, B1); PG8_BAR; PG8_SCHED;
;             PG8_LDA(At, 0, 1); PG8_STAGE(PG8_SB(0, 0), b2, voffB); PG8_STAGE(PG8_SB(0, 1), b2 + hstep, voffB); PG8_STAGE(PG8_SA(0, 0), a2, voffA);
;             PG8_WAIT_V(8); PG8_WAIT_L(0); PG8_BAR; PG8_MMA(1, 0, At, B0); PG8_MMA(1, 1, At, B1); PG8_BAR; PG8_SCHED;
;             PG8_LDB(B0, 1, 0); PG8_LDB(B1, 1, 1); PG8_SCHED; PG8_LDA(At, 1, 0); PG8_STAGE(PG8_SA(0, 1), a2 + hstep, voffA);
;             PG8_WAIT_V(8); PG8_WAIT_L(0); PG8_BAR; PG8_MMA(0, 0, At, B0); PG8_MMA(0, 1, At, B1); PG8_BAR; PG8_SCHED;
	s_setprio 1
	v_mfma_f32_16x16x32_bf16 v[60:63], v[142:145], v[200:203], 0
	v_mfma_f32_16x16x32_bf16 v[56:59], v[150:153], v[200:203], 0
	v_mfma_f32_16x16x32_bf16 v[52:55], v[142:145], v[218:221], 0
	v_mfma_f32_16x16x32_bf16 v[48:51], v[150:153], v[218:221], 0
	v_mfma_f32_16x16x32_bf16 v[44:47], v[142:145], v[226:229], 0
	v_mfma_f32_16x16x32_bf16 v[36:39], v[150:153], v[226:229], 0
	v_mfma_f32_16x16x32_bf16 v[28:31], v[142:145], v[234:237], 0
	v_mfma_f32_16x16x32_bf16 v[20:23], v[150:153], v[234:237], 0
	v_mfma_f32_16x16x32_bf16 v[60:63], v[146:149], v[214:217], v[60:63]
	v_mfma_f32_16x16x32_bf16 v[56:59], v[154:157], v[214:217], v[56:59]
	v_mfma_f32_16x16x32_bf16 v[52:55], v[146:149], v[222:225], v[52:55]
	v_mfma_f32_16x16x32_bf16 v[48:51], v[154:157], v[222:225], v[48:51]
	v_mfma_f32_16x16x32_bf16 v[44:47], v[146:149], v[230:233], v[44:47]
	v_mfma_f32_16x16x32_bf16 v[36:39], v[154:157], v[230:233], v[36:39]
	v_mfma_f32_16x16x32_bf16 v[28:31], v[146:149], v[238:241], v[28:31]
	v_mfma_f32_16x16x32_bf16 v[20:23], v[154:157], v[238:241], v[20:23]
	s_setprio 0
	s_setprio 1
	v_mfma_f32_16x16x32_bf16 v[40:43], v[184:187], v[200:203], 0
	v_mfma_f32_16x16x32_bf16 v[32:35], v[192:195], v[200:203], 0
	v_mfma_f32_16x16x32_bf16 v[24:27], v[184:187], v[218:221], 0
	v_mfma_f32_16x16x32_bf16 v[16:19], v[192:195], v[218:221], 0
	v_mfma_f32_16x16x32_bf16 v[12:15], v[184:187], v[226:229], 0
	v_mfma_f32_16x16x32_bf16 v[8:11], v[192:195], v[226:229], 0
	v_mfma_f32_16x16x32_bf16 v[4:7], v[184:187], v[234:237], 0
	v_mfma_f32_16x16x32_bf16 v[0:3], v[192:195], v[234:237], 0
	v_mfma_f32_16x16x32_bf16 v[40:43], v[188:191], v[214:217], v[40:43]
	v_mfma_f32_16x16x32_bf16 v[32:35], v[196:199], v[214:217], v[32:35]
	v_mfma_f32_16x16x32_bf16 v[24:27], v[188:191], v[222:225], v[24:27]
	v_mfma_f32_16x16x32_bf16 v[16:19], v[196:199], v[222:225], v[16:19]
	v_mfma_f32_16x16x32_bf16 v[12:15], v[188:191], v[230:233], v[12:15]
	v_mfma_f32_16x16x32_bf16 v[8:11], v[196:199], v[230:233], v[8:11]
	v_mfma_f32_16x16x32_bf16 v[4:7], v[188:191], v[238:241], v[4:7]
	v_mfma_f32_16x16x32_bf16 v[0:3], v[196:199], v[238:241], v[0:3]
	s_setprio 0
	s_barrier
	s_add_i32 s53, 0, 0x18000
	s_add_i32 s54, 0, 0x1c000
	v_add_u32_e32 v154, s53, v139
	v_add_u32_e32 v196, s54, v139
	ds_read_b128 v[142:145], v154
	ds_read_b128 v[146:149], v154 offset:1024
	ds_read_b128 v[150:153], v154 offset:2048
	ds_read_b128 v[154:157], v154 offset:3072
	ds_read_b128 v[184:187], v196
	ds_read_b128 v[188:191], v196 offset:1024
	ds_read_b128 v[192:195], v196 offset:2048
	ds_read_b128 v[196:199], v196 offset:3072
	s_add_u32 s46, s46, 0x80000
	s_addc_u32 s47, s47, 0
	s_mov_b32 m0, s19
	v_lshl_add_u64 v[246:247], s[46:47], 0, v[132:133]
	ds_read_b128 v[200:203], v141 offset:32768
	ds_read_b128 v[214:217], v141 offset:33792
	ds_read_b128 v[218:221], v141 offset:34816
	ds_read_b128 v[222:225], v141 offset:35840
	ds_read_b128 v[226:229], v141 offset:36864
	ds_read_b128 v[230:233], v141 offset:37888
	ds_read_b128 v[234:237], v141 offset:38912
	ds_read_b128 v[238:241], v141 offset:39936
	global_load_lds_dwordx4 v[246:247], off
	v_lshl_add_u64 v[246:247], s[46:47], 0, v[130:131]
	s_mov_b32 m0, s22
	s_nop 0
	global_load_lds_dwordx4 v[246:247], off
	s_waitcnt vmcnt(8)
	s_waitcnt lgkmcnt(0)
	s_barrier
	s_setprio 1
	v_mfma_f32_16x16x32_bf16 v[124:127], v[142:145], v[200:203], v[124:127]
	v_mfma_f32_16x16x32_bf16 v[120:123], v[150:153], v[200:203], v[120:123]
	v_mfma_f32_16x16x32_bf16 v[116:119], v[142:145], v[218:221], v[116:119]
	v_mfma_f32_16x16x32_bf16 v[112:115], v[150:153], v[218:221], v[112:115]
	v_mfma_f32_16x16x32_bf16 v[108:111], v[142:145], v[226:229], v[108:111]
	v_mfma_f32_16x16x32_bf16 v[100:103], v[150:153], v[226:229], v[100:103]
	v_mfma_f32_16x16x32_bf16 v[92:95], v[142:145], v[234:237], v[92:95]
	v_mfma_f32_16x16x32_bf16 v[84:87], v[150:153], v[234:237], v[84:87]
	v_mfma_f32_16x16x32_bf16 v[124:127], v[146:149], v[214:217], v[124:127]
	v_mfma_f32_16x16x32_bf16 v[120:123], v[154:157], v[214:217], v[120:123]
	v_mfma_f32_16x16x32_bf16 v[116:119], v[146:149], v[222:225], v[116:119]
	v_mfma_f32_16x16x32_bf16 v[112:115], v[154:157], v[222:225], v[112:115]
	v_mfma_f32_16x16x32_bf16 v[108:111], v[146:149], v[230:233], v[108:111]
	v_mfma_f32_16x16x32_bf16 v[100:103], v[154:157], v[230:233], v[100:103]
	v_mfma_f32_16x16x32_bf16 v[92:95], v[146:149], v[238:241], v[92:95]
	v_mfma_f32_16x16x32_bf16 v[84:87], v[154:157], v[238:241], v[84:87]
	s_setprio 0
	s_setprio 1
	v_mfma_f32_16x16x32_bf16 v[104:107], v[184:187], v[200:203], v[104:107]
	v_mfma_f32_16x16x32_bf16 v[96:99], v[192:195], v[200:203], v[96:99]
	v_mfma_f32_16x16x32_bf16 v[88:91], v[184:187], v[218:221], v[88:91]
	v_mfma_f32_16x16x32_bf16 v[80:83], v[192:195], v[218:221], v[80:83]
	v_mfma_f32_16x16x32_bf16 v[76:79], v[184:187], v[226:229], v[76:79]
	v_mfma_f32_16x16x32_bf16 v[72:75], v[192:195], v[226:229], v[72:75]
	v_mfma_f32_16x16x32_bf16 v[68:71], v[184:187], v[234:237], v[68:71]
	v_mfma_f32_16x16x32_bf16 v[64:67], v[192:195], v[234:237], v[64:67]
	v_mfma_f32_16x16x32_bf16 v[104:107], v[188:191], v[214:217], v[104:107]
	v_mfma_f32_16x16x32_bf16 v[96:99], v[196:199], v[214:217], v[96:99]
	v_mfma_f32_16x16x32_bf16 v[88:91], v[188:191], v[222:225], v[88:91]
	v_mfma_f32_16x16x32_bf16 v[80:83], v[196:199], v[222:225], v[80:83]
	v_mfma_f32_16x16x32_bf16 v[76:79], v[188:191], v[230:233], v[76:79]
	v_mfma_f32_16x16x32_bf16 v[72:75], v[196:199], v[230:233], v[72:75]
	v_mfma_f32_16x16x32_bf16 v[68:71], v[188:191], v[238:241], v[68:71]
	v_mfma_f32_16x16x32_bf16 v[64:67], v[196:199], v[238:241], v[64:67]
	s_setprio 0
	s_barrier
; #define PG8_STAGE(bufoff, gbase, voff) do { _Pragma("unroll") for (int _i = 0; _i < 2; ++_i) \
;         __builtin_amdgcn_global_load_lds((const unsigned*)((const char*)(gbase) + (voff)[_i]), (PG8_LAS unsigned*)(lds + (bufoff) + ldsw + _i * 8192), 16, 0, 0); } while (0)
; #define PG8_WAIT_V(n) asm volatile("s_waitcnt vmcnt(" #n ")" ::: "memory")
; #define PG8_WAIT_L(n) asm volatile("s_waitcnt lgkmcnt(" #n ")" ::: "memory")
; #define PG8_BAR __builtin_amdgcn_s_barrier()
; #define PG8_SCHED __builtin_amdgcn_sched_barrier(0)
; template <class Epi, class Sched, bool ALIGN_EPI = false, bool SP2 = false, bool F8 = false>
; __device__ __forceinline__ void gemm_phase(PG8_LAS unsigned char* lds, const Gemm g, const Sched& S, const Epi& E) {
;     ...
;         for (int t = 0; t < nt; t += 2) {
;             const bool last = (t == nt - 2);
;             const char* a1 = cA + (size_t)(t + 1) * kstep;
;             const char* a2 = last ? nA : cA + (size_t)(t + 2) * kstep; const char* b2 = last ? nB : cB + (size_t)(t + 2) * kstep;
;             const char* a3 = a2 + kstep; const char* b3 = b2 + kstep;
;             if (last && has_next) S.a_ready(nxt);
;             if constexpr (SP2) {
;             PG8_LDB(B0, 0, 0); PG8_LDB(B1, 0, 1); PG8_SCHED; PG8_LDA(At, 0, 0); PG8_STAGE(PG8_SA(1, 1), a1 + hstep, voffA);
;             PG8_WAIT_V(8); PG8_WAIT_L(0); PG8_BAR; PG8_MMA(0, 0, At, B0); PG8_MMA(0, 1, At, B1); PG8_BAR; PG8_SCHED;
;             PG8_LDA(At, 0, 1); PG8_STAGE(PG8_SB(0, 0), b2, voffB); PG8_STAGE(PG8_SB(0, 1), b2 + hstep, voffB); PG8_STAGE(PG8_SA(0, 0), a2, voffA);
;             PG8_WAIT_V(8); PG8_WAIT_L(0); PG8_BAR; PG8_MMA(1, 0, At, B0); PG8_MMA(1, 1, At, B1); PG8_BAR; PG8_SCHED;
;             PG8_LDB(B0, 1, 0); PG8_LDB(B1, 1, 1); PG8_SCHED; PG8_LDA(At, 1, 0); PG8_STAGE(PG8_SA(0, 1), a2 + hstep, voffA);
;             PG8_WAIT_V(8); PG8_WAIT_L(0); PG8_BAR; PG8_MMA(0, 0, At, B0); PG8_MMA(0, 1, At, B1); PG8_BAR; PG8_SCHED;
;             PG8_LDA(At, 1, 1); PG8_STAGE(PG8_SB(1, 0), b3, voffB); PG8_STAGE(PG8_SB(1, 1), b3 + hstep, voffB); PG8_STAGE(PG8_SA(1, 0), a3, voffA);
;             PG8_WAIT_V(8); PG8_WAIT_L(0); PG8_BAR; PG8_MMA(1, 0, At, B0); PG8_MMA(1, 1, At, B1); PG8_BAR; PG8_SCHED;
	s_add_i32 s46, s53, s8
	v_lshl_add_u64 v[158:159], v[158:159], 0, s[14:15]
	s_mov_b32 m0, s46
	ds_read_b128 v[200:203], v141 offset:49152
	ds_read_b128 v[214:217], v141 offset:50176
	ds_read_b128 v[218:221], v141 offset:51200
	ds_read_b128 v[222:225], v141 offset:52224
	ds_read_b128 v[226:229], v141 offset:53248
	ds_read_b128 v[230:233], v141 offset:54272
	ds_read_b128 v[234:237], v141 offset:55296
	ds_read_b128 v[238:241], v141 offset:56320
	global_load_lds_dwordx4 v[158:159], off
	s_add_i32 m0, s46, 0x2000
	s_add_u32 s44, s44, 0x80080
	v_lshl_add_u64 v[158:159], v[162:163], 0, s[14:15]
	s_addc_u32 s45, s45, 0
	s_add_i32 s46, s54, s8
	global_load_lds_dwordx4 v[158:159], off
	v_lshl_add_u64 v[158:159], s[44:45], 0, v[160:161]
	s_mov_b32 m0, s46
	s_nop 0
	global_load_lds_dwordx4 v[158:159], off
	v_lshl_add_u64 v[158:159], s[44:45], 0, v[128:129]
	s_add_i32 m0, s46, 0x2000
	s_nop 0
	global_load_lds_dwordx4 v[158:159], off
	v_lshl_add_u64 v[158:159], v[242:243], 0, s[14:15]
	s_mov_b32 m0, s23
	s_nop 0
	global_load_lds_dwordx4 v[158:159], off
	v_lshl_add_u64 v[158:159], v[244:245], 0, s[14:15]
	s_mov_b32 m0, s28
	s_nop 0
	global_load_lds_dwordx4 v[158:159], off
	s_waitcnt vmcnt(8)
	s_waitcnt lgkmcnt(0)
	s_barrier
	s_setprio 1
	v_mfma_f32_16x16x32_bf16 v[60:63], v[142:145], v[200:203], v[60:63]
	v_mfma_f32_16x16x32_bf16 v[56:59], v[150:153], v[200:203], v[56:59]
	v_mfma_f32_16x16x32_bf16 v[52:55], v[142:145], v[218:221], v[52:55]
	v_mfma_f32_16x16x32_bf16 v[48:51], v[150:153], v[218:221], v[48:51]
	v_mfma_f32_16x16x32_bf16 v[44:47], v[142:145], v[226:229], v[44:47]
	v_mfma_f32_16x16x32_bf16 v[36:39], v[150:153], v[226:229], v[36:39]
	v_mfma_f32_16x16x32_bf16 v[28:31], v[142:145], v[234:237], v[28:31]
	v_mfma_f32_16x16x32_bf16 v[20:23], v[150:153], v[234:237], v[20:23]
	v_mfma_f32_16x16x32_bf16 v[60:63], v[146:149], v[214:217], v[60:63]
	v_mfma_f32_16x16x32_bf16 v[56:59], v[154:157], v[214:217], v[56:59]
	v_mfma_f32_16x16x32_bf16 v[52:55], v[146:149], v[222:225], v[52:55]
	v_mfma_f32_16x16x32_bf16 v[48:51], v[154:157], v[222:225], v[48:51]
	v_mfma_f32_16x16x32_bf16 v[44:47], v[146:149], v[230:233], v[44:47]
	v_mfma_f32_16x16x32_bf16 v[36:39], v[154:157], v[230:233], v[36:39]
	v_mfma_f32_16x16x32_bf16 v[28:31], v[146:149], v[238:241], v[28:31]
	v_mfma_f32_16x16x32_bf16 v[20:23], v[154:157], v[238:241], v[20:23]
	s_setprio 0
	s_setprio 1
	v_mfma_f32_16x16x32_bf16 v[40:43], v[184:187], v[200:203], v[40:43]
	v_mfma_f32_16x16x32_bf16 v[32:35], v[192:195], v[200:203], v[32:35]
	v_mfma_f32_16x16x32_bf16 v[24:27], v[184:187], v[218:221], v[24:27]
	v_mfma_f32_16x16x32_bf16 v[16:19], v[192:195], v[218:221], v[16:19]
	v_mfma_f32_16x16x32_bf16 v[12:15], v[184:187], v[226:229], v[12:15]
	v_mfma_f32_16x16x32_bf16 v[8:11], v[192:195], v[226:229], v[8:11]
	v_mfma_f32_16x16x32_bf16 v[4:7], v[184:187], v[234:237], v[4:7]
	v_mfma_f32_16x16x32_bf16 v[0:3], v[192:195], v[234:237], v[0:3]
	v_mfma_f32_16x16x32_bf16 v[40:43], v[188:191], v[214:217], v[40:43]
	v_mfma_f32_16x16x32_bf16 v[32:35], v[196:199], v[214:217], v[32:35]
	v_mfma_f32_16x16x32_bf16 v[24:27], v[188:191], v[222:225], v[24:27]
	v_mfma_f32_16x16x32_bf16 v[16:19], v[196:199], v[222:225], v[16:19]
	v_mfma_f32_16x16x32_bf16 v[12:15], v[188:191], v[230:233], v[12:15]
	v_mfma_f32_16x16x32_bf16 v[8:11], v[196:199], v[230:233], v[8:11]
	v_mfma_f32_16x16x32_bf16 v[4:7], v[188:191], v[238:241], v[4:7]
	v_mfma_f32_16x16x32_bf16 v[0:3], v[196:199], v[238:241], v[0:3]
	s_setprio 0
	s_barrier
	s_add_i32 s52, s52, 2
	s_add_u32 s42, s42, 0x100
	s_addc_u32 s43, s43, 0
	s_add_u32 s50, s50, 0x100
	s_addc_u32 s51, s51, 0
	s_cmp_gt_u32 s52, 29
	s_cbranch_scc0 .LBB0_1102
	s_branch .Lgk_after_1102
.LBB0_1102:
	s_add_u32 s44, s42, 0xfff80080
	s_addc_u32 s45, s43, -1
	s_add_i32 s53, 0, 0x10000
	s_cmp_eq_u32 s52, 28
	s_cselect_b32 s47, s17, s45
	s_cselect_b32 s46, s48, s44
	s_cselect_b32 s45, s11, s51
	s_cselect_b32 s44, s49, s50
	s_add_i32 s56, 0, 0x14000
	v_add_u32_e32 v154, s53, v139
	v_add_u32_e32 v158, s56, v139
	ds_read_b128 v[142:145], v154
	ds_read_b128 v[146:149], v154 offset:1024
	ds_read_b128 v[150:153], v154 offset:2048
	ds_read_b128 v[154:157], v154 offset:3072
	ds_read_b128 v[184:187], v158
	ds_read_b128 v[188:191], v158 offset:1024
	ds_read_b128 v[192:195], v158 offset:2048
	ds_read_b128 v[196:199], v158 offset:3072
	v_lshl_add_u64 v[158:159], s[42:43], 0, v[134:135]
	s_add_i32 m0, s9, 0xc000
	ds_read_b128 v[200:203], v141
	ds_read_b128 v[214:217], v141 offset:1024
	ds_read_b128 v[218:221], v141 offset:2048
	ds_read_b128 v[222:225], v141 offset:3072
	ds_read_b128 v[226:229], v141 offset:4096
	ds_read_b128 v[230:233], v141 offset:5120
	ds_read_b128 v[234:237], v141 offset:6144
	ds_read_b128 v[238:241], v141 offset:7168
	global_load_lds_dwordx4 v[158:159], off
	v_lshl_add_u64 v[158:159], s[42:43], 0, v[136:137]
	s_add_i32 m0, s9, 0xe000
	s_nop 0
	global_load_lds_dwordx4 v[158:159], off
	s_waitcnt vmcnt(8)
	s_waitcnt lgkmcnt(0)
	s_barrier
; #define PG8_STAGE(bufoff, gbase, voff) do { _Pragma("unroll") for (int _i = 0; _i < 2; ++_i) \
;         __builtin_amdgcn_global_load_lds((const unsigned*)((const char*)(gbase) + (voff)[_i]), (PG8_LAS unsigned*)(lds + (bufoff) + ldsw + _i * 8192), 16, 0, 0); } while (0)
; #define PG8_WAIT_V(n) asm volatile("s_waitcnt vmcnt(" #n ")" ::: "memory")
; #define PG8_WAIT_L(n) asm volatile("s_waitcnt lgkmcnt(" #n ")" ::: "memory")
; #define PG8_BAR __builtin_amdgcn_s_barrier()
; #define PG8_SCHED __builtin_amdgcn_sched_barrier(0)
; template <class Epi, class Sched, bool ALIGN_EPI = false, bool SP2 = false, bool F8 = false>
; __device__ __forceinline__ void gemm_phase(PG8_LAS unsigned char* lds, const Gemm g, const Sched& S, const Epi& E) {
;     ...
;             PG8_WAIT_V(8); PG8_WAIT_L(0); PG8_BAR; PG8_MMA(0, 0, At, B0); PG8_MMA(0, 1, At, B1); PG8_BAR; PG8_SCHED;
;             PG8_LDA(At, 0, 1); PG8_STAGE(PG8_SB(0, 0), b2, voffB); PG8_STAGE(PG8_SB(0, 1), b2 + hstep, voffB); PG8_STAGE(PG8_SA(0, 0), a2, voffA);
;             PG8_WAIT_V(8); PG8_WAIT_L(0); PG8_BAR; PG8_MMA(1, 0, At, B0); PG8_MMA(1, 1, At, B1); PG8_BAR; PG8_SCHED;
;             PG8_LDB(B0, 1, 0); PG8_LDB(B1, 1, 1); PG8_SCHED; PG8_LDA(At, 1, 0); PG8_STAGE(PG8_SA(0, 1), a2 + hstep, voffA);
;             PG8_WAIT_V(8); PG8_WAIT_L(0); PG8_BAR; PG8_MMA(0, 0, At, B0); PG8_MMA(0, 1, At, B1); PG8_BAR; PG8_SCHED;
	s_setprio 1
	v_mfma_f32_16x16x32_bf16 v[124:127], v[142:145], v[200:203], v[124:127]
	v_mfma_f32_16x16x32_bf16 v[120:123], v[150:153], v[200:203], v[120:123]
	v_mfma_f32_16x16x32_bf16 v[116:119], v[142:145], v[218:221], v[116:119]
	v_mfma_f32_16x16x32_bf16 v[112:115], v[150:153], v[218:221], v[112:115]
	v_mfma_f32_16x16x32_bf16 v[108:111], v[142:145], v[226:229], v[108:111]
	v_mfma_f32_16x16x32_bf16 v[100:103], v[150:153], v[226:229], v[100:103]
	v_mfma_f32_16x16x32_bf16 v[92:95], v[142:145], v[234:237], v[92:95]
	v_mfma_f32_16x16x32_bf16 v[84:87], v[150:153], v[234:237], v[84:87]
	v_mfma_f32_16x16x32_bf16 v[124:127], v[146:149], v[214:217], v[124:127]
	v_mfma_f32_16x16x32_bf16 v[120:123], v[154:157], v[214:217], v[120:123]
	v_mfma_f32_16x16x32_bf16 v[116:119], v[146:149], v[222:225], v[116:119]
	v_mfma_f32_16x16x32_bf16 v[112:115], v[154:157], v[222:225], v[112:115]
	v_mfma_f32_16x16x32_bf16 v[108:111], v[146:149], v[230:233], v[108:111]
	v_mfma_f32_16x16x32_bf16 v[100:103], v[154:157], v[230:233], v[100:103]
	v_mfma_f32_16x16x32_bf16 v[92:95], v[146:149], v[238:241], v[92:95]
	v_mfma_f32_16x16x32_bf16 v[84:87], v[154:157], v[238:241], v[84:87]
	s_setprio 0
	s_setprio 1
	v_mfma_f32_16x16x32_bf16 v[104:107], v[184:187], v[200:203], v[104:107]
	v_mfma_f32_16x16x32_bf16 v[96:99], v[192:195], v[200:203], v[96:99]
	v_mfma_f32_16x16x32_bf16 v[88:91], v[184:187], v[218:221], v[88:91]
	v_mfma_f32_16x16x32_bf16 v[80:83], v[192:195], v[218:221], v[80:83]
	v_mfma_f32_16x16x32_bf16 v[76:79], v[184:187], v[226:229], v[76:79]
	v_mfma_f32_16x16x32_bf16 v[72:75], v[192:195], v[226:229], v[72:75]
	v_mfma_f32_16x16x32_bf16 v[68:71], v[184:187], v[234:237], v[68:71]
	v_mfma_f32_16x16x32_bf16 v[64:67], v[192:195], v[234:237], v[64:67]
	v_mfma_f32_16x16x32_bf16 v[104:107], v[188:191], v[214:217], v[104:107]
	v_mfma_f32_16x16x32_bf16 v[96:99], v[196:199], v[214:217], v[96:99]
	v_mfma_f32_16x16x32_bf16 v[88:91], v[188:191], v[222:225], v[88:91]
	v_mfma_f32_16x16x32_bf16 v[80:83], v[196:199], v[222:225], v[80:83]
	v_mfma_f32_16x16x32_bf16 v[76:79], v[188:191], v[230:233], v[76:79]
	v_mfma_f32_16x16x32_bf16 v[72:75], v[196:199], v[230:233], v[72:75]
	v_mfma_f32_16x16x32_bf16 v[68:71], v[188:191], v[238:241], v[68:71]
	v_mfma_f32_16x16x32_bf16 v[64:67], v[196:199], v[238:241], v[64:67]
	s_setprio 0
	s_barrier
	s_add_i32 s53, s53, s8
	v_lshl_add_u64 v[158:159], s[44:45], 0, v[160:161]
	s_mov_b32 m0, s53
	ds_read_b128 v[200:203], v141 offset:16384
	ds_read_b128 v[214:217], v141 offset:17408
	ds_read_b128 v[218:221], v141 offset:18432
	ds_read_b128 v[222:225], v141 offset:19456
	ds_read_b128 v[226:229], v141 offset:20480
	ds_read_b128 v[230:233], v141 offset:21504
	ds_read_b128 v[234:237], v141 offset:22528
	ds_read_b128 v[238:241], v141 offset:23552
	global_load_lds_dwordx4 v[158:159], off
	s_add_i32 m0, s53, 0x2000
	s_add_u32 s54, s44, 0x80000
	v_lshl_add_u64 v[162:163], s[44:45], 0, v[128:129]
	s_addc_u32 s55, s45, 0
	s_add_i32 s53, s56, s8
	global_load_lds_dwordx4 v[162:163], off
	v_lshl_add_u64 v[242:243], s[54:55], 0, v[160:161]
	s_mov_b32 m0, s53
	v_lshl_add_u64 v[244:245], s[46:47], 0, v[130:131]
	global_load_lds_dwordx4 v[242:243], off
	v_lshl_add_u64 v[242:243], s[54:55], 0, v[128:129]
	s_add_i32 m0, s53, 0x2000
	s_nop 0
	global_load_lds_dwordx4 v[242:243], off
	v_lshl_add_u64 v[242:243], s[46:47], 0, v[132:133]
	s_mov_b32 m0, s9
	s_nop 0
	global_load_lds_dwordx4 v[242:243], off
	s_mov_b32 m0, s13
	s_nop 0
	global_load_lds_dwordx4 v[244:245], off
	s_waitcnt vmcnt(8)
	s_waitcnt lgkmcnt(0)
	s_barrier
	s_setprio 1
	v_mfma_f32_16x16x32_bf16 v[60:63], v[142:145], v[200:203], v[60:63]
	v_mfma_f32_16x16x32_bf16 v[56:59], v[150:153], v[200:203], v[56:59]
	v_mfma_f32_16x16x32_bf16 v[52:55], v[142:145], v[218:221], v[52:55]
	v_mfma_f32_16x16x32_bf16 v[48:51], v[150:153], v[218:221], v[48:51]
	v_mfma_f32_16x16x32_bf16 v[44:47], v[142:145], v[226:229], v[44:47]
	v_mfma_f32_16x16x32_bf16 v[36:39], v[150:153], v[226:229], v[36:39]
	v_mfma_f32_16x16x32_bf16 v[28:31], v[142:145], v[234:237], v[28:31]
	v_mfma_f32_16x16x32_bf16 v[20:23], v[150:153], v[234:237], v[20:23]
	v_mfma_f32_16x16x32_bf16 v[60:63], v[146:149], v[214:217], v[60:63]
	v_mfma_f32_16x16x32_bf16 v[56:59], v[154:157], v[214:217], v[56:59]
	v_mfma_f32_16x16x32_bf16 v[52:55], v[146:149], v[222:225], v[52:55]
	v_mfma_f32_16x16x32_bf16 v[48:51], v[154:157], v[222:225], v[48:51]
	v_mfma_f32_16x16x32_bf16 v[44:47], v[146:149], v[230:233], v[44:47]
	v_mfma_f32_16x16x32_bf16 v[36:39], v[154:157], v[230:233], v[36:39]
	v_mfma_f32_16x16x32_bf16 v[28:31], v[146:149], v[238:241], v[28:31]
	v_mfma_f32_16x16x32_bf16 v[20:23], v[154:157], v[238:241], v[20:23]
	s_setprio 0
	s_setprio 1
	v_mfma_f32_16x16x32_bf16 v[40:43], v[184:187], v[200:203], v[40:43]
	v_mfma_f32_16x16x32_bf16 v[32:35], v[192:195], v[200:203], v[32:35]
	v_mfma_f32_16x16x32_bf16 v[24:27], v[184:187], v[218:221], v[24:27]
	v_mfma_f32_16x16x32_bf16 v[16:19], v[192:195], v[218:221], v[16:19]
	v_mfma_f32_16x16x32_bf16 v[12:15], v[184:187], v[226:229], v[12:15]
	v_mfma_f32_16x16x32_bf16 v[8:11], v[192:195], v[226:229], v[8:11]
	v_mfma_f32_16x16x32_bf16 v[4:7], v[184:187], v[234:237], v[4:7]
	v_mfma_f32_16x16x32_bf16 v[0:3], v[192:195], v[234:237], v[0:3]
	v_mfma_f32_16x16x32_bf16 v[40:43], v[188:191], v[214:217], v[40:43]
	v_mfma_f32_16x16x32_bf16 v[32:35], v[196:199], v[214:217], v[32:35]
	v_mfma_f32_16x16x32_bf16 v[24:27], v[188:191], v[222:225], v[24:27]
	v_mfma_f32_16x16x32_bf16 v[16:19], v[196:199], v[222:225], v[16:19]
	v_mfma_f32_16x16x32_bf16 v[12:15], v[188:191], v[230:233], v[12:15]
	v_mfma_f32_16x16x32_bf16 v[8:11], v[196:199], v[230:233], v[8:11]
	v_mfma_f32_16x16x32_bf16 v[4:7], v[188:191], v[238:241], v[4:7]
	v_mfma_f32_16x16x32_bf16 v[0:3], v[196:199], v[238:241], v[0:3]
	s_setprio 0
	s_barrier
; #define PG8_STAGE(bufoff, gbase, voff) do { _Pragma("unroll") for (int _i = 0; _i < 2; ++_i) \
;         __builtin_amdgcn_global_load_lds((const unsigned*)((const char*)(gbase) + (voff)[_i]), (PG8_LAS unsigned*)(lds + (bufoff) + ldsw + _i * 8192), 16, 0, 0); } while (0)
; #define PG8_WAIT_V(n) asm volatile("s_waitcnt vmcnt(" #n ")" ::: "memory")
; #define PG8_WAIT_L(n) asm volatile("s_waitcnt lgkmcnt(" #n ")" ::: "memory")
; #define PG8_BAR __builtin_amdgcn_s_barrier()
; #define PG8_SCHED __builtin_amdgcn_sched_barrier(0)
; template <class Epi, class Sched, bool ALIGN_EPI = false, bool SP2 = false, bool F8 = false>
; __device__ __forceinline__ void gemm_phase(PG8_LAS unsigned char* lds, const Gemm g, const Sched& S, const Epi& E) {
;     ...
;             PG8_LDB(B0, 1, 0); PG8_LDB(B1, 1, 1); PG8_SCHED; PG8_LDA(At, 1, 0); PG8_STAGE(PG8_SA(0, 1), a2 + hstep, voffA);
;             PG8_WAIT_V(8); PG8_WAIT_L(0); PG8_BAR; PG8_MMA(0, 0, At, B0); PG8_MMA(0, 1, At, B1); PG8_BAR; PG8_SCHED;
	s_add_i32 s53, 0, 0x18000
	s_add_i32 s54, 0, 0x1c000
	v_add_u32_e32 v154, s53, v139
	v_add_u32_e32 v196, s54, v139
	ds_read_b128 v[142:145], v154
	ds_read_b128 v[146:149], v154 offset:1024
	ds_read_b128 v[150:153], v154 offset:2048
	ds_read_b128 v[154:157], v154 offset:3072
	ds_read_b128 v[184:187], v196
	ds_read_b128 v[188:191], v196 offset:1024
	ds_read_b128 v[192:195], v196 offset:2048
	ds_read_b128 v[196:199], v196 offset:3072
	s_add_u32 s46, s46, 0x80000
	s_addc_u32 s47, s47, 0
	s_mov_b32 m0, s19
	v_lshl_add_u64 v[246:247], s[46:47], 0, v[132:133]
	ds_read_b128 v[200:203], v141 offset:32768
	ds_read_b128 v[214:217], v141 offset:33792
	ds_read_b128 v[218:221], v141 offset:34816
	ds_read_b128 v[222:225], v141 offset:35840
	ds_read_b128 v[226:229], v141 offset:36864
	ds_read_b128 v[230:233], v141 offset:37888
	ds_read_b128 v[234:237], v141 offset:38912
	ds_read_b128 v[238:241], v141 offset:39936
	global_load_lds_dwordx4 v[246:247], off
	v_lshl_add_u64 v[246:247], s[46:47], 0, v[130:131]
	s_mov_b32 m0, s22
	s_nop 0
	global_load_lds_dwordx4 v[246:247], off
	s_waitcnt vmcnt(8)
	s_waitcnt lgkmcnt(0)
	s_barrier
	s_setprio 1
	v_mfma_f32_16x16x32_bf16 v[124:127], v[142:145], v[200:203], v[124:127]
	v_mfma_f32_16x16x32_bf16 v[120:123], v[150:153], v[200:203], v[120:123]
	v_mfma_f32_16x16x32_bf16 v[116:119], v[142:145], v[218:221], v[116:119]
	v_mfma_f32_16x16x32_bf16 v[112:115], v[150:153], v[218:221], v[112:115]
	v_mfma_f32_16x16x32_bf16 v[108:111], v[142:145], v[226:229], v[108:111]
	v_mfma_f32_16x16x32_bf16 v[100:103], v[150:153], v[226:229], v[100:103]
	v_mfma_f32_16x16x32_bf16 v[92:95], v[142:145], v[234:237], v[92:95]
	v_mfma_f32_16x16x32_bf16 v[84:87], v[150:153], v[234:237], v[84:87]
	v_mfma_f32_16x16x32_bf16 v[124:127], v[146:149], v[214:217], v[124:127]
	v_mfma_f32_16x16x32_bf16 v[120:123], v[154:157], v[214:217], v[120:123]
	v_mfma_f32_16x16x32_bf16 v[116:119], v[146:149], v[222:225], v[116:119]
	v_mfma_f32_16x16x32_bf16 v[112:115], v[154:157], v[222:225], v[112:115]
	v_mfma_f32_16x16x32_bf16 v[108:111], v[146:149], v[230:233], v[108:111]
	v_mfma_f32_16x16x32_bf16 v[100:103], v[154:157], v[230:233], v[100:103]
	v_mfma_f32_16x16x32_bf16 v[92:95], v[146:149], v[238:241], v[92:95]
	v_mfma_f32_16x16x32_bf16 v[84:87], v[154:157], v[238:241], v[84:87]
	s_setprio 0
	s_setprio 1
	v_mfma_f32_16x16x32_bf16 v[104:107], v[184:187], v[200:203], v[104:107]
	v_mfma_f32_16x16x32_bf16 v[96:99], v[192:195], v[200:203], v[96:99]
	v_mfma_f32_16x16x32_bf16 v[88:91], v[184:187], v[218:221], v[88:91]
	v_mfma_f32_16x16x32_bf16 v[80:83], v[192:195], v[218:221], v[80:83]
	v_mfma_f32_16x16x32_bf16 v[76:79], v[184:187], v[226:229], v[76:79]
	v_mfma_f32_16x16x32_bf16 v[72:75], v[192:195], v[226:229], v[72:75]
	v_mfma_f32_16x16x32_bf16 v[68:71], v[184:187], v[234:237], v[68:71]
	v_mfma_f32_16x16x32_bf16 v[64:67], v[192:195], v[234:237], v[64:67]
	v_mfma_f32_16x16x32_bf16 v[104:107], v[188:191], v[214:217], v[104:107]
	v_mfma_f32_16x16x32_bf16 v[96:99], v[196:199], v[214:217], v[96:99]
	v_mfma_f32_16x16x32_bf16 v[88:91], v[188:191], v[222:225], v[88:91]
	v_mfma_f32_16x16x32_bf16 v[80:83], v[196:199], v[222:225], v[80:83]
	v_mfma_f32_16x16x32_bf16 v[76:79], v[188:191], v[230:233], v[76:79]
	v_mfma_f32_16x16x32_bf16 v[72:75], v[196:199], v[230:233], v[72:75]
	v_mfma_f32_16x16x32_bf16 v[68:71], v[188:191], v[238:241], v[68:71]
	v_mfma_f32_16x16x32_bf16 v[64:67], v[196:199], v[238:241], v[64:67]
	s_setprio 0
	s_barrier
; #define PG8_STAGE(bufoff, gbase, voff) do { _Pragma("unroll") for (int _i = 0; _i < 2; ++_i) \
;         __builtin_amdgcn_global_load_lds((const unsigned*)((const char*)(gbase) + (voff)[_i]), (PG8_LAS unsigned*)(lds + (bufoff) + ldsw + _i * 8192), 16, 0, 0); } while (0)
; #define PG8_WAIT_V(n) asm volatile("s_waitcnt vmcnt(" #n ")" ::: "memory")
; #define PG8_WAIT_L(n) asm volatile("s_waitcnt lgkmcnt(" #n ")" ::: "memory")
; #define PG8_BAR __builtin_amdgcn_s_barrier()
; #define PG8_SCHED __builtin_amdgcn_sched_barrier(0)
; template <class Epi, class Sched, bool ALIGN_EPI = false, bool SP2 = false, bool F8 = false>
; __device__ __forceinline__ void gemm_phase(PG8_LAS unsigned char* lds, const Gemm g, const Sched& S, const Epi& E) {
;     ...
;         for (int t = 0; t < nt; t += 2) {
;             const bool last = (t == nt - 2);
;             const char* a1 = cA + (size_t)(t + 1) * kstep;
;             const char* a2 = last ? nA : cA + (size_t)(t + 2) * kstep; const char* b2 = last ? nB : cB + (size_t)(t + 2) * kstep;
;             const char* a3 = a2 + kstep; const char* b3 = b2 + kstep;
;     ...
;             PG8_LDA(At, 1, 1); PG8_STAGE(PG8_SB(1, 0), b3, voffB); PG8_STAGE(PG8_SB(1, 1), b3 + hstep, voffB); PG8_STAGE(PG8_SA(1, 0), a3, voffA);
;             PG8_WAIT_V(8); PG8_WAIT_L(0); PG8_BAR; PG8_MMA(1, 0, At, B0); PG8_MMA(1, 1, At, B1); PG8_BAR; PG8_SCHED;
	s_add_i32 s46, s53, s8
	v_lshl_add_u64 v[158:159], v[158:159], 0, s[14:15]
	s_mov_b32 m0, s46
	ds_read_b128 v[200:203], v141 offset:49152
	ds_read_b128 v[214:217], v141 offset:50176
	ds_read_b128 v[218:221], v141 offset:51200
	ds_read_b128 v[222:225], v141 offset:52224
	ds_read_b128 v[226:229], v141 offset:53248
	ds_read_b128 v[230:233], v141 offset:54272
	ds_read_b128 v[234:237], v141 offset:55296
	ds_read_b128 v[238:241], v141 offset:56320
	global_load_lds_dwordx4 v[158:159], off
	s_add_i32 m0, s46, 0x2000
	s_add_u32 s44, s44, 0x80080
	v_lshl_add_u64 v[158:159], v[162:163], 0, s[14:15]
	s_addc_u32 s45, s45, 0
	s_add_i32 s46, s54, s8
	global_load_lds_dwordx4 v[158:159], off
	v_lshl_add_u64 v[158:159], s[44:45], 0, v[160:161]
	s_mov_b32 m0, s46
	s_nop 0
	global_load_lds_dwordx4 v[158:159], off
	v_lshl_add_u64 v[158:159], s[44:45], 0, v[128:129]
	s_add_i32 m0, s46, 0x2000
	s_nop 0
	global_load_lds_dwordx4 v[158:159], off
	v_lshl_add_u64 v[158:159], v[242:243], 0, s[14:15]
	s_mov_b32 m0, s23
	s_nop 0
	global_load_lds_dwordx4 v[158:159], off
	v_lshl_add_u64 v[158:159], v[244:245], 0, s[14:15]
	s_mov_b32 m0, s28
	s_nop 0
	global_load_lds_dwordx4 v[158:159], off
	s_waitcnt vmcnt(8)
	s_waitcnt lgkmcnt(0)
	s_barrier
	s_setprio 1
	v_mfma_f32_16x16x32_bf16 v[60:63], v[142:145], v[200:203], v[60:63]
	v_mfma_f32_16x16x32_bf16 v[56:59], v[150:153], v[200:203], v[56:59]
	v_mfma_f32_16x16x32_bf16 v[52:55], v[142:145], v[218:221], v[52:55]
	v_mfma_f32_16x16x32_bf16 v[48:51], v[150:153], v[218:221], v[48:51]
	v_mfma_f32_16x16x32_bf16 v[44:47], v[142:145], v[226:229], v[44:47]
	v_mfma_f32_16x16x32_bf16 v[36:39], v[150:153], v[226:229], v[36:39]
	v_mfma_f32_16x16x32_bf16 v[28:31], v[142:145], v[234:237], v[28:31]
	v_mfma_f32_16x16x32_bf16 v[20:23], v[150:153], v[234:237], v[20:23]
	v_mfma_f32_16x16x32_bf16 v[60:63], v[146:149], v[214:217], v[60:63]
	v_mfma_f32_16x16x32_bf16 v[56:59], v[154:157], v[214:217], v[56:59]
	v_mfma_f32_16x16x32_bf16 v[52:55], v[146:149], v[222:225], v[52:55]
	v_mfma_f32_16x16x32_bf16 v[48:51], v[154:157], v[222:225], v[48:51]
	v_mfma_f32_16x16x32_bf16 v[44:47], v[146:149], v[230:233], v[44:47]
	v_mfma_f32_16x16x32_bf16 v[36:39], v[154:157], v[230:233], v[36:39]
	v_mfma_f32_16x16x32_bf16 v[28:31], v[146:149], v[238:241], v[28:31]
	v_mfma_f32_16x16x32_bf16 v[20:23], v[154:157], v[238:241], v[20:23]
	s_setprio 0
	s_setprio 1
	v_mfma_f32_16x16x32_bf16 v[40:43], v[184:187], v[200:203], v[40:43]
	v_mfma_f32_16x16x32_bf16 v[32:35], v[192:195], v[200:203], v[32:35]
	v_mfma_f32_16x16x32_bf16 v[24:27], v[184:187], v[218:221], v[24:27]
	v_mfma_f32_16x16x32_bf16 v[16:19], v[192:195], v[218:221], v[16:19]
	v_mfma_f32_16x16x32_bf16 v[12:15], v[184:187], v[226:229], v[12:15]
	v_mfma_f32_16x16x32_bf16 v[8:11], v[192:195], v[226:229], v[8:11]
	v_mfma_f32_16x16x32_bf16 v[4:7], v[184:187], v[234:237], v[4:7]
	v_mfma_f32_16x16x32_bf16 v[0:3], v[192:195], v[234:237], v[0:3]
	v_mfma_f32_16x16x32_bf16 v[40:43], v[188:191], v[214:217], v[40:43]
	v_mfma_f32_16x16x32_bf16 v[32:35], v[196:199], v[214:217], v[32:35]
	v_mfma_f32_16x16x32_bf16 v[24:27], v[188:191], v[222:225], v[24:27]
	v_mfma_f32_16x16x32_bf16 v[16:19], v[196:199], v[222:225], v[16:19]
	v_mfma_f32_16x16x32_bf16 v[12:15], v[188:191], v[230:233], v[12:15]
	v_mfma_f32_16x16x32_bf16 v[8:11], v[196:199], v[230:233], v[8:11]
	v_mfma_f32_16x16x32_bf16 v[4:7], v[188:191], v[238:241], v[4:7]
	v_mfma_f32_16x16x32_bf16 v[0:3], v[196:199], v[238:241], v[0:3]
	s_setprio 0
	s_barrier
	s_add_i32 s52, s52, 2
	s_add_u32 s42, s42, 0x100
	s_addc_u32 s43, s43, 0
	s_add_u32 s50, s50, 0x100
	s_addc_u32 s51, s51, 0
	s_cmp_gt_u32 s52, 29
	s_cbranch_scc0 .LBB0_1102

; #define PG8_STAGE(bufoff, gbase, voff) do { _Pragma("unroll") for (int _i = 0; _i < 2; ++_i) \
;         __builtin_amdgcn_global_load_lds((const unsigned*)((const char*)(gbase) + (voff)[_i]), (PG8_LAS unsigned*)(lds + (bufoff) + ldsw + _i * 8192), 16, 0, 0); } while (0)
; #define PG8_WAIT_V(n) asm volatile("s_waitcnt vmcnt(" #n ")" ::: "memory")
; #define PG8_WAIT_L(n) asm volatile("s_waitcnt lgkmcnt(" #n ")" ::: "memory")
; #define PG8_BAR __builtin_amdgcn_s_barrier()
; #define PG8_SCHED __builtin_amdgcn_sched_barrier(0)
; template <class Epi, class Sched, bool ALIGN_EPI = false, bool SP2 = false, bool F8 = false>
; __device__ __forceinline__ void gemm_phase(PG8_LAS unsigned char* lds, const Gemm g, const Sched& S, const Epi& E) {
;     ...
;         const bool has_next = S.next(ui + 1, nxt);
;         const char* nA = has_next ? (const char*)g.A + (size_t)nxt.pm * tstep : cA; const char* nB = has_next ? (const char*)g.Bt + (size_t)nxt.pn * tstep : cB;
;         for (int t = 0; t < nt; t += 2) {
;             const bool last = (t == nt - 2);
;             const char* a1 = cA + (size_t)(t + 1) * kstep;
;             const char* a2 = last ? nA : cA + (size_t)(t + 2) * kstep; const char* b2 = last ? nB : cB + (size_t)(t + 2) * kstep;
;             const char* a3 = a2 + kstep; const char* b3 = b2 + kstep;
;             if (last && has_next) S.a_ready(nxt);
;             if constexpr (SP2) {
;             PG8_LDB(B0, 0, 0); PG8_LDB(B1, 0, 1); PG8_SCHED; PG8_LDA(At, 0, 0); PG8_STAGE(PG8_SA(1, 1), a1 + hstep, voffA);
;             PG8_WAIT_V(8); PG8_WAIT_L(0); PG8_BAR; PG8_MMA(0, 0, At, B0); PG8_MMA(0, 1, At, B1); PG8_BAR; PG8_SCHED;
;             PG8_LDA(At, 0, 1); PG8_STAGE(PG8_SB(0, 0), b2, voffB); PG8_STAGE(PG8_SB(0, 1), b2 + hstep, voffB); PG8_STAGE(PG8_SA(0, 0), a2, voffA);
;             PG8_WAIT_V(8); PG8_WAIT_L(0); PG8_BAR; PG8_MMA(1, 0, At, B0); PG8_MMA(1, 1, At, B1); PG8_BAR; PG8_SCHED;
.LBB0_1121:
	s_ashr_i32 s43, s42, 31
	s_lshl_b64 s[28:29], s[42:43], 19
	v_readlane_b32 s19, v253, 59
	s_add_u32 s44, s19, s28
	v_readlane_b32 s19, v253, 60
	s_addc_u32 s45, s19, s29
	s_and_b64 s[28:29], s[38:39], exec
	s_cselect_b32 s19, s45, s11
	s_cselect_b32 s23, s44, s10
	s_ashr_i32 s41, s40, 31
	s_lshl_b64 s[28:29], s[40:41], 19
	s_add_u32 s46, s22, s28
	s_addc_u32 s47, s50, s29
	s_and_b64 s[28:29], s[38:39], exec
	s_cselect_b32 s28, s47, s37
	s_cselect_b32 s29, s46, s36
	s_add_u32 s10, s10, 0x40080
	s_addc_u32 s11, s11, 0
	s_add_u32 s34, s36, 0x100
	s_addc_u32 s35, s37, 0
	s_mov_b32 s41, -2
	s_add_u32 s36, s10, 0xfffc0080
	s_addc_u32 s37, s11, -1
	s_add_i32 s43, 0, 0x10000
	s_cmp_eq_u32 s41, 12
	s_cselect_b32 s49, s19, s37
	s_cselect_b32 s48, s23, s36
	s_cselect_b32 s37, s28, s35
	s_cselect_b32 s36, s29, s34
	s_add_i32 s56, 0, 0x14000
	v_add_u32_e32 v0, s43, v213
	v_add_u32_e32 v12, s56, v213
	ds_read_b128 v[16:19], v0
	ds_read_b128 v[20:23], v0 offset:1024
	ds_read_b128 v[24:27], v0 offset:2048
	ds_read_b128 v[28:31], v0 offset:3072
	ds_read_b128 v[0:3], v12
	ds_read_b128 v[4:7], v12 offset:1024
	ds_read_b128 v[8:11], v12 offset:2048
	ds_read_b128 v[12:15], v12 offset:3072
	v_lshl_add_u64 v[162:163], s[10:11], 0, v[190:191]
	s_add_i32 m0, s51, 0xc000
	ds_read_b128 v[194:197], v215
	ds_read_b128 v[198:201], v215 offset:1024
	ds_read_b128 v[216:219], v215 offset:2048
	ds_read_b128 v[220:223], v215 offset:3072
	ds_read_b128 v[224:227], v215 offset:4096
	ds_read_b128 v[228:231], v215 offset:5120
	ds_read_b128 v[232:235], v215 offset:6144
	ds_read_b128 v[236:239], v215 offset:7168
	global_load_lds_dwordx4 v[162:163], off
	v_lshl_add_u64 v[162:163], s[10:11], 0, v[192:193]
	s_add_i32 m0, s51, 0xe000
	s_nop 0
	global_load_lds_dwordx4 v[162:163], off
	s_waitcnt vmcnt(8)
	s_waitcnt lgkmcnt(0)
	s_barrier
	s_setprio 1
	v_mfma_scale_f32_16x16x128_f8f6f4 v[156:159], v[16:23], v[194:201], 0, v202, v202 op_sel_hi:[0,0,0]
	v_mfma_scale_f32_16x16x128_f8f6f4 v[152:155], v[24:31], v[194:201], 0, v202, v202 op_sel_hi:[0,0,0]
	v_mfma_scale_f32_16x16x128_f8f6f4 v[140:143], v[16:23], v[216:223], 0, v202, v202 op_sel_hi:[0,0,0]
	v_mfma_scale_f32_16x16x128_f8f6f4 v[136:139], v[24:31], v[216:223], 0, v202, v202 op_sel_hi:[0,0,0]
	v_mfma_scale_f32_16x16x128_f8f6f4 v[124:127], v[16:23], v[224:231], 0, v202, v202 op_sel_hi:[0,0,0]
	v_mfma_scale_f32_16x16x128_f8f6f4 v[120:123], v[24:31], v[224:231], 0, v202, v202 op_sel_hi:[0,0,0]
	v_mfma_scale_f32_16x16x128_f8f6f4 v[108:111], v[16:23], v[232:239], 0, v202, v202 op_sel_hi:[0,0,0]
	v_mfma_scale_f32_16x16x128_f8f6f4 v[104:107], v[24:31], v[232:239], 0, v202, v202 op_sel_hi:[0,0,0]
	s_setprio 0
	s_setprio 1
	v_mfma_scale_f32_16x16x128_f8f6f4 v[148:151], v[0:7], v[194:201], 0, v202, v202 op_sel_hi:[0,0,0]
	v_mfma_scale_f32_16x16x128_f8f6f4 v[144:147], v[8:15], v[194:201], 0, v202, v202 op_sel_hi:[0,0,0]
	v_mfma_scale_f32_16x16x128_f8f6f4 v[132:135], v[0:7], v[216:223], 0, v202, v202 op_sel_hi:[0,0,0]
	v_mfma_scale_f32_16x16x128_f8f6f4 v[128:131], v[8:15], v[216:223], 0, v202, v202 op_sel_hi:[0,0,0]
	v_mfma_scale_f32_16x16x128_f8f6f4 v[116:119], v[0:7], v[224:231], 0, v202, v202 op_sel_hi:[0,0,0]
	v_mfma_scale_f32_16x16x128_f8f6f4 v[112:115], v[8:15], v[224:231], 0, v202, v202 op_sel_hi:[0,0,0]
	v_mfma_scale_f32_16x16x128_f8f6f4 v[100:103], v[0:7], v[232:239], 0, v202, v202 op_sel_hi:[0,0,0]
	v_mfma_scale_f32_16x16x128_f8f6f4 v[96:99], v[8:15], v[232:239], 0, v202, v202 op_sel_hi:[0,0,0]
	s_setprio 0
	s_barrier
	s_add_i32 s43, s43, s13
	v_lshl_add_u64 v[194:195], s[36:37], 0, v[160:161]
	s_mov_b32 m0, s43
	ds_read_b128 v[216:219], v215 offset:16384
	ds_read_b128 v[220:223], v215 offset:17408
	ds_read_b128 v[224:227], v215 offset:18432
	ds_read_b128 v[228:231], v215 offset:19456
	ds_read_b128 v[232:235], v215 offset:20480
	ds_read_b128 v[236:239], v215 offset:21504
	ds_read_b128 v[240:243], v215 offset:22528
	ds_read_b128 v[244:247], v215 offset:23552
	global_load_lds_dwordx4 v[194:195], off
	s_add_i32 m0, s43, 0x2000
	s_add_u32 s60, s36, 0x40000
	v_lshl_add_u64 v[196:197], s[36:37], 0, v[184:185]
	s_addc_u32 s61, s37, 0
	s_add_i32 s43, s56, s13
	global_load_lds_dwordx4 v[196:197], off
	v_lshl_add_u64 v[162:163], s[60:61], 0, v[160:161]
	s_mov_b32 m0, s43
	v_lshl_add_u64 v[198:199], s[48:49], 0, v[188:189]
	global_load_lds_dwordx4 v[162:163], off
	v_lshl_add_u64 v[162:163], s[60:61], 0, v[184:185]
	s_add_i32 m0, s43, 0x2000
	v_lshl_add_u64 v[200:201], s[48:49], 0, v[186:187]
	global_load_lds_dwordx4 v[162:163], off
	s_mov_b32 m0, s51
	s_nop 0
	global_load_lds_dwordx4 v[198:199], off
	s_mov_b32 m0, s52
	s_nop 0
	global_load_lds_dwordx4 v[200:201], off
	s_waitcnt vmcnt(8)
	s_waitcnt lgkmcnt(0)
	s_barrier
	s_setprio 1
	v_mfma_scale_f32_16x16x128_f8f6f4 v[92:95], v[16:23], v[216:223], 0, v202, v202 op_sel_hi:[0,0,0]
	v_mfma_scale_f32_16x16x128_f8f6f4 v[88:91], v[24:31], v[216:223], 0, v202, v202 op_sel_hi:[0,0,0]
	v_mfma_scale_f32_16x16x128_f8f6f4 v[76:79], v[16:23], v[224:231], 0, v202, v202 op_sel_hi:[0,0,0]
	v_mfma_scale_f32_16x16x128_f8f6f4 v[72:75], v[24:31], v[224:231], 0, v202, v202 op_sel_hi:[0,0,0]
	v_mfma_scale_f32_16x16x128_f8f6f4 v[60:63], v[16:23], v[232:239], 0, v202, v202 op_sel_hi:[0,0,0]
	v_mfma_scale_f32_16x16x128_f8f6f4 v[56:59], v[24:31], v[232:239], 0, v202, v202 op_sel_hi:[0,0,0]
	v_mfma_scale_f32_16x16x128_f8f6f4 v[44:47], v[16:23], v[240:247], 0, v202, v202 op_sel_hi:[0,0,0]
	v_mfma_scale_f32_16x16x128_f8f6f4 v[40:43], v[24:31], v[240:247], 0, v202, v202 op_sel_hi:[0,0,0]
	s_setprio 0
	s_setprio 1
	v_mfma_scale_f32_16x16x128_f8f6f4 v[84:87], v[0:7], v[216:223], 0, v202, v202 op_sel_hi:[0,0,0]
	v_mfma_scale_f32_16x16x128_f8f6f4 v[80:83], v[8:15], v[216:223], 0, v202, v202 op_sel_hi:[0,0,0]
	v_mfma_scale_f32_16x16x128_f8f6f4 v[68:71], v[0:7], v[224:231], 0, v202, v202 op_sel_hi:[0,0,0]
	v_mfma_scale_f32_16x16x128_f8f6f4 v[64:67], v[8:15], v[224:231], 0, v202, v202 op_sel_hi:[0,0,0]
	v_mfma_scale_f32_16x16x128_f8f6f4 v[52:55], v[0:7], v[232:239], 0, v202, v202 op_sel_hi:[0,0,0]
	v_mfma_scale_f32_16x16x128_f8f6f4 v[48:51], v[8:15], v[232:239], 0, v202, v202 op_sel_hi:[0,0,0]
	v_mfma_scale_f32_16x16x128_f8f6f4 v[36:39], v[0:7], v[240:247], 0, v202, v202 op_sel_hi:[0,0,0]
	v_mfma_scale_f32_16x16x128_f8f6f4 v[32:35], v[8:15], v[240:247], 0, v202, v202 op_sel_hi:[0,0,0]
	s_setprio 0
	s_barrier
; #define PG8_STAGE(bufoff, gbase, voff) do { _Pragma("unroll") for (int _i = 0; _i < 2; ++_i) \
;         __builtin_amdgcn_global_load_lds((const unsigned*)((const char*)(gbase) + (voff)[_i]), (PG8_LAS unsigned*)(lds + (bufoff) + ldsw + _i * 8192), 16, 0, 0); } while (0)
; #define PG8_WAIT_V(n) asm volatile("s_waitcnt vmcnt(" #n ")" ::: "memory")
; #define PG8_WAIT_L(n) asm volatile("s_waitcnt lgkmcnt(" #n ")" ::: "memory")
; #define PG8_BAR __builtin_amdgcn_s_barrier()
; #define PG8_SCHED __builtin_amdgcn_sched_barrier(0)
; template <class Epi, class Sched, bool ALIGN_EPI = false, bool SP2 = false, bool F8 = false>
; __device__ __forceinline__ void gemm_phase(PG8_LAS unsigned char* lds, const Gemm g, const Sched& S, const Epi& E) {
;     ...
;             PG8_LDB(B0, 1, 0); PG8_LDB(B1, 1, 1); PG8_SCHED; PG8_LDA(At, 1, 0); PG8_STAGE(PG8_SA(0, 1), a2 + hstep, voffA);
;             PG8_WAIT_V(8); PG8_WAIT_L(0); PG8_BAR; PG8_MMA(0, 0, At, B0); PG8_MMA(0, 1, At, B1); PG8_BAR; PG8_SCHED;
;             PG8_LDA(At, 1, 1); PG8_STAGE(PG8_SB(1, 0), b3, voffB); PG8_STAGE(PG8_SB(1, 1), b3 + hstep, voffB); PG8_STAGE(PG8_SA(1, 0), a3, voffA);
;             PG8_WAIT_V(8); PG8_WAIT_L(0); PG8_BAR; PG8_MMA(1, 0, At, B0); PG8_MMA(1, 1, At, B1); PG8_BAR; PG8_SCHED;
	s_add_i32 s43, 0, 0x18000
	s_add_i32 s56, 0, 0x1c000
	v_add_u32_e32 v12, s43, v213
	v_add_u32_e32 v28, s56, v213
	ds_read_b128 v[0:3], v12
	ds_read_b128 v[4:7], v12 offset:1024
	ds_read_b128 v[8:11], v12 offset:2048
	ds_read_b128 v[12:15], v12 offset:3072
	ds_read_b128 v[16:19], v28
	ds_read_b128 v[20:23], v28 offset:1024
	ds_read_b128 v[24:27], v28 offset:2048
	ds_read_b128 v[28:31], v28 offset:3072
	s_add_u32 s48, s48, 0x40000
	s_addc_u32 s49, s49, 0
	s_mov_b32 m0, s53
	v_lshl_add_u64 v[162:163], s[48:49], 0, v[188:189]
	ds_read_b128 v[216:219], v215 offset:32768
	ds_read_b128 v[220:223], v215 offset:33792
	ds_read_b128 v[224:227], v215 offset:34816
	ds_read_b128 v[228:231], v215 offset:35840
	ds_read_b128 v[232:235], v215 offset:36864
	ds_read_b128 v[236:239], v215 offset:37888
	ds_read_b128 v[240:243], v215 offset:38912
	ds_read_b128 v[244:247], v215 offset:39936
	global_load_lds_dwordx4 v[162:163], off
	v_lshl_add_u64 v[162:163], s[48:49], 0, v[186:187]
	s_mov_b32 m0, s54
	s_nop 0
	global_load_lds_dwordx4 v[162:163], off
	s_waitcnt vmcnt(8)
	s_waitcnt lgkmcnt(0)
	s_barrier
	s_setprio 1
	v_mfma_scale_f32_16x16x128_f8f6f4 v[156:159], v[0:7], v[216:223], v[156:159], v202, v202 op_sel_hi:[0,0,0]
	v_mfma_scale_f32_16x16x128_f8f6f4 v[152:155], v[8:15], v[216:223], v[152:155], v202, v202 op_sel_hi:[0,0,0]
	v_mfma_scale_f32_16x16x128_f8f6f4 v[140:143], v[0:7], v[224:231], v[140:143], v202, v202 op_sel_hi:[0,0,0]
	v_mfma_scale_f32_16x16x128_f8f6f4 v[136:139], v[8:15], v[224:231], v[136:139], v202, v202 op_sel_hi:[0,0,0]
	v_mfma_scale_f32_16x16x128_f8f6f4 v[124:127], v[0:7], v[232:239], v[124:127], v202, v202 op_sel_hi:[0,0,0]
	v_mfma_scale_f32_16x16x128_f8f6f4 v[120:123], v[8:15], v[232:239], v[120:123], v202, v202 op_sel_hi:[0,0,0]
	v_mfma_scale_f32_16x16x128_f8f6f4 v[108:111], v[0:7], v[240:247], v[108:111], v202, v202 op_sel_hi:[0,0,0]
	v_mfma_scale_f32_16x16x128_f8f6f4 v[104:107], v[8:15], v[240:247], v[104:107], v202, v202 op_sel_hi:[0,0,0]
	s_setprio 0
	s_setprio 1
	v_mfma_scale_f32_16x16x128_f8f6f4 v[148:151], v[16:23], v[216:223], v[148:151], v202, v202 op_sel_hi:[0,0,0]
	v_mfma_scale_f32_16x16x128_f8f6f4 v[144:147], v[24:31], v[216:223], v[144:147], v202, v202 op_sel_hi:[0,0,0]
	v_mfma_scale_f32_16x16x128_f8f6f4 v[132:135], v[16:23], v[224:231], v[132:135], v202, v202 op_sel_hi:[0,0,0]
	v_mfma_scale_f32_16x16x128_f8f6f4 v[128:131], v[24:31], v[224:231], v[128:131], v202, v202 op_sel_hi:[0,0,0]
	v_mfma_scale_f32_16x16x128_f8f6f4 v[116:119], v[16:23], v[232:239], v[116:119], v202, v202 op_sel_hi:[0,0,0]
	v_mfma_scale_f32_16x16x128_f8f6f4 v[112:115], v[24:31], v[232:239], v[112:115], v202, v202 op_sel_hi:[0,0,0]
	v_mfma_scale_f32_16x16x128_f8f6f4 v[100:103], v[16:23], v[240:247], v[100:103], v202, v202 op_sel_hi:[0,0,0]
	v_mfma_scale_f32_16x16x128_f8f6f4 v[96:99], v[24:31], v[240:247], v[96:99], v202, v202 op_sel_hi:[0,0,0]
	s_setprio 0
	s_barrier
	s_add_i32 s43, s43, s13
	v_lshl_add_u64 v[162:163], v[194:195], 0, s[14:15]
	s_mov_b32 m0, s43
	ds_read_b128 v[216:219], v215 offset:49152
	ds_read_b128 v[220:223], v215 offset:50176
	ds_read_b128 v[224:227], v215 offset:51200
	ds_read_b128 v[228:231], v215 offset:52224
	ds_read_b128 v[232:235], v215 offset:53248
	ds_read_b128 v[236:239], v215 offset:54272
	ds_read_b128 v[240:243], v215 offset:55296
	ds_read_b128 v[244:247], v215 offset:56320
	global_load_lds_dwordx4 v[162:163], off
	s_add_i32 m0, s43, 0x2000
	s_add_u32 s36, s36, 0x40080
	v_lshl_add_u64 v[162:163], v[196:197], 0, s[14:15]
	s_addc_u32 s37, s37, 0
	s_add_i32 s43, s56, s13
	global_load_lds_dwordx4 v[162:163], off
	v_lshl_add_u64 v[162:163], s[36:37], 0, v[160:161]
	s_mov_b32 m0, s43
	s_nop 0
	global_load_lds_dwordx4 v[162:163], off
	v_lshl_add_u64 v[162:163], s[36:37], 0, v[184:185]
	s_add_i32 m0, s43, 0x2000
	s_nop 0
	global_load_lds_dwordx4 v[162:163], off
	v_lshl_add_u64 v[162:163], v[198:199], 0, s[14:15]
	s_mov_b32 m0, s55
	s_nop 0
	global_load_lds_dwordx4 v[162:163], off
	v_lshl_add_u64 v[162:163], v[200:201], 0, s[14:15]
	s_mov_b32 m0, s58
	s_nop 0
	global_load_lds_dwordx4 v[162:163], off
	s_waitcnt vmcnt(8)
	s_waitcnt lgkmcnt(0)
	s_barrier
	s_setprio 1
	v_mfma_scale_f32_16x16x128_f8f6f4 v[92:95], v[0:7], v[216:223], v[92:95], v202, v202 op_sel_hi:[0,0,0]
	v_mfma_scale_f32_16x16x128_f8f6f4 v[88:91], v[8:15], v[216:223], v[88:91], v202, v202 op_sel_hi:[0,0,0]
	v_mfma_scale_f32_16x16x128_f8f6f4 v[76:79], v[0:7], v[224:231], v[76:79], v202, v202 op_sel_hi:[0,0,0]
	v_mfma_scale_f32_16x16x128_f8f6f4 v[72:75], v[8:15], v[224:231], v[72:75], v202, v202 op_sel_hi:[0,0,0]
	v_mfma_scale_f32_16x16x128_f8f6f4 v[60:63], v[0:7], v[232:239], v[60:63], v202, v202 op_sel_hi:[0,0,0]
	v_mfma_scale_f32_16x16x128_f8f6f4 v[56:59], v[8:15], v[232:239], v[56:59], v202, v202 op_sel_hi:[0,0,0]
	v_mfma_scale_f32_16x16x128_f8f6f4 v[44:47], v[0:7], v[240:247], v[44:47], v202, v202 op_sel_hi:[0,0,0]
	v_mfma_scale_f32_16x16x128_f8f6f4 v[40:43], v[8:15], v[240:247], v[40:43], v202, v202 op_sel_hi:[0,0,0]
	s_setprio 0
	s_setprio 1
	v_mfma_scale_f32_16x16x128_f8f6f4 v[84:87], v[16:23], v[216:223], v[84:87], v202, v202 op_sel_hi:[0,0,0]
	v_mfma_scale_f32_16x16x128_f8f6f4 v[80:83], v[24:31], v[216:223], v[80:83], v202, v202 op_sel_hi:[0,0,0]
	v_mfma_scale_f32_16x16x128_f8f6f4 v[68:71], v[16:23], v[224:231], v[68:71], v202, v202 op_sel_hi:[0,0,0]
	v_mfma_scale_f32_16x16x128_f8f6f4 v[64:67], v[24:31], v[224:231], v[64:67], v202, v202 op_sel_hi:[0,0,0]
	v_mfma_scale_f32_16x16x128_f8f6f4 v[52:55], v[16:23], v[232:239], v[52:55], v202, v202 op_sel_hi:[0,0,0]
	v_mfma_scale_f32_16x16x128_f8f6f4 v[48:51], v[24:31], v[232:239], v[48:51], v202, v202 op_sel_hi:[0,0,0]
	v_mfma_scale_f32_16x16x128_f8f6f4 v[36:39], v[16:23], v[240:247], v[36:39], v202, v202 op_sel_hi:[0,0,0]
	v_mfma_scale_f32_16x16x128_f8f6f4 v[32:35], v[24:31], v[240:247], v[32:35], v202, v202 op_sel_hi:[0,0,0]
	s_setprio 0
	s_barrier
	s_add_i32 s41, s41, 2
	s_add_u32 s10, s10, 0x100
	s_addc_u32 s11, s11, 0
	s_add_u32 s34, s34, 0x100
	s_addc_u32 s35, s35, 0
	s_cmp_gt_u32 s41, 13
	s_cbranch_scc0 .LBB0_1122
	s_branch .Lgk_after_1122
; #define PG8_STAGE(bufoff, gbase, voff) do { _Pragma("unroll") for (int _i = 0; _i < 2; ++_i) \
;         __builtin_amdgcn_global_load_lds((const unsigned*)((const char*)(gbase) + (voff)[_i]), (PG8_LAS unsigned*)(lds + (bufoff) + ldsw + _i * 8192), 16, 0, 0); } while (0)
; #define PG8_WAIT_V(n) asm volatile("s_waitcnt vmcnt(" #n ")" ::: "memory")
; #define PG8_WAIT_L(n) asm volatile("s_waitcnt lgkmcnt(" #n ")" ::: "memory")
; #define PG8_BAR __builtin_amdgcn_s_barrier()
; #define PG8_SCHED __builtin_amdgcn_sched_barrier(0)
; template <class Epi, class Sched, bool ALIGN_EPI = false, bool SP2 = false, bool F8 = false>
; __device__ __forceinline__ void gemm_phase(PG8_LAS unsigned char* lds, const Gemm g, const Sched& S, const Epi& E) {
;     ...
;             PG8_LDB(B0, 0, 0); PG8_LDB(B1, 0, 1); PG8_SCHED; PG8_LDA(At, 0, 0); PG8_STAGE(PG8_SA(1, 1), a1 + hstep, voffA);
;             PG8_WAIT_V(8); PG8_WAIT_L(0); PG8_BAR; PG8_MMA(0, 0, At, B0); PG8_MMA(0, 1, At, B1); PG8_BAR; PG8_SCHED;
;             PG8_LDA(At, 0, 1); PG8_STAGE(PG8_SB(0, 0), b2, voffB); PG8_STAGE(PG8_SB(0, 1), b2 + hstep, voffB); PG8_STAGE(PG8_SA(0, 0), a2, voffA);
;             PG8_WAIT_V(8); PG8_WAIT_L(0); PG8_BAR; PG8_MMA(1, 0, At, B0); PG8_MMA(1, 1, At, B1); PG8_BAR; PG8_SCHED;
.LBB0_1122:
	s_add_u32 s36, s10, 0xfffc0080
	s_addc_u32 s37, s11, -1
	s_add_i32 s43, 0, 0x10000
	s_cmp_eq_u32 s41, 12
	s_cselect_b32 s49, s19, s37
	s_cselect_b32 s48, s23, s36
	s_cselect_b32 s37, s28, s35
	s_cselect_b32 s36, s29, s34
	s_add_i32 s56, 0, 0x14000
	v_add_u32_e32 v0, s43, v213
	v_add_u32_e32 v12, s56, v213
	ds_read_b128 v[16:19], v0
	ds_read_b128 v[20:23], v0 offset:1024
	ds_read_b128 v[24:27], v0 offset:2048
	ds_read_b128 v[28:31], v0 offset:3072
	ds_read_b128 v[0:3], v12
	ds_read_b128 v[4:7], v12 offset:1024
	ds_read_b128 v[8:11], v12 offset:2048
	ds_read_b128 v[12:15], v12 offset:3072
	v_lshl_add_u64 v[162:163], s[10:11], 0, v[190:191]
	s_add_i32 m0, s51, 0xc000
	ds_read_b128 v[194:197], v215
	ds_read_b128 v[198:201], v215 offset:1024
	ds_read_b128 v[216:219], v215 offset:2048
	ds_read_b128 v[220:223], v215 offset:3072
	ds_read_b128 v[224:227], v215 offset:4096
	ds_read_b128 v[228:231], v215 offset:5120
	ds_read_b128 v[232:235], v215 offset:6144
	ds_read_b128 v[236:239], v215 offset:7168
	global_load_lds_dwordx4 v[162:163], off
	v_lshl_add_u64 v[162:163], s[10:11], 0, v[192:193]
	s_add_i32 m0, s51, 0xe000
	s_nop 0
	global_load_lds_dwordx4 v[162:163], off
	s_waitcnt vmcnt(8)
	s_waitcnt lgkmcnt(0)
	s_barrier
	s_setprio 1
	v_mfma_scale_f32_16x16x128_f8f6f4 v[156:159], v[16:23], v[194:201], v[156:159], v202, v202 op_sel_hi:[0,0,0]
	v_mfma_scale_f32_16x16x128_f8f6f4 v[152:155], v[24:31], v[194:201], v[152:155], v202, v202 op_sel_hi:[0,0,0]
	v_mfma_scale_f32_16x16x128_f8f6f4 v[140:143], v[16:23], v[216:223], v[140:143], v202, v202 op_sel_hi:[0,0,0]
	v_mfma_scale_f32_16x16x128_f8f6f4 v[136:139], v[24:31], v[216:223], v[136:139], v202, v202 op_sel_hi:[0,0,0]
	v_mfma_scale_f32_16x16x128_f8f6f4 v[124:127], v[16:23], v[224:231], v[124:127], v202, v202 op_sel_hi:[0,0,0]
	v_mfma_scale_f32_16x16x128_f8f6f4 v[120:123], v[24:31], v[224:231], v[120:123], v202, v202 op_sel_hi:[0,0,0]
	v_mfma_scale_f32_16x16x128_f8f6f4 v[108:111], v[16:23], v[232:239], v[108:111], v202, v202 op_sel_hi:[0,0,0]
	v_mfma_scale_f32_16x16x128_f8f6f4 v[104:107], v[24:31], v[232:239], v[104:107], v202, v202 op_sel_hi:[0,0,0]
	s_setprio 0
	s_setprio 1
	v_mfma_scale_f32_16x16x128_f8f6f4 v[148:151], v[0:7], v[194:201], v[148:151], v202, v202 op_sel_hi:[0,0,0]
	v_mfma_scale_f32_16x16x128_f8f6f4 v[144:147], v[8:15], v[194:201], v[144:147], v202, v202 op_sel_hi:[0,0,0]
	v_mfma_scale_f32_16x16x128_f8f6f4 v[132:135], v[0:7], v[216:223], v[132:135], v202, v202 op_sel_hi:[0,0,0]
	v_mfma_scale_f32_16x16x128_f8f6f4 v[128:131], v[8:15], v[216:223], v[128:131], v202, v202 op_sel_hi:[0,0,0]
	v_mfma_scale_f32_16x16x128_f8f6f4 v[116:119], v[0:7], v[224:231], v[116:119], v202, v202 op_sel_hi:[0,0,0]
	v_mfma_scale_f32_16x16x128_f8f6f4 v[112:115], v[8:15], v[224:231], v[112:115], v202, v202 op_sel_hi:[0,0,0]
	v_mfma_scale_f32_16x16x128_f8f6f4 v[100:103], v[0:7], v[232:239], v[100:103], v202, v202 op_sel_hi:[0,0,0]
	v_mfma_scale_f32_16x16x128_f8f6f4 v[96:99], v[8:15], v[232:239], v[96:99], v202, v202 op_sel_hi:[0,0,0]
	s_setprio 0
	s_barrier
	s_add_i32 s43, s43, s13
	v_lshl_add_u64 v[194:195], s[36:37], 0, v[160:161]
	s_mov_b32 m0, s43
	ds_read_b128 v[216:219], v215 offset:16384
	ds_read_b128 v[220:223], v215 offset:17408
	ds_read_b128 v[224:227], v215 offset:18432
	ds_read_b128 v[228:231], v215 offset:19456
	ds_read_b128 v[232:235], v215 offset:20480
	ds_read_b128 v[236:239], v215 offset:21504
	ds_read_b128 v[240:243], v215 offset:22528
	ds_read_b128 v[244:247], v215 offset:23552
	global_load_lds_dwordx4 v[194:195], off
	s_add_i32 m0, s43, 0x2000
	s_add_u32 s60, s36, 0x40000
	v_lshl_add_u64 v[196:197], s[36:37], 0, v[184:185]
	s_addc_u32 s61, s37, 0
	s_add_i32 s43, s56, s13
	global_load_lds_dwordx4 v[196:197], off
	v_lshl_add_u64 v[162:163], s[60:61], 0, v[160:161]
	s_mov_b32 m0, s43
	v_lshl_add_u64 v[198:199], s[48:49], 0, v[188:189]
	global_load_lds_dwordx4 v[162:163], off
	v_lshl_add_u64 v[162:163], s[60:61], 0, v[184:185]
	s_add_i32 m0, s43, 0x2000
	v_lshl_add_u64 v[200:201], s[48:49], 0, v[186:187]
	global_load_lds_dwordx4 v[162:163], off
	s_mov_b32 m0, s51
	s_nop 0
	global_load_lds_dwordx4 v[198:199], off
	s_mov_b32 m0, s52
	s_nop 0
	global_load_lds_dwordx4 v[200:201], off
	s_waitcnt vmcnt(8)
	s_waitcnt lgkmcnt(0)
	s_barrier
	s_setprio 1
	v_mfma_scale_f32_16x16x128_f8f6f4 v[92:95], v[16:23], v[216:223], v[92:95], v202, v202 op_sel_hi:[0,0,0]
	v_mfma_scale_f32_16x16x128_f8f6f4 v[88:91], v[24:31], v[216:223], v[88:91], v202, v202 op_sel_hi:[0,0,0]
	v_mfma_scale_f32_16x16x128_f8f6f4 v[76:79], v[16:23], v[224:231], v[76:79], v202, v202 op_sel_hi:[0,0,0]
	v_mfma_scale_f32_16x16x128_f8f6f4 v[72:75], v[24:31], v[224:231], v[72:75], v202, v202 op_sel_hi:[0,0,0]
	v_mfma_scale_f32_16x16x128_f8f6f4 v[60:63], v[16:23], v[232:239], v[60:63], v202, v202 op_sel_hi:[0,0,0]
	v_mfma_scale_f32_16x16x128_f8f6f4 v[56:59], v[24:31], v[232:239], v[56:59], v202, v202 op_sel_hi:[0,0,0]
	v_mfma_scale_f32_16x16x128_f8f6f4 v[44:47], v[16:23], v[240:247], v[44:47], v202, v202 op_sel_hi:[0,0,0]
	v_mfma_scale_f32_16x16x128_f8f6f4 v[40:43], v[24:31], v[240:247], v[40:43], v202, v202 op_sel_hi:[0,0,0]
	s_setprio 0
	s_setprio 1
	v_mfma_scale_f32_16x16x128_f8f6f4 v[84:87], v[0:7], v[216:223], v[84:87], v202, v202 op_sel_hi:[0,0,0]
	v_mfma_scale_f32_16x16x128_f8f6f4 v[80:83], v[8:15], v[216:223], v[80:83], v202, v202 op_sel_hi:[0,0,0]
	v_mfma_scale_f32_16x16x128_f8f6f4 v[68:71], v[0:7], v[224:231], v[68:71], v202, v202 op_sel_hi:[0,0,0]
	v_mfma_scale_f32_16x16x128_f8f6f4 v[64:67], v[8:15], v[224:231], v[64:67], v202, v202 op_sel_hi:[0,0,0]
	v_mfma_scale_f32_16x16x128_f8f6f4 v[52:55], v[0:7], v[232:239], v[52:55], v202, v202 op_sel_hi:[0,0,0]
	v_mfma_scale_f32_16x16x128_f8f6f4 v[48:51], v[8:15], v[232:239], v[48:51], v202, v202 op_sel_hi:[0,0,0]
	v_mfma_scale_f32_16x16x128_f8f6f4 v[36:39], v[0:7], v[240:247], v[36:39], v202, v202 op_sel_hi:[0,0,0]
	v_mfma_scale_f32_16x16x128_f8f6f4 v[32:35], v[8:15], v[240:247], v[32:35], v202, v202 op_sel_hi:[0,0,0]
	s_setprio 0
	s_barrier
; #define PG8_STAGE(bufoff, gbase, voff) do { _Pragma("unroll") for (int _i = 0; _i < 2; ++_i) \
;         __builtin_amdgcn_global_load_lds((const unsigned*)((const char*)(gbase) + (voff)[_i]), (PG8_LAS unsigned*)(lds + (bufoff) + ldsw + _i * 8192), 16, 0, 0); } while (0)
; #define PG8_WAIT_V(n) asm volatile("s_waitcnt vmcnt(" #n ")" ::: "memory")
; #define PG8_WAIT_L(n) asm volatile("s_waitcnt lgkmcnt(" #n ")" ::: "memory")
; #define PG8_BAR __builtin_amdgcn_s_barrier()
; #define PG8_SCHED __builtin_amdgcn_sched_barrier(0)
; template <class Epi, class Sched, bool ALIGN_EPI = false, bool SP2 = false, bool F8 = false>
; __device__ __forceinline__ void gemm_phase(PG8_LAS unsigned char* lds, const Gemm g, const Sched& S, const Epi& E) {
;     ...
;             PG8_LDB(B0, 1, 0); PG8_LDB(B1, 1, 1); PG8_SCHED; PG8_LDA(At, 1, 0); PG8_STAGE(PG8_SA(0, 1), a2 + hstep, voffA);
;             PG8_WAIT_V(8); PG8_WAIT_L(0); PG8_BAR; PG8_MMA(0, 0, At, B0); PG8_MMA(0, 1, At, B1); PG8_BAR; PG8_SCHED;
;             PG8_LDA(At, 1, 1); PG8_STAGE(PG8_SB(1, 0), b3, voffB); PG8_STAGE(PG8_SB(1, 1), b3 + hstep, voffB); PG8_STAGE(PG8_SA(1, 0), a3, voffA);
;             PG8_WAIT_V(8); PG8_WAIT_L(0); PG8_BAR; PG8_MMA(1, 0, At, B0); PG8_MMA(1, 1, At, B1); PG8_BAR; PG8_SCHED;
	s_add_i32 s43, 0, 0x18000
	s_add_i32 s56, 0, 0x1c000
	v_add_u32_e32 v12, s43, v213
	v_add_u32_e32 v28, s56, v213
	ds_read_b128 v[0:3], v12
	ds_read_b128 v[4:7], v12 offset:1024
	ds_read_b128 v[8:11], v12 offset:2048
	ds_read_b128 v[12:15], v12 offset:3072
	ds_read_b128 v[16:19], v28
	ds_read_b128 v[20:23], v28 offset:1024
	ds_read_b128 v[24:27], v28 offset:2048
	ds_read_b128 v[28:31], v28 offset:3072
	s_add_u32 s48, s48, 0x40000
	s_addc_u32 s49, s49, 0
	s_mov_b32 m0, s53
	v_lshl_add_u64 v[162:163], s[48:49], 0, v[188:189]
	ds_read_b128 v[216:219], v215 offset:32768
	ds_read_b128 v[220:223], v215 offset:33792
	ds_read_b128 v[224:227], v215 offset:34816
	ds_read_b128 v[228:231], v215 offset:35840
	ds_read_b128 v[232:235], v215 offset:36864
	ds_read_b128 v[236:239], v215 offset:37888
	ds_read_b128 v[240:243], v215 offset:38912
	ds_read_b128 v[244:247], v215 offset:39936
	global_load_lds_dwordx4 v[162:163], off
	v_lshl_add_u64 v[162:163], s[48:49], 0, v[186:187]
	s_mov_b32 m0, s54
	s_nop 0
	global_load_lds_dwordx4 v[162:163], off
	s_waitcnt vmcnt(8)
	s_waitcnt lgkmcnt(0)
	s_barrier
	s_setprio 1
	v_mfma_scale_f32_16x16x128_f8f6f4 v[156:159], v[0:7], v[216:223], v[156:159], v202, v202 op_sel_hi:[0,0,0]
	v_mfma_scale_f32_16x16x128_f8f6f4 v[152:155], v[8:15], v[216:223], v[152:155], v202, v202 op_sel_hi:[0,0,0]
	v_mfma_scale_f32_16x16x128_f8f6f4 v[140:143], v[0:7], v[224:231], v[140:143], v202, v202 op_sel_hi:[0,0,0]
	v_mfma_scale_f32_16x16x128_f8f6f4 v[136:139], v[8:15], v[224:231], v[136:139], v202, v202 op_sel_hi:[0,0,0]
	v_mfma_scale_f32_16x16x128_f8f6f4 v[124:127], v[0:7], v[232:239], v[124:127], v202, v202 op_sel_hi:[0,0,0]
	v_mfma_scale_f32_16x16x128_f8f6f4 v[120:123], v[8:15], v[232:239], v[120:123], v202, v202 op_sel_hi:[0,0,0]
	v_mfma_scale_f32_16x16x128_f8f6f4 v[108:111], v[0:7], v[240:247], v[108:111], v202, v202 op_sel_hi:[0,0,0]
	v_mfma_scale_f32_16x16x128_f8f6f4 v[104:107], v[8:15], v[240:247], v[104:107], v202, v202 op_sel_hi:[0,0,0]
	s_setprio 0
	s_setprio 1
	v_mfma_scale_f32_16x16x128_f8f6f4 v[148:151], v[16:23], v[216:223], v[148:151], v202, v202 op_sel_hi:[0,0,0]
	v_mfma_scale_f32_16x16x128_f8f6f4 v[144:147], v[24:31], v[216:223], v[144:147], v202, v202 op_sel_hi:[0,0,0]
	v_mfma_scale_f32_16x16x128_f8f6f4 v[132:135], v[16:23], v[224:231], v[132:135], v202, v202 op_sel_hi:[0,0,0]
	v_mfma_scale_f32_16x16x128_f8f6f4 v[128:131], v[24:31], v[224:231], v[128:131], v202, v202 op_sel_hi:[0,0,0]
	v_mfma_scale_f32_16x16x128_f8f6f4 v[116:119], v[16:23], v[232:239], v[116:119], v202, v202 op_sel_hi:[0,0,0]
	v_mfma_scale_f32_16x16x128_f8f6f4 v[112:115], v[24:31], v[232:239], v[112:115], v202, v202 op_sel_hi:[0,0,0]
	v_mfma_scale_f32_16x16x128_f8f6f4 v[100:103], v[16:23], v[240:247], v[100:103], v202, v202 op_sel_hi:[0,0,0]
	v_mfma_scale_f32_16x16x128_f8f6f4 v[96:99], v[24:31], v[240:247], v[96:99], v202, v202 op_sel_hi:[0,0,0]
	s_setprio 0
	s_barrier
	s_add_i32 s43, s43, s13
	v_lshl_add_u64 v[162:163], v[194:195], 0, s[14:15]
	s_mov_b32 m0, s43
	ds_read_b128 v[216:219], v215 offset:49152
	ds_read_b128 v[220:223], v215 offset:50176
	ds_read_b128 v[224:227], v215 offset:51200
	ds_read_b128 v[228:231], v215 offset:52224
	ds_read_b128 v[232:235], v215 offset:53248
	ds_read_b128 v[236:239], v215 offset:54272
	ds_read_b128 v[240:243], v215 offset:55296
	ds_read_b128 v[244:247], v215 offset:56320
	global_load_lds_dwordx4 v[162:163], off
	s_add_i32 m0, s43, 0x2000
	s_add_u32 s36, s36, 0x40080
	v_lshl_add_u64 v[162:163], v[196:197], 0, s[14:15]
	s_addc_u32 s37, s37, 0
	s_add_i32 s43, s56, s13
	global_load_lds_dwordx4 v[162:163], off
	v_lshl_add_u64 v[162:163], s[36:37], 0, v[160:161]
	s_mov_b32 m0, s43
	s_nop 0
	global_load_lds_dwordx4 v[162:163], off
	v_lshl_add_u64 v[162:163], s[36:37], 0, v[184:185]
	s_add_i32 m0, s43, 0x2000
	s_nop 0
	global_load_lds_dwordx4 v[162:163], off
	v_lshl_add_u64 v[162:163], v[198:199], 0, s[14:15]
	s_mov_b32 m0, s55
	s_nop 0
	global_load_lds_dwordx4 v[162:163], off
	v_lshl_add_u64 v[162:163], v[200:201], 0, s[14:15]
	s_mov_b32 m0, s58
	s_nop 0
	global_load_lds_dwordx4 v[162:163], off
	s_waitcnt vmcnt(8)
	s_waitcnt lgkmcnt(0)
	s_barrier
	s_setprio 1
	v_mfma_scale_f32_16x16x128_f8f6f4 v[92:95], v[0:7], v[216:223], v[92:95], v202, v202 op_sel_hi:[0,0,0]
	v_mfma_scale_f32_16x16x128_f8f6f4 v[88:91], v[8:15], v[216:223], v[88:91], v202, v202 op_sel_hi:[0,0,0]
	v_mfma_scale_f32_16x16x128_f8f6f4 v[76:79], v[0:7], v[224:231], v[76:79], v202, v202 op_sel_hi:[0,0,0]
	v_mfma_scale_f32_16x16x128_f8f6f4 v[72:75], v[8:15], v[224:231], v[72:75], v202, v202 op_sel_hi:[0,0,0]
	v_mfma_scale_f32_16x16x128_f8f6f4 v[60:63], v[0:7], v[232:239], v[60:63], v202, v202 op_sel_hi:[0,0,0]
	v_mfma_scale_f32_16x16x128_f8f6f4 v[56:59], v[8:15], v[232:239], v[56:59], v202, v202 op_sel_hi:[0,0,0]
	v_mfma_scale_f32_16x16x128_f8f6f4 v[44:47], v[0:7], v[240:247], v[44:47], v202, v202 op_sel_hi:[0,0,0]
	v_mfma_scale_f32_16x16x128_f8f6f4 v[40:43], v[8:15], v[240:247], v[40:43], v202, v202 op_sel_hi:[0,0,0]
	s_setprio 0
	s_setprio 1
	v_mfma_scale_f32_16x16x128_f8f6f4 v[84:87], v[16:23], v[216:223], v[84:87], v202, v202 op_sel_hi:[0,0,0]
	v_mfma_scale_f32_16x16x128_f8f6f4 v[80:83], v[24:31], v[216:223], v[80:83], v202, v202 op_sel_hi:[0,0,0]
	v_mfma_scale_f32_16x16x128_f8f6f4 v[68:71], v[16:23], v[224:231], v[68:71], v202, v202 op_sel_hi:[0,0,0]
	v_mfma_scale_f32_16x16x128_f8f6f4 v[64:67], v[24:31], v[224:231], v[64:67], v202, v202 op_sel_hi:[0,0,0]
	v_mfma_scale_f32_16x16x128_f8f6f4 v[52:55], v[16:23], v[232:239], v[52:55], v202, v202 op_sel_hi:[0,0,0]
	v_mfma_scale_f32_16x16x128_f8f6f4 v[48:51], v[24:31], v[232:239], v[48:51], v202, v202 op_sel_hi:[0,0,0]
	v_mfma_scale_f32_16x16x128_f8f6f4 v[36:39], v[16:23], v[240:247], v[36:39], v202, v202 op_sel_hi:[0,0,0]
	v_mfma_scale_f32_16x16x128_f8f6f4 v[32:35], v[24:31], v[240:247], v[32:35], v202, v202 op_sel_hi:[0,0,0]
	s_setprio 0
	s_barrier
	s_add_i32 s41, s41, 2
	s_add_u32 s10, s10, 0x100
	s_addc_u32 s11, s11, 0
	s_add_u32 s34, s34, 0x100
	s_addc_u32 s35, s35, 0
	s_cmp_gt_u32 s41, 13
	s_cbranch_scc0 .LBB0_1122

; #define PG8_STAGE(bufoff, gbase, voff) do { _Pragma("unroll") for (int _i = 0; _i < 2; ++_i) \
;         __builtin_amdgcn_global_load_lds((const unsigned*)((const char*)(gbase) + (voff)[_i]), (PG8_LAS unsigned*)(lds + (bufoff) + ldsw + _i * 8192), 16, 0, 0); } while (0)
; #define PG8_WAIT_V(n) asm volatile("s_waitcnt vmcnt(" #n ")" ::: "memory")
; #define PG8_WAIT_L(n) asm volatile("s_waitcnt lgkmcnt(" #n ")" ::: "memory")
; #define PG8_BAR __builtin_amdgcn_s_barrier()
; #define PG8_SCHED __builtin_amdgcn_sched_barrier(0)
; template <class Epi, class Sched, bool ALIGN_EPI = false, bool SP2 = false, bool F8 = false>
; __device__ __forceinline__ void gemm_phase(PG8_LAS unsigned char* lds, const Gemm g, const Sched& S, const Epi& E) {
;     ...
;         const bool has_next = S.next(ui + 1, nxt);
;         const char* nA = has_next ? (const char*)g.A + (size_t)nxt.pm * tstep : cA; const char* nB = has_next ? (const char*)g.Bt + (size_t)nxt.pn * tstep : cB;
;         for (int t = 0; t < nt; t += 2) {
;             const bool last = (t == nt - 2);
;             const char* a1 = cA + (size_t)(t + 1) * kstep;
;             const char* a2 = last ? nA : cA + (size_t)(t + 2) * kstep; const char* b2 = last ? nB : cB + (size_t)(t + 2) * kstep;
;             const char* a3 = a2 + kstep; const char* b3 = b2 + kstep;
;             if (last && has_next) S.a_ready(nxt);
;             if constexpr (SP2) {
;             PG8_LDB(B0, 0, 0); PG8_LDB(B1, 0, 1); PG8_SCHED; PG8_LDA(At, 0, 0); PG8_STAGE(PG8_SA(1, 1), a1 + hstep, voffA);
;             PG8_WAIT_V(8); PG8_WAIT_L(0); PG8_BAR; PG8_MMA(0, 0, At, B0); PG8_MMA(0, 1, At, B1); PG8_BAR; PG8_SCHED;
.LBB0_1147:
	s_ashr_i32 s37, s36, 31
	s_lshl_b64 s[40:41], s[36:37], 22
	s_add_u32 s40, s20, s40
	s_addc_u32 s41, s21, s41
	s_and_b64 s[42:43], s[38:39], exec
	s_cselect_b32 s37, s41, s47
	s_cselect_b32 s52, s40, s46
	s_ashr_i32 s17, s16, 31
	s_lshl_b64 s[42:43], s[16:17], 22
	s_add_u32 s42, s13, s42
	s_addc_u32 s43, s19, s43
	s_and_b64 s[50:51], s[38:39], exec
	s_cselect_b32 s17, s43, s49
	s_cselect_b32 s53, s42, s48
	s_add_u32 s46, s46, 0x200080
	s_addc_u32 s47, s47, 0
	s_add_u32 s54, s48, 0x100
	s_addc_u32 s55, s49, 0
	s_mov_b32 s56, -2
	s_add_u32 s48, s46, 0xffe00080
	s_addc_u32 s49, s47, -1
	s_add_i32 s58, 0, 0x10000
	s_cmpk_eq_i32 s56, 0x7c
	s_cselect_b32 s51, s37, s49
	s_cselect_b32 s50, s52, s48
	s_cselect_b32 s49, s17, s55
	s_cselect_b32 s48, s53, s54
	s_add_i32 s60, 0, 0x14000
	v_add_u32_e32 v154, s58, v147
	v_add_u32_e32 v158, s60, v147
	ds_read_b128 v[138:141], v154
	ds_read_b128 v[142:145], v154 offset:1024
	ds_read_b128 v[150:153], v154 offset:2048
	ds_read_b128 v[154:157], v154 offset:3072
	ds_read_b128 v[184:187], v158
	ds_read_b128 v[188:191], v158 offset:1024
	ds_read_b128 v[192:195], v158 offset:2048
	ds_read_b128 v[196:199], v158 offset:3072
	v_lshl_add_u64 v[158:159], s[46:47], 0, v[134:135]
	s_add_i32 m0, s23, 0xc000
	ds_read_b128 v[200:203], v149
	ds_read_b128 v[214:217], v149 offset:1024
	ds_read_b128 v[218:221], v149 offset:2048
	ds_read_b128 v[222:225], v149 offset:3072
	ds_read_b128 v[226:229], v149 offset:4096
	ds_read_b128 v[230:233], v149 offset:5120
	ds_read_b128 v[234:237], v149 offset:6144
	ds_read_b128 v[238:241], v149 offset:7168
	global_load_lds_dwordx4 v[158:159], off
	v_lshl_add_u64 v[158:159], s[46:47], 0, v[136:137]
	s_add_i32 m0, s23, 0xe000
	s_nop 0
	global_load_lds_dwordx4 v[158:159], off
	s_waitcnt vmcnt(8)
	s_waitcnt lgkmcnt(0)
	s_barrier
	s_setprio 1
	v_mfma_f32_16x16x32_bf16 v[124:127], v[138:141], v[200:203], 0
	v_mfma_f32_16x16x32_bf16 v[120:123], v[150:153], v[200:203], 0
	v_mfma_f32_16x16x32_bf16 v[108:111], v[138:141], v[218:221], 0
	v_mfma_f32_16x16x32_bf16 v[104:107], v[150:153], v[218:221], 0
	v_mfma_f32_16x16x32_bf16 v[92:95], v[138:141], v[226:229], 0
	v_mfma_f32_16x16x32_bf16 v[88:91], v[150:153], v[226:229], 0
	v_mfma_f32_16x16x32_bf16 v[76:79], v[138:141], v[234:237], 0
	v_mfma_f32_16x16x32_bf16 v[72:75], v[150:153], v[234:237], 0
	v_mfma_f32_16x16x32_bf16 v[124:127], v[142:145], v[214:217], v[124:127]
	v_mfma_f32_16x16x32_bf16 v[120:123], v[154:157], v[214:217], v[120:123]
	v_mfma_f32_16x16x32_bf16 v[108:111], v[142:145], v[222:225], v[108:111]
	v_mfma_f32_16x16x32_bf16 v[104:107], v[154:157], v[222:225], v[104:107]
	v_mfma_f32_16x16x32_bf16 v[92:95], v[142:145], v[230:233], v[92:95]
	v_mfma_f32_16x16x32_bf16 v[88:91], v[154:157], v[230:233], v[88:91]
	v_mfma_f32_16x16x32_bf16 v[76:79], v[142:145], v[238:241], v[76:79]
	v_mfma_f32_16x16x32_bf16 v[72:75], v[154:157], v[238:241], v[72:75]
	s_setprio 0
	s_setprio 1
	v_mfma_f32_16x16x32_bf16 v[116:119], v[184:187], v[200:203], 0
	v_mfma_f32_16x16x32_bf16 v[112:115], v[192:195], v[200:203], 0
	v_mfma_f32_16x16x32_bf16 v[100:103], v[184:187], v[218:221], 0
	v_mfma_f32_16x16x32_bf16 v[96:99], v[192:195], v[218:221], 0
	v_mfma_f32_16x16x32_bf16 v[84:87], v[184:187], v[226:229], 0
	v_mfma_f32_16x16x32_bf16 v[80:83], v[192:195], v[226:229], 0
	v_mfma_f32_16x16x32_bf16 v[68:71], v[184:187], v[234:237], 0
	v_mfma_f32_16x16x32_bf16 v[64:67], v[192:195], v[234:237], 0
	v_mfma_f32_16x16x32_bf16 v[116:119], v[188:191], v[214:217], v[116:119]
	v_mfma_f32_16x16x32_bf16 v[112:115], v[196:199], v[214:217], v[112:115]
	v_mfma_f32_16x16x32_bf16 v[100:103], v[188:191], v[222:225], v[100:103]
	v_mfma_f32_16x16x32_bf16 v[96:99], v[196:199], v[222:225], v[96:99]
	v_mfma_f32_16x16x32_bf16 v[84:87], v[188:191], v[230:233], v[84:87]
	v_mfma_f32_16x16x32_bf16 v[80:83], v[196:199], v[230:233], v[80:83]
	v_mfma_f32_16x16x32_bf16 v[68:71], v[188:191], v[238:241], v[68:71]
	v_mfma_f32_16x16x32_bf16 v[64:67], v[196:199], v[238:241], v[64:67]
	s_setprio 0
	s_barrier
	s_add_i32 s58, s58, s22
	v_lshl_add_u64 v[158:159], s[48:49], 0, v[160:161]
	s_mov_b32 m0, s58
	ds_read_b128 v[200:203], v149 offset:16384
	ds_read_b128 v[214:217], v149 offset:17408
	ds_read_b128 v[218:221], v149 offset:18432
	ds_read_b128 v[222:225], v149 offset:19456
	ds_read_b128 v[226:229], v149 offset:20480
	ds_read_b128 v[230:233], v149 offset:21504
	ds_read_b128 v[234:237], v149 offset:22528
	ds_read_b128 v[238:241], v149 offset:23552
	global_load_lds_dwordx4 v[158:159], off
	s_add_i32 m0, s58, 0x2000
	s_add_u32 s58, s48, 0x200000
	v_lshl_add_u64 v[162:163], s[48:49], 0, v[132:133]
	s_addc_u32 s59, s49, 0
	s_add_i32 s60, s60, s22
	global_load_lds_dwordx4 v[162:163], off
	v_lshl_add_u64 v[242:243], s[58:59], 0, v[160:161]
	s_mov_b32 m0, s60
	v_lshl_add_u64 v[244:245], s[50:51], 0, v[130:131]
	global_load_lds_dwordx4 v[242:243], off
	v_lshl_add_u64 v[242:243], s[58:59], 0, v[132:133]
	s_add_i32 m0, s60, 0x2000
	s_nop 0
	global_load_lds_dwordx4 v[242:243], off
	v_lshl_add_u64 v[242:243], s[50:51], 0, v[128:129]
	s_mov_b32 m0, s23
	s_nop 0
	global_load_lds_dwordx4 v[242:243], off
	s_mov_b32 m0, s28
	s_nop 0
	global_load_lds_dwordx4 v[244:245], off
	s_waitcnt vmcnt(8)
	s_waitcnt lgkmcnt(0)
	s_barrier
; #define PG8_STAGE(bufoff, gbase, voff) do { _Pragma("unroll") for (int _i = 0; _i < 2; ++_i) \
;         __builtin_amdgcn_global_load_lds((const unsigned*)((const char*)(gbase) + (voff)[_i]), (PG8_LAS unsigned*)(lds + (bufoff) + ldsw + _i * 8192), 16, 0, 0); } while (0)
; #define PG8_WAIT_V(n) asm volatile("s_waitcnt vmcnt(" #n ")" ::: "memory")
; #define PG8_WAIT_L(n) asm volatile("s_waitcnt lgkmcnt(" #n ")" ::: "memory")
; #define PG8_BAR __builtin_amdgcn_s_barrier()
; #define PG8_SCHED __builtin_amdgcn_sched_barrier(0)
; template <class Epi, class Sched, bool ALIGN_EPI = false, bool SP2 = false, bool F8 = false>
; __device__ __forceinline__ void gemm_phase(PG8_LAS unsigned char* lds, const Gemm g, const Sched& S, const Epi& E) {
;     ...
;             PG8_WAIT_V(8); PG8_WAIT_L(0); PG8_BAR; PG8_MMA(0, 0, At, B0); PG8_MMA(0, 1, At, B1); PG8_BAR; PG8_SCHED;
;             PG8_LDA(At, 0, 1); PG8_STAGE(PG8_SB(0, 0), b2, voffB); PG8_STAGE(PG8_SB(0, 1), b2 + hstep, voffB); PG8_STAGE(PG8_SA(0, 0), a2, voffA);
;             PG8_WAIT_V(8); PG8_WAIT_L(0); PG8_BAR; PG8_MMA(1, 0, At, B0); PG8_MMA(1, 1, At, B1); PG8_BAR; PG8_SCHED;
;             PG8_LDB(B0, 1, 0); PG8_LDB(B1, 1, 1); PG8_SCHED; PG8_LDA(At, 1, 0); PG8_STAGE(PG8_SA(0, 1), a2 + hstep, voffA);
;             PG8_WAIT_V(8); PG8_WAIT_L(0); PG8_BAR; PG8_MMA(0, 0, At, B0); PG8_MMA(0, 1, At, B1); PG8_BAR; PG8_SCHED;
;             PG8_LDA(At, 1, 1); PG8_STAGE(PG8_SB(1, 0), b3, voffB); PG8_STAGE(PG8_SB(1, 1), b3 + hstep, voffB); PG8_STAGE(PG8_SA(1, 0), a3, voffA);
	s_setprio 1
	v_mfma_f32_16x16x32_bf16 v[60:63], v[138:141], v[200:203], 0
	v_mfma_f32_16x16x32_bf16 v[56:59], v[150:153], v[200:203], 0
	v_mfma_f32_16x16x32_bf16 v[44:47], v[138:141], v[218:221], 0
	v_mfma_f32_16x16x32_bf16 v[40:43], v[150:153], v[218:221], 0
	v_mfma_f32_16x16x32_bf16 v[28:31], v[138:141], v[226:229], 0
	v_mfma_f32_16x16x32_bf16 v[24:27], v[150:153], v[226:229], 0
	v_mfma_f32_16x16x32_bf16 v[12:15], v[138:141], v[234:237], 0
	v_mfma_f32_16x16x32_bf16 v[8:11], v[150:153], v[234:237], 0
	v_mfma_f32_16x16x32_bf16 v[60:63], v[142:145], v[214:217], v[60:63]
	v_mfma_f32_16x16x32_bf16 v[56:59], v[154:157], v[214:217], v[56:59]
	v_mfma_f32_16x16x32_bf16 v[44:47], v[142:145], v[222:225], v[44:47]
	v_mfma_f32_16x16x32_bf16 v[40:43], v[154:157], v[222:225], v[40:43]
	v_mfma_f32_16x16x32_bf16 v[28:31], v[142:145], v[230:233], v[28:31]
	v_mfma_f32_16x16x32_bf16 v[24:27], v[154:157], v[230:233], v[24:27]
	v_mfma_f32_16x16x32_bf16 v[12:15], v[142:145], v[238:241], v[12:15]
	v_mfma_f32_16x16x32_bf16 v[8:11], v[154:157], v[238:241], v[8:11]
	s_setprio 0
	s_setprio 1
	v_mfma_f32_16x16x32_bf16 v[52:55], v[184:187], v[200:203], 0
	v_mfma_f32_16x16x32_bf16 v[48:51], v[192:195], v[200:203], 0
	v_mfma_f32_16x16x32_bf16 v[36:39], v[184:187], v[218:221], 0
	v_mfma_f32_16x16x32_bf16 v[32:35], v[192:195], v[218:221], 0
	v_mfma_f32_16x16x32_bf16 v[20:23], v[184:187], v[226:229], 0
	v_mfma_f32_16x16x32_bf16 v[16:19], v[192:195], v[226:229], 0
	v_mfma_f32_16x16x32_bf16 v[4:7], v[184:187], v[234:237], 0
	v_mfma_f32_16x16x32_bf16 v[0:3], v[192:195], v[234:237], 0
	v_mfma_f32_16x16x32_bf16 v[52:55], v[188:191], v[214:217], v[52:55]
	v_mfma_f32_16x16x32_bf16 v[48:51], v[196:199], v[214:217], v[48:51]
	v_mfma_f32_16x16x32_bf16 v[36:39], v[188:191], v[222:225], v[36:39]
	v_mfma_f32_16x16x32_bf16 v[32:35], v[196:199], v[222:225], v[32:35]
	v_mfma_f32_16x16x32_bf16 v[20:23], v[188:191], v[230:233], v[20:23]
	v_mfma_f32_16x16x32_bf16 v[16:19], v[196:199], v[230:233], v[16:19]
	v_mfma_f32_16x16x32_bf16 v[4:7], v[188:191], v[238:241], v[4:7]
	v_mfma_f32_16x16x32_bf16 v[0:3], v[196:199], v[238:241], v[0:3]
	s_setprio 0
	s_barrier
	s_add_i32 s58, 0, 0x18000
	s_add_i32 s59, 0, 0x1c000
	v_add_u32_e32 v154, s58, v147
	v_add_u32_e32 v196, s59, v147
	ds_read_b128 v[138:141], v154
	ds_read_b128 v[142:145], v154 offset:1024
	ds_read_b128 v[150:153], v154 offset:2048
	ds_read_b128 v[154:157], v154 offset:3072
	ds_read_b128 v[184:187], v196
	ds_read_b128 v[188:191], v196 offset:1024
	ds_read_b128 v[192:195], v196 offset:2048
	ds_read_b128 v[196:199], v196 offset:3072
	s_add_u32 s50, s50, 0x200000
	s_addc_u32 s51, s51, 0
	s_mov_b32 m0, s29
	v_lshl_add_u64 v[246:247], s[50:51], 0, v[128:129]
	ds_read_b128 v[200:203], v149 offset:32768
	ds_read_b128 v[214:217], v149 offset:33792
	ds_read_b128 v[218:221], v149 offset:34816
	ds_read_b128 v[222:225], v149 offset:35840
	ds_read_b128 v[226:229], v149 offset:36864
	ds_read_b128 v[230:233], v149 offset:37888
	ds_read_b128 v[234:237], v149 offset:38912
	ds_read_b128 v[238:241], v149 offset:39936
	global_load_lds_dwordx4 v[246:247], off
	v_lshl_add_u64 v[246:247], s[50:51], 0, v[130:131]
	s_mov_b32 m0, s34
	s_nop 0
	global_load_lds_dwordx4 v[246:247], off
	s_waitcnt vmcnt(8)
	s_waitcnt lgkmcnt(0)
	s_barrier
	s_setprio 1
	v_mfma_f32_16x16x32_bf16 v[124:127], v[138:141], v[200:203], v[124:127]
	v_mfma_f32_16x16x32_bf16 v[120:123], v[150:153], v[200:203], v[120:123]
	v_mfma_f32_16x16x32_bf16 v[108:111], v[138:141], v[218:221], v[108:111]
	v_mfma_f32_16x16x32_bf16 v[104:107], v[150:153], v[218:221], v[104:107]
	v_mfma_f32_16x16x32_bf16 v[92:95], v[138:141], v[226:229], v[92:95]
	v_mfma_f32_16x16x32_bf16 v[88:91], v[150:153], v[226:229], v[88:91]
	v_mfma_f32_16x16x32_bf16 v[76:79], v[138:141], v[234:237], v[76:79]
	v_mfma_f32_16x16x32_bf16 v[72:75], v[150:153], v[234:237], v[72:75]
	v_mfma_f32_16x16x32_bf16 v[124:127], v[142:145], v[214:217], v[124:127]
	v_mfma_f32_16x16x32_bf16 v[120:123], v[154:157], v[214:217], v[120:123]
	v_mfma_f32_16x16x32_bf16 v[108:111], v[142:145], v[222:225], v[108:111]
	v_mfma_f32_16x16x32_bf16 v[104:107], v[154:157], v[222:225], v[104:107]
	v_mfma_f32_16x16x32_bf16 v[92:95], v[142:145], v[230:233], v[92:95]
	v_mfma_f32_16x16x32_bf16 v[88:91], v[154:157], v[230:233], v[88:91]
	v_mfma_f32_16x16x32_bf16 v[76:79], v[142:145], v[238:241], v[76:79]
	v_mfma_f32_16x16x32_bf16 v[72:75], v[154:157], v[238:241], v[72:75]
	s_setprio 0
	s_setprio 1
	v_mfma_f32_16x16x32_bf16 v[116:119], v[184:187], v[200:203], v[116:119]
	v_mfma_f32_16x16x32_bf16 v[112:115], v[192:195], v[200:203], v[112:115]
	v_mfma_f32_16x16x32_bf16 v[100:103], v[184:187], v[218:221], v[100:103]
	v_mfma_f32_16x16x32_bf16 v[96:99], v[192:195], v[218:221], v[96:99]
	v_mfma_f32_16x16x32_bf16 v[84:87], v[184:187], v[226:229], v[84:87]
	v_mfma_f32_16x16x32_bf16 v[80:83], v[192:195], v[226:229], v[80:83]
	v_mfma_f32_16x16x32_bf16 v[68:71], v[184:187], v[234:237], v[68:71]
	v_mfma_f32_16x16x32_bf16 v[64:67], v[192:195], v[234:237], v[64:67]
	v_mfma_f32_16x16x32_bf16 v[116:119], v[188:191], v[214:217], v[116:119]
	v_mfma_f32_16x16x32_bf16 v[112:115], v[196:199], v[214:217], v[112:115]
	v_mfma_f32_16x16x32_bf16 v[100:103], v[188:191], v[222:225], v[100:103]
	v_mfma_f32_16x16x32_bf16 v[96:99], v[196:199], v[222:225], v[96:99]
	v_mfma_f32_16x16x32_bf16 v[84:87], v[188:191], v[230:233], v[84:87]
	v_mfma_f32_16x16x32_bf16 v[80:83], v[196:199], v[230:233], v[80:83]
	v_mfma_f32_16x16x32_bf16 v[68:71], v[188:191], v[238:241], v[68:71]
	v_mfma_f32_16x16x32_bf16 v[64:67], v[196:199], v[238:241], v[64:67]
	s_setprio 0
	s_barrier
; #define PG8_STAGE(bufoff, gbase, voff) do { _Pragma("unroll") for (int _i = 0; _i < 2; ++_i) \
;         __builtin_amdgcn_global_load_lds((const unsigned*)((const char*)(gbase) + (voff)[_i]), (PG8_LAS unsigned*)(lds + (bufoff) + ldsw + _i * 8192), 16, 0, 0); } while (0)
; #define PG8_WAIT_V(n) asm volatile("s_waitcnt vmcnt(" #n ")" ::: "memory")
; #define PG8_WAIT_L(n) asm volatile("s_waitcnt lgkmcnt(" #n ")" ::: "memory")
; #define PG8_BAR __builtin_amdgcn_s_barrier()
; #define PG8_SCHED __builtin_amdgcn_sched_barrier(0)
; template <class Epi, class Sched, bool ALIGN_EPI = false, bool SP2 = false, bool F8 = false>
; __device__ __forceinline__ void gemm_phase(PG8_LAS unsigned char* lds, const Gemm g, const Sched& S, const Epi& E) {
;     ...
;             const bool last = (t == nt - 2);
;             const char* a1 = cA + (size_t)(t + 1) * kstep;
;             const char* a2 = last ? nA : cA + (size_t)(t + 2) * kstep; const char* b2 = last ? nB : cB + (size_t)(t + 2) * kstep;
;             const char* a3 = a2 + kstep; const char* b3 = b2 + kstep;
;             if (last && has_next) S.a_ready(nxt);
;             if constexpr (SP2) {
;             PG8_LDB(B0, 0, 0); PG8_LDB(B1, 0, 1); PG8_SCHED; PG8_LDA(At, 0, 0); PG8_STAGE(PG8_SA(1, 1), a1 + hstep, voffA);
;     ...
;             PG8_LDA(At, 1, 1); PG8_STAGE(PG8_SB(1, 0), b3, voffB); PG8_STAGE(PG8_SB(1, 1), b3 + hstep, voffB); PG8_STAGE(PG8_SA(1, 0), a3, voffA);
;             PG8_WAIT_V(8); PG8_WAIT_L(0); PG8_BAR; PG8_MMA(1, 0, At, B0); PG8_MMA(1, 1, At, B1); PG8_BAR; PG8_SCHED;
	s_add_i32 s50, s58, s22
	v_lshl_add_u64 v[158:159], v[158:159], 0, s[14:15]
	s_mov_b32 m0, s50
	ds_read_b128 v[200:203], v149 offset:49152
	ds_read_b128 v[214:217], v149 offset:50176
	ds_read_b128 v[218:221], v149 offset:51200
	ds_read_b128 v[222:225], v149 offset:52224
	ds_read_b128 v[226:229], v149 offset:53248
	ds_read_b128 v[230:233], v149 offset:54272
	ds_read_b128 v[234:237], v149 offset:55296
	ds_read_b128 v[238:241], v149 offset:56320
	global_load_lds_dwordx4 v[158:159], off
	s_add_i32 m0, s50, 0x2000
	s_add_u32 s48, s48, 0x200080
	v_lshl_add_u64 v[158:159], v[162:163], 0, s[14:15]
	s_addc_u32 s49, s49, 0
	s_add_i32 s50, s59, s22
	global_load_lds_dwordx4 v[158:159], off
	v_lshl_add_u64 v[158:159], s[48:49], 0, v[160:161]
	s_mov_b32 m0, s50
	s_nop 0
	global_load_lds_dwordx4 v[158:159], off
	v_lshl_add_u64 v[158:159], s[48:49], 0, v[132:133]
	s_add_i32 m0, s50, 0x2000
	s_nop 0
	global_load_lds_dwordx4 v[158:159], off
	v_lshl_add_u64 v[158:159], v[242:243], 0, s[14:15]
	s_mov_b32 m0, s8
	s_nop 0
	global_load_lds_dwordx4 v[158:159], off
	v_lshl_add_u64 v[158:159], v[244:245], 0, s[14:15]
	s_mov_b32 m0, s9
	s_nop 0
	global_load_lds_dwordx4 v[158:159], off
	s_waitcnt vmcnt(8)
	s_waitcnt lgkmcnt(0)
	s_barrier
	s_setprio 1
	v_mfma_f32_16x16x32_bf16 v[60:63], v[138:141], v[200:203], v[60:63]
	v_mfma_f32_16x16x32_bf16 v[56:59], v[150:153], v[200:203], v[56:59]
	v_mfma_f32_16x16x32_bf16 v[44:47], v[138:141], v[218:221], v[44:47]
	v_mfma_f32_16x16x32_bf16 v[40:43], v[150:153], v[218:221], v[40:43]
	v_mfma_f32_16x16x32_bf16 v[28:31], v[138:141], v[226:229], v[28:31]
	v_mfma_f32_16x16x32_bf16 v[24:27], v[150:153], v[226:229], v[24:27]
	v_mfma_f32_16x16x32_bf16 v[12:15], v[138:141], v[234:237], v[12:15]
	v_mfma_f32_16x16x32_bf16 v[8:11], v[150:153], v[234:237], v[8:11]
	v_mfma_f32_16x16x32_bf16 v[60:63], v[142:145], v[214:217], v[60:63]
	v_mfma_f32_16x16x32_bf16 v[56:59], v[154:157], v[214:217], v[56:59]
	v_mfma_f32_16x16x32_bf16 v[44:47], v[142:145], v[222:225], v[44:47]
	v_mfma_f32_16x16x32_bf16 v[40:43], v[154:157], v[222:225], v[40:43]
	v_mfma_f32_16x16x32_bf16 v[28:31], v[142:145], v[230:233], v[28:31]
	v_mfma_f32_16x16x32_bf16 v[24:27], v[154:157], v[230:233], v[24:27]
	v_mfma_f32_16x16x32_bf16 v[12:15], v[142:145], v[238:241], v[12:15]
	v_mfma_f32_16x16x32_bf16 v[8:11], v[154:157], v[238:241], v[8:11]
	s_setprio 0
	s_setprio 1
	v_mfma_f32_16x16x32_bf16 v[52:55], v[184:187], v[200:203], v[52:55]
	v_mfma_f32_16x16x32_bf16 v[48:51], v[192:195], v[200:203], v[48:51]
	v_mfma_f32_16x16x32_bf16 v[36:39], v[184:187], v[218:221], v[36:39]
	v_mfma_f32_16x16x32_bf16 v[32:35], v[192:195], v[218:221], v[32:35]
	v_mfma_f32_16x16x32_bf16 v[20:23], v[184:187], v[226:229], v[20:23]
	v_mfma_f32_16x16x32_bf16 v[16:19], v[192:195], v[226:229], v[16:19]
	v_mfma_f32_16x16x32_bf16 v[4:7], v[184:187], v[234:237], v[4:7]
	v_mfma_f32_16x16x32_bf16 v[0:3], v[192:195], v[234:237], v[0:3]
	v_mfma_f32_16x16x32_bf16 v[52:55], v[188:191], v[214:217], v[52:55]
	v_mfma_f32_16x16x32_bf16 v[48:51], v[196:199], v[214:217], v[48:51]
	v_mfma_f32_16x16x32_bf16 v[36:39], v[188:191], v[222:225], v[36:39]
	v_mfma_f32_16x16x32_bf16 v[32:35], v[196:199], v[222:225], v[32:35]
	v_mfma_f32_16x16x32_bf16 v[20:23], v[188:191], v[230:233], v[20:23]
	v_mfma_f32_16x16x32_bf16 v[16:19], v[196:199], v[230:233], v[16:19]
	v_mfma_f32_16x16x32_bf16 v[4:7], v[188:191], v[238:241], v[4:7]
	v_mfma_f32_16x16x32_bf16 v[0:3], v[196:199], v[238:241], v[0:3]
	s_setprio 0
	s_barrier
	s_add_i32 s56, s56, 2
	s_add_u32 s46, s46, 0x100
	s_addc_u32 s47, s47, 0
	s_add_u32 s54, s54, 0x100
	s_addc_u32 s55, s55, 0
	s_cmpk_gt_u32 s56, 0x7d
	s_cbranch_scc0 .LBB0_1148
	s_branch .Lgk_after_1148
.LBB0_1148:
	s_add_u32 s48, s46, 0xffe00080
	s_addc_u32 s49, s47, -1
	s_add_i32 s58, 0, 0x10000
	s_cmpk_eq_i32 s56, 0x7c
	s_cselect_b32 s51, s37, s49
	s_cselect_b32 s50, s52, s48
	s_cselect_b32 s49, s17, s55
	s_cselect_b32 s48, s53, s54
	s_add_i32 s60, 0, 0x14000
	v_add_u32_e32 v154, s58, v147
	v_add_u32_e32 v158, s60, v147
	ds_read_b128 v[138:141], v154
	ds_read_b128 v[142:145], v154 offset:1024
	ds_read_b128 v[150:153], v154 offset:2048
	ds_read_b128 v[154:157], v154 offset:3072
	ds_read_b128 v[184:187], v158
	ds_read_b128 v[188:191], v158 offset:1024
	ds_read_b128 v[192:195], v158 offset:2048
	ds_read_b128 v[196:199], v158 offset:3072
	v_lshl_add_u64 v[158:159], s[46:47], 0, v[134:135]
	s_add_i32 m0, s23, 0xc000
	ds_read_b128 v[200:203], v149
	ds_read_b128 v[214:217], v149 offset:1024
	ds_read_b128 v[218:221], v149 offset:2048
	ds_read_b128 v[222:225], v149 offset:3072
	ds_read_b128 v[226:229], v149 offset:4096
	ds_read_b128 v[230:233], v149 offset:5120
	ds_read_b128 v[234:237], v149 offset:6144
	ds_read_b128 v[238:241], v149 offset:7168
	global_load_lds_dwordx4 v[158:159], off
	v_lshl_add_u64 v[158:159], s[46:47], 0, v[136:137]
	s_add_i32 m0, s23, 0xe000
	s_nop 0
	global_load_lds_dwordx4 v[158:159], off
	s_waitcnt vmcnt(8)
	s_waitcnt lgkmcnt(0)
	s_barrier
; #define PG8_STAGE(bufoff, gbase, voff) do { _Pragma("unroll") for (int _i = 0; _i < 2; ++_i) \
;         __builtin_amdgcn_global_load_lds((const unsigned*)((const char*)(gbase) + (voff)[_i]), (PG8_LAS unsigned*)(lds + (bufoff) + ldsw + _i * 8192), 16, 0, 0); } while (0)
; #define PG8_WAIT_V(n) asm volatile("s_waitcnt vmcnt(" #n ")" ::: "memory")
; #define PG8_WAIT_L(n) asm volatile("s_waitcnt lgkmcnt(" #n ")" ::: "memory")
; #define PG8_BAR __builtin_amdgcn_s_barrier()
; #define PG8_SCHED __builtin_amdgcn_sched_barrier(0)
; template <class Epi, class Sched, bool ALIGN_EPI = false, bool SP2 = false, bool F8 = false>
; __device__ __forceinline__ void gemm_phase(PG8_LAS unsigned char* lds, const Gemm g, const Sched& S, const Epi& E) {
;     ...
;             PG8_WAIT_V(8); PG8_WAIT_L(0); PG8_BAR; PG8_MMA(0, 0, At, B0); PG8_MMA(0, 1, At, B1); PG8_BAR; PG8_SCHED;
;             PG8_LDA(At, 0, 1); PG8_STAGE(PG8_SB(0, 0), b2, voffB); PG8_STAGE(PG8_SB(0, 1), b2 + hstep, voffB); PG8_STAGE(PG8_SA(0, 0), a2, voffA);
;             PG8_WAIT_V(8); PG8_WAIT_L(0); PG8_BAR; PG8_MMA(1, 0, At, B0); PG8_MMA(1, 1, At, B1); PG8_BAR; PG8_SCHED;
	s_setprio 1
	v_mfma_f32_16x16x32_bf16 v[124:127], v[138:141], v[200:203], v[124:127]
	v_mfma_f32_16x16x32_bf16 v[120:123], v[150:153], v[200:203], v[120:123]
	v_mfma_f32_16x16x32_bf16 v[108:111], v[138:141], v[218:221], v[108:111]
	v_mfma_f32_16x16x32_bf16 v[104:107], v[150:153], v[218:221], v[104:107]
	v_mfma_f32_16x16x32_bf16 v[92:95], v[138:141], v[226:229], v[92:95]
	v_mfma_f32_16x16x32_bf16 v[88:91], v[150:153], v[226:229], v[88:91]
	v_mfma_f32_16x16x32_bf16 v[76:79], v[138:141], v[234:237], v[76:79]
	v_mfma_f32_16x16x32_bf16 v[72:75], v[150:153], v[234:237], v[72:75]
	v_mfma_f32_16x16x32_bf16 v[124:127], v[142:145], v[214:217], v[124:127]
	v_mfma_f32_16x16x32_bf16 v[120:123], v[154:157], v[214:217], v[120:123]
	v_mfma_f32_16x16x32_bf16 v[108:111], v[142:145], v[222:225], v[108:111]
	v_mfma_f32_16x16x32_bf16 v[104:107], v[154:157], v[222:225], v[104:107]
	v_mfma_f32_16x16x32_bf16 v[92:95], v[142:145], v[230:233], v[92:95]
	v_mfma_f32_16x16x32_bf16 v[88:91], v[154:157], v[230:233], v[88:91]
	v_mfma_f32_16x16x32_bf16 v[76:79], v[142:145], v[238:241], v[76:79]
	v_mfma_f32_16x16x32_bf16 v[72:75], v[154:157], v[238:241], v[72:75]
	s_setprio 0
	s_setprio 1
	v_mfma_f32_16x16x32_bf16 v[116:119], v[184:187], v[200:203], v[116:119]
	v_mfma_f32_16x16x32_bf16 v[112:115], v[192:195], v[200:203], v[112:115]
	v_mfma_f32_16x16x32_bf16 v[100:103], v[184:187], v[218:221], v[100:103]
	v_mfma_f32_16x16x32_bf16 v[96:99], v[192:195], v[218:221], v[96:99]
	v_mfma_f32_16x16x32_bf16 v[84:87], v[184:187], v[226:229], v[84:87]
	v_mfma_f32_16x16x32_bf16 v[80:83], v[192:195], v[226:229], v[80:83]
	v_mfma_f32_16x16x32_bf16 v[68:71], v[184:187], v[234:237], v[68:71]
	v_mfma_f32_16x16x32_bf16 v[64:67], v[192:195], v[234:237], v[64:67]
	v_mfma_f32_16x16x32_bf16 v[116:119], v[188:191], v[214:217], v[116:119]
	v_mfma_f32_16x16x32_bf16 v[112:115], v[196:199], v[214:217], v[112:115]
	v_mfma_f32_16x16x32_bf16 v[100:103], v[188:191], v[222:225], v[100:103]
	v_mfma_f32_16x16x32_bf16 v[96:99], v[196:199], v[222:225], v[96:99]
	v_mfma_f32_16x16x32_bf16 v[84:87], v[188:191], v[230:233], v[84:87]
	v_mfma_f32_16x16x32_bf16 v[80:83], v[196:199], v[230:233], v[80:83]
	v_mfma_f32_16x16x32_bf16 v[68:71], v[188:191], v[238:241], v[68:71]
	v_mfma_f32_16x16x32_bf16 v[64:67], v[196:199], v[238:241], v[64:67]
	s_setprio 0
	s_barrier
	s_add_i32 s58, s58, s22
	v_lshl_add_u64 v[158:159], s[48:49], 0, v[160:161]
	s_mov_b32 m0, s58
	ds_read_b128 v[200:203], v149 offset:16384
	ds_read_b128 v[214:217], v149 offset:17408
	ds_read_b128 v[218:221], v149 offset:18432
	ds_read_b128 v[222:225], v149 offset:19456
	ds_read_b128 v[226:229], v149 offset:20480
	ds_read_b128 v[230:233], v149 offset:21504
	ds_read_b128 v[234:237], v149 offset:22528
	ds_read_b128 v[238:241], v149 offset:23552
	global_load_lds_dwordx4 v[158:159], off
	s_add_i32 m0, s58, 0x2000
	s_add_u32 s58, s48, 0x200000
	v_lshl_add_u64 v[162:163], s[48:49], 0, v[132:133]
	s_addc_u32 s59, s49, 0
	s_add_i32 s60, s60, s22
	global_load_lds_dwordx4 v[162:163], off
	v_lshl_add_u64 v[242:243], s[58:59], 0, v[160:161]
	s_mov_b32 m0, s60
	v_lshl_add_u64 v[244:245], s[50:51], 0, v[130:131]
	global_load_lds_dwordx4 v[242:243], off
	v_lshl_add_u64 v[242:243], s[58:59], 0, v[132:133]
	s_add_i32 m0, s60, 0x2000
	s_nop 0
	global_load_lds_dwordx4 v[242:243], off
	v_lshl_add_u64 v[242:243], s[50:51], 0, v[128:129]
	s_mov_b32 m0, s23
	s_nop 0
	global_load_lds_dwordx4 v[242:243], off
	s_mov_b32 m0, s28
	s_nop 0
	global_load_lds_dwordx4 v[244:245], off
	s_waitcnt vmcnt(8)
	s_waitcnt lgkmcnt(0)
	s_barrier
	s_setprio 1
	v_mfma_f32_16x16x32_bf16 v[60:63], v[138:141], v[200:203], v[60:63]
	v_mfma_f32_16x16x32_bf16 v[56:59], v[150:153], v[200:203], v[56:59]
	v_mfma_f32_16x16x32_bf16 v[44:47], v[138:141], v[218:221], v[44:47]
	v_mfma_f32_16x16x32_bf16 v[40:43], v[150:153], v[218:221], v[40:43]
	v_mfma_f32_16x16x32_bf16 v[28:31], v[138:141], v[226:229], v[28:31]
	v_mfma_f32_16x16x32_bf16 v[24:27], v[150:153], v[226:229], v[24:27]
	v_mfma_f32_16x16x32_bf16 v[12:15], v[138:141], v[234:237], v[12:15]
	v_mfma_f32_16x16x32_bf16 v[8:11], v[150:153], v[234:237], v[8:11]
	v_mfma_f32_16x16x32_bf16 v[60:63], v[142:145], v[214:217], v[60:63]
	v_mfma_f32_16x16x32_bf16 v[56:59], v[154:157], v[214:217], v[56:59]
	v_mfma_f32_16x16x32_bf16 v[44:47], v[142:145], v[222:225], v[44:47]
	v_mfma_f32_16x16x32_bf16 v[40:43], v[154:157], v[222:225], v[40:43]
	v_mfma_f32_16x16x32_bf16 v[28:31], v[142:145], v[230:233], v[28:31]
	v_mfma_f32_16x16x32_bf16 v[24:27], v[154:157], v[230:233], v[24:27]
	v_mfma_f32_16x16x32_bf16 v[12:15], v[142:145], v[238:241], v[12:15]
	v_mfma_f32_16x16x32_bf16 v[8:11], v[154:157], v[238:241], v[8:11]
	s_setprio 0
	s_setprio 1
	v_mfma_f32_16x16x32_bf16 v[52:55], v[184:187], v[200:203], v[52:55]
	v_mfma_f32_16x16x32_bf16 v[48:51], v[192:195], v[200:203], v[48:51]
	v_mfma_f32_16x16x32_bf16 v[36:39], v[184:187], v[218:221], v[36:39]
	v_mfma_f32_16x16x32_bf16 v[32:35], v[192:195], v[218:221], v[32:35]
	v_mfma_f32_16x16x32_bf16 v[20:23], v[184:187], v[226:229], v[20:23]
	v_mfma_f32_16x16x32_bf16 v[16:19], v[192:195], v[226:229], v[16:19]
	v_mfma_f32_16x16x32_bf16 v[4:7], v[184:187], v[234:237], v[4:7]
	v_mfma_f32_16x16x32_bf16 v[0:3], v[192:195], v[234:237], v[0:3]
	v_mfma_f32_16x16x32_bf16 v[52:55], v[188:191], v[214:217], v[52:55]
	v_mfma_f32_16x16x32_bf16 v[48:51], v[196:199], v[214:217], v[48:51]
	v_mfma_f32_16x16x32_bf16 v[36:39], v[188:191], v[222:225], v[36:39]
	v_mfma_f32_16x16x32_bf16 v[32:35], v[196:199], v[222:225], v[32:35]
	v_mfma_f32_16x16x32_bf16 v[20:23], v[188:191], v[230:233], v[20:23]
	v_mfma_f32_16x16x32_bf16 v[16:19], v[196:199], v[230:233], v[16:19]
	v_mfma_f32_16x16x32_bf16 v[4:7], v[188:191], v[238:241], v[4:7]
	v_mfma_f32_16x16x32_bf16 v[0:3], v[196:199], v[238:241], v[0:3]
	s_setprio 0
	s_barrier
; #define PG8_STAGE(bufoff, gbase, voff) do { _Pragma("unroll") for (int _i = 0; _i < 2; ++_i) \
;         __builtin_amdgcn_global_load_lds((const unsigned*)((const char*)(gbase) + (voff)[_i]), (PG8_LAS unsigned*)(lds + (bufoff) + ldsw + _i * 8192), 16, 0, 0); } while (0)
; #define PG8_WAIT_V(n) asm volatile("s_waitcnt vmcnt(" #n ")" ::: "memory")
; #define PG8_WAIT_L(n) asm volatile("s_waitcnt lgkmcnt(" #n ")" ::: "memory")
; #define PG8_BAR __builtin_amdgcn_s_barrier()
; #define PG8_SCHED __builtin_amdgcn_sched_barrier(0)
; template <class Epi, class Sched, bool ALIGN_EPI = false, bool SP2 = false, bool F8 = false>
; __device__ __forceinline__ void gemm_phase(PG8_LAS unsigned char* lds, const Gemm g, const Sched& S, const Epi& E) {
;     ...
;             PG8_LDB(B0, 1, 0); PG8_LDB(B1, 1, 1); PG8_SCHED; PG8_LDA(At, 1, 0); PG8_STAGE(PG8_SA(0, 1), a2 + hstep, voffA);
;             PG8_WAIT_V(8); PG8_WAIT_L(0); PG8_BAR; PG8_MMA(0, 0, At, B0); PG8_MMA(0, 1, At, B1); PG8_BAR; PG8_SCHED;
	s_add_i32 s58, 0, 0x18000
	s_add_i32 s59, 0, 0x1c000
	v_add_u32_e32 v154, s58, v147
	v_add_u32_e32 v196, s59, v147
	ds_read_b128 v[138:141], v154
	ds_read_b128 v[142:145], v154 offset:1024
	ds_read_b128 v[150:153], v154 offset:2048
	ds_read_b128 v[154:157], v154 offset:3072
	ds_read_b128 v[184:187], v196
	ds_read_b128 v[188:191], v196 offset:1024
	ds_read_b128 v[192:195], v196 offset:2048
	ds_read_b128 v[196:199], v196 offset:3072
	s_add_u32 s50, s50, 0x200000
	s_addc_u32 s51, s51, 0
	s_mov_b32 m0, s29
	v_lshl_add_u64 v[246:247], s[50:51], 0, v[128:129]
	ds_read_b128 v[200:203], v149 offset:32768
	ds_read_b128 v[214:217], v149 offset:33792
	ds_read_b128 v[218:221], v149 offset:34816
	ds_read_b128 v[222:225], v149 offset:35840
	ds_read_b128 v[226:229], v149 offset:36864
	ds_read_b128 v[230:233], v149 offset:37888
	ds_read_b128 v[234:237], v149 offset:38912
	ds_read_b128 v[238:241], v149 offset:39936
	global_load_lds_dwordx4 v[246:247], off
	v_lshl_add_u64 v[246:247], s[50:51], 0, v[130:131]
	s_mov_b32 m0, s34
	s_nop 0
	global_load_lds_dwordx4 v[246:247], off
	s_waitcnt vmcnt(8)
	s_waitcnt lgkmcnt(0)
	s_barrier
	s_setprio 1
	v_mfma_f32_16x16x32_bf16 v[124:127], v[138:141], v[200:203], v[124:127]
	v_mfma_f32_16x16x32_bf16 v[120:123], v[150:153], v[200:203], v[120:123]
	v_mfma_f32_16x16x32_bf16 v[108:111], v[138:141], v[218:221], v[108:111]
	v_mfma_f32_16x16x32_bf16 v[104:107], v[150:153], v[218:221], v[104:107]
	v_mfma_f32_16x16x32_bf16 v[92:95], v[138:141], v[226:229], v[92:95]
	v_mfma_f32_16x16x32_bf16 v[88:91], v[150:153], v[226:229], v[88:91]
	v_mfma_f32_16x16x32_bf16 v[76:79], v[138:141], v[234:237], v[76:79]
	v_mfma_f32_16x16x32_bf16 v[72:75], v[150:153], v[234:237], v[72:75]
	v_mfma_f32_16x16x32_bf16 v[124:127], v[142:145], v[214:217], v[124:127]
	v_mfma_f32_16x16x32_bf16 v[120:123], v[154:157], v[214:217], v[120:123]
	v_mfma_f32_16x16x32_bf16 v[108:111], v[142:145], v[222:225], v[108:111]
	v_mfma_f32_16x16x32_bf16 v[104:107], v[154:157], v[222:225], v[104:107]
	v_mfma_f32_16x16x32_bf16 v[92:95], v[142:145], v[230:233], v[92:95]
	v_mfma_f32_16x16x32_bf16 v[88:91], v[154:157], v[230:233], v[88:91]
	v_mfma_f32_16x16x32_bf16 v[76:79], v[142:145], v[238:241], v[76:79]
	v_mfma_f32_16x16x32_bf16 v[72:75], v[154:157], v[238:241], v[72:75]
	s_setprio 0
	s_setprio 1
	v_mfma_f32_16x16x32_bf16 v[116:119], v[184:187], v[200:203], v[116:119]
	v_mfma_f32_16x16x32_bf16 v[112:115], v[192:195], v[200:203], v[112:115]
	v_mfma_f32_16x16x32_bf16 v[100:103], v[184:187], v[218:221], v[100:103]
	v_mfma_f32_16x16x32_bf16 v[96:99], v[192:195], v[218:221], v[96:99]
	v_mfma_f32_16x16x32_bf16 v[84:87], v[184:187], v[226:229], v[84:87]
	v_mfma_f32_16x16x32_bf16 v[80:83], v[192:195], v[226:229], v[80:83]
	v_mfma_f32_16x16x32_bf16 v[68:71], v[184:187], v[234:237], v[68:71]
	v_mfma_f32_16x16x32_bf16 v[64:67], v[192:195], v[234:237], v[64:67]
	v_mfma_f32_16x16x32_bf16 v[116:119], v[188:191], v[214:217], v[116:119]
	v_mfma_f32_16x16x32_bf16 v[112:115], v[196:199], v[214:217], v[112:115]
	v_mfma_f32_16x16x32_bf16 v[100:103], v[188:191], v[222:225], v[100:103]
	v_mfma_f32_16x16x32_bf16 v[96:99], v[196:199], v[222:225], v[96:99]
	v_mfma_f32_16x16x32_bf16 v[84:87], v[188:191], v[230:233], v[84:87]
	v_mfma_f32_16x16x32_bf16 v[80:83], v[196:199], v[230:233], v[80:83]
	v_mfma_f32_16x16x32_bf16 v[68:71], v[188:191], v[238:241], v[68:71]
	v_mfma_f32_16x16x32_bf16 v[64:67], v[196:199], v[238:241], v[64:67]
	s_setprio 0
	s_barrier
; #define PG8_STAGE(bufoff, gbase, voff) do { _Pragma("unroll") for (int _i = 0; _i < 2; ++_i) \
;         __builtin_amdgcn_global_load_lds((const unsigned*)((const char*)(gbase) + (voff)[_i]), (PG8_LAS unsigned*)(lds + (bufoff) + ldsw + _i * 8192), 16, 0, 0); } while (0)
; #define PG8_WAIT_V(n) asm volatile("s_waitcnt vmcnt(" #n ")" ::: "memory")
; #define PG8_WAIT_L(n) asm volatile("s_waitcnt lgkmcnt(" #n ")" ::: "memory")
; #define PG8_BAR __builtin_amdgcn_s_barrier()
; #define PG8_SCHED __builtin_amdgcn_sched_barrier(0)
; template <class Epi, class Sched, bool ALIGN_EPI = false, bool SP2 = false, bool F8 = false>
; __device__ __forceinline__ void gemm_phase(PG8_LAS unsigned char* lds, const Gemm g, const Sched& S, const Epi& E) {
;     ...
;         for (int t = 0; t < nt; t += 2) {
;     ...
;             PG8_LDA(At, 1, 1); PG8_STAGE(PG8_SB(1, 0), b3, voffB); PG8_STAGE(PG8_SB(1, 1), b3 + hstep, voffB); PG8_STAGE(PG8_SA(1, 0), a3, voffA);
;             PG8_WAIT_V(8); PG8_WAIT_L(0); PG8_BAR; PG8_MMA(1, 0, At, B0); PG8_MMA(1, 1, At, B1); PG8_BAR; PG8_SCHED;
	s_add_i32 s50, s58, s22
	v_lshl_add_u64 v[158:159], v[158:159], 0, s[14:15]
	s_mov_b32 m0, s50
	ds_read_b128 v[200:203], v149 offset:49152
	ds_read_b128 v[214:217], v149 offset:50176
	ds_read_b128 v[218:221], v149 offset:51200
	ds_read_b128 v[222:225], v149 offset:52224
	ds_read_b128 v[226:229], v149 offset:53248
	ds_read_b128 v[230:233], v149 offset:54272
	ds_read_b128 v[234:237], v149 offset:55296
	ds_read_b128 v[238:241], v149 offset:56320
	global_load_lds_dwordx4 v[158:159], off
	s_add_i32 m0, s50, 0x2000
	s_add_u32 s48, s48, 0x200080
	v_lshl_add_u64 v[158:159], v[162:163], 0, s[14:15]
	s_addc_u32 s49, s49, 0
	s_add_i32 s50, s59, s22
	global_load_lds_dwordx4 v[158:159], off
	v_lshl_add_u64 v[158:159], s[48:49], 0, v[160:161]
	s_mov_b32 m0, s50
	s_nop 0
	global_load_lds_dwordx4 v[158:159], off
	v_lshl_add_u64 v[158:159], s[48:49], 0, v[132:133]
	s_add_i32 m0, s50, 0x2000
	s_nop 0
	global_load_lds_dwordx4 v[158:159], off
	v_lshl_add_u64 v[158:159], v[242:243], 0, s[14:15]
	s_mov_b32 m0, s8
	s_nop 0
	global_load_lds_dwordx4 v[158:159], off
	v_lshl_add_u64 v[158:159], v[244:245], 0, s[14:15]
	s_mov_b32 m0, s9
	s_nop 0
	global_load_lds_dwordx4 v[158:159], off
	s_waitcnt vmcnt(8)
	s_waitcnt lgkmcnt(0)
	s_barrier
	s_setprio 1
	v_mfma_f32_16x16x32_bf16 v[60:63], v[138:141], v[200:203], v[60:63]
	v_mfma_f32_16x16x32_bf16 v[56:59], v[150:153], v[200:203], v[56:59]
	v_mfma_f32_16x16x32_bf16 v[44:47], v[138:141], v[218:221], v[44:47]
	v_mfma_f32_16x16x32_bf16 v[40:43], v[150:153], v[218:221], v[40:43]
	v_mfma_f32_16x16x32_bf16 v[28:31], v[138:141], v[226:229], v[28:31]
	v_mfma_f32_16x16x32_bf16 v[24:27], v[150:153], v[226:229], v[24:27]
	v_mfma_f32_16x16x32_bf16 v[12:15], v[138:141], v[234:237], v[12:15]
	v_mfma_f32_16x16x32_bf16 v[8:11], v[150:153], v[234:237], v[8:11]
	v_mfma_f32_16x16x32_bf16 v[60:63], v[142:145], v[214:217], v[60:63]
	v_mfma_f32_16x16x32_bf16 v[56:59], v[154:157], v[214:217], v[56:59]
	v_mfma_f32_16x16x32_bf16 v[44:47], v[142:145], v[222:225], v[44:47]
	v_mfma_f32_16x16x32_bf16 v[40:43], v[154:157], v[222:225], v[40:43]
	v_mfma_f32_16x16x32_bf16 v[28:31], v[142:145], v[230:233], v[28:31]
	v_mfma_f32_16x16x32_bf16 v[24:27], v[154:157], v[230:233], v[24:27]
	v_mfma_f32_16x16x32_bf16 v[12:15], v[142:145], v[238:241], v[12:15]
	v_mfma_f32_16x16x32_bf16 v[8:11], v[154:157], v[238:241], v[8:11]
	s_setprio 0
	s_setprio 1
	v_mfma_f32_16x16x32_bf16 v[52:55], v[184:187], v[200:203], v[52:55]
	v_mfma_f32_16x16x32_bf16 v[48:51], v[192:195], v[200:203], v[48:51]
	v_mfma_f32_16x16x32_bf16 v[36:39], v[184:187], v[218:221], v[36:39]
	v_mfma_f32_16x16x32_bf16 v[32:35], v[192:195], v[218:221], v[32:35]
	v_mfma_f32_16x16x32_bf16 v[20:23], v[184:187], v[226:229], v[20:23]
	v_mfma_f32_16x16x32_bf16 v[16:19], v[192:195], v[226:229], v[16:19]
	v_mfma_f32_16x16x32_bf16 v[4:7], v[184:187], v[234:237], v[4:7]
	v_mfma_f32_16x16x32_bf16 v[0:3], v[192:195], v[234:237], v[0:3]
	v_mfma_f32_16x16x32_bf16 v[52:55], v[188:191], v[214:217], v[52:55]
	v_mfma_f32_16x16x32_bf16 v[48:51], v[196:199], v[214:217], v[48:51]
	v_mfma_f32_16x16x32_bf16 v[36:39], v[188:191], v[222:225], v[36:39]
	v_mfma_f32_16x16x32_bf16 v[32:35], v[196:199], v[222:225], v[32:35]
	v_mfma_f32_16x16x32_bf16 v[20:23], v[188:191], v[230:233], v[20:23]
	v_mfma_f32_16x16x32_bf16 v[16:19], v[196:199], v[230:233], v[16:19]
	v_mfma_f32_16x16x32_bf16 v[4:7], v[188:191], v[238:241], v[4:7]
	v_mfma_f32_16x16x32_bf16 v[0:3], v[196:199], v[238:241], v[0:3]
	s_setprio 0
	s_barrier
	s_add_i32 s56, s56, 2
	s_add_u32 s46, s46, 0x100
	s_addc_u32 s47, s47, 0
	s_add_u32 s54, s54, 0x100
	s_addc_u32 s55, s55, 0
	s_cmpk_gt_u32 s56, 0x7d
	s_cbranch_scc0 .LBB0_1148
